# v2_div_to_rcp
# speedup vs baseline: 1.0420x; 1.0339x over previous
.LBB0_18:
	s_or_b64 exec, exec, s[0:1]
	v_mul_f32_e32 v30, v28, v28
	v_fmamk_f32 v31, v30, 0xb94c1982, v19
	v_fmaak_f32 v31, v30, v31, 0xbe2aaa9d
	v_mul_f32_e32 v31, v30, v31
	v_fmac_f32_e32 v28, v28, v31
	v_fmamk_f32 v31, v30, 0x37d75334, v20
	v_fmaak_f32 v31, v30, v31, 0x3d2aabf7
	v_fmaak_f32 v31, v30, v31, 0xbf000004
	v_fma_f32 v30, v30, v31, 1.0
	v_and_b32_e32 v31, 1, v17
	v_cmp_eq_u32_e32 vcc, 0, v31
	v_lshlrev_b32_e32 v17, 30, v17
	v_xor_b32_e32 v14, v14, v11
	v_cndmask_b32_e32 v28, v30, v28, vcc
	v_cmp_class_f32_e64 vcc, v11, s45
	v_mul_f32_e32 v11, 0x3fb8aa3b, v9
	v_and_b32_e32 v17, 0x80000000, v17
	v_rndne_f32_e32 v11, v11
	v_xor_b32_e32 v14, v14, v17
	v_fmamk_f32 v17, v11, 0xbf317218, v9
	v_fmac_f32_e32 v17, 0x3102e308, v11
	v_xor_b32_e32 v14, v14, v28
	v_fmamk_f32 v28, v17, 0x395133b1, v21
	v_fmaak_f32 v28, v17, v28, 0x3c0887f9
	v_fmaak_f32 v28, v17, v28, 0x3d2aaa81
	v_cvt_i32_f32_e32 v30, v11
	v_fmaak_f32 v28, v17, v28, 0x3e2aaaab
	v_fma_f32 v28, v17, v28, 0.5
	v_mul_f32_e32 v28, v17, v28
	v_cndmask_b32_e32 v14, v24, v14, vcc
	v_fmac_f32_e32 v17, v17, v28
	v_ldexp_f32 v28, 1.0, v30
	v_cmp_eq_f32_e32 vcc, s46, v11
	s_mov_b64 s[0:1], s[78:79]
	s_load_dwordx2 s[4:5], s[0:1], 0x100
	v_cndmask_b32_e32 v11, v28, v25, vcc
	v_add_f32_e32 v28, -1.0, v11
	v_fmac_f32_e32 v28, v11, v17
	s_mov_b64 s[0:1], s[78:79]
	v_add_f32_e32 v11, v28, v28
	s_mov_b64 s[6:7], s[78:79]
	v_cndmask_b32_e32 v11, v28, v11, vcc
	v_cmp_nlt_f32_e32 vcc, s47, v9
	s_load_dwordx2 s[0:1], s[0:1], 0x60
	s_load_dwordx2 s[6:7], s[6:7], 0x68
	v_cndmask_b32_e32 v11, v18, v11, vcc
	v_cmp_ngt_f32_e32 vcc, s48, v9
	v_mul_f32_e32 v28, v16, v16
	v_fmamk_f32 v32, v28, 0xb94c1982, v19
	v_cndmask_b32_e32 v17, -1.0, v11, vcc
	v_ashrrev_i32_e32 v11, 31, v10
	v_lshlrev_b64 v[10:11], 10, v[10:11]
	v_or3_b32 v9, 0, v11, 0
	v_or3_b32 v8, v8, v10, v34
	v_lshlrev_b64 v[10:11], 6, v[8:9]
	s_waitcnt lgkmcnt(0)
	v_lshl_add_u64 v[8:9], s[0:1], 0, v[10:11]
	v_lshl_add_u64 v[10:11], s[6:7], 0, v[10:11]
	global_load_dword v30, v[10:11], off
	global_load_dword v31, v[8:9], off
	v_fmaak_f32 v32, v28, v32, 0xbe2aaa9d
	v_mul_f32_e32 v32, v28, v32
	v_fmac_f32_e32 v16, v16, v32
	v_fmamk_f32 v32, v28, 0x37d75334, v20
	v_fmaak_f32 v32, v28, v32, 0x3d2aabf7
	v_fmaak_f32 v32, v28, v32, 0xbf000004
	v_fma_f32 v28, v28, v32, 1.0
	v_and_b32_e32 v32, 1, v15
	v_cmp_eq_u32_e32 vcc, 0, v32
	v_lshlrev_b32_e32 v15, 30, v15
	v_lshl_add_u64 v[4:5], v[4:5], 2, s[4:5]
	v_cndmask_b32_e64 v16, -v16, v28, vcc
	v_bitop3_b32 v15, v15, v16, s44 bitop3:0x6c
	v_cmp_class_f32_e64 vcc, v12, s45
	v_add_f32_e32 v16, v14, v14
	v_mul_f32_e32 v14, v14, v16
	v_cndmask_b32_e32 v15, v24, v15, vcc
	v_mul_f32_e32 v16, v29, v29
	v_fma_f32 v14, v17, v15, -v14
	v_add_f32_e32 v15, 1.0, v17
	v_fmamk_f32 v17, v16, 0xb94c1982, v19
	v_fmaak_f32 v17, v16, v17, 0xbe2aaa9d
	v_mul_f32_e32 v17, v16, v17
	v_fmac_f32_e32 v29, v29, v17
	v_fmamk_f32 v17, v16, 0x37d75334, v20
	v_fmaak_f32 v17, v16, v17, 0x3d2aabf7
	v_fmaak_f32 v17, v16, v17, 0xbf000004
	v_fma_f32 v16, v16, v17, 1.0
	v_and_b32_e32 v17, 1, v2
	v_lshlrev_b32_e32 v2, 30, v2
	v_cmp_eq_u32_e64 s[0:1], 0, v17
	v_and_b32_e32 v2, 0x80000000, v2
	v_xor_b32_e32 v12, v13, v12
	v_cndmask_b32_e64 v16, v16, v29, s[0:1]
	v_xor_b32_e32 v2, v12, v2
	v_xor_b32_e32 v2, v2, v16
	v_cndmask_b32_e32 v2, v24, v2, vcc
	v_mul_f32_e32 v2, v15, v2
	v_mul_f32_e32 v12, v27, v27
	v_mul_f32_e32 v13, v27, v2
	v_fmac_f32_e32 v12, v26, v26
	v_fmac_f32_e32 v13, v26, v14
	v_mul_f32_e32 v14, v27, v14
	v_fma_f32 v2, v26, v2, -v14
	v_div_scale_f32 v14, s[0:1], v12, v12, v2
	v_rcp_f32_e32 v17, v14
	v_rcp_f32_e32 v15, v12
	s_nop 0
	v_mul_f32_e32 v15, v13, v15
	v_add_u32_e32 v7, s26, v7
	v_fma_f32 v13, -v14, v17, 1.0
	v_fmac_f32_e32 v17, v13, v17
	v_div_scale_f32 v13, vcc, v2, v12, v2
	v_mul_f32_e32 v16, v13, v17
	v_fma_f32 v26, -v14, v16, v13
	v_fmac_f32_e32 v16, v26, v17
	v_fma_f32 v13, -v14, v16, v13
	v_div_fmas_f32 v13, v13, v17, v16
	v_div_fixup_f32 v14, v13, v12, v2
	v_lshlrev_b32_e32 v2, 7, v6
	v_lshl_add_u64 v[4:5], v[4:5], 0, v[2:3]
	v_add_co_u32_e32 v12, vcc, s49, v4
	s_waitcnt vmcnt(1)
	v_mul_f32_e32 v2, v14, v30
	s_waitcnt vmcnt(0)
	v_fma_f32 v2, v15, v31, -v2
	v_addc_co_u32_e32 v13, vcc, 0, v5, vcc
	global_store_dword v[12:13], v2, off
	global_load_dword v2, v[8:9], off
	s_nop 0
	global_load_dword v6, v[10:11], off
	v_lshl_add_u64 v[4:5], v[4:5], 0, s[22:23]
	v_cmp_lt_i32_e32 vcc, s50, v7
	s_or_b64 s[14:15], vcc, s[14:15]
	s_waitcnt vmcnt(1)
	v_mul_f32_e32 v2, v14, v2
	s_waitcnt vmcnt(0)
	v_fmac_f32_e32 v2, v15, v6
	global_store_dword v[4:5], v2, off offset:4
	global_load_dword v2, v[10:11], off offset:4
	s_nop 0
	global_load_dword v6, v[8:9], off offset:4
	s_waitcnt vmcnt(1)
	v_mul_f32_e32 v2, v14, v2
	s_waitcnt vmcnt(0)
	v_fma_f32 v2, v15, v6, -v2
	global_store_dword v[4:5], v2, off offset:8
	global_load_dword v2, v[8:9], off offset:4
	s_nop 0
	global_load_dword v6, v[10:11], off offset:4
	s_waitcnt vmcnt(1)
	v_mul_f32_e32 v2, v14, v2
	s_waitcnt vmcnt(0)
	v_fmac_f32_e32 v2, v15, v6
	global_store_dword v[4:5], v2, off offset:12
	global_load_dword v2, v[10:11], off offset:8
	s_nop 0
	global_load_dword v6, v[8:9], off offset:8
	s_waitcnt vmcnt(1)
	v_mul_f32_e32 v2, v14, v2
	s_waitcnt vmcnt(0)
	v_fma_f32 v2, v15, v6, -v2
	global_store_dword v[4:5], v2, off offset:16
	global_load_dword v2, v[8:9], off offset:8
	s_nop 0
	global_load_dword v6, v[10:11], off offset:8
	s_waitcnt vmcnt(1)
	v_mul_f32_e32 v2, v14, v2
	s_waitcnt vmcnt(0)
	v_fmac_f32_e32 v2, v15, v6
	global_store_dword v[4:5], v2, off offset:20
	global_load_dword v2, v[10:11], off offset:12
	s_nop 0
	global_load_dword v6, v[8:9], off offset:12
	s_waitcnt vmcnt(1)
	v_mul_f32_e32 v2, v14, v2
	s_waitcnt vmcnt(0)
	v_fma_f32 v2, v15, v6, -v2
	global_store_dword v[4:5], v2, off offset:24
	global_load_dword v2, v[8:9], off offset:12
	s_nop 0
	global_load_dword v6, v[10:11], off offset:12
	s_waitcnt vmcnt(1)
	v_mul_f32_e32 v2, v14, v2
	s_waitcnt vmcnt(0)
	v_fmac_f32_e32 v2, v15, v6
	global_store_dword v[4:5], v2, off offset:28
	global_load_dword v2, v[10:11], off offset:16
	s_nop 0
	global_load_dword v6, v[8:9], off offset:16
	s_waitcnt vmcnt(1)
	v_mul_f32_e32 v2, v14, v2
	s_waitcnt vmcnt(0)
	v_fma_f32 v2, v15, v6, -v2
	global_store_dword v[4:5], v2, off offset:32
	global_load_dword v2, v[8:9], off offset:16
	s_nop 0
	global_load_dword v6, v[10:11], off offset:16
	s_waitcnt vmcnt(1)
	v_mul_f32_e32 v2, v14, v2
	s_waitcnt vmcnt(0)
	v_fmac_f32_e32 v2, v15, v6
	global_store_dword v[4:5], v2, off offset:36
	global_load_dword v2, v[10:11], off offset:20
	s_nop 0
	global_load_dword v6, v[8:9], off offset:20
	s_waitcnt vmcnt(1)
	v_mul_f32_e32 v2, v14, v2
	s_waitcnt vmcnt(0)
	v_fma_f32 v2, v15, v6, -v2
	global_store_dword v[4:5], v2, off offset:40
	global_load_dword v2, v[8:9], off offset:20
	s_nop 0
	global_load_dword v6, v[10:11], off offset:20
	s_waitcnt vmcnt(1)
	v_mul_f32_e32 v2, v14, v2
	s_waitcnt vmcnt(0)
	v_fmac_f32_e32 v2, v15, v6
	global_store_dword v[4:5], v2, off offset:44
	global_load_dword v2, v[10:11], off offset:24
	s_nop 0
	global_load_dword v6, v[8:9], off offset:24
	s_waitcnt vmcnt(1)
	v_mul_f32_e32 v2, v14, v2
	s_waitcnt vmcnt(0)
	v_fma_f32 v2, v15, v6, -v2
	global_store_dword v[4:5], v2, off offset:48
	global_load_dword v2, v[8:9], off offset:24
	s_nop 0
	global_load_dword v6, v[10:11], off offset:24
	s_waitcnt vmcnt(1)
	v_mul_f32_e32 v2, v14, v2
	s_waitcnt vmcnt(0)
	v_fmac_f32_e32 v2, v15, v6
	global_store_dword v[4:5], v2, off offset:52
	global_load_dword v2, v[10:11], off offset:28
	s_nop 0
	global_load_dword v6, v[8:9], off offset:28
	s_waitcnt vmcnt(1)
	v_mul_f32_e32 v2, v14, v2
	s_waitcnt vmcnt(0)
	v_fma_f32 v2, v15, v6, -v2
	global_store_dword v[4:5], v2, off offset:56
	global_load_dword v2, v[8:9], off offset:28
	s_nop 0
	global_load_dword v6, v[10:11], off offset:28
	s_waitcnt vmcnt(1)
	v_mul_f32_e32 v2, v14, v2
	s_waitcnt vmcnt(0)
	v_fmac_f32_e32 v2, v15, v6
	global_store_dword v[4:5], v2, off offset:60
	global_load_dword v2, v[10:11], off offset:32
	s_nop 0
	global_load_dword v6, v[8:9], off offset:32
	s_waitcnt vmcnt(1)
	v_mul_f32_e32 v2, v14, v2
	s_waitcnt vmcnt(0)
	v_fma_f32 v2, v15, v6, -v2
	global_store_dword v[4:5], v2, off offset:64
	global_load_dword v2, v[8:9], off offset:32
	s_nop 0
	global_load_dword v6, v[10:11], off offset:32
	s_waitcnt vmcnt(1)
	v_mul_f32_e32 v2, v14, v2
	s_waitcnt vmcnt(0)
	v_fmac_f32_e32 v2, v15, v6
	global_store_dword v[4:5], v2, off offset:68
	global_load_dword v2, v[10:11], off offset:36
	s_nop 0
	global_load_dword v6, v[8:9], off offset:36
	s_waitcnt vmcnt(1)
	v_mul_f32_e32 v2, v14, v2
	s_waitcnt vmcnt(0)
	v_fma_f32 v2, v15, v6, -v2
	global_store_dword v[4:5], v2, off offset:72
	global_load_dword v2, v[8:9], off offset:36
	s_nop 0
	global_load_dword v6, v[10:11], off offset:36
	s_waitcnt vmcnt(1)
	v_mul_f32_e32 v2, v14, v2
	s_waitcnt vmcnt(0)
	v_fmac_f32_e32 v2, v15, v6
	global_store_dword v[4:5], v2, off offset:76
	global_load_dword v2, v[10:11], off offset:40
	s_nop 0
	global_load_dword v6, v[8:9], off offset:40
	s_waitcnt vmcnt(1)
	v_mul_f32_e32 v2, v14, v2
	s_waitcnt vmcnt(0)
	v_fma_f32 v2, v15, v6, -v2
	global_store_dword v[4:5], v2, off offset:80
	global_load_dword v2, v[8:9], off offset:40
	s_nop 0
	global_load_dword v6, v[10:11], off offset:40
	s_waitcnt vmcnt(1)
	v_mul_f32_e32 v2, v14, v2
	s_waitcnt vmcnt(0)
	v_fmac_f32_e32 v2, v15, v6
	global_store_dword v[4:5], v2, off offset:84
	global_load_dword v2, v[10:11], off offset:44
	s_nop 0
	global_load_dword v6, v[8:9], off offset:44
	s_waitcnt vmcnt(1)
	v_mul_f32_e32 v2, v14, v2
	s_waitcnt vmcnt(0)
	v_fma_f32 v2, v15, v6, -v2
	global_store_dword v[4:5], v2, off offset:88
	global_load_dword v2, v[8:9], off offset:44
	s_nop 0
	global_load_dword v6, v[10:11], off offset:44
	s_waitcnt vmcnt(1)
	v_mul_f32_e32 v2, v14, v2
	s_waitcnt vmcnt(0)
	v_fmac_f32_e32 v2, v15, v6
	global_store_dword v[4:5], v2, off offset:92
	global_load_dword v2, v[10:11], off offset:48
	s_nop 0
	global_load_dword v6, v[8:9], off offset:48
	s_waitcnt vmcnt(1)
	v_mul_f32_e32 v2, v14, v2
	s_waitcnt vmcnt(0)
	v_fma_f32 v2, v15, v6, -v2
	global_store_dword v[4:5], v2, off offset:96
	global_load_dword v2, v[8:9], off offset:48
	s_nop 0
	global_load_dword v6, v[10:11], off offset:48
	s_waitcnt vmcnt(1)
	v_mul_f32_e32 v2, v14, v2
	s_waitcnt vmcnt(0)
	v_fmac_f32_e32 v2, v15, v6
	global_store_dword v[4:5], v2, off offset:100
	global_load_dword v2, v[10:11], off offset:52
	s_nop 0
	global_load_dword v6, v[8:9], off offset:52
	s_waitcnt vmcnt(1)
	v_mul_f32_e32 v2, v14, v2
	s_waitcnt vmcnt(0)
	v_fma_f32 v2, v15, v6, -v2
	global_store_dword v[4:5], v2, off offset:104
	global_load_dword v2, v[8:9], off offset:52
	s_nop 0
	global_load_dword v6, v[10:11], off offset:52
	s_waitcnt vmcnt(1)
	v_mul_f32_e32 v2, v14, v2
	s_waitcnt vmcnt(0)
	v_fmac_f32_e32 v2, v15, v6
	global_store_dword v[4:5], v2, off offset:108
	global_load_dword v2, v[10:11], off offset:56
	s_nop 0
	global_load_dword v6, v[8:9], off offset:56
	s_waitcnt vmcnt(1)
	v_mul_f32_e32 v2, v14, v2
	s_waitcnt vmcnt(0)
	v_fma_f32 v2, v15, v6, -v2
	global_store_dword v[4:5], v2, off offset:112
	global_load_dword v2, v[8:9], off offset:56
	s_nop 0
	global_load_dword v6, v[10:11], off offset:56
	s_waitcnt vmcnt(1)
	v_mul_f32_e32 v2, v14, v2
	s_waitcnt vmcnt(0)
	v_fmac_f32_e32 v2, v15, v6
	global_store_dword v[4:5], v2, off offset:116
	global_load_dword v2, v[10:11], off offset:60
	s_nop 0
	global_load_dword v6, v[8:9], off offset:60
	s_waitcnt vmcnt(1)
	v_mul_f32_e32 v2, v14, v2
	s_waitcnt vmcnt(0)
	v_fma_f32 v2, v15, v6, -v2
	global_store_dword v[4:5], v2, off offset:120
	global_load_dword v2, v[8:9], off offset:60
	s_nop 0
	global_load_dword v6, v[10:11], off offset:60
	s_waitcnt vmcnt(1)
	v_mul_f32_e32 v2, v14, v2
	s_waitcnt vmcnt(0)
	v_fmac_f32_e32 v2, v15, v6
	global_store_dword v[4:5], v2, off offset:124
	s_andn2_b64 exec, exec, s[14:15]
	s_cbranch_execz .LBB0_41

.LBB0_44:
	s_or_b64 exec, exec, s[0:1]
	v_lshlrev_b32_e32 v2, 2, v6
	v_and_b32_e32 v2, 0xff0, v2
	v_lshl_add_u64 v[4:5], v[4:5], 0, v[2:3]
	global_load_dwordx4 v[10:13], v[4:5], off
	v_add_u32_e32 v15, 0x200, v7
	v_cmp_lt_i32_e32 vcc, s14, v7
	v_mul_i32_i24_e32 v14, 0x1010, v8
	s_or_b64 s[12:13], vcc, s[12:13]
	v_add3_u32 v2, 0, v14, v2
	v_add_u32_e32 v6, 0x800, v6
	s_waitcnt vmcnt(0)
	v_mul_f32_e32 v7, 0xbfb8aa3b, v12
	v_mul_f32_e32 v9, 0xbfb8aa3b, v13
	v_exp_f32_e32 v8, v7
	v_exp_f32_e32 v9, v9
	v_mul_f32_e32 v4, 0xbfb8aa3b, v10
	v_mul_f32_e32 v5, 0xbfb8aa3b, v11
	v_exp_f32_e32 v4, v4
	v_exp_f32_e32 v5, v5
	v_pk_add_f32 v[8:9], v[8:9], 1.0 op_sel_hi:[1,0]
	v_pk_add_f32 v[4:5], v[4:5], 1.0 op_sel_hi:[1,0]
	v_div_scale_f32 v16, s[0:1], v8, v8, v12
	v_div_scale_f32 v18, s[4:5], v5, v5, v11
	v_rcp_f32_e32 v23, v16
	v_div_scale_f32 v20, s[6:7], v4, v4, v10
	v_rcp_f32_e32 v24, v18
	v_rcp_f32_e32 v25, v20
	v_fma_f32 v27, -v16, v23, 1.0
	v_div_scale_f32 v17, s[0:1], v12, v8, v12
	v_fma_f32 v28, -v18, v24, 1.0
	v_fmac_f32_e32 v23, v27, v23
	v_div_scale_f32 v19, s[4:5], v11, v5, v11
	v_fma_f32 v29, -v20, v25, 1.0
	v_fmac_f32_e32 v24, v28, v24
	v_mul_f32_e32 v27, v17, v23
	v_div_scale_f32 v21, s[6:7], v10, v4, v10
	v_fmac_f32_e32 v25, v29, v25
	v_mul_f32_e32 v28, v19, v24
	v_fma_f32 v31, -v16, v27, v17
	v_mul_f32_e32 v29, v21, v25
	v_fma_f32 v32, -v18, v28, v19
	v_fmac_f32_e32 v27, v31, v23
	v_fma_f32 v33, -v20, v29, v21
	v_fmac_f32_e32 v28, v32, v24
	v_fma_f32 v14, -v16, v27, v17
	s_mov_b64 vcc, s[0:1]
	v_fmac_f32_e32 v29, v33, v25
	v_fma_f32 v16, -v18, v28, v19
	v_rcp_f32_e32 v7, v9
	s_nop 0
	v_mul_f32_e32 v13, v13, v7
	v_div_fmas_f32 v7, v14, v23, v27
	s_mov_b64 vcc, s[4:5]
	v_fma_f32 v17, -v20, v29, v21
	v_div_fixup_f32 v12, v7, v8, v12
	v_div_fmas_f32 v7, v16, v24, v28
	s_mov_b64 vcc, s[6:7]
	v_div_fixup_f32 v11, v7, v5, v11
	v_div_fmas_f32 v5, v17, v25, v29
	v_div_fixup_f32 v10, v5, v4, v10
	v_mov_b32_e32 v7, v15
	ds_write_b128 v2, v[10:13]
	s_andn2_b64 exec, exec, s[12:13]
	s_cbranch_execz .LBB0_49

.LBB0_822:
	s_add_u32 s12, s10, 0x100
	s_addc_u32 s13, s11, 0
	s_add_i32 s42, 0, 0x10000
	v_add_u32_e32 v158, s42, v147
	ds_read_b128 v[142:145], v158
	ds_read_b128 v[150:153], v158 offset:1024
	ds_read_b128 v[154:157], v158 offset:2048
	ds_read_b128 v[158:161], v158 offset:3072
	s_cmp_eq_u32 s41, 8
	s_cselect_b32 s17, s5, s13
	s_cselect_b32 s16, s4, s12
	s_cselect_b32 s15, s7, s40
	s_cselect_b32 s14, s6, s39
	v_lshl_add_u64 v[198:199], s[10:11], 0, v[138:139]
	s_add_i32 m0, s24, 0xc000
	ds_read_b128 v[162:165], v149
	ds_read_b128 v[166:169], v149 offset:1024
	ds_read_b128 v[170:173], v149 offset:2048
	ds_read_b128 v[174:177], v149 offset:3072
	ds_read_b128 v[178:181], v149 offset:4096
	ds_read_b128 v[182:185], v149 offset:5120
	ds_read_b128 v[186:189], v149 offset:6144
	ds_read_b128 v[190:193], v149 offset:7168
	global_load_lds_dwordx4 v[198:199], off
	v_lshl_add_u64 v[198:199], s[10:11], 0, v[140:141]
	s_add_i32 m0, s24, 0xe000
	s_nop 0
	global_load_lds_dwordx4 v[198:199], off
	s_waitcnt lgkmcnt(8)
	s_barrier
	s_waitcnt lgkmcnt(0)
	s_setprio 1
	s_waitcnt lgkmcnt(0)
	v_mfma_f32_16x16x32_bf16 v[126:129], v[142:145], v[162:165], v[126:129]
	v_mfma_f32_16x16x32_bf16 v[122:125], v[154:157], v[162:165], v[122:125]
	v_mfma_f32_16x16x32_bf16 v[110:113], v[142:145], v[170:173], v[110:113]
	v_mfma_f32_16x16x32_bf16 v[106:109], v[154:157], v[170:173], v[106:109]
	v_mfma_f32_16x16x32_bf16 v[94:97], v[142:145], v[178:181], v[94:97]
	v_mfma_f32_16x16x32_bf16 v[90:93], v[154:157], v[178:181], v[90:93]
	v_mfma_f32_16x16x32_bf16 v[78:81], v[142:145], v[186:189], v[78:81]
	v_mfma_f32_16x16x32_bf16 v[74:77], v[154:157], v[186:189], v[74:77]
	v_mfma_f32_16x16x32_bf16 v[126:129], v[150:153], v[166:169], v[126:129]
	v_mfma_f32_16x16x32_bf16 v[122:125], v[158:161], v[166:169], v[122:125]
	v_mfma_f32_16x16x32_bf16 v[110:113], v[150:153], v[174:177], v[110:113]
	v_mfma_f32_16x16x32_bf16 v[106:109], v[158:161], v[174:177], v[106:109]
	v_mfma_f32_16x16x32_bf16 v[94:97], v[150:153], v[182:185], v[94:97]
	v_mfma_f32_16x16x32_bf16 v[90:93], v[158:161], v[182:185], v[90:93]
	v_mfma_f32_16x16x32_bf16 v[78:81], v[150:153], v[190:193], v[78:81]
	v_mfma_f32_16x16x32_bf16 v[74:77], v[158:161], v[190:193], v[74:77]
	s_setprio 0
	s_barrier
	s_add_i32 s43, 0, 0x14000
	s_add_i32 s10, s42, s23
	v_add_u32_e32 v210, s43, v147
	v_lshl_add_u64 v[214:215], s[14:15], 0, v[134:135]
	s_mov_b32 m0, s10
	ds_read_b128 v[198:201], v210
	ds_read_b128 v[202:205], v210 offset:1024
	ds_read_b128 v[206:209], v210 offset:2048
	ds_read_b128 v[210:213], v210 offset:3072
	global_load_lds_dwordx4 v[214:215], off
	v_lshl_add_u64 v[216:217], s[14:15], 0, v[130:131]
	s_add_i32 m0, s10, 0x2000
	s_nop 0
	global_load_lds_dwordx4 v[216:217], off
	s_barrier
	s_waitcnt lgkmcnt(0)
	s_setprio 1
	s_waitcnt lgkmcnt(0)
	v_mfma_f32_16x16x32_bf16 v[118:121], v[198:201], v[162:165], v[118:121]
	v_mfma_f32_16x16x32_bf16 v[114:117], v[206:209], v[162:165], v[114:117]
	v_mfma_f32_16x16x32_bf16 v[102:105], v[198:201], v[170:173], v[102:105]
	v_mfma_f32_16x16x32_bf16 v[98:101], v[206:209], v[170:173], v[98:101]
	v_mfma_f32_16x16x32_bf16 v[86:89], v[198:201], v[178:181], v[86:89]
	v_mfma_f32_16x16x32_bf16 v[82:85], v[206:209], v[178:181], v[82:85]
	v_mfma_f32_16x16x32_bf16 v[70:73], v[198:201], v[186:189], v[70:73]
	v_mfma_f32_16x16x32_bf16 v[66:69], v[206:209], v[186:189], v[66:69]
	v_mfma_f32_16x16x32_bf16 v[118:121], v[202:205], v[166:169], v[118:121]
	v_mfma_f32_16x16x32_bf16 v[114:117], v[210:213], v[166:169], v[114:117]
	v_mfma_f32_16x16x32_bf16 v[102:105], v[202:205], v[174:177], v[102:105]
	v_mfma_f32_16x16x32_bf16 v[98:101], v[210:213], v[174:177], v[98:101]
	v_mfma_f32_16x16x32_bf16 v[86:89], v[202:205], v[182:185], v[86:89]
	v_mfma_f32_16x16x32_bf16 v[82:85], v[210:213], v[182:185], v[82:85]
	v_mfma_f32_16x16x32_bf16 v[70:73], v[202:205], v[190:193], v[70:73]
	v_mfma_f32_16x16x32_bf16 v[66:69], v[210:213], v[190:193], v[66:69]
	s_setprio 0
	s_mov_b32 m0, s24
	v_lshl_add_u64 v[218:219], s[16:17], 0, v[136:137]
	s_barrier
	ds_read_b128 v[162:165], v149 offset:16384
	ds_read_b128 v[166:169], v149 offset:17408
	ds_read_b128 v[170:173], v149 offset:18432
	ds_read_b128 v[174:177], v149 offset:19456
	ds_read_b128 v[178:181], v149 offset:20480
	ds_read_b128 v[182:185], v149 offset:21504
	ds_read_b128 v[186:189], v149 offset:22528
	ds_read_b128 v[190:193], v149 offset:23552
	global_load_lds_dwordx4 v[218:219], off
	v_lshl_add_u64 v[220:221], s[16:17], 0, v[132:133]
	s_mov_b32 m0, s25
	s_nop 0
	global_load_lds_dwordx4 v[220:221], off
	s_barrier
	s_waitcnt lgkmcnt(0)
	s_setprio 1
	s_waitcnt lgkmcnt(0)
	v_mfma_f32_16x16x32_bf16 v[62:65], v[142:145], v[162:165], v[62:65]
	v_mfma_f32_16x16x32_bf16 v[58:61], v[154:157], v[162:165], v[58:61]
	v_mfma_f32_16x16x32_bf16 v[44:47], v[142:145], v[170:173], v[44:47]
	v_mfma_f32_16x16x32_bf16 v[40:43], v[154:157], v[170:173], v[40:43]
	v_mfma_f32_16x16x32_bf16 v[28:31], v[142:145], v[178:181], v[28:31]
	v_mfma_f32_16x16x32_bf16 v[24:27], v[154:157], v[178:181], v[24:27]
	v_mfma_f32_16x16x32_bf16 v[12:15], v[142:145], v[186:189], v[12:15]
	v_mfma_f32_16x16x32_bf16 v[8:11], v[154:157], v[186:189], v[8:11]
	v_mfma_f32_16x16x32_bf16 v[62:65], v[150:153], v[166:169], v[62:65]
	v_mfma_f32_16x16x32_bf16 v[58:61], v[158:161], v[166:169], v[58:61]
	v_mfma_f32_16x16x32_bf16 v[44:47], v[150:153], v[174:177], v[44:47]
	v_mfma_f32_16x16x32_bf16 v[40:43], v[158:161], v[174:177], v[40:43]
	v_mfma_f32_16x16x32_bf16 v[28:31], v[150:153], v[182:185], v[28:31]
	v_mfma_f32_16x16x32_bf16 v[24:27], v[158:161], v[182:185], v[24:27]
	v_mfma_f32_16x16x32_bf16 v[12:15], v[150:153], v[190:193], v[12:15]
	v_mfma_f32_16x16x32_bf16 v[8:11], v[158:161], v[190:193], v[8:11]
	s_setprio 0
	s_barrier
	s_add_u32 s10, s14, 0x30000
	s_addc_u32 s11, s15, 0
	s_add_i32 s42, s43, s23
	v_lshl_add_u64 v[142:143], s[10:11], 0, v[134:135]
	s_mov_b32 m0, s42
	s_nop 0
	global_load_lds_dwordx4 v[142:143], off
	v_lshl_add_u64 v[142:143], s[10:11], 0, v[130:131]
	s_add_i32 m0, s42, 0x2000
	s_nop 0
	global_load_lds_dwordx4 v[142:143], off
	s_waitcnt vmcnt(6)
	s_barrier
	s_setprio 1
	v_mfma_f32_16x16x32_bf16 v[54:57], v[198:201], v[162:165], v[54:57]
	v_mfma_f32_16x16x32_bf16 v[50:53], v[206:209], v[162:165], v[50:53]
	v_mfma_f32_16x16x32_bf16 v[36:39], v[198:201], v[170:173], v[36:39]
	v_mfma_f32_16x16x32_bf16 v[32:35], v[206:209], v[170:173], v[32:35]
	v_mfma_f32_16x16x32_bf16 v[20:23], v[198:201], v[178:181], v[20:23]
	v_mfma_f32_16x16x32_bf16 v[16:19], v[206:209], v[178:181], v[16:19]
	v_mfma_f32_16x16x32_bf16 v[4:7], v[198:201], v[186:189], v[4:7]
	v_mfma_f32_16x16x32_bf16 v[0:3], v[206:209], v[186:189], v[0:3]
	v_mfma_f32_16x16x32_bf16 v[54:57], v[202:205], v[166:169], v[54:57]
	v_mfma_f32_16x16x32_bf16 v[50:53], v[210:213], v[166:169], v[50:53]
	v_mfma_f32_16x16x32_bf16 v[36:39], v[202:205], v[174:177], v[36:39]
	v_mfma_f32_16x16x32_bf16 v[32:35], v[210:213], v[174:177], v[32:35]
	v_mfma_f32_16x16x32_bf16 v[20:23], v[202:205], v[182:185], v[20:23]
	v_mfma_f32_16x16x32_bf16 v[16:19], v[210:213], v[182:185], v[16:19]
	v_mfma_f32_16x16x32_bf16 v[4:7], v[202:205], v[190:193], v[4:7]
	v_mfma_f32_16x16x32_bf16 v[0:3], v[210:213], v[190:193], v[0:3]
	s_setprio 0
	s_add_i32 s42, 0, 0x18000
	v_add_u32_e32 v158, s42, v147
	s_barrier
	ds_read_b128 v[142:145], v158
	ds_read_b128 v[150:153], v158 offset:1024
	ds_read_b128 v[154:157], v158 offset:2048
	ds_read_b128 v[158:161], v158 offset:3072
	s_add_u32 s10, s16, 0x30000
	s_addc_u32 s11, s17, 0
	s_mov_b32 m0, s26
	v_lshl_add_u64 v[198:199], s[10:11], 0, v[136:137]
	ds_read_b128 v[162:165], v149 offset:32768
	ds_read_b128 v[166:169], v149 offset:33792
	ds_read_b128 v[170:173], v149 offset:34816
	ds_read_b128 v[174:177], v149 offset:35840
	ds_read_b128 v[178:181], v149 offset:36864
	ds_read_b128 v[182:185], v149 offset:37888
	ds_read_b128 v[186:189], v149 offset:38912
	ds_read_b128 v[190:193], v149 offset:39936
	global_load_lds_dwordx4 v[198:199], off
	v_lshl_add_u64 v[198:199], s[10:11], 0, v[132:133]
	s_mov_b32 m0, s27
	s_nop 0
	global_load_lds_dwordx4 v[198:199], off
	s_waitcnt lgkmcnt(8)
	s_barrier
	s_waitcnt lgkmcnt(0)
	s_setprio 1
	s_waitcnt lgkmcnt(0)
	v_mfma_f32_16x16x32_bf16 v[126:129], v[142:145], v[162:165], v[126:129]
	v_mfma_f32_16x16x32_bf16 v[122:125], v[154:157], v[162:165], v[122:125]
	v_mfma_f32_16x16x32_bf16 v[110:113], v[142:145], v[170:173], v[110:113]
	v_mfma_f32_16x16x32_bf16 v[106:109], v[154:157], v[170:173], v[106:109]
	v_mfma_f32_16x16x32_bf16 v[94:97], v[142:145], v[178:181], v[94:97]
	v_mfma_f32_16x16x32_bf16 v[90:93], v[154:157], v[178:181], v[90:93]
	v_mfma_f32_16x16x32_bf16 v[78:81], v[142:145], v[186:189], v[78:81]
	v_mfma_f32_16x16x32_bf16 v[74:77], v[154:157], v[186:189], v[74:77]
	v_mfma_f32_16x16x32_bf16 v[126:129], v[150:153], v[166:169], v[126:129]
	v_mfma_f32_16x16x32_bf16 v[122:125], v[158:161], v[166:169], v[122:125]
	v_mfma_f32_16x16x32_bf16 v[110:113], v[150:153], v[174:177], v[110:113]
	v_mfma_f32_16x16x32_bf16 v[106:109], v[158:161], v[174:177], v[106:109]
	v_mfma_f32_16x16x32_bf16 v[94:97], v[150:153], v[182:185], v[94:97]
	v_mfma_f32_16x16x32_bf16 v[90:93], v[158:161], v[182:185], v[90:93]
	v_mfma_f32_16x16x32_bf16 v[78:81], v[150:153], v[190:193], v[78:81]
	v_mfma_f32_16x16x32_bf16 v[74:77], v[158:161], v[190:193], v[74:77]
	s_setprio 0
	s_barrier
	s_add_i32 s16, 0, 0x1c000
	s_add_i32 s10, s42, s23
	v_add_u32_e32 v210, s16, v147
	v_lshl_add_u64 v[214:215], v[214:215], 0, s[66:67]
	s_mov_b32 m0, s10
	ds_read_b128 v[198:201], v210
	ds_read_b128 v[202:205], v210 offset:1024
	ds_read_b128 v[206:209], v210 offset:2048
	ds_read_b128 v[210:213], v210 offset:3072
	global_load_lds_dwordx4 v[214:215], off
	v_lshl_add_u64 v[214:215], v[216:217], 0, s[66:67]
	s_add_i32 m0, s10, 0x2000
	s_nop 0
	global_load_lds_dwordx4 v[214:215], off
	s_barrier
	s_waitcnt lgkmcnt(0)
	s_setprio 1
	s_waitcnt lgkmcnt(0)
	v_mfma_f32_16x16x32_bf16 v[118:121], v[198:201], v[162:165], v[118:121]
	v_mfma_f32_16x16x32_bf16 v[114:117], v[206:209], v[162:165], v[114:117]
	v_mfma_f32_16x16x32_bf16 v[102:105], v[198:201], v[170:173], v[102:105]
	v_mfma_f32_16x16x32_bf16 v[98:101], v[206:209], v[170:173], v[98:101]
	v_mfma_f32_16x16x32_bf16 v[86:89], v[198:201], v[178:181], v[86:89]
	v_mfma_f32_16x16x32_bf16 v[82:85], v[206:209], v[178:181], v[82:85]
	v_mfma_f32_16x16x32_bf16 v[70:73], v[198:201], v[186:189], v[70:73]
	v_mfma_f32_16x16x32_bf16 v[66:69], v[206:209], v[186:189], v[66:69]
	v_mfma_f32_16x16x32_bf16 v[118:121], v[202:205], v[166:169], v[118:121]
	v_mfma_f32_16x16x32_bf16 v[114:117], v[210:213], v[166:169], v[114:117]
	v_mfma_f32_16x16x32_bf16 v[102:105], v[202:205], v[174:177], v[102:105]
	v_mfma_f32_16x16x32_bf16 v[98:101], v[210:213], v[174:177], v[98:101]
	v_mfma_f32_16x16x32_bf16 v[86:89], v[202:205], v[182:185], v[86:89]
	v_mfma_f32_16x16x32_bf16 v[82:85], v[210:213], v[182:185], v[82:85]
	v_mfma_f32_16x16x32_bf16 v[70:73], v[202:205], v[190:193], v[70:73]
	v_mfma_f32_16x16x32_bf16 v[66:69], v[210:213], v[190:193], v[66:69]
	s_setprio 0
	s_mov_b32 m0, s28
	v_lshl_add_u64 v[214:215], v[218:219], 0, s[66:67]
	s_barrier
	ds_read_b128 v[162:165], v149 offset:49152
	ds_read_b128 v[166:169], v149 offset:50176
	ds_read_b128 v[170:173], v149 offset:51200
	ds_read_b128 v[174:177], v149 offset:52224
	ds_read_b128 v[178:181], v149 offset:53248
	ds_read_b128 v[182:185], v149 offset:54272
	ds_read_b128 v[186:189], v149 offset:55296
	ds_read_b128 v[190:193], v149 offset:56320
	global_load_lds_dwordx4 v[214:215], off
	v_lshl_add_u64 v[214:215], v[220:221], 0, s[66:67]
	s_mov_b32 m0, s29
	s_nop 0
	global_load_lds_dwordx4 v[214:215], off
	s_barrier
	s_waitcnt lgkmcnt(0)
	s_setprio 1
	s_waitcnt lgkmcnt(0)
	v_mfma_f32_16x16x32_bf16 v[62:65], v[142:145], v[162:165], v[62:65]
	v_mfma_f32_16x16x32_bf16 v[58:61], v[154:157], v[162:165], v[58:61]
	v_mfma_f32_16x16x32_bf16 v[44:47], v[142:145], v[170:173], v[44:47]
	v_mfma_f32_16x16x32_bf16 v[40:43], v[154:157], v[170:173], v[40:43]
	v_mfma_f32_16x16x32_bf16 v[28:31], v[142:145], v[178:181], v[28:31]
	v_mfma_f32_16x16x32_bf16 v[24:27], v[154:157], v[178:181], v[24:27]
	v_mfma_f32_16x16x32_bf16 v[12:15], v[142:145], v[186:189], v[12:15]
	v_mfma_f32_16x16x32_bf16 v[8:11], v[154:157], v[186:189], v[8:11]
	v_mfma_f32_16x16x32_bf16 v[62:65], v[150:153], v[166:169], v[62:65]
	v_mfma_f32_16x16x32_bf16 v[58:61], v[158:161], v[166:169], v[58:61]
	v_mfma_f32_16x16x32_bf16 v[44:47], v[150:153], v[174:177], v[44:47]
	v_mfma_f32_16x16x32_bf16 v[40:43], v[158:161], v[174:177], v[40:43]
	v_mfma_f32_16x16x32_bf16 v[28:31], v[150:153], v[182:185], v[28:31]
	v_mfma_f32_16x16x32_bf16 v[24:27], v[158:161], v[182:185], v[24:27]
	v_mfma_f32_16x16x32_bf16 v[12:15], v[150:153], v[190:193], v[12:15]
	v_mfma_f32_16x16x32_bf16 v[8:11], v[158:161], v[190:193], v[8:11]
	s_setprio 0
	s_barrier
	s_add_u32 s10, s14, 0x30080
	s_addc_u32 s11, s15, 0
	s_add_i32 s14, s16, s23
	v_lshl_add_u64 v[142:143], s[10:11], 0, v[134:135]
	s_mov_b32 m0, s14
	s_nop 0
	global_load_lds_dwordx4 v[142:143], off
	v_lshl_add_u64 v[142:143], s[10:11], 0, v[130:131]
	s_add_i32 m0, s14, 0x2000
	s_nop 0
	global_load_lds_dwordx4 v[142:143], off
	s_waitcnt vmcnt(6)
	s_barrier
	s_setprio 1
	v_mfma_f32_16x16x32_bf16 v[54:57], v[198:201], v[162:165], v[54:57]
	v_mfma_f32_16x16x32_bf16 v[50:53], v[206:209], v[162:165], v[50:53]
	v_mfma_f32_16x16x32_bf16 v[36:39], v[198:201], v[170:173], v[36:39]
	v_mfma_f32_16x16x32_bf16 v[32:35], v[206:209], v[170:173], v[32:35]
	v_mfma_f32_16x16x32_bf16 v[20:23], v[198:201], v[178:181], v[20:23]
	v_mfma_f32_16x16x32_bf16 v[16:19], v[206:209], v[178:181], v[16:19]
	v_mfma_f32_16x16x32_bf16 v[4:7], v[198:201], v[186:189], v[4:7]
	v_mfma_f32_16x16x32_bf16 v[0:3], v[206:209], v[186:189], v[0:3]
	v_mfma_f32_16x16x32_bf16 v[54:57], v[202:205], v[166:169], v[54:57]
	v_mfma_f32_16x16x32_bf16 v[50:53], v[210:213], v[166:169], v[50:53]
	v_mfma_f32_16x16x32_bf16 v[36:39], v[202:205], v[174:177], v[36:39]
	v_mfma_f32_16x16x32_bf16 v[32:35], v[210:213], v[174:177], v[32:35]
	v_mfma_f32_16x16x32_bf16 v[20:23], v[202:205], v[182:185], v[20:23]
	v_mfma_f32_16x16x32_bf16 v[16:19], v[210:213], v[182:185], v[16:19]
	v_mfma_f32_16x16x32_bf16 v[4:7], v[202:205], v[190:193], v[4:7]
	v_mfma_f32_16x16x32_bf16 v[0:3], v[210:213], v[190:193], v[0:3]
	s_setprio 0
	s_add_i32 s41, s41, 2
	s_add_u32 s39, s39, 0x100
	s_addc_u32 s40, s40, 0
	s_cmp_gt_u32 s41, 9
	s_mov_b64 s[10:11], s[12:13]
	s_barrier
	s_cbranch_scc0 .LBB0_822
	v_lshl_add_u32 v142, s38, 8, v146
	v_ashrrev_i32_e32 v143, 31, v142
	v_lshlrev_b64 v[144:145], 14, v[142:143]
	v_mul_f32_e32 v143, 0x3d372713, v126
	v_mul_f32_e32 v143, v126, v143
	v_fma_f32 v143, v126, v143, v126
	v_mul_f32_e32 v143, 0xbfcc422a, v143
	v_mul_f32_e32 v143, 0x3fb8aa3b, v143
	v_exp_f32_e32 v150, v143
	v_mul_f32_e32 v143, 0x3d372713, v122
	v_mul_f32_e32 v143, v122, v143
	v_fma_f32 v143, v122, v143, v122
	v_mul_f32_e32 v143, 0xbfcc422a, v143
	v_mul_f32_e32 v143, 0x3fb8aa3b, v143
	v_exp_f32_e32 v152, v143
	v_mul_f32_e32 v143, 0x3d372713, v127
	v_mul_f32_e32 v143, v127, v143
	v_fma_f32 v143, v127, v143, v127
	v_mul_f32_e32 v143, 0xbfcc422a, v143
	v_mul_f32_e32 v143, 0x3fb8aa3b, v143
	v_exp_f32_e32 v151, v143
	v_lshl_or_b32 v154, s37, 8, v148
	s_lshl_b32 s10, s36, 4
	s_ashr_i32 s11, s10, 31
	v_pk_add_f32 v[150:151], v[150:151], 1.0 op_sel_hi:[1,0]
	s_lshl_b64 s[10:11], s[10:11], 1
	s_mov_b32 s36, s31
	s_mov_b32 s37, s35
	s_mov_b32 s38, s34
	v_rcp_f32_e32 v143, v151
	s_nop 0
	v_mul_f32_e32 v143, v127, v143
	s_nop 0
	v_rcp_f32_e32 v127, v150
	s_nop 0
	v_mul_f32_e32 v150, v126, v127
	v_mul_f32_e32 v126, 0x3d372713, v123
	v_mul_f32_e32 v126, v123, v126
	v_fma_f32 v126, v123, v126, v123
	v_mul_f32_e32 v126, 0xbfcc422a, v126
	v_mul_f32_e32 v126, 0x3fb8aa3b, v126
	v_exp_f32_e32 v153, v126
	v_cvt_pk_bf16_f32 v150, v150, v143
	v_pk_add_f32 v[126:127], v[152:153], 1.0 op_sel_hi:[1,0]
	s_nop 0
	s_nop 0
	v_rcp_f32_e32 v151, v127
	s_nop 0
	v_mul_f32_e32 v152, v123, v151
	s_nop 0
	v_rcp_f32_e32 v123, v126
	s_nop 0
	v_mul_f32_e32 v153, v122, v123
	v_mul_f32_e32 v123, 0x3d372713, v124
	v_mul_f32_e32 v123, v124, v123
	v_fma_f32 v123, v124, v123, v124
	v_mul_f32_e32 v123, 0xbfcc422a, v123
	v_mul_f32_e32 v123, 0x3fb8aa3b, v123
	v_mul_f32_e32 v122, 0x3d372713, v128
	v_exp_f32_e32 v126, v123
	v_mul_f32_e32 v123, 0x3d372713, v129
	v_mul_f32_e32 v122, v128, v122
	v_mul_f32_e32 v123, v129, v123
	v_fma_f32 v122, v128, v122, v128
	v_fma_f32 v123, v129, v123, v129
	v_mul_f32_e32 v122, 0xbfcc422a, v122
	v_mul_f32_e32 v123, 0xbfcc422a, v123
	v_mul_f32_e32 v122, 0x3fb8aa3b, v122
	v_mul_f32_e32 v123, 0x3fb8aa3b, v123
	v_exp_f32_e32 v122, v122
	v_exp_f32_e32 v123, v123
	v_cvt_pk_bf16_f32 v152, v153, v152
	v_pk_add_f32 v[122:123], v[122:123], 1.0 op_sel_hi:[1,0]
	s_nop 0
	s_nop 0
	v_rcp_f32_e32 v127, v123
	s_nop 0
	v_mul_f32_e32 v129, v129, v127
	s_nop 0
	v_rcp_f32_e32 v123, v122
	s_nop 0
	v_mul_f32_e32 v128, v128, v123
	v_mul_f32_e32 v122, 0x3d372713, v125
	v_mul_f32_e32 v122, v125, v122
	v_fma_f32 v122, v125, v122, v125
	v_mul_f32_e32 v122, 0xbfcc422a, v122
	v_mul_f32_e32 v122, 0x3fb8aa3b, v122
	v_exp_f32_e32 v127, v122
	s_nop 0
	v_pk_add_f32 v[122:123], v[126:127], 1.0 op_sel_hi:[1,0]
	s_nop 0
	s_nop 0
	v_rcp_f32_e32 v126, v123
	s_nop 0
	v_mul_f32_e32 v123, v125, v126
	v_div_scale_f32 v125, s[12:13], v122, v122, v124
	v_rcp_f32_e32 v126, v125
	s_nop 0
	v_fma_f32 v127, -v125, v126, 1.0
	v_fmac_f32_e32 v126, v127, v126
	v_div_scale_f32 v127, vcc, v124, v122, v124
	v_mul_f32_e32 v151, v127, v126
	v_fma_f32 v155, -v125, v151, v127
	v_fmac_f32_e32 v151, v155, v126
	v_fma_f32 v125, -v125, v151, v127
	v_div_fmas_f32 v125, v125, v126, v151
	v_ashrrev_i32_e32 v126, 4, v154
	v_ashrrev_i32_e32 v127, 31, v126
	v_div_fixup_f32 v122, v125, v122, v124
	v_lshlrev_b64 v[124:125], 9, v[126:127]
	v_mul_f32_e32 v127, 0x3d372713, v118
	v_cvt_pk_bf16_f32 v153, v122, v123
	v_lshl_add_u64 v[122:123], s[0:1], 0, v[144:145]
	v_mul_f32_e32 v127, v118, v127
	v_cvt_pk_bf16_f32 v151, v128, v129
	v_lshl_add_u64 v[128:129], v[122:123], 0, v[124:125]
	v_fma_f32 v127, v118, v127, v118
	v_lshl_add_u64 v[128:129], v[128:129], 0, s[10:11]
	v_mul_f32_e32 v127, 0xbfcc422a, v127
	v_lshl_add_u64 v[128:129], v[128:129], 0, v[48:49]
	v_mul_f32_e32 v127, 0x3fb8aa3b, v127
	global_store_dwordx4 v[128:129], v[150:153], off
	v_exp_f32_e32 v128, v127
	v_mul_f32_e32 v127, 0x3d372713, v114
	v_mul_f32_e32 v127, v114, v127
	v_fma_f32 v127, v114, v127, v114
	v_mul_f32_e32 v127, 0xbfcc422a, v127
	v_mul_f32_e32 v127, 0x3fb8aa3b, v127
	v_exp_f32_e32 v144, v127
	v_mul_f32_e32 v127, 0x3d372713, v119
	v_mul_f32_e32 v127, v119, v127
	v_fma_f32 v127, v119, v127, v119
	v_mul_f32_e32 v127, 0xbfcc422a, v127
	v_mul_f32_e32 v127, 0x3fb8aa3b, v127
	v_exp_f32_e32 v129, v127
	s_nop 0
	v_pk_add_f32 v[128:129], v[128:129], 1.0 op_sel_hi:[1,0]
	s_nop 0
	s_nop 0
	v_rcp_f32_e32 v127, v129
	s_nop 0
	v_mul_f32_e32 v127, v119, v127
	s_nop 0
	v_rcp_f32_e32 v119, v128
	s_nop 0
	v_mul_f32_e32 v128, v118, v119
	v_mul_f32_e32 v118, 0x3d372713, v115
	v_mul_f32_e32 v118, v115, v118
	v_fma_f32 v118, v115, v118, v115
	v_mul_f32_e32 v118, 0xbfcc422a, v118
	v_mul_f32_e32 v118, 0x3fb8aa3b, v118
	v_exp_f32_e32 v145, v118
	s_nop 0
	v_pk_add_f32 v[118:119], v[144:145], 1.0 op_sel_hi:[1,0]
	s_nop 0
	s_nop 0
	v_rcp_f32_e32 v129, v119
	s_nop 0
	v_mul_f32_e32 v129, v115, v129
	s_nop 0
	v_rcp_f32_e32 v115, v118
	s_nop 0
	v_mul_f32_e32 v143, v114, v115
	v_mul_f32_e32 v115, 0x3d372713, v116
	v_mul_f32_e32 v115, v116, v115
	v_fma_f32 v115, v116, v115, v116
	v_mul_f32_e32 v115, 0xbfcc422a, v115
	v_mul_f32_e32 v115, 0x3fb8aa3b, v115
	v_mul_f32_e32 v114, 0x3d372713, v120
	v_exp_f32_e32 v118, v115
	v_mul_f32_e32 v115, 0x3d372713, v121
	v_mul_f32_e32 v114, v120, v114
	v_mul_f32_e32 v115, v121, v115
	v_fma_f32 v114, v120, v114, v120
	v_fma_f32 v115, v121, v115, v121
	v_mul_f32_e32 v114, 0xbfcc422a, v114
	v_mul_f32_e32 v115, 0xbfcc422a, v115
	v_mul_f32_e32 v114, 0x3fb8aa3b, v114
	v_mul_f32_e32 v115, 0x3fb8aa3b, v115
	v_exp_f32_e32 v114, v114
	v_exp_f32_e32 v115, v115
	s_nop 0
	v_pk_add_f32 v[114:115], v[114:115], 1.0 op_sel_hi:[1,0]
	s_nop 0
	s_nop 0
	v_rcp_f32_e32 v119, v115
	s_nop 0
	v_mul_f32_e32 v121, v121, v119
	s_nop 0
	v_rcp_f32_e32 v115, v114
	s_nop 0
	v_mul_f32_e32 v120, v120, v115
	v_mul_f32_e32 v114, 0x3d372713, v117
	v_mul_f32_e32 v114, v117, v114
	v_fma_f32 v114, v117, v114, v117
	v_mul_f32_e32 v114, 0xbfcc422a, v114
	v_mul_f32_e32 v114, 0x3fb8aa3b, v114
	v_exp_f32_e32 v119, v114
	s_nop 0
	v_pk_add_f32 v[114:115], v[118:119], 1.0 op_sel_hi:[1,0]
	s_nop 0
	s_nop 0
	v_rcp_f32_e32 v118, v115
	s_nop 0
	v_mul_f32_e32 v115, v117, v118
	s_nop 0
	v_rcp_f32_e32 v117, v114
	s_nop 0
	v_mul_f32_e32 v119, v116, v117
	v_or_b32_e32 v114, 8, v126
	v_cvt_pk_bf16_f32 v119, v119, v115
	v_ashrrev_i32_e32 v115, 31, v114
	v_lshlrev_b64 v[114:115], 9, v[114:115]
	v_cvt_pk_bf16_f32 v117, v120, v121
	v_lshl_add_u64 v[120:121], v[122:123], 0, v[114:115]
	v_lshl_add_u64 v[120:121], v[120:121], 0, s[10:11]
	v_cvt_pk_bf16_f32 v116, v128, v127
	v_cvt_pk_bf16_f32 v118, v143, v129
	v_lshl_add_u64 v[120:121], v[120:121], 0, v[48:49]
	global_store_dwordx4 v[120:121], v[116:119], off
	s_nop 1
	v_mul_f32_e32 v119, 0x3d372713, v106
	v_mul_f32_e32 v119, v106, v119
	v_fma_f32 v119, v106, v119, v106
	v_mul_f32_e32 v119, 0xbfcc422a, v119
	v_mul_f32_e32 v119, 0x3fb8aa3b, v119
	v_mul_f32_e32 v118, 0x3d372713, v110
	v_exp_f32_e32 v120, v119
	v_mul_f32_e32 v119, 0x3d372713, v111
	v_mul_f32_e32 v118, v110, v118
	v_mul_f32_e32 v119, v111, v119
	v_fma_f32 v118, v110, v118, v110
	v_fma_f32 v119, v111, v119, v111
	v_mul_f32_e32 v118, 0xbfcc422a, v118
	v_mul_f32_e32 v119, 0xbfcc422a, v119
	v_mul_f32_e32 v118, 0x3fb8aa3b, v118
	v_mul_f32_e32 v119, 0x3fb8aa3b, v119
	v_exp_f32_e32 v118, v118
	v_exp_f32_e32 v119, v119
	v_or_b32_e32 v116, 16, v142
	v_ashrrev_i32_e32 v117, 31, v116
	v_lshlrev_b64 v[116:117], 14, v[116:117]
	v_pk_add_f32 v[118:119], v[118:119], 1.0 op_sel_hi:[1,0]
	s_nop 0
	s_nop 0
	v_rcp_f32_e32 v121, v119
	s_nop 0
	v_mul_f32_e32 v119, v111, v121
	s_nop 0
	v_rcp_f32_e32 v111, v118
	s_nop 0
	v_mul_f32_e32 v118, v110, v111
	v_mul_f32_e32 v110, 0x3d372713, v107
	v_mul_f32_e32 v110, v107, v110
	v_fma_f32 v110, v107, v110, v107
	v_mul_f32_e32 v110, 0xbfcc422a, v110
	v_mul_f32_e32 v110, 0x3fb8aa3b, v110
	v_exp_f32_e32 v121, v110
	s_nop 0
	v_pk_add_f32 v[110:111], v[120:121], 1.0 op_sel_hi:[1,0]
	s_nop 0
	s_nop 0
	v_rcp_f32_e32 v120, v111
	s_nop 0
	v_mul_f32_e32 v120, v107, v120
	s_nop 0
	v_rcp_f32_e32 v107, v110
	s_nop 0
	v_mul_f32_e32 v121, v106, v107
	v_mul_f32_e32 v107, 0x3d372713, v108
	v_mul_f32_e32 v107, v108, v107
	v_fma_f32 v107, v108, v107, v108
	v_mul_f32_e32 v107, 0xbfcc422a, v107
	v_mul_f32_e32 v107, 0x3fb8aa3b, v107
	v_mul_f32_e32 v106, 0x3d372713, v112
	v_exp_f32_e32 v110, v107
	v_mul_f32_e32 v107, 0x3d372713, v113
	v_mul_f32_e32 v106, v112, v106
	v_mul_f32_e32 v107, v113, v107
	v_fma_f32 v106, v112, v106, v112
	v_fma_f32 v107, v113, v107, v113
	v_mul_f32_e32 v106, 0xbfcc422a, v106
	v_mul_f32_e32 v107, 0xbfcc422a, v107
	v_mul_f32_e32 v106, 0x3fb8aa3b, v106
	v_mul_f32_e32 v107, 0x3fb8aa3b, v107
	v_exp_f32_e32 v106, v106
	v_exp_f32_e32 v107, v107
	s_nop 0
	v_pk_add_f32 v[106:107], v[106:107], 1.0 op_sel_hi:[1,0]
	s_nop 0
	s_nop 0
	v_rcp_f32_e32 v111, v107
	s_nop 0
	v_mul_f32_e32 v113, v113, v111
	s_nop 0
	v_rcp_f32_e32 v107, v106
	s_nop 0
	v_mul_f32_e32 v112, v112, v107
	v_mul_f32_e32 v106, 0x3d372713, v109
	v_mul_f32_e32 v106, v109, v106
	v_fma_f32 v106, v109, v106, v109
	v_mul_f32_e32 v106, 0xbfcc422a, v106
	v_mul_f32_e32 v106, 0x3fb8aa3b, v106
	v_exp_f32_e32 v111, v106
	s_nop 0
	v_pk_add_f32 v[106:107], v[110:111], 1.0 op_sel_hi:[1,0]
	s_nop 0
	s_nop 0
	v_rcp_f32_e32 v110, v107
	s_nop 0
	v_mul_f32_e32 v107, v109, v110
	s_nop 0
	v_rcp_f32_e32 v109, v106
	s_nop 0
	v_mul_f32_e32 v106, v108, v109
	v_cvt_pk_bf16_f32 v111, v106, v107
	v_lshl_add_u64 v[106:107], s[0:1], 0, v[116:117]
	v_cvt_pk_bf16_f32 v109, v112, v113
	v_lshl_add_u64 v[112:113], v[106:107], 0, v[124:125]
	v_lshl_add_u64 v[112:113], v[112:113], 0, s[10:11]
	v_cvt_pk_bf16_f32 v108, v118, v119
	v_cvt_pk_bf16_f32 v110, v121, v120
	v_lshl_add_u64 v[112:113], v[112:113], 0, v[48:49]
	global_store_dwordx4 v[112:113], v[108:111], off
	s_nop 1
	v_mul_f32_e32 v109, 0x3d372713, v98
	v_mul_f32_e32 v109, v98, v109
	v_fma_f32 v109, v98, v109, v98
	v_mul_f32_e32 v109, 0xbfcc422a, v109
	v_mul_f32_e32 v109, 0x3fb8aa3b, v109
	v_mul_f32_e32 v108, 0x3d372713, v102
	v_exp_f32_e32 v110, v109
	v_mul_f32_e32 v109, 0x3d372713, v103
	v_mul_f32_e32 v108, v102, v108
	v_mul_f32_e32 v109, v103, v109
	v_fma_f32 v108, v102, v108, v102
	v_fma_f32 v109, v103, v109, v103
	v_mul_f32_e32 v108, 0xbfcc422a, v108
	v_mul_f32_e32 v109, 0xbfcc422a, v109
	v_mul_f32_e32 v108, 0x3fb8aa3b, v108
	v_mul_f32_e32 v109, 0x3fb8aa3b, v109
	v_exp_f32_e32 v108, v108
	v_exp_f32_e32 v109, v109
	s_nop 0
	v_pk_add_f32 v[108:109], v[108:109], 1.0 op_sel_hi:[1,0]
	s_nop 0
	s_nop 0
	v_rcp_f32_e32 v111, v109
	s_nop 0
	v_mul_f32_e32 v109, v103, v111
	s_nop 0
	v_rcp_f32_e32 v103, v108
	s_nop 0
	v_mul_f32_e32 v108, v102, v103
	v_mul_f32_e32 v102, 0x3d372713, v99
	v_mul_f32_e32 v102, v99, v102
	v_fma_f32 v102, v99, v102, v99
	v_mul_f32_e32 v102, 0xbfcc422a, v102
	v_mul_f32_e32 v102, 0x3fb8aa3b, v102
	v_exp_f32_e32 v111, v102
	s_nop 0
	v_pk_add_f32 v[102:103], v[110:111], 1.0 op_sel_hi:[1,0]
	s_nop 0
	s_nop 0
	v_rcp_f32_e32 v110, v103
	s_nop 0
	v_mul_f32_e32 v110, v99, v110
	s_nop 0
	v_rcp_f32_e32 v99, v102
	s_nop 0
	v_mul_f32_e32 v111, v98, v99
	v_mul_f32_e32 v99, 0x3d372713, v100
	v_mul_f32_e32 v99, v100, v99
	v_fma_f32 v99, v100, v99, v100
	v_mul_f32_e32 v99, 0xbfcc422a, v99
	v_mul_f32_e32 v99, 0x3fb8aa3b, v99
	v_mul_f32_e32 v98, 0x3d372713, v104
	v_exp_f32_e32 v102, v99
	v_mul_f32_e32 v99, 0x3d372713, v105
	v_mul_f32_e32 v98, v104, v98
	v_mul_f32_e32 v99, v105, v99
	v_fma_f32 v98, v104, v98, v104
	v_fma_f32 v99, v105, v99, v105
	v_mul_f32_e32 v98, 0xbfcc422a, v98
	v_mul_f32_e32 v99, 0xbfcc422a, v99
	v_mul_f32_e32 v98, 0x3fb8aa3b, v98
	v_mul_f32_e32 v99, 0x3fb8aa3b, v99
	v_exp_f32_e32 v98, v98
	v_exp_f32_e32 v99, v99
	s_nop 0
	v_pk_add_f32 v[98:99], v[98:99], 1.0 op_sel_hi:[1,0]
	s_nop 0
	s_nop 0
	v_rcp_f32_e32 v103, v99
	s_nop 0
	v_mul_f32_e32 v105, v105, v103
	s_nop 0
	v_rcp_f32_e32 v99, v98
	s_nop 0
	v_mul_f32_e32 v104, v104, v99
	v_mul_f32_e32 v98, 0x3d372713, v101
	v_mul_f32_e32 v98, v101, v98
	v_fma_f32 v98, v101, v98, v101
	v_mul_f32_e32 v98, 0xbfcc422a, v98
	v_mul_f32_e32 v98, 0x3fb8aa3b, v98
	v_exp_f32_e32 v103, v98
	s_nop 0
	v_pk_add_f32 v[98:99], v[102:103], 1.0 op_sel_hi:[1,0]
	s_nop 0
	s_nop 0
	v_rcp_f32_e32 v102, v99
	s_nop 0
	v_mul_f32_e32 v101, v101, v102
	s_nop 0
	v_rcp_f32_e32 v99, v98
	s_nop 0
	v_mul_f32_e32 v102, v100, v99
	v_cvt_pk_bf16_f32 v101, v102, v101
	v_lshl_add_u64 v[102:103], v[106:107], 0, v[114:115]
	v_lshl_add_u64 v[102:103], v[102:103], 0, s[10:11]
	v_cvt_pk_bf16_f32 v98, v108, v109
	v_cvt_pk_bf16_f32 v99, v104, v105
	v_cvt_pk_bf16_f32 v100, v111, v110
	v_lshl_add_u64 v[102:103], v[102:103], 0, v[48:49]
	global_store_dwordx4 v[102:103], v[98:101], off
	s_nop 1
	v_mul_f32_e32 v101, 0x3d372713, v90
	v_mul_f32_e32 v101, v90, v101
	v_fma_f32 v101, v90, v101, v90
	v_mul_f32_e32 v101, 0xbfcc422a, v101
	v_mul_f32_e32 v101, 0x3fb8aa3b, v101
	v_mul_f32_e32 v100, 0x3d372713, v94
	v_exp_f32_e32 v102, v101
	v_mul_f32_e32 v101, 0x3d372713, v95
	v_mul_f32_e32 v100, v94, v100
	v_mul_f32_e32 v101, v95, v101
	v_fma_f32 v100, v94, v100, v94
	v_fma_f32 v101, v95, v101, v95
	v_mul_f32_e32 v100, 0xbfcc422a, v100
	v_mul_f32_e32 v101, 0xbfcc422a, v101
	v_mul_f32_e32 v100, 0x3fb8aa3b, v100
	v_mul_f32_e32 v101, 0x3fb8aa3b, v101
	v_exp_f32_e32 v100, v100
	v_exp_f32_e32 v101, v101
	v_or_b32_e32 v98, 32, v142
	v_ashrrev_i32_e32 v99, 31, v98
	v_lshlrev_b64 v[98:99], 14, v[98:99]
	v_pk_add_f32 v[100:101], v[100:101], 1.0 op_sel_hi:[1,0]
	s_nop 0
	s_nop 0
	v_rcp_f32_e32 v103, v101
	s_nop 0
	v_mul_f32_e32 v101, v95, v103
	s_nop 0
	v_rcp_f32_e32 v95, v100
	s_nop 0
	v_mul_f32_e32 v100, v94, v95
	v_mul_f32_e32 v94, 0x3d372713, v91
	v_mul_f32_e32 v94, v91, v94
	v_fma_f32 v94, v91, v94, v91
	v_mul_f32_e32 v94, 0xbfcc422a, v94
	v_mul_f32_e32 v94, 0x3fb8aa3b, v94
	v_exp_f32_e32 v103, v94
	s_nop 0
	v_pk_add_f32 v[94:95], v[102:103], 1.0 op_sel_hi:[1,0]
	s_nop 0
	s_nop 0
	v_rcp_f32_e32 v102, v95
	s_nop 0
	v_mul_f32_e32 v102, v91, v102
	s_nop 0
	v_rcp_f32_e32 v91, v94
	s_nop 0
	v_mul_f32_e32 v103, v90, v91
	v_mul_f32_e32 v91, 0x3d372713, v92
	v_mul_f32_e32 v91, v92, v91
	v_fma_f32 v91, v92, v91, v92
	v_mul_f32_e32 v91, 0xbfcc422a, v91
	v_mul_f32_e32 v91, 0x3fb8aa3b, v91
	v_mul_f32_e32 v90, 0x3d372713, v96
	v_exp_f32_e32 v94, v91
	v_mul_f32_e32 v91, 0x3d372713, v97
	v_mul_f32_e32 v90, v96, v90
	v_mul_f32_e32 v91, v97, v91
	v_fma_f32 v90, v96, v90, v96
	v_fma_f32 v91, v97, v91, v97
	v_mul_f32_e32 v90, 0xbfcc422a, v90
	v_mul_f32_e32 v91, 0xbfcc422a, v91
	v_mul_f32_e32 v90, 0x3fb8aa3b, v90
	v_mul_f32_e32 v91, 0x3fb8aa3b, v91
	v_exp_f32_e32 v90, v90
	v_exp_f32_e32 v91, v91
	s_nop 0
	v_pk_add_f32 v[90:91], v[90:91], 1.0 op_sel_hi:[1,0]
	s_nop 0
	s_nop 0
	v_rcp_f32_e32 v95, v91
	s_nop 0
	v_mul_f32_e32 v97, v97, v95
	s_nop 0
	v_rcp_f32_e32 v91, v90
	s_nop 0
	v_mul_f32_e32 v96, v96, v91
	v_mul_f32_e32 v90, 0x3d372713, v93
	v_mul_f32_e32 v90, v93, v90
	v_fma_f32 v90, v93, v90, v93
	v_mul_f32_e32 v90, 0xbfcc422a, v90
	v_mul_f32_e32 v90, 0x3fb8aa3b, v90
	v_exp_f32_e32 v95, v90
	s_nop 0
	v_pk_add_f32 v[90:91], v[94:95], 1.0 op_sel_hi:[1,0]
	s_nop 0
	s_nop 0
	v_rcp_f32_e32 v94, v91
	s_nop 0
	v_mul_f32_e32 v91, v93, v94
	s_nop 0
	v_rcp_f32_e32 v93, v90
	s_nop 0
	v_mul_f32_e32 v90, v92, v93
	v_cvt_pk_bf16_f32 v95, v90, v91
	v_lshl_add_u64 v[90:91], s[0:1], 0, v[98:99]
	v_cvt_pk_bf16_f32 v93, v96, v97
	v_lshl_add_u64 v[96:97], v[90:91], 0, v[124:125]
	v_lshl_add_u64 v[96:97], v[96:97], 0, s[10:11]
	v_cvt_pk_bf16_f32 v92, v100, v101
	v_cvt_pk_bf16_f32 v94, v103, v102
	v_lshl_add_u64 v[96:97], v[96:97], 0, v[48:49]
	global_store_dwordx4 v[96:97], v[92:95], off
	s_nop 1
	v_mul_f32_e32 v93, 0x3d372713, v82
	v_mul_f32_e32 v93, v82, v93
	v_fma_f32 v93, v82, v93, v82
	v_mul_f32_e32 v93, 0xbfcc422a, v93
	v_mul_f32_e32 v93, 0x3fb8aa3b, v93
	v_mul_f32_e32 v92, 0x3d372713, v86
	v_exp_f32_e32 v94, v93
	v_mul_f32_e32 v93, 0x3d372713, v87
	v_mul_f32_e32 v92, v86, v92
	v_mul_f32_e32 v93, v87, v93
	v_fma_f32 v92, v86, v92, v86
	v_fma_f32 v93, v87, v93, v87
	v_mul_f32_e32 v92, 0xbfcc422a, v92
	v_mul_f32_e32 v93, 0xbfcc422a, v93
	v_mul_f32_e32 v92, 0x3fb8aa3b, v92
	v_mul_f32_e32 v93, 0x3fb8aa3b, v93
	v_exp_f32_e32 v92, v92
	v_exp_f32_e32 v93, v93
	s_nop 0
	v_pk_add_f32 v[92:93], v[92:93], 1.0 op_sel_hi:[1,0]
	s_nop 0
	s_nop 0
	v_rcp_f32_e32 v95, v93
	s_nop 0
	v_mul_f32_e32 v93, v87, v95
	s_nop 0
	v_rcp_f32_e32 v87, v92
	s_nop 0
	v_mul_f32_e32 v92, v86, v87
	v_mul_f32_e32 v86, 0x3d372713, v83
	v_mul_f32_e32 v86, v83, v86
	v_fma_f32 v86, v83, v86, v83
	v_mul_f32_e32 v86, 0xbfcc422a, v86
	v_mul_f32_e32 v86, 0x3fb8aa3b, v86
	v_exp_f32_e32 v95, v86
	s_nop 0
	v_pk_add_f32 v[86:87], v[94:95], 1.0 op_sel_hi:[1,0]
	s_nop 0
	s_nop 0
	v_rcp_f32_e32 v94, v87
	s_nop 0
	v_mul_f32_e32 v94, v83, v94
	s_nop 0
	v_rcp_f32_e32 v83, v86
	s_nop 0
	v_mul_f32_e32 v95, v82, v83
	v_mul_f32_e32 v83, 0x3d372713, v84
	v_mul_f32_e32 v83, v84, v83
	v_fma_f32 v83, v84, v83, v84
	v_mul_f32_e32 v83, 0xbfcc422a, v83
	v_mul_f32_e32 v83, 0x3fb8aa3b, v83
	v_mul_f32_e32 v82, 0x3d372713, v88
	v_exp_f32_e32 v86, v83
	v_mul_f32_e32 v83, 0x3d372713, v89
	v_mul_f32_e32 v82, v88, v82
	v_mul_f32_e32 v83, v89, v83
	v_fma_f32 v82, v88, v82, v88
	v_fma_f32 v83, v89, v83, v89
	v_mul_f32_e32 v82, 0xbfcc422a, v82
	v_mul_f32_e32 v83, 0xbfcc422a, v83
	v_mul_f32_e32 v82, 0x3fb8aa3b, v82
	v_mul_f32_e32 v83, 0x3fb8aa3b, v83
	v_exp_f32_e32 v82, v82
	v_exp_f32_e32 v83, v83
	s_nop 0
	v_pk_add_f32 v[82:83], v[82:83], 1.0 op_sel_hi:[1,0]
	s_nop 0
	s_nop 0
	v_rcp_f32_e32 v87, v83
	s_nop 0
	v_mul_f32_e32 v89, v89, v87
	s_nop 0
	v_rcp_f32_e32 v83, v82
	s_nop 0
	v_mul_f32_e32 v88, v88, v83
	v_mul_f32_e32 v82, 0x3d372713, v85
	v_mul_f32_e32 v82, v85, v82
	v_fma_f32 v82, v85, v82, v85
	v_mul_f32_e32 v82, 0xbfcc422a, v82
	v_mul_f32_e32 v82, 0x3fb8aa3b, v82
	v_exp_f32_e32 v87, v82
	s_nop 0
	v_pk_add_f32 v[82:83], v[86:87], 1.0 op_sel_hi:[1,0]
	s_nop 0
	s_nop 0
	v_rcp_f32_e32 v86, v83
	s_nop 0
	v_mul_f32_e32 v85, v85, v86
	s_nop 0
	v_rcp_f32_e32 v83, v82
	s_nop 0
	v_mul_f32_e32 v86, v84, v83
	v_cvt_pk_bf16_f32 v85, v86, v85
	v_lshl_add_u64 v[86:87], v[90:91], 0, v[114:115]
	v_lshl_add_u64 v[86:87], v[86:87], 0, s[10:11]
	v_cvt_pk_bf16_f32 v82, v92, v93
	v_cvt_pk_bf16_f32 v83, v88, v89
	v_cvt_pk_bf16_f32 v84, v95, v94
	v_lshl_add_u64 v[86:87], v[86:87], 0, v[48:49]
	global_store_dwordx4 v[86:87], v[82:85], off
	s_nop 1
	v_mul_f32_e32 v85, 0x3d372713, v74
	v_mul_f32_e32 v85, v74, v85
	v_fma_f32 v85, v74, v85, v74
	v_mul_f32_e32 v85, 0xbfcc422a, v85
	v_mul_f32_e32 v85, 0x3fb8aa3b, v85
	v_mul_f32_e32 v84, 0x3d372713, v78
	v_exp_f32_e32 v86, v85
	v_mul_f32_e32 v85, 0x3d372713, v79
	v_mul_f32_e32 v84, v78, v84
	v_mul_f32_e32 v85, v79, v85
	v_fma_f32 v84, v78, v84, v78
	v_fma_f32 v85, v79, v85, v79
	v_mul_f32_e32 v84, 0xbfcc422a, v84
	v_mul_f32_e32 v85, 0xbfcc422a, v85
	v_mul_f32_e32 v84, 0x3fb8aa3b, v84
	v_mul_f32_e32 v85, 0x3fb8aa3b, v85
	v_exp_f32_e32 v84, v84
	v_exp_f32_e32 v85, v85
	v_or_b32_e32 v82, 48, v142
	v_ashrrev_i32_e32 v83, 31, v82
	v_lshlrev_b64 v[82:83], 14, v[82:83]
	v_pk_add_f32 v[84:85], v[84:85], 1.0 op_sel_hi:[1,0]
	s_nop 0
	s_nop 0
	v_rcp_f32_e32 v87, v85
	s_nop 0
	v_mul_f32_e32 v85, v79, v87
	s_nop 0
	v_rcp_f32_e32 v79, v84
	s_nop 0
	v_mul_f32_e32 v84, v78, v79
	v_mul_f32_e32 v78, 0x3d372713, v75
	v_mul_f32_e32 v78, v75, v78
	v_fma_f32 v78, v75, v78, v75
	v_mul_f32_e32 v78, 0xbfcc422a, v78
	v_mul_f32_e32 v78, 0x3fb8aa3b, v78
	v_exp_f32_e32 v87, v78
	s_nop 0
	v_pk_add_f32 v[78:79], v[86:87], 1.0 op_sel_hi:[1,0]
	s_nop 0
	s_nop 0
	v_rcp_f32_e32 v86, v79
	s_nop 0
	v_mul_f32_e32 v86, v75, v86
	s_nop 0
	v_rcp_f32_e32 v75, v78
	s_nop 0
	v_mul_f32_e32 v87, v74, v75
	v_mul_f32_e32 v75, 0x3d372713, v76
	v_mul_f32_e32 v75, v76, v75
	v_fma_f32 v75, v76, v75, v76
	v_mul_f32_e32 v75, 0xbfcc422a, v75
	v_mul_f32_e32 v75, 0x3fb8aa3b, v75
	v_mul_f32_e32 v74, 0x3d372713, v80
	v_exp_f32_e32 v78, v75
	v_mul_f32_e32 v75, 0x3d372713, v81
	v_mul_f32_e32 v74, v80, v74
	v_mul_f32_e32 v75, v81, v75
	v_fma_f32 v74, v80, v74, v80
	v_fma_f32 v75, v81, v75, v81
	v_mul_f32_e32 v74, 0xbfcc422a, v74
	v_mul_f32_e32 v75, 0xbfcc422a, v75
	v_mul_f32_e32 v74, 0x3fb8aa3b, v74
	v_mul_f32_e32 v75, 0x3fb8aa3b, v75
	v_exp_f32_e32 v74, v74
	v_exp_f32_e32 v75, v75
	s_nop 0
	v_pk_add_f32 v[74:75], v[74:75], 1.0 op_sel_hi:[1,0]
	s_nop 0
	s_nop 0
	v_rcp_f32_e32 v79, v75
	s_nop 0
	v_mul_f32_e32 v81, v81, v79
	s_nop 0
	v_rcp_f32_e32 v75, v74
	s_nop 0
	v_mul_f32_e32 v80, v80, v75
	v_mul_f32_e32 v74, 0x3d372713, v77
	v_mul_f32_e32 v74, v77, v74
	v_fma_f32 v74, v77, v74, v77
	v_mul_f32_e32 v74, 0xbfcc422a, v74
	v_mul_f32_e32 v74, 0x3fb8aa3b, v74
	v_exp_f32_e32 v79, v74
	s_nop 0
	v_pk_add_f32 v[74:75], v[78:79], 1.0 op_sel_hi:[1,0]
	s_nop 0
	s_nop 0
	v_rcp_f32_e32 v78, v75
	s_nop 0
	v_mul_f32_e32 v75, v77, v78
	s_nop 0
	v_rcp_f32_e32 v77, v74
	s_nop 0
	v_mul_f32_e32 v74, v76, v77
	v_cvt_pk_bf16_f32 v79, v74, v75
	v_lshl_add_u64 v[74:75], s[0:1], 0, v[82:83]
	v_cvt_pk_bf16_f32 v77, v80, v81
	v_lshl_add_u64 v[80:81], v[74:75], 0, v[124:125]
	v_lshl_add_u64 v[80:81], v[80:81], 0, s[10:11]
	v_cvt_pk_bf16_f32 v76, v84, v85
	v_cvt_pk_bf16_f32 v78, v87, v86
	v_lshl_add_u64 v[80:81], v[80:81], 0, v[48:49]
	global_store_dwordx4 v[80:81], v[76:79], off
	s_nop 1
	v_mul_f32_e32 v77, 0x3d372713, v66
	v_mul_f32_e32 v77, v66, v77
	v_fma_f32 v77, v66, v77, v66
	v_mul_f32_e32 v77, 0xbfcc422a, v77
	v_mul_f32_e32 v77, 0x3fb8aa3b, v77
	v_mul_f32_e32 v76, 0x3d372713, v70
	v_exp_f32_e32 v78, v77
	v_mul_f32_e32 v77, 0x3d372713, v71
	v_mul_f32_e32 v76, v70, v76
	v_mul_f32_e32 v77, v71, v77
	v_fma_f32 v76, v70, v76, v70
	v_fma_f32 v77, v71, v77, v71
	v_mul_f32_e32 v76, 0xbfcc422a, v76
	v_mul_f32_e32 v77, 0xbfcc422a, v77
	v_mul_f32_e32 v76, 0x3fb8aa3b, v76
	v_mul_f32_e32 v77, 0x3fb8aa3b, v77
	v_exp_f32_e32 v76, v76
	v_exp_f32_e32 v77, v77
	s_nop 0
	v_pk_add_f32 v[76:77], v[76:77], 1.0 op_sel_hi:[1,0]
	s_nop 0
	s_nop 0
	v_rcp_f32_e32 v79, v77
	s_nop 0
	v_mul_f32_e32 v77, v71, v79
	s_nop 0
	v_rcp_f32_e32 v71, v76
	s_nop 0
	v_mul_f32_e32 v76, v70, v71
	v_mul_f32_e32 v70, 0x3d372713, v67
	v_mul_f32_e32 v70, v67, v70
	v_fma_f32 v70, v67, v70, v67
	v_mul_f32_e32 v70, 0xbfcc422a, v70
	v_mul_f32_e32 v70, 0x3fb8aa3b, v70
	v_exp_f32_e32 v79, v70
	s_nop 0
	v_pk_add_f32 v[70:71], v[78:79], 1.0 op_sel_hi:[1,0]
	s_nop 0
	s_nop 0
	v_rcp_f32_e32 v78, v71
	s_nop 0
	v_mul_f32_e32 v78, v67, v78
	s_nop 0
	v_rcp_f32_e32 v67, v70
	s_nop 0
	v_mul_f32_e32 v79, v66, v67
	v_mul_f32_e32 v67, 0x3d372713, v68
	v_mul_f32_e32 v67, v68, v67
	v_fma_f32 v67, v68, v67, v68
	v_mul_f32_e32 v67, 0xbfcc422a, v67
	v_mul_f32_e32 v67, 0x3fb8aa3b, v67
	v_mul_f32_e32 v66, 0x3d372713, v72
	v_exp_f32_e32 v70, v67
	v_mul_f32_e32 v67, 0x3d372713, v73
	v_mul_f32_e32 v66, v72, v66
	v_mul_f32_e32 v67, v73, v67
	v_fma_f32 v66, v72, v66, v72
	v_fma_f32 v67, v73, v67, v73
	v_mul_f32_e32 v66, 0xbfcc422a, v66
	v_mul_f32_e32 v67, 0xbfcc422a, v67
	v_mul_f32_e32 v66, 0x3fb8aa3b, v66
	v_mul_f32_e32 v67, 0x3fb8aa3b, v67
	v_exp_f32_e32 v66, v66
	v_exp_f32_e32 v67, v67
	s_nop 0
	v_pk_add_f32 v[66:67], v[66:67], 1.0 op_sel_hi:[1,0]
	s_nop 0
	s_nop 0
	v_rcp_f32_e32 v71, v67
	s_nop 0
	v_mul_f32_e32 v73, v73, v71
	s_nop 0
	v_rcp_f32_e32 v67, v66
	s_nop 0
	v_mul_f32_e32 v72, v72, v67
	v_mul_f32_e32 v66, 0x3d372713, v69
	v_mul_f32_e32 v66, v69, v66
	v_fma_f32 v66, v69, v66, v69
	v_mul_f32_e32 v66, 0xbfcc422a, v66
	v_mul_f32_e32 v66, 0x3fb8aa3b, v66
	v_exp_f32_e32 v71, v66
	s_nop 0
	v_pk_add_f32 v[66:67], v[70:71], 1.0 op_sel_hi:[1,0]
	s_nop 0
	s_nop 0
	v_rcp_f32_e32 v70, v67
	s_nop 0
	v_mul_f32_e32 v69, v69, v70
	s_nop 0
	v_rcp_f32_e32 v67, v66
	s_nop 0
	v_mul_f32_e32 v70, v68, v67
	v_cvt_pk_bf16_f32 v69, v70, v69
	v_lshl_add_u64 v[70:71], v[74:75], 0, v[114:115]
	v_lshl_add_u64 v[70:71], v[70:71], 0, s[10:11]
	v_cvt_pk_bf16_f32 v66, v76, v77
	v_cvt_pk_bf16_f32 v67, v72, v73
	v_cvt_pk_bf16_f32 v68, v79, v78
	v_lshl_add_u64 v[70:71], v[70:71], 0, v[48:49]
	global_store_dwordx4 v[70:71], v[66:69], off
	s_nop 1
	v_mul_f32_e32 v67, 0x3d372713, v58
	v_mul_f32_e32 v67, v58, v67
	v_fma_f32 v67, v58, v67, v58
	v_mul_f32_e32 v67, 0xbfcc422a, v67
	v_mul_f32_e32 v67, 0x3fb8aa3b, v67
	v_mul_f32_e32 v66, 0x3d372713, v62
	v_exp_f32_e32 v68, v67
	v_mul_f32_e32 v67, 0x3d372713, v63
	v_mul_f32_e32 v66, v62, v66
	v_mul_f32_e32 v67, v63, v67
	v_fma_f32 v66, v62, v66, v62
	v_fma_f32 v67, v63, v67, v63
	v_mul_f32_e32 v66, 0xbfcc422a, v66
	v_mul_f32_e32 v67, 0xbfcc422a, v67
	v_mul_f32_e32 v66, 0x3fb8aa3b, v66
	v_mul_f32_e32 v67, 0x3fb8aa3b, v67
	v_exp_f32_e32 v66, v66
	v_exp_f32_e32 v67, v67
	s_nop 0
	v_pk_add_f32 v[66:67], v[66:67], 1.0 op_sel_hi:[1,0]
	s_nop 0
	s_nop 0
	v_rcp_f32_e32 v69, v67
	s_nop 0
	v_mul_f32_e32 v67, v63, v69
	s_nop 0
	v_rcp_f32_e32 v63, v66
	s_nop 0
	v_mul_f32_e32 v66, v62, v63
	v_mul_f32_e32 v62, 0x3d372713, v59
	v_mul_f32_e32 v62, v59, v62
	v_fma_f32 v62, v59, v62, v59
	v_mul_f32_e32 v62, 0xbfcc422a, v62
	v_mul_f32_e32 v62, 0x3fb8aa3b, v62
	v_exp_f32_e32 v69, v62
	s_nop 0
	v_pk_add_f32 v[62:63], v[68:69], 1.0 op_sel_hi:[1,0]
	s_nop 0
	s_nop 0
	v_rcp_f32_e32 v68, v63
	s_nop 0
	v_mul_f32_e32 v68, v59, v68
	s_nop 0
	v_rcp_f32_e32 v59, v62
	s_nop 0
	v_mul_f32_e32 v69, v58, v59
	v_mul_f32_e32 v59, 0x3d372713, v60
	v_mul_f32_e32 v59, v60, v59
	v_fma_f32 v59, v60, v59, v60
	v_mul_f32_e32 v59, 0xbfcc422a, v59
	v_mul_f32_e32 v59, 0x3fb8aa3b, v59
	v_mul_f32_e32 v58, 0x3d372713, v64
	v_exp_f32_e32 v62, v59
	v_mul_f32_e32 v59, 0x3d372713, v65
	v_mul_f32_e32 v58, v64, v58
	v_mul_f32_e32 v59, v65, v59
	v_fma_f32 v58, v64, v58, v64
	v_fma_f32 v59, v65, v59, v65
	v_mul_f32_e32 v58, 0xbfcc422a, v58
	v_mul_f32_e32 v59, 0xbfcc422a, v59
	v_mul_f32_e32 v58, 0x3fb8aa3b, v58
	v_mul_f32_e32 v59, 0x3fb8aa3b, v59
	v_exp_f32_e32 v58, v58
	v_exp_f32_e32 v59, v59
	s_nop 0
	v_pk_add_f32 v[58:59], v[58:59], 1.0 op_sel_hi:[1,0]
	s_nop 0
	s_nop 0
	v_rcp_f32_e32 v63, v59
	s_nop 0
	v_mul_f32_e32 v65, v65, v63
	s_nop 0
	v_rcp_f32_e32 v59, v58
	s_nop 0
	v_mul_f32_e32 v64, v64, v59
	v_mul_f32_e32 v58, 0x3d372713, v61
	v_mul_f32_e32 v58, v61, v58
	v_fma_f32 v58, v61, v58, v61
	v_mul_f32_e32 v58, 0xbfcc422a, v58
	v_mul_f32_e32 v58, 0x3fb8aa3b, v58
	v_exp_f32_e32 v63, v58
	s_nop 0
	v_pk_add_f32 v[58:59], v[62:63], 1.0 op_sel_hi:[1,0]
	s_nop 0
	s_nop 0
	v_rcp_f32_e32 v62, v59
	s_nop 0
	v_mul_f32_e32 v59, v61, v62
	s_mov_b64 s[12:13], 0x200000
	v_rcp_f32_e32 v61, v58
	s_nop 0
	v_mul_f32_e32 v58, v60, v61
	v_cvt_pk_bf16_f32 v63, v58, v59
	v_lshl_add_u64 v[58:59], v[122:123], 0, s[12:13]
	v_cvt_pk_bf16_f32 v61, v64, v65
	v_lshl_add_u64 v[64:65], v[58:59], 0, v[124:125]
	v_lshl_add_u64 v[64:65], v[64:65], 0, s[10:11]
	v_cvt_pk_bf16_f32 v60, v66, v67
	v_cvt_pk_bf16_f32 v62, v69, v68
	v_lshl_add_u64 v[64:65], v[64:65], 0, v[48:49]
	global_store_dwordx4 v[64:65], v[60:63], off
	s_nop 1
	v_mul_f32_e32 v61, 0x3d372713, v50
	v_mul_f32_e32 v61, v50, v61
	v_fma_f32 v61, v50, v61, v50
	v_mul_f32_e32 v61, 0xbfcc422a, v61
	v_mul_f32_e32 v61, 0x3fb8aa3b, v61
	v_mul_f32_e32 v60, 0x3d372713, v54
	v_exp_f32_e32 v62, v61
	v_mul_f32_e32 v61, 0x3d372713, v55
	v_mul_f32_e32 v60, v54, v60
	v_mul_f32_e32 v61, v55, v61
	v_fma_f32 v60, v54, v60, v54
	v_fma_f32 v61, v55, v61, v55
	v_mul_f32_e32 v60, 0xbfcc422a, v60
	v_mul_f32_e32 v61, 0xbfcc422a, v61
	v_mul_f32_e32 v60, 0x3fb8aa3b, v60
	v_mul_f32_e32 v61, 0x3fb8aa3b, v61
	v_exp_f32_e32 v60, v60
	v_exp_f32_e32 v61, v61
	s_nop 0
	v_pk_add_f32 v[60:61], v[60:61], 1.0 op_sel_hi:[1,0]
	s_nop 0
	s_nop 0
	v_rcp_f32_e32 v63, v61
	s_nop 0
	v_mul_f32_e32 v61, v55, v63
	s_nop 0
	v_rcp_f32_e32 v55, v60
	s_nop 0
	v_mul_f32_e32 v60, v54, v55
	v_mul_f32_e32 v54, 0x3d372713, v51
	v_mul_f32_e32 v54, v51, v54
	v_fma_f32 v54, v51, v54, v51
	v_mul_f32_e32 v54, 0xbfcc422a, v54
	v_mul_f32_e32 v54, 0x3fb8aa3b, v54
	v_exp_f32_e32 v63, v54
	s_nop 0
	v_pk_add_f32 v[54:55], v[62:63], 1.0 op_sel_hi:[1,0]
	s_nop 0
	s_nop 0
	v_rcp_f32_e32 v62, v55
	s_nop 0
	v_mul_f32_e32 v62, v51, v62
	s_nop 0
	v_rcp_f32_e32 v51, v54
	s_nop 0
	v_mul_f32_e32 v63, v50, v51
	v_mul_f32_e32 v51, 0x3d372713, v52
	v_mul_f32_e32 v51, v52, v51
	v_fma_f32 v51, v52, v51, v52
	v_mul_f32_e32 v51, 0xbfcc422a, v51
	v_mul_f32_e32 v51, 0x3fb8aa3b, v51
	v_mul_f32_e32 v50, 0x3d372713, v56
	v_exp_f32_e32 v54, v51
	v_mul_f32_e32 v51, 0x3d372713, v57
	v_mul_f32_e32 v50, v56, v50
	v_mul_f32_e32 v51, v57, v51
	v_fma_f32 v50, v56, v50, v56
	v_fma_f32 v51, v57, v51, v57
	v_mul_f32_e32 v50, 0xbfcc422a, v50
	v_mul_f32_e32 v51, 0xbfcc422a, v51
	v_mul_f32_e32 v50, 0x3fb8aa3b, v50
	v_mul_f32_e32 v51, 0x3fb8aa3b, v51
	v_exp_f32_e32 v50, v50
	v_exp_f32_e32 v51, v51
	s_nop 0
	v_pk_add_f32 v[50:51], v[50:51], 1.0 op_sel_hi:[1,0]
	s_nop 0
	s_nop 0
	v_rcp_f32_e32 v55, v51
	s_nop 0
	v_mul_f32_e32 v57, v57, v55
	s_nop 0
	v_rcp_f32_e32 v51, v50
	s_nop 0
	v_mul_f32_e32 v56, v56, v51
	v_mul_f32_e32 v50, 0x3d372713, v53
	v_mul_f32_e32 v50, v53, v50
	v_fma_f32 v50, v53, v50, v53
	v_mul_f32_e32 v50, 0xbfcc422a, v50
	v_mul_f32_e32 v50, 0x3fb8aa3b, v50
	v_exp_f32_e32 v55, v50
	s_nop 0
	v_pk_add_f32 v[50:51], v[54:55], 1.0 op_sel_hi:[1,0]
	s_nop 0
	s_nop 0
	v_rcp_f32_e32 v54, v51
	s_nop 0
	v_mul_f32_e32 v53, v53, v54
	s_nop 0
	v_rcp_f32_e32 v51, v50
	s_nop 0
	v_mul_f32_e32 v54, v52, v51
	v_cvt_pk_bf16_f32 v53, v54, v53
	v_lshl_add_u64 v[54:55], v[58:59], 0, v[114:115]
	v_lshl_add_u64 v[54:55], v[54:55], 0, s[10:11]
	v_cvt_pk_bf16_f32 v50, v60, v61
	v_cvt_pk_bf16_f32 v51, v56, v57
	v_cvt_pk_bf16_f32 v52, v63, v62
	v_lshl_add_u64 v[54:55], v[54:55], 0, v[48:49]
	global_store_dwordx4 v[54:55], v[50:53], off
	s_nop 1
	v_mul_f32_e32 v51, 0x3d372713, v40
	v_mul_f32_e32 v51, v40, v51
	v_fma_f32 v51, v40, v51, v40
	v_mul_f32_e32 v51, 0xbfcc422a, v51
	v_mul_f32_e32 v51, 0x3fb8aa3b, v51
	v_mul_f32_e32 v50, 0x3d372713, v44
	v_exp_f32_e32 v52, v51
	v_mul_f32_e32 v51, 0x3d372713, v45
	v_mul_f32_e32 v50, v44, v50
	v_mul_f32_e32 v51, v45, v51
	v_fma_f32 v50, v44, v50, v44
	v_fma_f32 v51, v45, v51, v45
	v_mul_f32_e32 v50, 0xbfcc422a, v50
	v_mul_f32_e32 v51, 0xbfcc422a, v51
	v_mul_f32_e32 v50, 0x3fb8aa3b, v50
	v_mul_f32_e32 v51, 0x3fb8aa3b, v51
	v_exp_f32_e32 v50, v50
	v_exp_f32_e32 v51, v51
	s_nop 0
	v_pk_add_f32 v[50:51], v[50:51], 1.0 op_sel_hi:[1,0]
	s_nop 0
	s_nop 0
	v_rcp_f32_e32 v53, v51
	s_nop 0
	v_mul_f32_e32 v51, v45, v53
	s_nop 0
	v_rcp_f32_e32 v45, v50
	s_nop 0
	v_mul_f32_e32 v50, v44, v45
	v_mul_f32_e32 v44, 0x3d372713, v41
	v_mul_f32_e32 v44, v41, v44
	v_fma_f32 v44, v41, v44, v41
	v_mul_f32_e32 v44, 0xbfcc422a, v44
	v_mul_f32_e32 v44, 0x3fb8aa3b, v44
	v_exp_f32_e32 v53, v44
	s_nop 0
	v_pk_add_f32 v[44:45], v[52:53], 1.0 op_sel_hi:[1,0]
	s_nop 0
	s_nop 0
	v_rcp_f32_e32 v52, v45
	s_nop 0
	v_mul_f32_e32 v52, v41, v52
	s_nop 0
	v_rcp_f32_e32 v41, v44
	s_nop 0
	v_mul_f32_e32 v53, v40, v41
	v_mul_f32_e32 v41, 0x3d372713, v42
	v_mul_f32_e32 v41, v42, v41
	v_fma_f32 v41, v42, v41, v42
	v_mul_f32_e32 v41, 0xbfcc422a, v41
	v_mul_f32_e32 v41, 0x3fb8aa3b, v41
	v_mul_f32_e32 v40, 0x3d372713, v46
	v_exp_f32_e32 v44, v41
	v_mul_f32_e32 v41, 0x3d372713, v47
	v_mul_f32_e32 v40, v46, v40
	v_mul_f32_e32 v41, v47, v41
	v_fma_f32 v40, v46, v40, v46
	v_fma_f32 v41, v47, v41, v47
	v_mul_f32_e32 v40, 0xbfcc422a, v40
	v_mul_f32_e32 v41, 0xbfcc422a, v41
	v_mul_f32_e32 v40, 0x3fb8aa3b, v40
	v_mul_f32_e32 v41, 0x3fb8aa3b, v41
	v_exp_f32_e32 v40, v40
	v_exp_f32_e32 v41, v41
	s_nop 0
	v_pk_add_f32 v[40:41], v[40:41], 1.0 op_sel_hi:[1,0]
	s_nop 0
	s_nop 0
	v_rcp_f32_e32 v45, v41
	s_nop 0
	v_mul_f32_e32 v47, v47, v45
	s_nop 0
	v_rcp_f32_e32 v41, v40
	s_nop 0
	v_mul_f32_e32 v46, v46, v41
	v_mul_f32_e32 v40, 0x3d372713, v43
	v_mul_f32_e32 v40, v43, v40
	v_fma_f32 v40, v43, v40, v43
	v_mul_f32_e32 v40, 0xbfcc422a, v40
	v_mul_f32_e32 v40, 0x3fb8aa3b, v40
	v_exp_f32_e32 v45, v40
	s_nop 0
	v_pk_add_f32 v[40:41], v[44:45], 1.0 op_sel_hi:[1,0]
	s_nop 0
	s_nop 0
	v_rcp_f32_e32 v44, v41
	s_nop 0
	v_mul_f32_e32 v41, v43, v44
	s_mov_b64 s[12:13], 0x240000
	v_rcp_f32_e32 v43, v40
	s_nop 0
	v_mul_f32_e32 v40, v42, v43
	v_cvt_pk_bf16_f32 v45, v40, v41
	v_lshl_add_u64 v[40:41], v[122:123], 0, s[12:13]
	v_cvt_pk_bf16_f32 v43, v46, v47
	v_lshl_add_u64 v[46:47], v[40:41], 0, v[124:125]
	v_lshl_add_u64 v[46:47], v[46:47], 0, s[10:11]
	v_cvt_pk_bf16_f32 v42, v50, v51
	v_cvt_pk_bf16_f32 v44, v53, v52
	v_lshl_add_u64 v[46:47], v[46:47], 0, v[48:49]
	global_store_dwordx4 v[46:47], v[42:45], off
	s_nop 1
	v_mul_f32_e32 v43, 0x3d372713, v32
	v_mul_f32_e32 v43, v32, v43
	v_fma_f32 v43, v32, v43, v32
	v_mul_f32_e32 v43, 0xbfcc422a, v43
	v_mul_f32_e32 v43, 0x3fb8aa3b, v43
	v_mul_f32_e32 v42, 0x3d372713, v36
	v_exp_f32_e32 v44, v43
	v_mul_f32_e32 v43, 0x3d372713, v37
	v_mul_f32_e32 v42, v36, v42
	v_mul_f32_e32 v43, v37, v43
	v_fma_f32 v42, v36, v42, v36
	v_fma_f32 v43, v37, v43, v37
	v_mul_f32_e32 v42, 0xbfcc422a, v42
	v_mul_f32_e32 v43, 0xbfcc422a, v43
	v_mul_f32_e32 v42, 0x3fb8aa3b, v42
	v_mul_f32_e32 v43, 0x3fb8aa3b, v43
	v_exp_f32_e32 v42, v42
	v_exp_f32_e32 v43, v43
	s_nop 0
	v_pk_add_f32 v[42:43], v[42:43], 1.0 op_sel_hi:[1,0]
	s_nop 0
	s_nop 0
	v_rcp_f32_e32 v45, v43
	s_nop 0
	v_mul_f32_e32 v43, v37, v45
	s_nop 0
	v_rcp_f32_e32 v37, v42
	s_nop 0
	v_mul_f32_e32 v42, v36, v37
	v_mul_f32_e32 v36, 0x3d372713, v33
	v_mul_f32_e32 v36, v33, v36
	v_fma_f32 v36, v33, v36, v33
	v_mul_f32_e32 v36, 0xbfcc422a, v36
	v_mul_f32_e32 v36, 0x3fb8aa3b, v36
	v_exp_f32_e32 v45, v36
	s_nop 0
	v_pk_add_f32 v[36:37], v[44:45], 1.0 op_sel_hi:[1,0]
	s_nop 0
	s_nop 0
	v_rcp_f32_e32 v44, v37
	s_nop 0
	v_mul_f32_e32 v44, v33, v44
	s_nop 0
	v_rcp_f32_e32 v33, v36
	s_nop 0
	v_mul_f32_e32 v45, v32, v33
	v_mul_f32_e32 v33, 0x3d372713, v34
	v_mul_f32_e32 v33, v34, v33
	v_fma_f32 v33, v34, v33, v34
	v_mul_f32_e32 v33, 0xbfcc422a, v33
	v_mul_f32_e32 v33, 0x3fb8aa3b, v33
	v_mul_f32_e32 v32, 0x3d372713, v38
	v_exp_f32_e32 v36, v33
	v_mul_f32_e32 v33, 0x3d372713, v39
	v_mul_f32_e32 v32, v38, v32
	v_mul_f32_e32 v33, v39, v33
	v_fma_f32 v32, v38, v32, v38
	v_fma_f32 v33, v39, v33, v39
	v_mul_f32_e32 v32, 0xbfcc422a, v32
	v_mul_f32_e32 v33, 0xbfcc422a, v33
	v_mul_f32_e32 v32, 0x3fb8aa3b, v32
	v_mul_f32_e32 v33, 0x3fb8aa3b, v33
	v_exp_f32_e32 v32, v32
	v_exp_f32_e32 v33, v33
	s_nop 0
	v_pk_add_f32 v[32:33], v[32:33], 1.0 op_sel_hi:[1,0]
	s_nop 0
	s_nop 0
	v_rcp_f32_e32 v37, v33
	s_nop 0
	v_mul_f32_e32 v39, v39, v37
	s_nop 0
	v_rcp_f32_e32 v33, v32
	s_nop 0
	v_mul_f32_e32 v38, v38, v33
	v_mul_f32_e32 v32, 0x3d372713, v35
	v_mul_f32_e32 v32, v35, v32
	v_fma_f32 v32, v35, v32, v35
	v_mul_f32_e32 v32, 0xbfcc422a, v32
	v_mul_f32_e32 v32, 0x3fb8aa3b, v32
	v_exp_f32_e32 v37, v32
	s_nop 0
	v_pk_add_f32 v[32:33], v[36:37], 1.0 op_sel_hi:[1,0]
	s_nop 0
	s_nop 0
	v_rcp_f32_e32 v36, v33
	s_nop 0
	v_mul_f32_e32 v35, v35, v36
	s_nop 0
	v_rcp_f32_e32 v33, v32
	s_nop 0
	v_mul_f32_e32 v36, v34, v33
	v_cvt_pk_bf16_f32 v35, v36, v35
	v_lshl_add_u64 v[36:37], v[40:41], 0, v[114:115]
	v_lshl_add_u64 v[36:37], v[36:37], 0, s[10:11]
	v_cvt_pk_bf16_f32 v32, v42, v43
	v_cvt_pk_bf16_f32 v33, v38, v39
	v_cvt_pk_bf16_f32 v34, v45, v44
	v_lshl_add_u64 v[36:37], v[36:37], 0, v[48:49]
	global_store_dwordx4 v[36:37], v[32:35], off
	s_nop 1
	v_mul_f32_e32 v33, 0x3d372713, v24
	v_mul_f32_e32 v33, v24, v33
	v_fma_f32 v33, v24, v33, v24
	v_mul_f32_e32 v33, 0xbfcc422a, v33
	v_mul_f32_e32 v33, 0x3fb8aa3b, v33
	v_mul_f32_e32 v32, 0x3d372713, v28
	v_exp_f32_e32 v34, v33
	v_mul_f32_e32 v33, 0x3d372713, v29
	v_mul_f32_e32 v32, v28, v32
	v_mul_f32_e32 v33, v29, v33
	v_fma_f32 v32, v28, v32, v28
	v_fma_f32 v33, v29, v33, v29
	v_mul_f32_e32 v32, 0xbfcc422a, v32
	v_mul_f32_e32 v33, 0xbfcc422a, v33
	v_mul_f32_e32 v32, 0x3fb8aa3b, v32
	v_mul_f32_e32 v33, 0x3fb8aa3b, v33
	v_exp_f32_e32 v32, v32
	v_exp_f32_e32 v33, v33
	s_nop 0
	v_pk_add_f32 v[32:33], v[32:33], 1.0 op_sel_hi:[1,0]
	s_nop 0
	s_nop 0
	v_rcp_f32_e32 v35, v33
	s_nop 0
	v_mul_f32_e32 v33, v29, v35
	s_nop 0
	v_rcp_f32_e32 v29, v32
	s_nop 0
	v_mul_f32_e32 v32, v28, v29
	v_mul_f32_e32 v28, 0x3d372713, v25
	v_mul_f32_e32 v28, v25, v28
	v_fma_f32 v28, v25, v28, v25
	v_mul_f32_e32 v28, 0xbfcc422a, v28
	v_mul_f32_e32 v28, 0x3fb8aa3b, v28
	v_exp_f32_e32 v35, v28
	s_nop 0
	v_pk_add_f32 v[28:29], v[34:35], 1.0 op_sel_hi:[1,0]
	s_nop 0
	s_nop 0
	v_rcp_f32_e32 v34, v29
	s_nop 0
	v_mul_f32_e32 v34, v25, v34
	s_nop 0
	v_rcp_f32_e32 v25, v28
	s_nop 0
	v_mul_f32_e32 v35, v24, v25
	v_mul_f32_e32 v25, 0x3d372713, v26
	v_mul_f32_e32 v25, v26, v25
	v_fma_f32 v25, v26, v25, v26
	v_mul_f32_e32 v25, 0xbfcc422a, v25
	v_mul_f32_e32 v25, 0x3fb8aa3b, v25
	v_mul_f32_e32 v24, 0x3d372713, v30
	v_exp_f32_e32 v28, v25
	v_mul_f32_e32 v25, 0x3d372713, v31
	v_mul_f32_e32 v24, v30, v24
	v_mul_f32_e32 v25, v31, v25
	v_fma_f32 v24, v30, v24, v30
	v_fma_f32 v25, v31, v25, v31
	v_mul_f32_e32 v24, 0xbfcc422a, v24
	v_mul_f32_e32 v25, 0xbfcc422a, v25
	v_mul_f32_e32 v24, 0x3fb8aa3b, v24
	v_mul_f32_e32 v25, 0x3fb8aa3b, v25
	v_exp_f32_e32 v24, v24
	v_exp_f32_e32 v25, v25
	s_nop 0
	v_pk_add_f32 v[24:25], v[24:25], 1.0 op_sel_hi:[1,0]
	s_nop 0
	s_nop 0
	v_rcp_f32_e32 v29, v25
	s_nop 0
	v_mul_f32_e32 v31, v31, v29
	s_nop 0
	v_rcp_f32_e32 v25, v24
	s_nop 0
	v_mul_f32_e32 v30, v30, v25
	v_mul_f32_e32 v24, 0x3d372713, v27
	v_mul_f32_e32 v24, v27, v24
	v_fma_f32 v24, v27, v24, v27
	v_mul_f32_e32 v24, 0xbfcc422a, v24
	v_mul_f32_e32 v24, 0x3fb8aa3b, v24
	v_exp_f32_e32 v29, v24
	s_nop 0
	v_pk_add_f32 v[24:25], v[28:29], 1.0 op_sel_hi:[1,0]
	s_nop 0
	s_nop 0
	v_rcp_f32_e32 v28, v25
	s_nop 0
	v_mul_f32_e32 v25, v27, v28
	s_mov_b64 s[12:13], 0x280000
	v_rcp_f32_e32 v27, v24
	s_nop 0
	v_mul_f32_e32 v24, v26, v27
	v_cvt_pk_bf16_f32 v29, v24, v25
	v_lshl_add_u64 v[24:25], v[122:123], 0, s[12:13]
	v_cvt_pk_bf16_f32 v27, v30, v31
	v_lshl_add_u64 v[30:31], v[24:25], 0, v[124:125]
	v_lshl_add_u64 v[30:31], v[30:31], 0, s[10:11]
	v_cvt_pk_bf16_f32 v26, v32, v33
	v_cvt_pk_bf16_f32 v28, v35, v34
	v_lshl_add_u64 v[30:31], v[30:31], 0, v[48:49]
	global_store_dwordx4 v[30:31], v[26:29], off
	s_nop 1
	v_mul_f32_e32 v27, 0x3d372713, v16
	v_mul_f32_e32 v27, v16, v27
	v_fma_f32 v27, v16, v27, v16
	v_mul_f32_e32 v27, 0xbfcc422a, v27
	v_mul_f32_e32 v27, 0x3fb8aa3b, v27
	v_mul_f32_e32 v26, 0x3d372713, v20
	v_exp_f32_e32 v28, v27
	v_mul_f32_e32 v27, 0x3d372713, v21
	v_mul_f32_e32 v26, v20, v26
	v_mul_f32_e32 v27, v21, v27
	v_fma_f32 v26, v20, v26, v20
	v_fma_f32 v27, v21, v27, v21
	v_mul_f32_e32 v26, 0xbfcc422a, v26
	v_mul_f32_e32 v27, 0xbfcc422a, v27
	v_mul_f32_e32 v26, 0x3fb8aa3b, v26
	v_mul_f32_e32 v27, 0x3fb8aa3b, v27
	v_exp_f32_e32 v26, v26
	v_exp_f32_e32 v27, v27
	s_nop 0
	v_pk_add_f32 v[26:27], v[26:27], 1.0 op_sel_hi:[1,0]
	s_nop 0
	s_nop 0
	v_rcp_f32_e32 v29, v27
	s_nop 0
	v_mul_f32_e32 v27, v21, v29
	s_nop 0
	v_rcp_f32_e32 v21, v26
	s_nop 0
	v_mul_f32_e32 v26, v20, v21
	v_mul_f32_e32 v20, 0x3d372713, v17
	v_mul_f32_e32 v20, v17, v20
	v_fma_f32 v20, v17, v20, v17
	v_mul_f32_e32 v20, 0xbfcc422a, v20
	v_mul_f32_e32 v20, 0x3fb8aa3b, v20
	v_exp_f32_e32 v29, v20
	s_nop 0
	v_pk_add_f32 v[20:21], v[28:29], 1.0 op_sel_hi:[1,0]
	s_nop 0
	s_nop 0
	v_rcp_f32_e32 v28, v21
	s_nop 0
	v_mul_f32_e32 v28, v17, v28
	s_nop 0
	v_rcp_f32_e32 v17, v20
	s_nop 0
	v_mul_f32_e32 v29, v16, v17
	v_mul_f32_e32 v17, 0x3d372713, v18
	v_mul_f32_e32 v17, v18, v17
	v_fma_f32 v17, v18, v17, v18
	v_mul_f32_e32 v17, 0xbfcc422a, v17
	v_mul_f32_e32 v17, 0x3fb8aa3b, v17
	v_mul_f32_e32 v16, 0x3d372713, v22
	v_exp_f32_e32 v20, v17
	v_mul_f32_e32 v17, 0x3d372713, v23
	v_mul_f32_e32 v16, v22, v16
	v_mul_f32_e32 v17, v23, v17
	v_fma_f32 v16, v22, v16, v22
	v_fma_f32 v17, v23, v17, v23
	v_mul_f32_e32 v16, 0xbfcc422a, v16
	v_mul_f32_e32 v17, 0xbfcc422a, v17
	v_mul_f32_e32 v16, 0x3fb8aa3b, v16
	v_mul_f32_e32 v17, 0x3fb8aa3b, v17
	v_exp_f32_e32 v16, v16
	v_exp_f32_e32 v17, v17
	s_nop 0
	v_pk_add_f32 v[16:17], v[16:17], 1.0 op_sel_hi:[1,0]
	s_nop 0
	s_nop 0
	v_rcp_f32_e32 v21, v17
	s_nop 0
	v_mul_f32_e32 v23, v23, v21
	s_nop 0
	v_rcp_f32_e32 v17, v16
	s_nop 0
	v_mul_f32_e32 v22, v22, v17
	v_mul_f32_e32 v16, 0x3d372713, v19
	v_mul_f32_e32 v16, v19, v16
	v_fma_f32 v16, v19, v16, v19
	v_mul_f32_e32 v16, 0xbfcc422a, v16
	v_mul_f32_e32 v16, 0x3fb8aa3b, v16
	v_exp_f32_e32 v21, v16
	s_nop 0
	v_pk_add_f32 v[16:17], v[20:21], 1.0 op_sel_hi:[1,0]
	s_nop 0
	s_nop 0
	v_rcp_f32_e32 v20, v17
	s_nop 0
	v_mul_f32_e32 v19, v19, v20
	s_nop 0
	v_rcp_f32_e32 v17, v16
	s_nop 0
	v_mul_f32_e32 v20, v18, v17
	v_cvt_pk_bf16_f32 v19, v20, v19
	v_lshl_add_u64 v[20:21], v[24:25], 0, v[114:115]
	v_lshl_add_u64 v[20:21], v[20:21], 0, s[10:11]
	v_cvt_pk_bf16_f32 v16, v26, v27
	v_cvt_pk_bf16_f32 v17, v22, v23
	v_cvt_pk_bf16_f32 v18, v29, v28
	v_lshl_add_u64 v[20:21], v[20:21], 0, v[48:49]
	global_store_dwordx4 v[20:21], v[16:19], off
	s_nop 1
	v_mul_f32_e32 v17, 0x3d372713, v8
	v_mul_f32_e32 v17, v8, v17
	v_fma_f32 v17, v8, v17, v8
	v_mul_f32_e32 v17, 0xbfcc422a, v17
	v_mul_f32_e32 v17, 0x3fb8aa3b, v17
	v_mul_f32_e32 v16, 0x3d372713, v12
	v_exp_f32_e32 v18, v17
	v_mul_f32_e32 v17, 0x3d372713, v13
	v_mul_f32_e32 v16, v12, v16
	v_mul_f32_e32 v17, v13, v17
	v_fma_f32 v16, v12, v16, v12
	v_fma_f32 v17, v13, v17, v13
	v_mul_f32_e32 v16, 0xbfcc422a, v16
	v_mul_f32_e32 v17, 0xbfcc422a, v17
	v_mul_f32_e32 v16, 0x3fb8aa3b, v16
	v_mul_f32_e32 v17, 0x3fb8aa3b, v17
	v_exp_f32_e32 v16, v16
	v_exp_f32_e32 v17, v17
	s_nop 0
	v_pk_add_f32 v[16:17], v[16:17], 1.0 op_sel_hi:[1,0]
	s_nop 0
	s_nop 0
	v_rcp_f32_e32 v19, v17
	s_nop 0
	v_mul_f32_e32 v17, v13, v19
	s_nop 0
	v_rcp_f32_e32 v13, v16
	s_nop 0
	v_mul_f32_e32 v16, v12, v13
	v_mul_f32_e32 v12, 0x3d372713, v9
	v_mul_f32_e32 v12, v9, v12
	v_fma_f32 v12, v9, v12, v9
	v_mul_f32_e32 v12, 0xbfcc422a, v12
	v_mul_f32_e32 v12, 0x3fb8aa3b, v12
	v_exp_f32_e32 v19, v12
	s_nop 0
	v_pk_add_f32 v[12:13], v[18:19], 1.0 op_sel_hi:[1,0]
	s_nop 0
	s_nop 0
	v_rcp_f32_e32 v18, v13
	s_nop 0
	v_mul_f32_e32 v18, v9, v18
	s_nop 0
	v_rcp_f32_e32 v9, v12
	s_nop 0
	v_mul_f32_e32 v19, v8, v9
	v_mul_f32_e32 v9, 0x3d372713, v10
	v_mul_f32_e32 v9, v10, v9
	v_fma_f32 v9, v10, v9, v10
	v_mul_f32_e32 v9, 0xbfcc422a, v9
	v_mul_f32_e32 v9, 0x3fb8aa3b, v9
	v_mul_f32_e32 v8, 0x3d372713, v14
	v_exp_f32_e32 v12, v9
	v_mul_f32_e32 v9, 0x3d372713, v15
	v_mul_f32_e32 v8, v14, v8
	v_mul_f32_e32 v9, v15, v9
	v_fma_f32 v8, v14, v8, v14
	v_fma_f32 v9, v15, v9, v15
	v_mul_f32_e32 v8, 0xbfcc422a, v8
	v_mul_f32_e32 v9, 0xbfcc422a, v9
	v_mul_f32_e32 v8, 0x3fb8aa3b, v8
	v_mul_f32_e32 v9, 0x3fb8aa3b, v9
	v_exp_f32_e32 v8, v8
	v_exp_f32_e32 v9, v9
	s_nop 0
	v_pk_add_f32 v[8:9], v[8:9], 1.0 op_sel_hi:[1,0]
	s_nop 0
	s_nop 0
	v_rcp_f32_e32 v13, v9
	s_nop 0
	v_mul_f32_e32 v15, v15, v13
	s_nop 0
	v_rcp_f32_e32 v9, v8
	s_nop 0
	v_mul_f32_e32 v14, v14, v9
	v_mul_f32_e32 v8, 0x3d372713, v11
	v_mul_f32_e32 v8, v11, v8
	v_fma_f32 v8, v11, v8, v11
	v_mul_f32_e32 v8, 0xbfcc422a, v8
	v_mul_f32_e32 v8, 0x3fb8aa3b, v8
	v_exp_f32_e32 v13, v8
	s_nop 0
	v_pk_add_f32 v[8:9], v[12:13], 1.0 op_sel_hi:[1,0]
	s_nop 0
	s_nop 0
	v_rcp_f32_e32 v12, v9
	s_nop 0
	v_mul_f32_e32 v9, v11, v12
	s_mov_b64 s[12:13], 0x2c0000
	v_rcp_f32_e32 v11, v8
	s_nop 0
	v_mul_f32_e32 v8, v10, v11
	v_cvt_pk_bf16_f32 v13, v8, v9
	v_lshl_add_u64 v[8:9], v[122:123], 0, s[12:13]
	v_cvt_pk_bf16_f32 v11, v14, v15
	v_lshl_add_u64 v[14:15], v[8:9], 0, v[124:125]
	v_lshl_add_u64 v[14:15], v[14:15], 0, s[10:11]
	v_cvt_pk_bf16_f32 v10, v16, v17
	v_cvt_pk_bf16_f32 v12, v19, v18
	v_lshl_add_u64 v[14:15], v[14:15], 0, v[48:49]
	global_store_dwordx4 v[14:15], v[10:13], off
	s_nop 1
	v_mul_f32_e32 v11, 0x3d372713, v0
	v_mul_f32_e32 v11, v0, v11
	v_fma_f32 v11, v0, v11, v0
	v_mul_f32_e32 v11, 0xbfcc422a, v11
	v_mul_f32_e32 v11, 0x3fb8aa3b, v11
	v_mul_f32_e32 v10, 0x3d372713, v4
	v_exp_f32_e32 v12, v11
	v_mul_f32_e32 v11, 0x3d372713, v5
	v_mul_f32_e32 v10, v4, v10
	v_mul_f32_e32 v11, v5, v11
	v_fma_f32 v10, v4, v10, v4
	v_fma_f32 v11, v5, v11, v5
	v_mul_f32_e32 v10, 0xbfcc422a, v10
	v_mul_f32_e32 v11, 0xbfcc422a, v11
	v_mul_f32_e32 v10, 0x3fb8aa3b, v10
	v_mul_f32_e32 v11, 0x3fb8aa3b, v11
	v_exp_f32_e32 v10, v10
	v_exp_f32_e32 v11, v11
	s_nop 0
	v_pk_add_f32 v[10:11], v[10:11], 1.0 op_sel_hi:[1,0]
	s_nop 0
	s_nop 0
	v_rcp_f32_e32 v13, v11
	s_nop 0
	v_mul_f32_e32 v11, v5, v13
	s_nop 0
	v_rcp_f32_e32 v5, v10
	s_nop 0
	v_mul_f32_e32 v10, v4, v5
	v_mul_f32_e32 v4, 0x3d372713, v1
	v_mul_f32_e32 v4, v1, v4
	v_fma_f32 v4, v1, v4, v1
	v_mul_f32_e32 v4, 0xbfcc422a, v4
	v_mul_f32_e32 v4, 0x3fb8aa3b, v4
	v_exp_f32_e32 v13, v4
	s_nop 0
	v_pk_add_f32 v[4:5], v[12:13], 1.0 op_sel_hi:[1,0]
	s_nop 0
	s_nop 0
	v_rcp_f32_e32 v12, v5
	s_nop 0
	v_mul_f32_e32 v12, v1, v12
	s_nop 0
	v_rcp_f32_e32 v1, v4
	s_nop 0
	v_mul_f32_e32 v13, v0, v1
	v_mul_f32_e32 v1, 0x3d372713, v2
	v_mul_f32_e32 v1, v2, v1
	v_fma_f32 v1, v2, v1, v2
	v_mul_f32_e32 v1, 0xbfcc422a, v1
	v_mul_f32_e32 v1, 0x3fb8aa3b, v1
	v_mul_f32_e32 v0, 0x3d372713, v6
	v_exp_f32_e32 v4, v1
	v_mul_f32_e32 v1, 0x3d372713, v7
	v_mul_f32_e32 v0, v6, v0
	v_mul_f32_e32 v1, v7, v1
	v_fma_f32 v0, v6, v0, v6
	v_fma_f32 v1, v7, v1, v7
	v_mul_f32_e32 v0, 0xbfcc422a, v0
	v_mul_f32_e32 v1, 0xbfcc422a, v1
	v_mul_f32_e32 v0, 0x3fb8aa3b, v0
	v_mul_f32_e32 v1, 0x3fb8aa3b, v1
	v_exp_f32_e32 v0, v0
	v_exp_f32_e32 v1, v1
	s_nop 0
	v_pk_add_f32 v[0:1], v[0:1], 1.0 op_sel_hi:[1,0]
	s_nop 0
	s_nop 0
	v_rcp_f32_e32 v5, v1
	s_nop 0
	v_mul_f32_e32 v7, v7, v5
	s_nop 0
	v_rcp_f32_e32 v1, v0
	s_nop 0
	v_mul_f32_e32 v6, v6, v1
	v_mul_f32_e32 v0, 0x3d372713, v3
	v_mul_f32_e32 v0, v3, v0
	v_fma_f32 v0, v3, v0, v3
	v_mul_f32_e32 v0, 0xbfcc422a, v0
	v_mul_f32_e32 v0, 0x3fb8aa3b, v0
	v_exp_f32_e32 v5, v0
	s_nop 0
	v_pk_add_f32 v[0:1], v[4:5], 1.0 op_sel_hi:[1,0]
	s_nop 0
	s_nop 0
	v_rcp_f32_e32 v4, v1
	s_nop 0
	v_mul_f32_e32 v3, v3, v4
	s_mov_b64 s[12:13], s[6:7]
	v_rcp_f32_e32 v1, v0
	s_nop 0
	v_mul_f32_e32 v4, v2, v1
	v_cvt_pk_bf16_f32 v3, v4, v3
	v_lshl_add_u64 v[4:5], v[8:9], 0, v[114:115]
	v_lshl_add_u64 v[4:5], v[4:5], 0, s[10:11]
	v_cvt_pk_bf16_f32 v0, v10, v11
	v_cvt_pk_bf16_f32 v1, v6, v7
	v_cvt_pk_bf16_f32 v2, v13, v12
	v_lshl_add_u64 v[4:5], v[4:5], 0, v[48:49]
	s_and_b64 vcc, exec, s[8:9]
	s_mov_b64 s[10:11], s[4:5]
	global_store_dwordx4 v[4:5], v[0:3], off
	s_cbranch_vccz .LBB0_819
	s_waitcnt vmcnt(0)
	s_cmpk_gt_u32 s18, 0xff
	s_cbranch_scc1 .LBB0_826
	s_barrier

.LBB0_920:
	s_xor_b64 s[62:63], s[62:63], -1
	s_andn2_b64 vcc, exec, s[80:81]
	s_cbranch_vccnz .LBB0_855
	ds_read_b128 v[0:3], v187 offset:52224
	ds_read_b128 v[4:7], v150 offset:27648
	ds_read_b128 v[32:35], v187 offset:52256
	ds_read_b128 v[36:39], v150 offset:27680
	v_readlane_b32 s0, v254, 2
	v_readlane_b32 s1, v254, 3
	s_waitcnt lgkmcnt(2)
	v_mfma_f32_32x32x16_bf16 v[16:31], v[0:3], v[4:7], 0
	ds_read_b128 v[0:3], v188 offset:52224
	ds_read_b128 v[4:7], v152 offset:27648
	ds_read_b128 v[40:43], v187 offset:52288
	ds_read_b128 v[44:47], v150 offset:27712
	v_cmp_lt_i32_e32 vcc, v231, v230
	v_lshl_add_u64 v[182:183], s[84:85], 0, v[154:155]
	s_nop 0
	v_cndmask_b32_e32 v48, v229, v231, vcc
	s_mul_i32 vcc_lo, s16, 0x180
	s_waitcnt lgkmcnt(2)
	v_mfma_f32_32x32x16_bf16 v[0:15], v[0:3], v[4:7], 0
	v_mfma_f32_32x32x16_bf16 v[16:31], v[32:35], v[36:39], v[16:31]
	ds_read_b128 v[32:35], v188 offset:52256
	ds_read_b128 v[36:39], v152 offset:27680
	ds_read_b128 v[98:101], v188 offset:52288
	ds_read_b128 v[102:105], v152 offset:27712
	s_waitcnt lgkmcnt(2)
	v_mfma_f32_32x32x16_bf16 v[0:15], v[32:35], v[36:39], v[0:15]
	v_mfma_f32_32x32x16_bf16 v[16:31], v[40:43], v[44:47], v[16:31]
	s_waitcnt lgkmcnt(0)
	v_mfma_f32_32x32x16_bf16 v[0:15], v[98:101], v[102:105], v[0:15]
	s_nop 9
	v_cndmask_b32_e64 v16, v16, 0, s[0:1]
	v_readlane_b32 s0, v254, 4
	v_readlane_b32 s1, v254, 5
	v_cndmask_b32_e64 v0, v0, 0, s[18:19]
	s_nop 0
	v_cndmask_b32_e64 v1, v1, 0, s[0:1]
	v_readlane_b32 s0, v254, 6
	v_add_f32_e32 v16, v16, v0
	v_cndmask_b32_e64 v0, 0, v17, s[18:19]
	v_readlane_b32 s1, v254, 7
	v_add_f32_e32 v17, v0, v1
	s_nop 0
	v_cndmask_b32_e64 v1, v19, 0, s[0:1]
	v_readlane_b32 s0, v254, 8
	v_readlane_b32 s1, v254, 9
	s_nop 1
	v_cndmask_b32_e64 v0, v18, 0, s[0:1]
	v_readlane_b32 s0, v254, 10
	v_readlane_b32 s1, v254, 11
	s_nop 1
	v_cndmask_b32_e64 v3, v3, 0, s[0:1]
	v_readlane_b32 s0, v254, 12
	v_readlane_b32 s1, v254, 13
	s_nop 1
	v_cndmask_b32_e64 v2, v2, 0, s[0:1]
	v_readlane_b32 s0, v254, 14
	v_pk_add_f32 v[0:1], v[0:1], v[2:3]
	v_readlane_b32 s1, v254, 15
	v_cvt_pk_bf16_f32 v3, v0, v1
	v_cvt_pk_bf16_f32 v2, v16, v17
	v_cndmask_b32_e64 v1, v21, 0, s[0:1]
	v_readlane_b32 s0, v254, 16
	v_readlane_b32 s1, v254, 17
	s_nop 1
	v_cndmask_b32_e64 v0, v20, 0, s[0:1]
	v_readlane_b32 s0, v254, 23
	v_readlane_b32 s1, v254, 24
	s_nop 1
	v_cndmask_b32_e64 v5, v5, 0, s[0:1]
	v_readlane_b32 s0, v254, 25
	v_readlane_b32 s1, v254, 26
	s_nop 1
	v_cndmask_b32_e64 v4, v4, 0, s[0:1]
	v_readlane_b32 s0, v254, 27
	v_readlane_b32 s1, v254, 28
	v_pk_add_f32 v[0:1], v[0:1], v[4:5]
	s_nop 0
	v_cndmask_b32_e64 v5, v23, 0, s[0:1]
	v_readlane_b32 s0, v254, 29
	v_readlane_b32 s1, v254, 30
	v_cvt_pk_bf16_f32 v0, v0, v1
	s_nop 0
	v_cndmask_b32_e64 v4, v22, 0, s[0:1]
	v_readlane_b32 s0, v254, 31
	v_readlane_b32 s1, v254, 32
	s_nop 1
	v_cndmask_b32_e64 v7, v7, 0, s[0:1]
	v_readlane_b32 s0, v254, 33
	v_readlane_b32 s1, v254, 34
	s_nop 1
	v_cndmask_b32_e64 v6, v6, 0, s[0:1]
	v_pk_add_f32 v[4:5], v[4:5], v[6:7]
	v_readlane_b32 s0, v254, 35
	v_cvt_pk_bf16_f32 v1, v4, v5
	v_readlane_b32 s1, v254, 36
	ds_write2_b64 v151, v[2:3], v[0:1] offset1:2
	s_nop 0
	v_cndmask_b32_e64 v1, v25, 0, s[0:1]
	v_readlane_b32 s0, v254, 37
	v_readlane_b32 s1, v254, 38
	s_nop 1
	v_cndmask_b32_e64 v0, v24, 0, s[0:1]
	v_readlane_b32 s0, v254, 39
	v_readlane_b32 s1, v254, 40
	s_nop 1
	v_cndmask_b32_e64 v3, v9, 0, s[0:1]
	v_readlane_b32 s0, v254, 41
	v_readlane_b32 s1, v254, 42
	s_nop 1
	v_cndmask_b32_e64 v2, v8, 0, s[0:1]
	v_readlane_b32 s0, v254, 43
	v_readlane_b32 s1, v254, 44
	v_pk_add_f32 v[0:1], v[0:1], v[2:3]
	s_nop 0
	v_cndmask_b32_e64 v3, v27, 0, s[0:1]
	v_readlane_b32 s0, v254, 45
	v_readlane_b32 s1, v254, 46
	v_cvt_pk_bf16_f32 v0, v0, v1
	s_nop 0
	v_cndmask_b32_e64 v2, v26, 0, s[0:1]
	v_readlane_b32 s0, v254, 47
	v_readlane_b32 s1, v254, 48
	s_nop 1
	v_cndmask_b32_e64 v5, v11, 0, s[0:1]
	v_readlane_b32 s0, v254, 49
	v_readlane_b32 s1, v254, 50
	s_nop 1
	v_cndmask_b32_e64 v4, v10, 0, s[0:1]
	v_readlane_b32 s0, v254, 51
	v_pk_add_f32 v[2:3], v[2:3], v[4:5]
	v_readlane_b32 s1, v254, 52
	v_cvt_pk_bf16_f32 v1, v2, v3
	s_nop 0
	v_cndmask_b32_e64 v3, v29, 0, s[0:1]
	v_readlane_b32 s0, v254, 53
	v_readlane_b32 s1, v254, 54
	s_nop 1
	v_cndmask_b32_e64 v2, v28, 0, s[0:1]
	v_readlane_b32 s0, v254, 55
	v_readlane_b32 s1, v254, 56
	s_nop 1
	v_cndmask_b32_e64 v5, v13, 0, s[0:1]
	v_readlane_b32 s0, v254, 57
	v_readlane_b32 s1, v254, 58
	s_nop 1
	v_cndmask_b32_e64 v4, v12, 0, s[0:1]
	v_readlane_b32 s0, v254, 59
	v_readlane_b32 s1, v254, 60
	v_pk_add_f32 v[2:3], v[2:3], v[4:5]
	s_nop 0
	v_cndmask_b32_e64 v5, v31, 0, s[0:1]
	v_readlane_b32 s0, v254, 61
	v_readlane_b32 s1, v254, 62
	v_cvt_pk_bf16_f32 v2, v2, v3
	s_nop 0
	v_cndmask_b32_e64 v4, v30, 0, s[0:1]
	v_readlane_b32 s0, v254, 63
	v_readlane_b32 s1, v255, 0
	s_nop 1
	v_cndmask_b32_e64 v7, v15, 0, s[0:1]
	v_readlane_b32 s0, v255, 1
	v_readlane_b32 s1, v255, 2
	s_nop 1
	v_cndmask_b32_e64 v6, v14, 0, s[0:1]
	v_pk_add_f32 v[4:5], v[4:5], v[6:7]
	v_readlane_b32 s0, v255, 3
	v_cvt_pk_bf16_f32 v3, v4, v5
	ds_write2_b64 v151, v[0:1], v[2:3] offset0:4 offset1:6
	ds_read_b128 v[0:3], v187 offset:55296
	ds_read_b128 v[4:7], v150 offset:27648
	ds_read_b128 v[32:35], v187 offset:55328
	ds_read_b128 v[36:39], v150 offset:27680
	s_waitcnt lgkmcnt(2)
	v_mfma_f32_32x32x16_bf16 v[0:15], v[0:3], v[4:7], 0
	ds_read_b128 v[16:19], v187 offset:61440
	ds_read_b128 v[20:23], v152 offset:27648
	ds_read_b128 v[40:43], v187 offset:55360
	ds_read_b128 v[44:47], v150 offset:27712
	v_readlane_b32 s1, v255, 4
	s_waitcnt lgkmcnt(2)
	v_mfma_f32_32x32x16_bf16 v[16:31], v[16:19], v[20:23], 0
	v_mfma_f32_32x32x16_bf16 v[0:15], v[32:35], v[36:39], v[0:15]
	ds_read_b128 v[32:35], v187 offset:61472
	ds_read_b128 v[36:39], v152 offset:27680
	ds_read_b128 v[98:101], v187 offset:61504
	ds_read_b128 v[102:105], v152 offset:27712
	s_waitcnt lgkmcnt(2)
	v_mfma_f32_32x32x16_bf16 v[16:31], v[32:35], v[36:39], v[16:31]
	v_mfma_f32_32x32x16_bf16 v[0:15], v[40:43], v[44:47], v[0:15]
	s_waitcnt lgkmcnt(0)
	v_mfma_f32_32x32x16_bf16 v[16:31], v[98:101], v[102:105], v[16:31]
	s_nop 9
	v_cndmask_b32_e64 v1, v1, 0, s[0:1]
	v_readlane_b32 s0, v255, 5
	v_readlane_b32 s1, v255, 6
	s_nop 1
	v_cndmask_b32_e64 v0, v0, 0, s[0:1]
	v_readlane_b32 s0, v255, 7
	v_readlane_b32 s1, v255, 8
	s_nop 1
	v_cndmask_b32_e64 v17, v17, 0, s[0:1]
	v_readlane_b32 s0, v255, 9
	v_readlane_b32 s1, v255, 10
	s_nop 1
	v_cndmask_b32_e64 v16, v16, 0, s[0:1]
	v_readlane_b32 s0, v255, 11
	v_readlane_b32 s1, v255, 12
	v_pk_add_f32 v[0:1], v[0:1], v[16:17]
	s_nop 0
	v_cndmask_b32_e64 v3, v3, 0, s[0:1]
	v_readlane_b32 s0, v255, 13
	v_readlane_b32 s1, v255, 14
	v_cvt_pk_bf16_f32 v0, v0, v1
	s_nop 0
	v_cndmask_b32_e64 v2, v2, 0, s[0:1]
	v_readlane_b32 s0, v255, 15
	v_readlane_b32 s1, v255, 16
	s_nop 1
	v_cndmask_b32_e64 v17, v19, 0, s[0:1]
	v_readlane_b32 s0, v255, 17
	v_readlane_b32 s1, v255, 18
	s_nop 1
	v_cndmask_b32_e64 v16, v18, 0, s[0:1]
	v_readlane_b32 s0, v255, 19
	v_pk_add_f32 v[2:3], v[2:3], v[16:17]
	v_readlane_b32 s1, v255, 20
	v_cvt_pk_bf16_f32 v1, v2, v3
	s_nop 0
	v_cndmask_b32_e64 v3, v5, 0, s[0:1]
	v_readlane_b32 s0, v255, 21
	v_readlane_b32 s1, v255, 22
	s_nop 1
	v_cndmask_b32_e64 v2, v4, 0, s[0:1]
	v_readlane_b32 s0, v255, 23
	v_readlane_b32 s1, v255, 24
	s_nop 1
	v_cndmask_b32_e64 v5, v21, 0, s[0:1]
	v_readlane_b32 s0, v255, 25
	v_readlane_b32 s1, v255, 26
	s_nop 1
	v_cndmask_b32_e64 v4, v20, 0, s[0:1]
	v_readlane_b32 s0, v255, 27
	v_readlane_b32 s1, v255, 28
	v_pk_add_f32 v[2:3], v[2:3], v[4:5]
	s_nop 0
	v_cndmask_b32_e64 v5, v7, 0, s[0:1]
	v_readlane_b32 s0, v255, 29
	v_readlane_b32 s1, v255, 30
	v_cvt_pk_bf16_f32 v2, v2, v3
	s_nop 0
	v_cndmask_b32_e64 v4, v6, 0, s[0:1]
	v_readlane_b32 s0, v255, 31
	v_readlane_b32 s1, v255, 32
	v_cndmask_b32_e64 v6, v22, 0, s[24:25]
	s_nop 0
	v_cndmask_b32_e64 v7, v23, 0, s[0:1]
	v_pk_add_f32 v[4:5], v[4:5], v[6:7]
	v_cndmask_b32_e64 v7, v31, 0, s[56:57]
	v_cvt_pk_bf16_f32 v3, v4, v5
	ds_write2_b64 v151, v[0:1], v[2:3] offset0:8 offset1:10
	v_cndmask_b32_e64 v1, v9, 0, s[26:27]
	v_cndmask_b32_e64 v0, v8, 0, s[28:29]
	v_cndmask_b32_e64 v3, v25, 0, s[30:31]
	v_cndmask_b32_e64 v2, v24, 0, s[34:35]
	v_pk_add_f32 v[0:1], v[0:1], v[2:3]
	v_cndmask_b32_e64 v3, v11, 0, s[36:37]
	v_cndmask_b32_e64 v2, v10, 0, s[38:39]
	v_cndmask_b32_e64 v5, v27, 0, s[40:41]
	v_cndmask_b32_e64 v4, v26, 0, s[42:43]
	v_pk_add_f32 v[2:3], v[2:3], v[4:5]
	v_cvt_pk_bf16_f32 v0, v0, v1
	v_cvt_pk_bf16_f32 v1, v2, v3
	v_cndmask_b32_e64 v3, v13, 0, s[44:45]
	v_cndmask_b32_e64 v2, v12, 0, s[46:47]
	v_cndmask_b32_e64 v5, v29, 0, s[48:49]
	v_cndmask_b32_e64 v4, v28, 0, s[50:51]
	v_pk_add_f32 v[2:3], v[2:3], v[4:5]
	v_cndmask_b32_e64 v5, v15, 0, s[52:53]
	v_cndmask_b32_e64 v4, v14, 0, s[54:55]
	v_cndmask_b32_e64 v6, v30, 0, s[58:59]
	v_pk_add_f32 v[4:5], v[4:5], v[6:7]
	v_cvt_pk_bf16_f32 v2, v2, v3
	v_cvt_pk_bf16_f32 v3, v4, v5
	ds_write2_b64 v151, v[0:1], v[2:3] offset0:12 offset1:14
	s_waitcnt lgkmcnt(0)
	ds_read_b128 v[0:3], v189
	v_add_u32_e32 v12, v151, v186
	ds_read_b128 v[4:7], v12
	ds_read_b128 v[8:11], v189 offset:32
	ds_read_b128 v[130:133], v12 offset:32
	s_waitcnt lgkmcnt(2)
	v_mfma_f32_32x32x16_bf16 v[32:47], v[0:3], v[4:7], 0
	s_lshl_b32 s0, s17, 1
	s_add_i32 s0, s0, s6
	s_lshl_b32 s1, vcc_lo, 2
	s_mul_i32 s84, s0, 0x60
	s_add_i32 s16, s1, 0
	s_lshl_b32 s0, s84, 2
	s_add_i32 s16, s16, s0
	s_waitcnt lgkmcnt(0)
	v_mfma_f32_32x32x16_bf16 v[32:47], v[8:11], v[130:133], v[32:47]
	ds_read_b128 v[0:3], v189 offset:64
	ds_read_b128 v[126:129], v12 offset:64
	ds_read_b128 v[8:11], v189 offset:96
	ds_read_b128 v[118:121], v12 offset:96
	s_add_i32 s16, s16, 0x20400
	s_and_b64 s[0:1], s[60:61], exec
	v_readlane_b32 s0, v253, 42
	v_readlane_b32 s1, v253, 43
	s_movk_i32 s17, 0x140
	s_waitcnt lgkmcnt(2)
	v_mfma_f32_32x32x16_bf16 v[32:47], v[0:3], v[126:129], v[32:47]
	s_waitcnt lgkmcnt(0)
	v_mfma_f32_32x32x16_bf16 v[32:47], v[8:11], v[118:121], v[32:47]
	ds_read_b128 v[0:3], v190
	ds_read_b128 v[122:125], v191 offset:27648
	ds_read_b128 v[8:11], v190 offset:32
	ds_read_b128 v[12:15], v190 offset:64
	ds_read_b128 v[114:117], v191 offset:27680
	ds_read_b128 v[110:113], v191 offset:27712
	s_waitcnt lgkmcnt(4)
	v_mfma_f32_32x32x16_bf16 v[32:47], v[0:3], v[122:125], v[32:47]
	s_waitcnt lgkmcnt(1)
	v_mfma_f32_32x32x16_bf16 v[32:47], v[8:11], v[114:117], v[32:47]
	s_waitcnt lgkmcnt(0)
	v_mfma_f32_32x32x16_bf16 v[32:47], v[12:15], v[110:113], v[32:47]
	ds_read_b128 v[0:3], v192
	ds_read_b128 v[106:109], v193 offset:27648
	ds_read_b128 v[8:11], v192 offset:32
	ds_read_b128 v[12:15], v192 offset:64
	ds_read_b128 v[102:105], v193 offset:27680
	ds_read_b128 v[98:101], v193 offset:27712
	s_waitcnt lgkmcnt(4)
	v_mfma_f32_32x32x16_bf16 v[32:47], v[0:3], v[106:109], v[32:47]
	s_waitcnt lgkmcnt(1)
	v_mfma_f32_32x32x16_bf16 v[32:47], v[8:11], v[102:105], v[32:47]
	ds_read_b128 v[0:3], v189 offset:4608
	ds_read_b128 v[8:11], v189 offset:4640
	s_waitcnt lgkmcnt(1)
	v_mfma_f32_32x32x16_bf16 v[16:31], v[0:3], v[4:7], 0
	s_waitcnt lgkmcnt(0)
	v_mfma_f32_32x32x16_bf16 v[16:31], v[8:11], v[130:133], v[16:31]
	ds_read_b128 v[0:3], v189 offset:4672
	ds_read_b128 v[8:11], v189 offset:4704
	s_waitcnt lgkmcnt(1)
	v_mfma_f32_32x32x16_bf16 v[16:31], v[0:3], v[126:129], v[16:31]
	s_waitcnt lgkmcnt(0)
	v_mfma_f32_32x32x16_bf16 v[16:31], v[8:11], v[118:121], v[16:31]
	ds_read_b128 v[0:3], v198
	ds_read_b128 v[8:11], v198 offset:32
	s_waitcnt lgkmcnt(1)
	v_mfma_f32_32x32x16_bf16 v[16:31], v[0:3], v[122:125], v[16:31]
	s_waitcnt lgkmcnt(0)
	v_mfma_f32_32x32x16_bf16 v[16:31], v[8:11], v[114:117], v[16:31]
	ds_read_b128 v[0:3], v198 offset:64
	ds_read_b128 v[8:11], v199
	s_waitcnt lgkmcnt(1)
	v_mfma_f32_32x32x16_bf16 v[16:31], v[0:3], v[110:113], v[16:31]
	s_waitcnt lgkmcnt(0)
	v_mfma_f32_32x32x16_bf16 v[16:31], v[8:11], v[106:109], v[16:31]
	ds_read_b128 v[0:3], v199 offset:32
	ds_read_b128 v[8:11], v199 offset:64
	s_waitcnt lgkmcnt(1)
	v_mfma_f32_32x32x16_bf16 v[16:31], v[0:3], v[102:105], v[16:31]
	ds_read_b128 v[0:3], v189 offset:9216
	ds_read_b128 v[134:137], v189 offset:9248
	v_mfma_f32_32x32x16_bf16 v[32:47], v[12:15], v[98:101], v[32:47]
	s_waitcnt lgkmcnt(2)
	v_mfma_f32_32x32x16_bf16 v[16:31], v[8:11], v[98:101], v[16:31]
	s_nop 9
	v_add_f32_e32 v202, 0, v32
	v_add_f32_e32 v202, v33, v202
	v_add_f32_e32 v202, v34, v202
	v_add_f32_e32 v202, v35, v202
	s_waitcnt lgkmcnt(1)
	v_mfma_f32_32x32x16_bf16 v[0:15], v[0:3], v[4:7], 0
	s_waitcnt lgkmcnt(0)
	v_mfma_f32_32x32x16_bf16 v[0:15], v[134:137], v[130:133], v[0:15]
	ds_read_b128 v[130:133], v189 offset:9280
	ds_read_b128 v[134:137], v189 offset:9312
	s_waitcnt lgkmcnt(1)
	v_mfma_f32_32x32x16_bf16 v[0:15], v[130:133], v[126:129], v[0:15]
	s_waitcnt lgkmcnt(0)
	v_mfma_f32_32x32x16_bf16 v[0:15], v[134:137], v[118:121], v[0:15]
	ds_read_b128 v[118:121], v200
	ds_read_b128 v[126:129], v200 offset:32
	s_waitcnt lgkmcnt(1)
	v_mfma_f32_32x32x16_bf16 v[0:15], v[118:121], v[122:125], v[0:15]
	ds_read_b128 v[118:121], v200 offset:64
	ds_read_b128 v[122:125], v201
	ds_read_b128 v[130:133], v201 offset:32
	ds_read_b128 v[134:137], v201 offset:64
	s_waitcnt lgkmcnt(4)
	v_mfma_f32_32x32x16_bf16 v[0:15], v[126:129], v[114:117], v[0:15]
	v_add_f32_e32 v114, v36, v202
	v_add_f32_e32 v114, v37, v114
	v_add_f32_e32 v114, v38, v114
	v_add_f32_e32 v114, v39, v114
	v_add_f32_e32 v114, v40, v114
	v_add_f32_e32 v114, v41, v114
	v_add_f32_e32 v114, v42, v114
	s_waitcnt lgkmcnt(3)
	v_mfma_f32_32x32x16_bf16 v[0:15], v[118:121], v[110:113], v[0:15]
	v_add_f32_e32 v110, v43, v114
	v_add_f32_e32 v110, v44, v110
	v_add_f32_e32 v110, v45, v110
	v_add_f32_e32 v110, v46, v110
	v_add_f32_e32 v110, v47, v110
	v_add_f32_e32 v110, v110, v16
	v_add_f32_e32 v110, v17, v110
	s_waitcnt lgkmcnt(2)
	v_mfma_f32_32x32x16_bf16 v[0:15], v[122:125], v[106:109], v[0:15]
	v_add_f32_e32 v106, v18, v110
	v_add_f32_e32 v106, v19, v106
	v_add_f32_e32 v106, v20, v106
	v_add_f32_e32 v106, v21, v106
	v_add_f32_e32 v106, v22, v106
	v_add_f32_e32 v106, v23, v106
	v_add_f32_e32 v106, v24, v106
	s_waitcnt lgkmcnt(1)
	v_mfma_f32_32x32x16_bf16 v[0:15], v[130:133], v[102:105], v[0:15]
	v_add_f32_e32 v102, v25, v106
	v_add_f32_e32 v102, v26, v102
	v_add_f32_e32 v102, v27, v102
	v_add_f32_e32 v102, v28, v102
	v_add_f32_e32 v102, v29, v102
	v_add_f32_e32 v102, v30, v102
	v_add_f32_e32 v102, v31, v102
	s_waitcnt lgkmcnt(0)
	v_mfma_f32_32x32x16_bf16 v[0:15], v[134:137], v[98:101], v[0:15]
	v_lshlrev_b32_e32 v121, 2, v48
	s_nop 10
	v_add_f32_e32 v98, v102, v0
	v_add_f32_e32 v98, v1, v98
	v_add_f32_e32 v98, v2, v98
	v_add_f32_e32 v98, v3, v98
	v_add_f32_e32 v98, v4, v98
	v_add_f32_e32 v98, v5, v98
	v_add_f32_e32 v98, v6, v98
	v_add_f32_e32 v98, v7, v98
	v_add_f32_e32 v98, v8, v98
	v_add_f32_e32 v98, v9, v98
	v_add_f32_e32 v98, v10, v98
	v_add_f32_e32 v98, v11, v98
	v_add_f32_e32 v98, v12, v98
	v_add_f32_e32 v98, v13, v98
	v_add_f32_e32 v98, v14, v98
	v_add_f32_e32 v98, v15, v98
	ds_bpermute_b32 v48, v121, v98
	s_waitcnt lgkmcnt(0)
	v_add_f32_e32 v48, v98, v48
	v_lshlrev_b64 v[98:99], 11, v[182:183]
	v_lshl_add_u64 v[98:99], s[0:1], 0, v[98:99]
	s_movk_i32 s0, 0x780
	s_cselect_b32 s0, 0x300, s0
	s_ashr_i32 vcc_hi, vcc_lo, 31
	s_add_i32 s0, s84, s0
	v_lshl_add_u64 v[98:99], vcc, 1, v[98:99]
	s_ashr_i32 s85, s84, 31
	s_ashr_i32 s0, s0, 3
	v_mul_f32_e32 v48, 0x3c2aaaab, v48
	v_lshl_add_u64 v[114:115], s[84:85], 1, v[98:99]
	v_mov_b32_e32 v98, s0
	s_ashr_i32 s0, s0, 31
	v_cndmask_b32_e64 v120, 0, v48, s[60:61]
	v_mov_b32_e32 v99, s0
	v_alignbit_b32 v48, v183, v182, 6
	v_mad_u64_u32 v[98:99], s[0:1], v48, s17, v[98:99]
	v_mov_b32_e32 v48, v99
	v_lshrrev_b32_e32 v99, 6, v183
	v_mad_u64_u32 v[100:101], s[0:1], v99, s17, v[48:49]
	v_mov_b32_e32 v99, v100
	v_lshlrev_b64 v[98:99], 10, v[98:99]
	v_lshlrev_b32_e32 v48, 4, v182
	v_lshl_add_u64 v[98:99], s[70:71], 0, v[98:99]
	v_and_b32_e32 v48, 0x3f0, v48
	v_lshl_add_u64 v[98:99], v[98:99], 0, v[48:49]
	v_lshlrev_b32_e32 v48, 1, v156
	v_lshl_add_u64 v[102:103], v[98:99], 0, v[48:49]
	s_waitcnt vmcnt(0)
	v_lshrrev_b32_e32 v98, 6, v224
	v_mul_u32_u24_e32 v98, 0x1400, v98
	v_and_b32_e32 v100, 63, v224
	v_lshl_add_u32 v98, v100, 4, v98
	v_add_u32_e32 v98, 0x21000, v98
	ds_write_b128 v98, v[50:53]
	ds_write_b128 v98, v[54:57] offset:1024
	ds_write_b128 v98, v[58:61] offset:2048
	ds_write_b128 v98, v[62:65] offset:3072
	ds_write_b128 v98, v[66:69] offset:4096
	v_add_co_u32_e32 v104, vcc, 0x1000, v102
	s_nop 1
	v_addc_co_u32_e32 v105, vcc, 0, v103, vcc
	v_add_co_u32_e32 v106, vcc, 0x2000, v102
	s_nop 1
	v_addc_co_u32_e32 v107, vcc, 0, v103, vcc
	global_load_dwordx2 v[98:99], v[102:103], off
	global_load_dwordx2 v[100:101], v[102:103], off offset:1024
	global_load_dwordx2 v[50:51], v[102:103], off offset:2048
	global_load_dwordx2 v[52:53], v[102:103], off offset:3072
	global_load_dwordx2 v[54:55], v[104:105], off
	global_load_dwordx2 v[56:57], v[104:105], off offset:1024
	global_load_dwordx2 v[58:59], v[104:105], off offset:2048
	global_load_dwordx2 v[60:61], v[104:105], off offset:3072
	global_load_dwordx2 v[62:63], v[106:107], off
	global_load_dwordx2 v[64:65], v[106:107], off offset:1024
	global_load_dwordx2 v[66:67], v[106:107], off offset:2048
	global_load_dwordx2 v[68:69], v[106:107], off offset:3072
	v_pk_add_f32 v[204:205], v[32:33], v[120:121] op_sel_hi:[1,0] neg_lo:[0,1] neg_hi:[0,1]
	v_pk_add_f32 v[110:111], v[38:39], v[120:121] op_sel_hi:[1,0] neg_lo:[0,1] neg_hi:[0,1]
	v_pk_mul_f32 v[206:207], v[204:205], v[204:205]
	v_pk_add_f32 v[118:119], v[36:37], v[120:121] op_sel_hi:[1,0] neg_lo:[0,1] neg_hi:[0,1]
	v_pk_add_f32 v[108:109], v[40:41], v[120:121] op_sel_hi:[1,0] neg_lo:[0,1] neg_hi:[0,1]
	v_pk_add_f32 v[46:47], v[46:47], v[120:121] op_sel_hi:[1,0] neg_lo:[0,1] neg_hi:[0,1]
	v_pk_add_f32 v[38:39], v[22:23], v[120:121] op_sel_hi:[1,0] neg_lo:[0,1] neg_hi:[0,1]
	v_pk_add_f32 v[40:41], v[20:21], v[120:121] op_sel_hi:[1,0] neg_lo:[0,1] neg_hi:[0,1]
	v_pk_add_f32 v[32:33], v[26:27], v[120:121] op_sel_hi:[1,0] neg_lo:[0,1] neg_hi:[0,1]
	v_pk_add_f32 v[30:31], v[30:31], v[120:121] op_sel_hi:[1,0] neg_lo:[0,1] neg_hi:[0,1]
	v_pk_add_f32 v[28:29], v[28:29], v[120:121] op_sel_hi:[1,0] neg_lo:[0,1] neg_hi:[0,1]
	v_pk_add_f32 v[26:27], v[0:1], v[120:121] op_sel_hi:[1,0] neg_lo:[0,1] neg_hi:[0,1]
	v_pk_add_f32 v[20:21], v[6:7], v[120:121] op_sel_hi:[1,0] neg_lo:[0,1] neg_hi:[0,1]
	v_pk_add_f32 v[22:23], v[4:5], v[120:121] op_sel_hi:[1,0] neg_lo:[0,1] neg_hi:[0,1]
	v_pk_mul_f32 v[36:37], v[118:119], v[118:119]
	v_pk_mul_f32 v[208:209], v[110:111], v[110:111]
	v_pk_mul_f32 v[212:213], v[108:109], v[108:109]
	v_pk_mul_f32 v[214:215], v[46:47], v[46:47]
	v_pk_mul_f32 v[220:221], v[40:41], v[40:41]
	v_pk_mul_f32 v[218:219], v[38:39], v[38:39]
	v_pk_mul_f32 v[222:223], v[32:33], v[32:33]
	v_pk_mul_f32 v[246:247], v[28:29], v[28:29]
	v_pk_mul_f32 v[244:245], v[30:31], v[30:31]
	v_pk_mul_f32 v[0:1], v[26:27], v[26:27]
	v_pk_mul_f32 v[4:5], v[22:23], v[22:23]
	v_pk_mul_f32 v[6:7], v[20:21], v[20:21]
	s_waitcnt vmcnt(11)
	v_lshlrev_b32_e32 v234, 16, v98
	v_and_b32_e32 v235, 0xffff0000, v98
	v_mul_f32_e32 v98, 0xbfb8aa3b, v234
	v_exp_f32_e32 v104, v98
	v_mul_f32_e32 v98, 0xbfb8aa3b, v235
	v_exp_f32_e32 v105, v98
	v_lshlrev_b32_e32 v250, 16, v99
	v_and_b32_e32 v251, 0xffff0000, v99
	v_mul_f32_e32 v99, 0xbfb8aa3b, v251
	v_pk_add_f32 v[122:123], v[104:105], 1.0 op_sel_hi:[1,0]
	v_exp_f32_e32 v99, v99
	v_div_scale_f32 v98, s[0:1], v123, v123, v235
	v_rcp_f32_e32 v104, v98
	s_waitcnt vmcnt(10)
	v_lshlrev_b32_e32 v126, 16, v100
	v_and_b32_e32 v127, 0xffff0000, v100
	v_lshlrev_b32_e32 v130, 16, v101
	v_fma_f32 v105, -v98, v104, 1.0
	v_fmac_f32_e32 v104, v105, v104
	v_div_scale_f32 v105, vcc, v235, v123, v235
	v_mul_f32_e32 v106, v105, v104
	v_fma_f32 v107, -v98, v106, v105
	v_fmac_f32_e32 v106, v107, v104
	v_fma_f32 v98, -v98, v106, v105
	v_div_fmas_f32 v248, v98, v104, v106
	v_div_scale_f32 v98, s[0:1], v122, v122, v234
	v_rcp_f32_e32 v104, v98
	v_and_b32_e32 v131, 0xffff0000, v101
	v_fma_f32 v105, -v98, v104, 1.0
	v_fmac_f32_e32 v104, v105, v104
	v_div_scale_f32 v105, vcc, v234, v122, v234
	v_mul_f32_e32 v106, v105, v104
	v_fma_f32 v107, -v98, v106, v105
	v_fmac_f32_e32 v106, v107, v104
	v_fma_f32 v98, -v98, v106, v105
	v_div_fmas_f32 v249, v98, v104, v106
	v_mul_f32_e32 v98, 0xbfb8aa3b, v250
	v_exp_f32_e32 v98, v98
	s_nop 0
	v_pk_add_f32 v[124:125], v[98:99], 1.0 op_sel_hi:[1,0]
	s_nop 0
	v_div_scale_f32 v98, s[0:1], v125, v125, v251
	v_rcp_f32_e32 v99, v98
	s_nop 0
	v_fma_f32 v104, -v98, v99, 1.0
	v_fmac_f32_e32 v99, v104, v99
	v_div_scale_f32 v104, vcc, v251, v125, v251
	v_mul_f32_e32 v105, v104, v99
	v_fma_f32 v106, -v98, v105, v104
	v_fmac_f32_e32 v105, v106, v99
	v_fma_f32 v98, -v98, v105, v104
	v_div_fmas_f32 v233, v98, v99, v105
	v_div_scale_f32 v98, s[0:1], v124, v124, v250
	v_rcp_f32_e32 v99, v98
	s_nop 0
	v_fma_f32 v104, -v98, v99, 1.0
	v_fmac_f32_e32 v99, v104, v99
	v_div_scale_f32 v104, vcc, v250, v124, v250
	v_mul_f32_e32 v105, v104, v99
	v_fma_f32 v106, -v98, v105, v104
	v_fmac_f32_e32 v105, v106, v99
	v_fma_f32 v98, -v98, v105, v104
	v_div_fmas_f32 v238, v98, v99, v105
	v_mul_f32_e32 v98, 0xbfb8aa3b, v126
	v_mul_f32_e32 v99, 0xbfb8aa3b, v127
	v_exp_f32_e32 v98, v98
	v_exp_f32_e32 v99, v99
	v_pk_add_f32 v[106:107], v[42:43], v[120:121] op_sel_hi:[1,0] neg_lo:[0,1] neg_hi:[0,1]
	v_pk_add_f32 v[42:43], v[18:19], v[120:121] op_sel_hi:[1,0] neg_lo:[0,1] neg_hi:[0,1]
	v_pk_mul_f32 v[210:211], v[106:107], v[106:107]
	v_pk_add_f32 v[112:113], v[98:99], 1.0 op_sel_hi:[1,0]
	v_pk_mul_f32 v[18:19], v[42:43], v[42:43]
	v_div_scale_f32 v98, s[0:1], v113, v113, v127
	v_rcp_f32_e32 v99, v98
	s_nop 0
	v_fma_f32 v100, -v98, v99, 1.0
	v_fmac_f32_e32 v99, v100, v99
	v_div_scale_f32 v100, vcc, v127, v113, v127
	v_mul_f32_e32 v104, v100, v99
	v_fma_f32 v105, -v98, v104, v100
	v_fmac_f32_e32 v104, v105, v99
	v_fma_f32 v98, -v98, v104, v100
	v_div_fmas_f32 v128, v98, v99, v104
	v_div_scale_f32 v98, s[0:1], v112, v112, v126
	v_rcp_f32_e32 v99, v98
	v_div_fixup_f32 v127, v128, v113, v127
	v_fma_f32 v100, -v98, v99, 1.0
	v_fmac_f32_e32 v99, v100, v99
	v_div_scale_f32 v100, vcc, v126, v112, v126
	v_mul_f32_e32 v104, v100, v99
	v_fma_f32 v105, -v98, v104, v100
	v_fmac_f32_e32 v104, v105, v99
	v_fma_f32 v98, -v98, v104, v100
	v_div_fmas_f32 v129, v98, v99, v104
	v_mul_f32_e32 v98, 0xbfb8aa3b, v130
	v_mul_f32_e32 v99, 0xbfb8aa3b, v131
	v_exp_f32_e32 v98, v98
	v_exp_f32_e32 v99, v99
	v_div_fixup_f32 v126, v129, v112, v126
	v_pk_add_f32 v[116:117], v[98:99], 1.0 op_sel_hi:[1,0]
	s_nop 0
	v_div_scale_f32 v98, s[0:1], v117, v117, v131
	v_rcp_f32_e32 v99, v98
	s_nop 0
	v_fma_f32 v100, -v98, v99, 1.0
	v_fmac_f32_e32 v99, v100, v99
	v_div_scale_f32 v100, vcc, v131, v117, v131
	v_mul_f32_e32 v101, v100, v99
	v_fma_f32 v104, -v98, v101, v100
	v_fmac_f32_e32 v101, v104, v99
	v_fma_f32 v98, -v98, v101, v100
	v_div_fmas_f32 v132, v98, v99, v101
	v_div_scale_f32 v98, s[0:1], v116, v116, v130
	v_rcp_f32_e32 v99, v98
	s_mov_b64 s[0:1], 0x2db14200
	v_div_fixup_f32 v117, v132, v117, v131
	v_fma_f32 v100, -v98, v99, 1.0
	v_fmac_f32_e32 v99, v100, v99
	v_div_scale_f32 v100, vcc, v130, v116, v130
	v_mul_f32_e32 v101, v100, v99
	v_fma_f32 v104, -v98, v101, v100
	v_fmac_f32_e32 v101, v104, v99
	v_fma_f32 v98, -v98, v101, v100
	v_div_fmas_f32 v133, v98, v99, v101
	v_pk_add_f32 v[100:101], v[10:11], v[120:121] op_sel_hi:[1,0] neg_lo:[0,1] neg_hi:[0,1]
	v_pk_add_f32 v[10:11], v[34:35], v[120:121] op_sel_hi:[1,0] neg_lo:[0,1] neg_hi:[0,1]
	v_pk_add_f32 v[98:99], v[12:13], v[120:121] op_sel_hi:[1,0] neg_lo:[0,1] neg_hi:[0,1]
	v_pk_add_f32 v[12:13], v[14:15], v[120:121] op_sel_hi:[1,0] neg_lo:[0,1] neg_hi:[0,1]
	v_pk_mul_f32 v[202:203], v[10:11], v[10:11]
	v_pk_add_f32 v[104:105], v[44:45], v[120:121] op_sel_hi:[1,0] neg_lo:[0,1] neg_hi:[0,1]
	v_pk_add_f32 v[44:45], v[16:17], v[120:121] op_sel_hi:[1,0] neg_lo:[0,1] neg_hi:[0,1]
	v_pk_add_f32 v[34:35], v[24:25], v[120:121] op_sel_hi:[1,0] neg_lo:[0,1] neg_hi:[0,1]
	v_pk_add_f32 v[24:25], v[2:3], v[120:121] op_sel_hi:[1,0] neg_lo:[0,1] neg_hi:[0,1]
	v_pk_add_f32 v[14:15], v[8:9], v[120:121] op_sel_hi:[1,0] neg_lo:[0,1] neg_hi:[0,1]
	v_add_f32_e32 v120, v206, v207
	v_add_f32_e32 v120, v202, v120
	v_add_f32_e32 v120, v203, v120
	v_add_f32_e32 v36, v36, v120
	v_add_f32_e32 v36, v37, v36
	v_add_f32_e32 v36, v208, v36
	v_add_f32_e32 v36, v209, v36
	v_add_f32_e32 v36, v212, v36
	v_add_f32_e32 v36, v213, v36
	v_add_f32_e32 v36, v210, v36
	v_pk_mul_f32 v[216:217], v[104:105], v[104:105]
	v_add_f32_e32 v36, v211, v36
	v_add_f32_e32 v36, v216, v36
	v_add_f32_e32 v36, v217, v36
	v_add_f32_e32 v36, v214, v36
	v_pk_mul_f32 v[16:17], v[44:45], v[44:45]
	v_add_f32_e32 v36, v215, v36
	v_add_f32_e32 v16, v16, v36
	v_add_f32_e32 v16, v17, v16
	v_add_f32_e32 v16, v18, v16
	v_add_f32_e32 v16, v19, v16
	v_add_f32_e32 v16, v220, v16
	v_add_f32_e32 v16, v221, v16
	v_add_f32_e32 v16, v218, v16
	v_pk_mul_f32 v[242:243], v[34:35], v[34:35]
	v_add_f32_e32 v16, v219, v16
	v_add_f32_e32 v16, v242, v16
	v_add_f32_e32 v16, v243, v16
	v_add_f32_e32 v16, v222, v16
	v_add_f32_e32 v16, v223, v16
	v_add_f32_e32 v16, v246, v16
	v_add_f32_e32 v16, v247, v16
	v_add_f32_e32 v16, v244, v16
	v_add_f32_e32 v16, v245, v16
	v_add_f32_e32 v0, v0, v16
	v_pk_mul_f32 v[2:3], v[24:25], v[24:25]
	v_add_f32_e32 v0, v1, v0
	v_add_f32_e32 v0, v2, v0
	v_add_f32_e32 v0, v3, v0
	v_add_f32_e32 v0, v4, v0
	v_add_f32_e32 v0, v5, v0
	v_add_f32_e32 v0, v6, v0
	v_pk_mul_f32 v[8:9], v[14:15], v[14:15]
	v_add_f32_e32 v0, v7, v0
	v_add_f32_e32 v0, v8, v0
	v_pk_mul_f32 v[134:135], v[100:101], v[100:101]
	v_add_f32_e32 v0, v9, v0
	v_add_f32_e32 v0, v134, v0
	v_pk_mul_f32 v[136:137], v[98:99], v[98:99]
	v_add_f32_e32 v0, v135, v0
	v_add_f32_e32 v0, v136, v0
	v_pk_mul_f32 v[182:183], v[12:13], v[12:13]
	v_add_f32_e32 v0, v137, v0
	v_add_f32_e32 v0, v182, v0
	v_add_f32_e32 v0, v183, v0
	ds_bpermute_b32 v1, v121, v0
	v_lshl_add_u32 v19, v156, 2, s16
	ds_read_b128 v[4:7], v19
	v_lshl_add_u64 v[36:37], v[114:115], 0, s[0:1]
	v_div_fixup_f32 v115, v248, v123, v235
	s_waitcnt lgkmcnt(1)
	v_add_f32_e32 v0, v0, v1
	v_fmamk_f32 v0, v0, 0x3c2aaaab, v232
	v_mul_f32_e32 v1, 0x4b800000, v0
	v_cmp_gt_f32_e32 vcc, s92, v0
	v_div_fixup_f32 v114, v249, v122, v234
	v_div_fixup_f32 v9, v233, v125, v251
	v_cndmask_b32_e32 v0, v0, v1, vcc
	v_rsq_f32_e32 v0, v0
	v_div_fixup_f32 v8, v238, v124, v250
	v_lshl_add_u64 v[16:17], v[36:37], 0, v[48:49]
	v_div_fixup_f32 v116, v133, v116, v130
	v_mul_f32_e32 v1, 0x45800000, v0
	v_cndmask_b32_e32 v18, v0, v1, vcc
	v_pk_mul_f32 v[120:121], v[204:205], v[18:19] op_sel_hi:[1,0]
	v_pk_mul_f32 v[10:11], v[10:11], v[18:19] op_sel_hi:[1,0]
	s_waitcnt lgkmcnt(0)
	v_pk_mul_f32 v[4:5], v[4:5], v[120:121]
	v_pk_mul_f32 v[6:7], v[6:7], v[10:11]
	v_pk_mul_f32 v[4:5], v[114:115], v[4:5]
	v_pk_mul_f32 v[6:7], v[8:9], v[6:7]
	v_cvt_pk_bf16_f32 v4, v4, v5
	v_cvt_pk_bf16_f32 v5, v6, v7
	global_store_dwordx2 v[16:17], v[4:5], off
	ds_read_b128 v[0:3], v19 offset:256
	v_pk_mul_f32 v[118:119], v[118:119], v[18:19] op_sel_hi:[1,0]
	v_pk_mul_f32 v[110:111], v[110:111], v[18:19] op_sel_hi:[1,0]
	v_lshlrev_b32_e32 v48, 1, v158
	v_lshl_add_u64 v[112:113], v[36:37], 0, v[48:49]
	v_pk_mul_f32 v[108:109], v[108:109], v[18:19] op_sel_hi:[1,0]
	v_pk_mul_f32 v[106:107], v[106:107], v[18:19] op_sel_hi:[1,0]
	v_pk_mul_f32 v[46:47], v[46:47], v[18:19] op_sel_hi:[1,0]
	v_pk_mul_f32 v[44:45], v[44:45], v[18:19] op_sel_hi:[1,0]
	v_pk_mul_f32 v[42:43], v[42:43], v[18:19] op_sel_hi:[1,0]
	v_pk_mul_f32 v[38:39], v[38:39], v[18:19] op_sel_hi:[1,0]
	v_pk_mul_f32 v[34:35], v[34:35], v[18:19] op_sel_hi:[1,0]
	v_pk_mul_f32 v[32:33], v[32:33], v[18:19] op_sel_hi:[1,0]
	v_pk_mul_f32 v[28:29], v[28:29], v[18:19] op_sel_hi:[1,0]
	v_pk_mul_f32 v[30:31], v[30:31], v[18:19] op_sel_hi:[1,0]
	v_pk_mul_f32 v[26:27], v[26:27], v[18:19] op_sel_hi:[1,0]
	v_pk_mul_f32 v[22:23], v[22:23], v[18:19] op_sel_hi:[1,0]
	v_pk_mul_f32 v[20:21], v[20:21], v[18:19] op_sel_hi:[1,0]
	s_waitcnt vmcnt(10)
	v_mov_b32_e32 v4, v50
	v_mov_b32_e32 v5, v51
	v_lshlrev_b32_e32 v134, 16, v4
	v_and_b32_e32 v135, 0xffff0000, v4
	v_mul_f32_e32 v4, 0xbfb8aa3b, v134
	v_exp_f32_e32 v6, v4
	v_mul_f32_e32 v4, 0xbfb8aa3b, v135
	v_exp_f32_e32 v7, v4
	v_lshlrev_b32_e32 v182, 16, v5
	v_and_b32_e32 v183, 0xffff0000, v5
	v_mul_f32_e32 v5, 0xbfb8aa3b, v183
	v_pk_add_f32 v[122:123], v[6:7], 1.0 op_sel_hi:[1,0]
	v_exp_f32_e32 v5, v5
	v_div_scale_f32 v4, s[0:1], v123, v123, v135
	v_rcp_f32_e32 v6, v4
	s_nop 0
	v_fma_f32 v7, -v4, v6, 1.0
	v_fmac_f32_e32 v6, v7, v6
	v_div_scale_f32 v7, vcc, v135, v123, v135
	v_mul_f32_e32 v8, v7, v6
	v_fma_f32 v9, -v4, v8, v7
	v_fmac_f32_e32 v8, v9, v6
	v_fma_f32 v4, -v4, v8, v7
	v_div_fmas_f32 v136, v4, v6, v8
	v_div_scale_f32 v4, s[0:1], v122, v122, v134
	v_rcp_f32_e32 v6, v4
	s_nop 0
	v_fma_f32 v7, -v4, v6, 1.0
	v_fmac_f32_e32 v6, v7, v6
	v_div_scale_f32 v7, vcc, v134, v122, v134
	v_mul_f32_e32 v8, v7, v6
	v_fma_f32 v9, -v4, v8, v7
	v_fmac_f32_e32 v8, v9, v6
	v_fma_f32 v4, -v4, v8, v7
	v_div_fmas_f32 v137, v4, v6, v8
	v_mul_f32_e32 v4, 0xbfb8aa3b, v182
	v_exp_f32_e32 v4, v4
	s_nop 0
	v_pk_add_f32 v[124:125], v[4:5], 1.0 op_sel_hi:[1,0]
	s_nop 0
	v_div_scale_f32 v4, s[0:1], v125, v125, v183
	v_rcp_f32_e32 v5, v4
	s_nop 0
	v_fma_f32 v6, -v4, v5, 1.0
	v_fmac_f32_e32 v5, v6, v5
	v_div_scale_f32 v6, vcc, v183, v125, v183
	v_mul_f32_e32 v7, v6, v5
	v_fma_f32 v8, -v4, v7, v6
	v_fmac_f32_e32 v7, v8, v5
	v_fma_f32 v4, -v4, v7, v6
	v_div_fmas_f32 v202, v4, v5, v7
	v_div_scale_f32 v4, s[0:1], v124, v124, v182
	v_rcp_f32_e32 v5, v4
	s_movk_i32 s0, 0x1000
	v_fma_f32 v6, -v4, v5, 1.0
	v_fmac_f32_e32 v5, v6, v5
	v_div_scale_f32 v6, vcc, v182, v124, v182
	v_mul_f32_e32 v7, v6, v5
	v_fma_f32 v8, -v4, v7, v6
	v_fmac_f32_e32 v7, v8, v5
	v_fma_f32 v4, -v4, v7, v6
	v_div_fmas_f32 v203, v4, v5, v7
	v_lshl_add_u32 v4, v158, 2, s16
	ds_read_b128 v[8:11], v4
	v_add_co_u32_e32 v120, vcc, s0, v102
	s_movk_i32 s0, 0x2000
	s_nop 0
	v_addc_co_u32_e32 v121, vcc, 0, v103, vcc
	s_waitcnt lgkmcnt(0)
	v_pk_mul_f32 v[8:9], v[8:9], v[118:119]
	v_pk_mul_f32 v[10:11], v[10:11], v[110:111]
	v_pk_mul_f32 v[8:9], v[126:127], v[8:9]
	v_pk_mul_f32 v[10:11], v[116:117], v[10:11]
	v_cvt_pk_bf16_f32 v8, v8, v9
	v_cvt_pk_bf16_f32 v9, v10, v11
	global_store_dwordx2 v[112:113], v[8:9], off
	v_add_co_u32_e32 v114, vcc, s0, v102
	ds_read_b128 v[4:7], v19 offset:352
	s_nop 0
	v_addc_co_u32_e32 v115, vcc, 0, v103, vcc
	v_pk_mul_f32 v[0:1], v[0:1], v[26:27]
	s_waitcnt vmcnt(10)
	v_mov_b32_e32 v8, v52
	v_mov_b32_e32 v9, v53
	v_lshlrev_b32_e32 v126, 16, v8
	v_and_b32_e32 v127, 0xffff0000, v8
	v_mul_f32_e32 v8, 0xbfb8aa3b, v126
	v_exp_f32_e32 v10, v8
	v_mul_f32_e32 v8, 0xbfb8aa3b, v127
	v_exp_f32_e32 v11, v8
	v_lshlrev_b32_e32 v130, 16, v9
	v_and_b32_e32 v131, 0xffff0000, v9
	v_mul_f32_e32 v9, 0xbfb8aa3b, v131
	v_pk_add_f32 v[102:103], v[10:11], 1.0 op_sel_hi:[1,0]
	v_exp_f32_e32 v9, v9
	v_div_scale_f32 v8, s[0:1], v103, v103, v127
	v_rcp_f32_e32 v10, v8
	s_nop 0
	v_fma_f32 v11, -v8, v10, 1.0
	v_fmac_f32_e32 v10, v11, v10
	v_div_scale_f32 v11, vcc, v127, v103, v127
	v_mul_f32_e32 v48, v11, v10
	v_fma_f32 v110, -v8, v48, v11
	v_fmac_f32_e32 v48, v110, v10
	v_fma_f32 v8, -v8, v48, v11
	v_div_fmas_f32 v128, v8, v10, v48
	v_div_scale_f32 v8, s[0:1], v102, v102, v126
	v_rcp_f32_e32 v10, v8
	v_div_fixup_f32 v103, v128, v103, v127
	v_fma_f32 v11, -v8, v10, 1.0
	v_fmac_f32_e32 v10, v11, v10
	v_div_scale_f32 v11, vcc, v126, v102, v126
	v_mul_f32_e32 v48, v11, v10
	v_fma_f32 v110, -v8, v48, v11
	v_fmac_f32_e32 v48, v110, v10
	v_fma_f32 v8, -v8, v48, v11
	v_div_fmas_f32 v129, v8, v10, v48
	v_mul_f32_e32 v8, 0xbfb8aa3b, v130
	v_exp_f32_e32 v8, v8
	v_div_fixup_f32 v102, v129, v102, v126
	v_pk_add_f32 v[116:117], v[8:9], 1.0 op_sel_hi:[1,0]
	s_nop 0
	v_div_scale_f32 v8, s[0:1], v117, v117, v131
	v_rcp_f32_e32 v9, v8
	s_nop 0
	v_fma_f32 v10, -v8, v9, 1.0
	v_fmac_f32_e32 v9, v10, v9
	v_div_scale_f32 v10, vcc, v131, v117, v131
	v_mul_f32_e32 v11, v10, v9
	v_fma_f32 v48, -v8, v11, v10
	v_fmac_f32_e32 v11, v48, v9
	v_fma_f32 v8, -v8, v11, v10
	v_div_fmas_f32 v132, v8, v9, v11
	v_div_scale_f32 v8, s[0:1], v116, v116, v130
	v_rcp_f32_e32 v9, v8
	s_nop 0
	v_fma_f32 v10, -v8, v9, 1.0
	v_fmac_f32_e32 v9, v10, v9
	v_div_scale_f32 v10, vcc, v130, v116, v130
	v_mul_f32_e32 v11, v10, v9
	v_fma_f32 v48, -v8, v11, v10
	v_fmac_f32_e32 v11, v48, v9
	v_fma_f32 v8, -v8, v11, v10
	v_div_fmas_f32 v133, v8, v9, v11
	v_lshl_add_u32 v8, v160, 2, s16
	ds_read_b128 v[8:11], v8
	v_lshlrev_b32_e32 v48, 1, v160
	v_lshl_add_u64 v[118:119], v[36:37], 0, v[48:49]
	v_lshl_add_u32 v48, v162, 2, s16
	ds_read_b128 v[110:113], v48
	s_waitcnt lgkmcnt(1)
	v_pk_mul_f32 v[8:9], v[8:9], v[108:109]
	v_div_fixup_f32 v109, v136, v123, v135
	v_div_fixup_f32 v108, v137, v122, v134
	v_pk_mul_f32 v[10:11], v[10:11], v[106:107]
	v_div_fixup_f32 v107, v202, v125, v183
	v_div_fixup_f32 v106, v203, v124, v182
	v_pk_mul_f32 v[8:9], v[108:109], v[8:9]
	v_pk_mul_f32 v[10:11], v[106:107], v[10:11]
	v_cvt_pk_bf16_f32 v8, v8, v9
	v_cvt_pk_bf16_f32 v9, v10, v11
	global_store_dwordx2 v[118:119], v[8:9], off
	s_waitcnt lgkmcnt(0)
	v_pk_mul_f32 v[46:47], v[112:113], v[46:47]
	s_waitcnt vmcnt(10)
	v_mov_b32_e32 v8, v54
	v_mov_b32_e32 v9, v55
	v_lshlrev_b32_e32 v118, 16, v8
	v_and_b32_e32 v119, 0xffff0000, v8
	v_mul_f32_e32 v8, 0xbfb8aa3b, v118
	v_exp_f32_e32 v10, v8
	v_mul_f32_e32 v8, 0xbfb8aa3b, v119
	v_exp_f32_e32 v11, v8
	v_lshlrev_b32_e32 v124, 16, v9
	v_and_b32_e32 v125, 0xffff0000, v9
	v_mul_f32_e32 v9, 0xbfb8aa3b, v125
	v_pk_add_f32 v[106:107], v[10:11], 1.0 op_sel_hi:[1,0]
	v_exp_f32_e32 v9, v9
	v_div_scale_f32 v8, s[0:1], v107, v107, v119
	v_rcp_f32_e32 v10, v8
	s_nop 0
	v_fma_f32 v11, -v8, v10, 1.0
	v_fmac_f32_e32 v10, v11, v10
	v_div_scale_f32 v11, vcc, v119, v107, v119
	v_mul_f32_e32 v48, v11, v10
	v_fma_f32 v108, -v8, v48, v11
	v_fmac_f32_e32 v48, v108, v10
	v_fma_f32 v8, -v8, v48, v11
	v_div_fmas_f32 v122, v8, v10, v48
	v_div_scale_f32 v8, s[0:1], v106, v106, v118
	v_rcp_f32_e32 v10, v8
	s_nop 0
	v_fma_f32 v11, -v8, v10, 1.0
	v_fmac_f32_e32 v10, v11, v10
	v_div_scale_f32 v11, vcc, v118, v106, v118
	v_mul_f32_e32 v48, v11, v10
	v_fma_f32 v108, -v8, v48, v11
	v_fmac_f32_e32 v48, v108, v10
	v_fma_f32 v8, -v8, v48, v11
	v_div_fmas_f32 v123, v8, v10, v48
	v_mul_f32_e32 v8, 0xbfb8aa3b, v124
	v_exp_f32_e32 v8, v8
	s_nop 0
	v_pk_add_f32 v[108:109], v[8:9], 1.0 op_sel_hi:[1,0]
	s_nop 0
	v_div_scale_f32 v8, s[0:1], v109, v109, v125
	v_rcp_f32_e32 v9, v8
	s_nop 0
	v_fma_f32 v10, -v8, v9, 1.0
	v_fmac_f32_e32 v9, v10, v9
	v_div_scale_f32 v10, vcc, v125, v109, v125
	v_mul_f32_e32 v11, v10, v9
	v_fma_f32 v48, -v8, v11, v10
	v_fmac_f32_e32 v11, v48, v9
	v_fma_f32 v8, -v8, v11, v10
	v_div_fmas_f32 v134, v8, v9, v11
	v_div_scale_f32 v8, s[0:1], v108, v108, v124
	v_rcp_f32_e32 v9, v8
	s_nop 0
	v_fma_f32 v10, -v8, v9, 1.0
	v_fmac_f32_e32 v9, v10, v9
	v_div_scale_f32 v10, vcc, v124, v108, v124
	v_mul_f32_e32 v11, v10, v9
	v_fma_f32 v48, -v8, v11, v10
	v_fmac_f32_e32 v11, v48, v9
	v_fma_f32 v8, -v8, v11, v10
	v_div_fmas_f32 v135, v8, v9, v11
	v_pk_mul_f32 v[10:11], v[104:105], v[18:19] op_sel_hi:[1,0]
	v_lshlrev_b32_e32 v48, 1, v162
	v_pk_mul_f32 v[10:11], v[110:111], v[10:11]
	v_lshl_add_u64 v[8:9], v[36:37], 0, v[48:49]
	v_pk_mul_f32 v[10:11], v[102:103], v[10:11]
	v_div_fixup_f32 v103, v132, v117, v131
	v_div_fixup_f32 v102, v133, v116, v130
	v_pk_mul_f32 v[46:47], v[102:103], v[46:47]
	v_cvt_pk_bf16_f32 v10, v10, v11
	v_cvt_pk_bf16_f32 v11, v46, v47
	global_store_dwordx2 v[8:9], v[10:11], off
	s_waitcnt vmcnt(10)
	v_mov_b32_e32 v8, v56
	v_mov_b32_e32 v9, v57
	v_lshlrev_b32_e32 v116, 16, v8
	v_and_b32_e32 v117, 0xffff0000, v8
	v_mul_f32_e32 v8, 0xbfb8aa3b, v116
	v_exp_f32_e32 v10, v8
	v_mul_f32_e32 v8, 0xbfb8aa3b, v117
	v_exp_f32_e32 v11, v8
	v_lshlrev_b32_e32 v128, 16, v9
	v_and_b32_e32 v129, 0xffff0000, v9
	v_mul_f32_e32 v9, 0xbfb8aa3b, v129
	v_pk_add_f32 v[46:47], v[10:11], 1.0 op_sel_hi:[1,0]
	v_exp_f32_e32 v9, v9
	v_div_scale_f32 v8, s[0:1], v47, v47, v117
	v_rcp_f32_e32 v10, v8
	s_nop 0
	v_fma_f32 v11, -v8, v10, 1.0
	v_fmac_f32_e32 v10, v11, v10
	v_div_scale_f32 v11, vcc, v117, v47, v117
	v_mul_f32_e32 v48, v11, v10
	v_fma_f32 v102, -v8, v48, v11
	v_fmac_f32_e32 v48, v102, v10
	v_fma_f32 v8, -v8, v48, v11
	v_div_fmas_f32 v126, v8, v10, v48
	v_div_scale_f32 v8, s[0:1], v46, v46, v116
	v_rcp_f32_e32 v10, v8
	s_nop 0
	v_fma_f32 v11, -v8, v10, 1.0
	v_fmac_f32_e32 v10, v11, v10
	v_div_scale_f32 v11, vcc, v116, v46, v116
	v_mul_f32_e32 v48, v11, v10
	v_fma_f32 v102, -v8, v48, v11
	v_fmac_f32_e32 v48, v102, v10
	v_fma_f32 v8, -v8, v48, v11
	v_div_fmas_f32 v127, v8, v10, v48
	v_mul_f32_e32 v8, 0xbfb8aa3b, v128
	v_exp_f32_e32 v8, v8
	s_nop 0
	v_pk_add_f32 v[110:111], v[8:9], 1.0 op_sel_hi:[1,0]
	s_nop 0
	v_div_scale_f32 v8, s[0:1], v111, v111, v129
	v_rcp_f32_e32 v9, v8
	s_nop 0
	v_fma_f32 v10, -v8, v9, 1.0
	v_fmac_f32_e32 v9, v10, v9
	v_div_scale_f32 v10, vcc, v129, v111, v129
	v_mul_f32_e32 v11, v10, v9
	v_fma_f32 v48, -v8, v11, v10
	v_fmac_f32_e32 v11, v48, v9
	v_fma_f32 v8, -v8, v11, v10
	v_div_fmas_f32 v130, v8, v9, v11
	v_div_scale_f32 v8, s[0:1], v110, v110, v128
	v_rcp_f32_e32 v9, v8
	s_nop 0
	v_fma_f32 v10, -v8, v9, 1.0
	v_fmac_f32_e32 v9, v10, v9
	v_div_scale_f32 v10, vcc, v128, v110, v128
	v_mul_f32_e32 v11, v10, v9
	v_fma_f32 v48, -v8, v11, v10
	v_fmac_f32_e32 v11, v48, v9
	v_fma_f32 v8, -v8, v11, v10
	v_div_fmas_f32 v131, v8, v9, v11
	v_lshl_add_u32 v8, v174, 2, s16
	ds_read_b128 v[8:11], v8
	v_lshlrev_b32_e32 v48, 1, v174
	v_lshl_add_u64 v[112:113], v[36:37], 0, v[48:49]
	v_lshl_add_u32 v48, v176, 2, s16
	ds_read_b128 v[102:105], v48
	s_waitcnt lgkmcnt(1)
	v_pk_mul_f32 v[8:9], v[8:9], v[44:45]
	v_div_fixup_f32 v45, v122, v107, v119
	v_div_fixup_f32 v44, v123, v106, v118
	v_pk_mul_f32 v[10:11], v[10:11], v[42:43]
	v_div_fixup_f32 v43, v134, v109, v125
	v_div_fixup_f32 v42, v135, v108, v124
	v_pk_mul_f32 v[8:9], v[44:45], v[8:9]
	v_pk_mul_f32 v[10:11], v[42:43], v[10:11]
	v_cvt_pk_bf16_f32 v8, v8, v9
	v_cvt_pk_bf16_f32 v9, v10, v11
	global_store_dwordx2 v[112:113], v[8:9], off
	s_waitcnt lgkmcnt(0)
	v_pk_mul_f32 v[38:39], v[104:105], v[38:39]
	s_waitcnt vmcnt(10)
	v_mov_b32_e32 v8, v58
	v_mov_b32_e32 v9, v59
	v_lshlrev_b32_e32 v106, 16, v8
	v_and_b32_e32 v107, 0xffff0000, v8
	v_mul_f32_e32 v8, 0xbfb8aa3b, v106
	v_exp_f32_e32 v10, v8
	v_mul_f32_e32 v8, 0xbfb8aa3b, v107
	v_exp_f32_e32 v11, v8
	v_lshlrev_b32_e32 v112, 16, v9
	v_and_b32_e32 v113, 0xffff0000, v9
	v_mul_f32_e32 v9, 0xbfb8aa3b, v113
	v_pk_add_f32 v[42:43], v[10:11], 1.0 op_sel_hi:[1,0]
	v_exp_f32_e32 v9, v9
	v_div_scale_f32 v8, s[0:1], v43, v43, v107
	v_rcp_f32_e32 v10, v8
	s_nop 0
	v_fma_f32 v11, -v8, v10, 1.0
	v_fmac_f32_e32 v10, v11, v10
	v_div_scale_f32 v11, vcc, v107, v43, v107
	v_mul_f32_e32 v44, v11, v10
	v_fma_f32 v45, -v8, v44, v11
	v_fmac_f32_e32 v44, v45, v10
	v_fma_f32 v8, -v8, v44, v11
	v_div_fmas_f32 v108, v8, v10, v44
	v_div_scale_f32 v8, s[0:1], v42, v42, v106
	v_rcp_f32_e32 v10, v8
	s_nop 0
	v_fma_f32 v11, -v8, v10, 1.0
	v_fmac_f32_e32 v10, v11, v10
	v_div_scale_f32 v11, vcc, v106, v42, v106
	v_mul_f32_e32 v44, v11, v10
	v_fma_f32 v45, -v8, v44, v11
	v_fmac_f32_e32 v44, v45, v10
	v_fma_f32 v8, -v8, v44, v11
	v_div_fmas_f32 v109, v8, v10, v44
	v_mul_f32_e32 v8, 0xbfb8aa3b, v112
	v_exp_f32_e32 v8, v8
	s_nop 0
	v_pk_add_f32 v[44:45], v[8:9], 1.0 op_sel_hi:[1,0]
	s_nop 0
	v_div_scale_f32 v8, s[0:1], v45, v45, v113
	v_rcp_f32_e32 v9, v8
	s_nop 0
	v_fma_f32 v10, -v8, v9, 1.0
	v_fmac_f32_e32 v9, v10, v9
	v_div_scale_f32 v10, vcc, v113, v45, v113
	v_mul_f32_e32 v11, v10, v9
	v_fma_f32 v48, -v8, v11, v10
	v_fmac_f32_e32 v11, v48, v9
	v_fma_f32 v8, -v8, v11, v10
	v_div_fmas_f32 v118, v8, v9, v11
	v_div_scale_f32 v8, s[0:1], v44, v44, v112
	v_rcp_f32_e32 v9, v8
	s_nop 0
	v_fma_f32 v10, -v8, v9, 1.0
	v_fmac_f32_e32 v9, v10, v9
	v_div_scale_f32 v10, vcc, v112, v44, v112
	v_mul_f32_e32 v11, v10, v9
	v_fma_f32 v48, -v8, v11, v10
	v_fmac_f32_e32 v11, v48, v9
	v_fma_f32 v8, -v8, v11, v10
	v_div_fmas_f32 v119, v8, v9, v11
	v_pk_mul_f32 v[10:11], v[40:41], v[18:19] op_sel_hi:[1,0]
	v_div_fixup_f32 v41, v126, v47, v117
	v_pk_mul_f32 v[10:11], v[102:103], v[10:11]
	v_div_fixup_f32 v40, v127, v46, v116
	v_pk_mul_f32 v[10:11], v[40:41], v[10:11]
	v_div_fixup_f32 v41, v130, v111, v129
	v_div_fixup_f32 v40, v131, v110, v128
	v_lshlrev_b32_e32 v48, 1, v176
	v_pk_mul_f32 v[38:39], v[40:41], v[38:39]
	v_lshl_add_u64 v[8:9], v[36:37], 0, v[48:49]
	v_cvt_pk_bf16_f32 v10, v10, v11
	v_cvt_pk_bf16_f32 v11, v38, v39
	global_store_dwordx2 v[8:9], v[10:11], off
	v_lshlrev_b32_e32 v48, 1, v178
	v_lshl_add_u64 v[104:105], v[36:37], 0, v[48:49]
	s_waitcnt vmcnt(10)
	v_mov_b32_e32 v8, v60
	v_mov_b32_e32 v9, v61
	v_lshlrev_b32_e32 v110, 16, v8
	v_and_b32_e32 v111, 0xffff0000, v8
	v_mul_f32_e32 v8, 0xbfb8aa3b, v110
	v_exp_f32_e32 v10, v8
	v_mul_f32_e32 v8, 0xbfb8aa3b, v111
	v_exp_f32_e32 v11, v8
	v_lshlrev_b32_e32 v120, 16, v9
	v_and_b32_e32 v121, 0xffff0000, v9
	v_mul_f32_e32 v9, 0xbfb8aa3b, v121
	v_pk_add_f32 v[46:47], v[10:11], 1.0 op_sel_hi:[1,0]
	v_exp_f32_e32 v9, v9
	v_div_scale_f32 v8, s[0:1], v47, v47, v111
	v_rcp_f32_e32 v10, v8
	s_nop 0
	v_fma_f32 v11, -v8, v10, 1.0
	v_fmac_f32_e32 v10, v11, v10
	v_div_scale_f32 v11, vcc, v111, v47, v111
	v_mul_f32_e32 v38, v11, v10
	v_fma_f32 v39, -v8, v38, v11
	v_fmac_f32_e32 v38, v39, v10
	v_fma_f32 v8, -v8, v38, v11
	v_div_fmas_f32 v116, v8, v10, v38
	v_div_scale_f32 v8, s[0:1], v46, v46, v110
	v_rcp_f32_e32 v10, v8
	s_nop 0
	v_fma_f32 v11, -v8, v10, 1.0
	v_fmac_f32_e32 v10, v11, v10
	v_div_scale_f32 v11, vcc, v110, v46, v110
	v_mul_f32_e32 v38, v11, v10
	v_fma_f32 v39, -v8, v38, v11
	v_fmac_f32_e32 v38, v39, v10
	v_fma_f32 v8, -v8, v38, v11
	v_div_fmas_f32 v117, v8, v10, v38
	v_mul_f32_e32 v8, 0xbfb8aa3b, v120
	v_exp_f32_e32 v8, v8
	s_nop 0
	v_pk_add_f32 v[102:103], v[8:9], 1.0 op_sel_hi:[1,0]
	s_nop 0
	v_div_scale_f32 v8, s[0:1], v103, v103, v121
	v_rcp_f32_e32 v9, v8
	s_nop 0
	v_fma_f32 v10, -v8, v9, 1.0
	v_fmac_f32_e32 v9, v10, v9
	v_div_scale_f32 v10, vcc, v121, v103, v121
	v_mul_f32_e32 v11, v10, v9
	v_fma_f32 v38, -v8, v11, v10
	v_fmac_f32_e32 v11, v38, v9
	v_fma_f32 v8, -v8, v11, v10
	v_div_fmas_f32 v122, v8, v9, v11
	v_div_scale_f32 v8, s[0:1], v102, v102, v120
	v_rcp_f32_e32 v9, v8
	s_nop 0
	v_fma_f32 v10, -v8, v9, 1.0
	v_fmac_f32_e32 v9, v10, v9
	v_div_scale_f32 v10, vcc, v120, v102, v120
	v_mul_f32_e32 v11, v10, v9
	v_fma_f32 v38, -v8, v11, v10
	v_fmac_f32_e32 v11, v38, v9
	v_fma_f32 v8, -v8, v11, v10
	v_div_fmas_f32 v123, v8, v9, v11
	v_lshl_add_u32 v8, v178, 2, s16
	ds_read_b128 v[8:11], v8
	v_lshl_add_u32 v38, v180, 2, s16
	ds_read_b128 v[38:41], v38
	s_waitcnt lgkmcnt(1)
	v_pk_mul_f32 v[8:9], v[8:9], v[34:35]
	v_div_fixup_f32 v35, v108, v43, v107
	v_div_fixup_f32 v34, v109, v42, v106
	v_pk_mul_f32 v[10:11], v[10:11], v[32:33]
	v_div_fixup_f32 v33, v118, v45, v113
	v_div_fixup_f32 v32, v119, v44, v112
	v_pk_mul_f32 v[8:9], v[34:35], v[8:9]
	v_pk_mul_f32 v[10:11], v[32:33], v[10:11]
	v_cvt_pk_bf16_f32 v8, v8, v9
	v_cvt_pk_bf16_f32 v9, v10, v11
	global_store_dwordx2 v[104:105], v[8:9], off
	s_waitcnt lgkmcnt(0)
	v_pk_mul_f32 v[28:29], v[38:39], v[28:29]
	v_pk_mul_f32 v[30:31], v[40:41], v[30:31]
	s_waitcnt vmcnt(10)
	v_mov_b32_e32 v8, v62
	v_mov_b32_e32 v9, v63
	v_lshlrev_b32_e32 v42, 16, v8
	v_and_b32_e32 v43, 0xffff0000, v8
	v_mul_f32_e32 v8, 0xbfb8aa3b, v42
	v_exp_f32_e32 v10, v8
	v_mul_f32_e32 v8, 0xbfb8aa3b, v43
	v_exp_f32_e32 v11, v8
	v_lshlrev_b32_e32 v104, 16, v9
	v_and_b32_e32 v105, 0xffff0000, v9
	v_mul_f32_e32 v9, 0xbfb8aa3b, v105
	v_pk_add_f32 v[10:11], v[10:11], 1.0 op_sel_hi:[1,0]
	v_exp_f32_e32 v9, v9
	v_div_scale_f32 v8, s[0:1], v11, v11, v43
	v_rcp_f32_e32 v32, v8
	s_nop 0
	v_fma_f32 v33, -v8, v32, 1.0
	v_fmac_f32_e32 v32, v33, v32
	v_div_scale_f32 v33, vcc, v43, v11, v43
	v_mul_f32_e32 v34, v33, v32
	v_fma_f32 v35, -v8, v34, v33
	v_fmac_f32_e32 v34, v35, v32
	v_fma_f32 v8, -v8, v34, v33
	v_div_fmas_f32 v44, v8, v32, v34
	v_div_scale_f32 v8, s[0:1], v10, v10, v42
	v_rcp_f32_e32 v32, v8
	v_div_fixup_f32 v11, v44, v11, v43
	v_fma_f32 v33, -v8, v32, 1.0
	v_fmac_f32_e32 v32, v33, v32
	v_div_scale_f32 v33, vcc, v42, v10, v42
	v_mul_f32_e32 v34, v33, v32
	v_fma_f32 v35, -v8, v34, v33
	v_fmac_f32_e32 v34, v35, v32
	v_fma_f32 v8, -v8, v34, v33
	v_div_fmas_f32 v45, v8, v32, v34
	v_mul_f32_e32 v8, 0xbfb8aa3b, v104
	v_exp_f32_e32 v8, v8
	v_div_fixup_f32 v10, v45, v10, v42
	v_pk_mul_f32 v[0:1], v[10:11], v[0:1]
	v_pk_mul_f32 v[10:11], v[24:25], v[18:19] op_sel_hi:[1,0]
	v_pk_add_f32 v[8:9], v[8:9], 1.0 op_sel_hi:[1,0]
	v_pk_mul_f32 v[2:3], v[2:3], v[10:11]
	v_div_scale_f32 v32, s[0:1], v9, v9, v105
	v_rcp_f32_e32 v33, v32
	v_cvt_pk_bf16_f32 v0, v0, v1
	v_fma_f32 v34, -v32, v33, 1.0
	v_fmac_f32_e32 v33, v34, v33
	v_div_scale_f32 v34, vcc, v105, v9, v105
	v_mul_f32_e32 v35, v34, v33
	v_fma_f32 v48, -v32, v35, v34
	v_fmac_f32_e32 v35, v48, v33
	v_fma_f32 v32, -v32, v35, v34
	v_div_fmas_f32 v106, v32, v33, v35
	v_div_scale_f32 v32, s[0:1], v8, v8, v104
	v_rcp_f32_e32 v33, v32
	v_div_fixup_f32 v9, v106, v9, v105
	v_fma_f32 v34, -v32, v33, 1.0
	v_fmac_f32_e32 v33, v34, v33
	v_div_scale_f32 v34, vcc, v104, v8, v104
	v_mul_f32_e32 v35, v34, v33
	v_fma_f32 v48, -v32, v35, v34
	v_fmac_f32_e32 v35, v48, v33
	v_fma_f32 v32, -v32, v35, v34
	v_div_fmas_f32 v107, v32, v33, v35
	v_div_fixup_f32 v35, v116, v47, v111
	v_div_fixup_f32 v34, v117, v46, v110
	v_pk_mul_f32 v[28:29], v[34:35], v[28:29]
	v_div_fixup_f32 v35, v122, v103, v121
	v_div_fixup_f32 v34, v123, v102, v120
	v_lshlrev_b32_e32 v48, 1, v180
	v_pk_mul_f32 v[30:31], v[34:35], v[30:31]
	v_lshl_add_u64 v[32:33], v[36:37], 0, v[48:49]
	v_cvt_pk_bf16_f32 v28, v28, v29
	v_cvt_pk_bf16_f32 v29, v30, v31
	global_store_dwordx2 v[32:33], v[28:29], off
	v_div_fixup_f32 v8, v107, v8, v104
	v_pk_mul_f32 v[2:3], v[8:9], v[2:3]
	s_waitcnt vmcnt(10)
	v_mov_b32_e32 v28, v64
	v_mov_b32_e32 v29, v65
	v_lshlrev_b32_e32 v32, 16, v28
	v_cvt_pk_bf16_f32 v1, v2, v3
	global_store_dwordx2 v[16:17], v[0:1], off offset:128
	v_and_b32_e32 v33, 0xffff0000, v28
	v_mul_f32_e32 v28, 0xbfb8aa3b, v32
	v_exp_f32_e32 v30, v28
	v_mul_f32_e32 v28, 0xbfb8aa3b, v33
	v_exp_f32_e32 v31, v28
	s_waitcnt vmcnt(10)
	v_mov_b32_e32 v0, v66
	v_mov_b32_e32 v1, v67
	v_lshlrev_b32_e32 v44, 16, v1
	v_pk_add_f32 v[30:31], v[30:31], 1.0 op_sel_hi:[1,0]
	v_and_b32_e32 v45, 0xffff0000, v1
	v_div_scale_f32 v28, s[0:1], v31, v31, v33
	v_rcp_f32_e32 v34, v28
	v_mul_f32_e32 v1, 0xbfb8aa3b, v45
	v_exp_f32_e32 v1, v1
	v_fma_f32 v35, -v28, v34, 1.0
	v_fmac_f32_e32 v34, v35, v34
	v_div_scale_f32 v35, vcc, v33, v31, v33
	v_mul_f32_e32 v36, v35, v34
	v_fma_f32 v37, -v28, v36, v35
	v_fmac_f32_e32 v36, v37, v34
	v_fma_f32 v28, -v28, v36, v35
	v_div_fmas_f32 v34, v28, v34, v36
	v_div_scale_f32 v28, s[0:1], v30, v30, v32
	v_rcp_f32_e32 v35, v28
	s_nop 0
	v_fma_f32 v36, -v28, v35, 1.0
	v_fmac_f32_e32 v35, v36, v35
	v_div_scale_f32 v36, vcc, v32, v30, v32
	v_mul_f32_e32 v37, v36, v35
	v_fma_f32 v38, -v28, v37, v36
	v_fmac_f32_e32 v37, v38, v35
	v_fma_f32 v28, -v28, v37, v36
	v_div_fmas_f32 v35, v28, v35, v37
	v_lshlrev_b32_e32 v36, 16, v29
	v_and_b32_e32 v37, 0xffff0000, v29
	v_mul_f32_e32 v28, 0xbfb8aa3b, v36
	v_mul_f32_e32 v29, 0xbfb8aa3b, v37
	v_exp_f32_e32 v28, v28
	v_exp_f32_e32 v29, v29
	s_nop 0
	v_pk_add_f32 v[28:29], v[28:29], 1.0 op_sel_hi:[1,0]
	s_nop 0
	v_div_scale_f32 v38, s[0:1], v29, v29, v37
	v_rcp_f32_e32 v39, v38
	s_nop 0
	v_fma_f32 v40, -v38, v39, 1.0
	v_fmac_f32_e32 v39, v40, v39
	v_div_scale_f32 v40, vcc, v37, v29, v37
	v_mul_f32_e32 v41, v40, v39
	v_fma_f32 v46, -v38, v41, v40
	v_fmac_f32_e32 v41, v46, v39
	v_fma_f32 v38, -v38, v41, v40
	v_div_fmas_f32 v38, v38, v39, v41
	v_div_scale_f32 v39, s[0:1], v28, v28, v36
	v_rcp_f32_e32 v40, v39
	s_nop 0
	v_fma_f32 v41, -v39, v40, 1.0
	v_fmac_f32_e32 v40, v41, v40
	v_div_scale_f32 v41, vcc, v36, v28, v36
	v_mul_f32_e32 v46, v41, v40
	v_fma_f32 v47, -v39, v46, v41
	v_fmac_f32_e32 v46, v47, v40
	v_fma_f32 v39, -v39, v46, v41
	v_div_fmas_f32 v39, v39, v40, v46
	v_lshlrev_b32_e32 v40, 16, v0
	v_and_b32_e32 v41, 0xffff0000, v0
	v_mul_f32_e32 v0, 0xbfb8aa3b, v40
	v_exp_f32_e32 v2, v0
	v_mul_f32_e32 v0, 0xbfb8aa3b, v41
	v_exp_f32_e32 v3, v0
	s_nop 0
	v_pk_add_f32 v[24:25], v[2:3], 1.0 op_sel_hi:[1,0]
	s_nop 0
	v_div_scale_f32 v0, s[0:1], v25, v25, v41
	v_rcp_f32_e32 v2, v0
	s_nop 0
	v_fma_f32 v3, -v0, v2, 1.0
	v_fmac_f32_e32 v2, v3, v2
	v_div_scale_f32 v3, vcc, v41, v25, v41
	v_mul_f32_e32 v8, v3, v2
	v_fma_f32 v9, -v0, v8, v3
	v_fmac_f32_e32 v8, v9, v2
	v_fma_f32 v0, -v0, v8, v3
	v_div_fmas_f32 v42, v0, v2, v8
	v_div_scale_f32 v0, s[0:1], v24, v24, v40
	v_rcp_f32_e32 v2, v0
	s_nop 0
	v_fma_f32 v3, -v0, v2, 1.0
	v_fmac_f32_e32 v2, v3, v2
	v_div_scale_f32 v3, vcc, v40, v24, v40
	v_mul_f32_e32 v8, v3, v2
	v_fma_f32 v9, -v0, v8, v3
	v_fmac_f32_e32 v8, v9, v2
	v_fma_f32 v0, -v0, v8, v3
	v_div_fmas_f32 v43, v0, v2, v8
	v_mul_f32_e32 v0, 0xbfb8aa3b, v44
	v_exp_f32_e32 v0, v0
	s_nop 0
	v_pk_add_f32 v[26:27], v[0:1], 1.0 op_sel_hi:[1,0]
	s_nop 0
	v_div_scale_f32 v0, s[0:1], v27, v27, v45
	v_rcp_f32_e32 v1, v0
	s_nop 0
	v_fma_f32 v2, -v0, v1, 1.0
	v_fmac_f32_e32 v1, v2, v1
	v_div_scale_f32 v2, vcc, v45, v27, v45
	v_mul_f32_e32 v3, v2, v1
	v_fma_f32 v8, -v0, v3, v2
	v_fmac_f32_e32 v3, v8, v1
	v_fma_f32 v0, -v0, v3, v2
	v_div_fmas_f32 v46, v0, v1, v3
	v_div_scale_f32 v0, s[0:1], v26, v26, v44
	v_rcp_f32_e32 v1, v0
	s_nop 0
	v_fma_f32 v2, -v0, v1, 1.0
	v_fmac_f32_e32 v1, v2, v1
	v_div_scale_f32 v2, vcc, v44, v26, v44
	v_mul_f32_e32 v3, v2, v1
	v_fma_f32 v8, -v0, v3, v2
	v_fmac_f32_e32 v3, v8, v1
	v_fma_f32 v0, -v0, v3, v2
	v_div_fmas_f32 v47, v0, v1, v3
	ds_read_b128 v[0:3], v19 offset:288
	ds_read_b128 v[8:11], v19 offset:320
	s_waitcnt lgkmcnt(1)
	v_pk_mul_f32 v[0:1], v[0:1], v[22:23]
	v_div_fixup_f32 v23, v34, v31, v33
	v_div_fixup_f32 v22, v35, v30, v32
	v_pk_mul_f32 v[2:3], v[2:3], v[20:21]
	v_div_fixup_f32 v21, v38, v29, v37
	v_div_fixup_f32 v20, v39, v28, v36
	v_pk_mul_f32 v[0:1], v[22:23], v[0:1]
	v_pk_mul_f32 v[2:3], v[20:21], v[2:3]
	v_cvt_pk_bf16_f32 v0, v0, v1
	v_cvt_pk_bf16_f32 v1, v2, v3
	global_store_dwordx2 v[16:17], v[0:1], off offset:144
	s_waitcnt vmcnt(10)
	v_mov_b32_e32 v0, v68
	v_mov_b32_e32 v1, v69
	v_lshrrev_b32_e32 v124, 6, v224
	v_mul_u32_u24_e32 v124, 0x1400, v124
	v_and_b32_e32 v126, 63, v224
	v_lshl_add_u32 v124, v126, 4, v124
	v_add_u32_e32 v124, 0x21000, v124
	ds_read_b128 v[50:53], v124
	ds_read_b128 v[54:57], v124 offset:1024
	ds_read_b128 v[58:61], v124 offset:2048
	ds_read_b128 v[62:65], v124 offset:3072
	ds_read_b128 v[66:69], v124 offset:4096
	v_lshlrev_b32_e32 v19, 16, v0
	v_and_b32_e32 v20, 0xffff0000, v0
	v_mul_f32_e32 v0, 0xbfb8aa3b, v19
	v_exp_f32_e32 v2, v0
	v_mul_f32_e32 v0, 0xbfb8aa3b, v20
	v_exp_f32_e32 v3, v0
	v_pk_mul_f32 v[14:15], v[14:15], v[18:19] op_sel_hi:[1,0]
	v_pk_add_f32 v[2:3], v[2:3], 1.0 op_sel_hi:[1,0]
	s_nop 0
	v_div_scale_f32 v0, s[0:1], v3, v3, v20
	v_rcp_f32_e32 v21, v0
	s_waitcnt lgkmcnt(0)
	v_pk_mul_f32 v[8:9], v[8:9], v[14:15]
	v_div_fixup_f32 v15, v42, v25, v41
	v_div_fixup_f32 v14, v43, v24, v40
	v_fma_f32 v22, -v0, v21, 1.0
	v_fmac_f32_e32 v21, v22, v21
	v_div_scale_f32 v22, vcc, v20, v3, v20
	v_mul_f32_e32 v23, v22, v21
	v_fma_f32 v28, -v0, v23, v22
	v_fmac_f32_e32 v23, v28, v21
	v_fma_f32 v0, -v0, v23, v22
	v_div_fmas_f32 v21, v0, v21, v23
	v_div_scale_f32 v0, s[0:1], v2, v2, v19
	v_rcp_f32_e32 v22, v0
	v_pk_mul_f32 v[8:9], v[14:15], v[8:9]
	v_pk_mul_f32 v[14:15], v[100:101], v[18:19] op_sel_hi:[1,0]
	v_cvt_pk_bf16_f32 v8, v8, v9
	v_fma_f32 v23, -v0, v22, 1.0
	v_fmac_f32_e32 v22, v23, v22
	v_div_scale_f32 v23, vcc, v19, v2, v19
	v_mul_f32_e32 v28, v23, v22
	v_fma_f32 v29, -v0, v28, v23
	v_fmac_f32_e32 v28, v29, v22
	v_fma_f32 v0, -v0, v28, v23
	v_div_fmas_f32 v22, v0, v22, v28
	v_lshlrev_b32_e32 v23, 16, v1
	v_and_b32_e32 v28, 0xffff0000, v1
	v_mul_f32_e32 v0, 0xbfb8aa3b, v23
	v_mul_f32_e32 v1, 0xbfb8aa3b, v28
	v_exp_f32_e32 v0, v0
	v_exp_f32_e32 v1, v1
	v_pk_mul_f32 v[10:11], v[10:11], v[14:15]
	v_div_fixup_f32 v15, v46, v27, v45
	v_div_fixup_f32 v14, v47, v26, v44
	v_pk_add_f32 v[0:1], v[0:1], 1.0 op_sel_hi:[1,0]
	v_pk_mul_f32 v[10:11], v[14:15], v[10:11]
	v_div_scale_f32 v29, s[0:1], v1, v1, v28
	v_rcp_f32_e32 v30, v29
	v_cvt_pk_bf16_f32 v9, v10, v11
	global_store_dwordx2 v[16:17], v[8:9], off offset:160
	v_pk_mul_f32 v[8:9], v[98:99], v[18:19] op_sel_hi:[1,0]
	v_fma_f32 v31, -v29, v30, 1.0
	v_fmac_f32_e32 v30, v31, v30
	v_div_scale_f32 v31, vcc, v28, v1, v28
	v_mul_f32_e32 v32, v31, v30
	v_fma_f32 v33, -v29, v32, v31
	v_fmac_f32_e32 v32, v33, v30
	v_fma_f32 v29, -v29, v32, v31
	v_div_fmas_f32 v29, v29, v30, v32
	v_pk_mul_f32 v[4:5], v[4:5], v[8:9]
	v_div_fixup_f32 v3, v21, v3, v20
	v_div_fixup_f32 v2, v22, v2, v19
	v_pk_mul_f32 v[2:3], v[2:3], v[4:5]
	v_pk_mul_f32 v[4:5], v[12:13], v[18:19] op_sel_hi:[1,0]
	v_div_fixup_f32 v1, v29, v1, v28
	v_pk_mul_f32 v[4:5], v[6:7], v[4:5]
	v_rcp_f32_e32 v30, v0
	s_nop 0
	v_mul_f32_e32 v0, v23, v30
	v_pk_mul_f32 v[0:1], v[0:1], v[4:5]
	v_cvt_pk_bf16_f32 v2, v2, v3
	v_cvt_pk_bf16_f32 v3, v0, v1
	global_store_dwordx2 v[16:17], v[2:3], off offset:176
	s_branch .LBB0_855

.LBB0_982:
	s_add_i32 s22, s7, 0x100
	s_add_u32 s7, s14, s7
	s_addc_u32 s23, s15, 0
	s_add_u32 s24, s7, 0x100
	s_addc_u32 s25, s23, 0
	s_and_b64 s[20:21], s[18:19], exec
	s_cselect_b32 s25, s11, s25
	s_cselect_b32 s24, s10, s24
	s_add_i32 s49, 0, 0x10000
	s_and_b64 s[18:19], s[18:19], exec
	s_cselect_b32 s19, 0, s22
	s_cselect_b32 s18, 0, 0
	s_add_u32 s26, s0, s19
	s_addc_u32 s27, s1, s18
	s_add_u32 s28, s7, 0x10080
	s_addc_u32 s29, s23, 0
	s_add_i32 s53, s49, s35
	s_add_i32 m0, s13, 0xc000
	s_add_i32 s54, s13, 0xe000
	s_add_i32 s52, 0, 0x14000
	s_add_i32 s51, s53, 0x2000
	s_add_u32 s22, s26, 0x10000
	v_add_u32_e32 v36, s49, v205
	s_addc_u32 s23, s27, 0
	s_add_i32 s48, s52, s35
	ds_read_b128 v[16:19], v36
	ds_read_b128 v[20:23], v36 offset:1024
	ds_read_b128 v[32:35], v36 offset:2048
	ds_read_b128 v[36:39], v36 offset:3072
	s_add_i32 s47, s48, 0x2000
	s_add_i32 s46, 0, 0x18000
	s_add_u32 s20, s24, 0x10000
	s_addc_u32 s21, s25, 0
	s_add_i32 s45, s46, s35
	s_add_i32 s44, 0, 0x1c000
	s_add_i32 s7, s45, 0x2000
	s_add_u32 s18, s26, 0x10080
	s_addc_u32 s19, s27, 0
	s_add_i32 s50, s44, s35
	s_add_i32 s49, s50, 0x2000
	v_lshl_add_u64 v[190:191], s[28:29], 0, v[48:49]
	ds_read_b128 v[98:101], v206
	ds_read_b128 v[110:113], v206 offset:1024
	ds_read_b128 v[114:117], v206 offset:2048
	ds_read_b128 v[130:133], v206 offset:3072
	ds_read_b128 v[138:141], v206 offset:4096
	ds_read_b128 v[150:153], v206 offset:5120
	ds_read_b128 v[162:165], v206 offset:6144
	ds_read_b128 v[174:177], v206 offset:7168
	global_load_lds_dwordx4 v[190:191], off
	v_lshl_add_u64 v[190:191], s[28:29], 0, v[180:181]
	s_mov_b32 m0, s54
	s_nop 0
	global_load_lds_dwordx4 v[190:191], off
	s_waitcnt lgkmcnt(8)
	s_barrier
	s_waitcnt lgkmcnt(0)
	s_setprio 1
	s_waitcnt lgkmcnt(0)
	v_mfma_f32_16x16x32_bf16 v[170:173], v[16:19], v[98:101], v[170:173]
	v_mfma_f32_16x16x32_bf16 v[166:169], v[32:35], v[98:101], v[166:169]
	v_mfma_f32_16x16x32_bf16 v[146:149], v[16:19], v[114:117], v[146:149]
	v_mfma_f32_16x16x32_bf16 v[142:145], v[32:35], v[114:117], v[142:145]
	v_mfma_f32_16x16x32_bf16 v[122:125], v[16:19], v[138:141], v[122:125]
	v_mfma_f32_16x16x32_bf16 v[118:121], v[32:35], v[138:141], v[118:121]
	v_mfma_f32_16x16x32_bf16 v[94:97], v[16:19], v[162:165], v[94:97]
	v_mfma_f32_16x16x32_bf16 v[90:93], v[32:35], v[162:165], v[90:93]
	v_mfma_f32_16x16x32_bf16 v[170:173], v[20:23], v[110:113], v[170:173]
	v_mfma_f32_16x16x32_bf16 v[166:169], v[36:39], v[110:113], v[166:169]
	v_mfma_f32_16x16x32_bf16 v[146:149], v[20:23], v[130:133], v[146:149]
	v_mfma_f32_16x16x32_bf16 v[142:145], v[36:39], v[130:133], v[142:145]
	v_mfma_f32_16x16x32_bf16 v[122:125], v[20:23], v[150:153], v[122:125]
	v_mfma_f32_16x16x32_bf16 v[118:121], v[36:39], v[150:153], v[118:121]
	v_mfma_f32_16x16x32_bf16 v[94:97], v[20:23], v[174:177], v[94:97]
	v_mfma_f32_16x16x32_bf16 v[90:93], v[36:39], v[174:177], v[90:93]
	s_setprio 0
	s_barrier
	v_add_u32_e32 v202, s52, v205
	s_mov_b32 m0, s53
	ds_read_b128 v[190:193], v202
	ds_read_b128 v[198:201], v202 offset:1024
	ds_read_b128 v[208:211], v202 offset:2048
	ds_read_b128 v[212:215], v202 offset:3072
	v_lshl_add_u64 v[202:203], s[26:27], 0, v[182:183]
	global_load_lds_dwordx4 v[202:203], off
	v_lshl_add_u64 v[242:243], s[26:27], 0, v[178:179]
	s_mov_b32 m0, s51
	s_nop 0
	global_load_lds_dwordx4 v[242:243], off
	s_barrier
	s_waitcnt lgkmcnt(0)
	s_setprio 1
	s_waitcnt lgkmcnt(0)
	v_mfma_f32_16x16x32_bf16 v[158:161], v[190:193], v[98:101], v[158:161]
	v_mfma_f32_16x16x32_bf16 v[98:101], v[208:211], v[98:101], v[154:157]
	v_mfma_f32_16x16x32_bf16 v[106:109], v[190:193], v[138:141], v[106:109]
	v_mfma_f32_16x16x32_bf16 v[102:105], v[208:211], v[138:141], v[102:105]
	v_mfma_f32_16x16x32_bf16 v[86:89], v[190:193], v[162:165], v[86:89]
	v_mfma_f32_16x16x32_bf16 v[82:85], v[208:211], v[162:165], v[82:85]
	v_mfma_f32_16x16x32_bf16 v[158:161], v[198:201], v[110:113], v[158:161]
	v_mfma_f32_16x16x32_bf16 v[98:101], v[212:215], v[110:113], v[98:101]
	v_mfma_f32_16x16x32_bf16 v[110:113], v[190:193], v[114:117], v[134:137]
	v_mfma_f32_16x16x32_bf16 v[114:117], v[208:211], v[114:117], v[126:129]
	v_mfma_f32_16x16x32_bf16 v[106:109], v[198:201], v[150:153], v[106:109]
	v_mfma_f32_16x16x32_bf16 v[102:105], v[212:215], v[150:153], v[102:105]
	v_mfma_f32_16x16x32_bf16 v[86:89], v[198:201], v[174:177], v[86:89]
	v_mfma_f32_16x16x32_bf16 v[82:85], v[212:215], v[174:177], v[82:85]
	v_mfma_f32_16x16x32_bf16 v[110:113], v[198:201], v[130:133], v[110:113]
	v_mfma_f32_16x16x32_bf16 v[114:117], v[212:215], v[130:133], v[114:117]
	s_setprio 0
	s_mov_b32 m0, s13
	v_lshl_add_u64 v[244:245], s[24:25], 0, v[48:49]
	s_barrier
	ds_read_b128 v[126:129], v206 offset:16384
	ds_read_b128 v[130:133], v206 offset:17408
	ds_read_b128 v[134:137], v206 offset:18432
	ds_read_b128 v[138:141], v206 offset:19456
	ds_read_b128 v[150:153], v206 offset:20480
	ds_read_b128 v[154:157], v206 offset:21504
	ds_read_b128 v[162:165], v206 offset:22528
	ds_read_b128 v[174:177], v206 offset:23552
	global_load_lds_dwordx4 v[244:245], off
	v_lshl_add_u64 v[246:247], s[24:25], 0, v[180:181]
	s_mov_b32 m0, s38
	s_nop 0
	global_load_lds_dwordx4 v[246:247], off
	s_barrier
	s_waitcnt lgkmcnt(0)
	s_setprio 1
	s_waitcnt lgkmcnt(0)
	v_mfma_f32_16x16x32_bf16 v[78:81], v[16:19], v[126:129], v[78:81]
	v_mfma_f32_16x16x32_bf16 v[74:77], v[32:35], v[126:129], v[74:77]
	v_mfma_f32_16x16x32_bf16 v[62:65], v[16:19], v[134:137], v[62:65]
	v_mfma_f32_16x16x32_bf16 v[58:61], v[32:35], v[134:137], v[58:61]
	v_mfma_f32_16x16x32_bf16 v[44:47], v[16:19], v[150:153], v[44:47]
	v_mfma_f32_16x16x32_bf16 v[40:43], v[32:35], v[150:153], v[40:43]
	v_mfma_f32_16x16x32_bf16 v[12:15], v[16:19], v[162:165], v[12:15]
	v_mfma_f32_16x16x32_bf16 v[8:11], v[32:35], v[162:165], v[8:11]
	v_mfma_f32_16x16x32_bf16 v[78:81], v[20:23], v[130:133], v[78:81]
	v_mfma_f32_16x16x32_bf16 v[74:77], v[36:39], v[130:133], v[74:77]
	v_mfma_f32_16x16x32_bf16 v[62:65], v[20:23], v[138:141], v[62:65]
	v_mfma_f32_16x16x32_bf16 v[58:61], v[36:39], v[138:141], v[58:61]
	v_mfma_f32_16x16x32_bf16 v[44:47], v[20:23], v[154:157], v[44:47]
	v_mfma_f32_16x16x32_bf16 v[40:43], v[36:39], v[154:157], v[40:43]
	v_mfma_f32_16x16x32_bf16 v[12:15], v[20:23], v[174:177], v[12:15]
	v_mfma_f32_16x16x32_bf16 v[8:11], v[36:39], v[174:177], v[8:11]
	s_setprio 0
	s_barrier
	s_mov_b32 m0, s48
	v_lshl_add_u64 v[16:17], s[22:23], 0, v[182:183]
	global_load_lds_dwordx4 v[16:17], off
	v_lshl_add_u64 v[16:17], s[22:23], 0, v[178:179]
	s_mov_b32 m0, s47
	s_nop 0
	global_load_lds_dwordx4 v[16:17], off
	s_waitcnt vmcnt(6)
	s_barrier
	s_setprio 1
	v_mfma_f32_16x16x32_bf16 v[28:31], v[190:193], v[150:153], v[28:31]
	v_mfma_f32_16x16x32_bf16 v[24:27], v[208:211], v[150:153], v[24:27]
	v_mfma_f32_16x16x32_bf16 v[4:7], v[190:193], v[162:165], v[4:7]
	v_mfma_f32_16x16x32_bf16 v[0:3], v[208:211], v[162:165], v[0:3]
	v_mfma_f32_16x16x32_bf16 v[16:19], v[190:193], v[126:129], v[70:73]
	v_mfma_f32_16x16x32_bf16 v[20:23], v[208:211], v[126:129], v[66:69]
	v_mfma_f32_16x16x32_bf16 v[32:35], v[190:193], v[134:137], v[54:57]
	v_mfma_f32_16x16x32_bf16 v[36:39], v[208:211], v[134:137], v[50:53]
	v_mfma_f32_16x16x32_bf16 v[28:31], v[198:201], v[154:157], v[28:31]
	v_mfma_f32_16x16x32_bf16 v[24:27], v[212:215], v[154:157], v[24:27]
	v_mfma_f32_16x16x32_bf16 v[4:7], v[198:201], v[174:177], v[4:7]
	v_mfma_f32_16x16x32_bf16 v[0:3], v[212:215], v[174:177], v[0:3]
	v_mfma_f32_16x16x32_bf16 v[16:19], v[198:201], v[130:133], v[16:19]
	v_mfma_f32_16x16x32_bf16 v[20:23], v[212:215], v[130:133], v[20:23]
	v_mfma_f32_16x16x32_bf16 v[32:35], v[198:201], v[138:141], v[32:35]
	v_mfma_f32_16x16x32_bf16 v[36:39], v[212:215], v[138:141], v[36:39]
	s_setprio 0
	v_add_u32_e32 v70, s46, v205
	s_barrier
	ds_read_b128 v[50:53], v70
	ds_read_b128 v[54:57], v70 offset:1024
	ds_read_b128 v[66:69], v70 offset:2048
	ds_read_b128 v[70:73], v70 offset:3072
	s_mov_b32 m0, s39
	v_lshl_add_u64 v[134:135], s[20:21], 0, v[48:49]
	ds_read_b128 v[126:129], v206 offset:32768
	ds_read_b128 v[130:133], v206 offset:33792
	ds_read_b128 v[138:141], v206 offset:34816
	ds_read_b128 v[150:153], v206 offset:35840
	ds_read_b128 v[162:165], v206 offset:36864
	ds_read_b128 v[174:177], v206 offset:37888
	ds_read_b128 v[190:193], v206 offset:38912
	ds_read_b128 v[198:201], v206 offset:39936
	global_load_lds_dwordx4 v[134:135], off
	v_lshl_add_u64 v[134:135], s[20:21], 0, v[180:181]
	s_mov_b32 m0, s40
	s_nop 0
	global_load_lds_dwordx4 v[134:135], off
	s_waitcnt lgkmcnt(8)
	s_barrier
	s_waitcnt lgkmcnt(0)
	s_setprio 1
	s_waitcnt lgkmcnt(0)
	v_mfma_f32_16x16x32_bf16 v[134:137], v[50:53], v[126:129], v[170:173]
	v_mfma_f32_16x16x32_bf16 v[170:173], v[54:57], v[130:133], v[134:137]
	v_mfma_f32_16x16x32_bf16 v[134:137], v[66:69], v[126:129], v[166:169]
	v_mfma_f32_16x16x32_bf16 v[166:169], v[70:73], v[130:133], v[134:137]
	v_mfma_f32_16x16x32_bf16 v[134:137], v[50:53], v[138:141], v[146:149]
	v_mfma_f32_16x16x32_bf16 v[146:149], v[54:57], v[150:153], v[134:137]
	v_mfma_f32_16x16x32_bf16 v[134:137], v[66:69], v[138:141], v[142:145]
	v_mfma_f32_16x16x32_bf16 v[122:125], v[50:53], v[162:165], v[122:125]
	v_mfma_f32_16x16x32_bf16 v[118:121], v[66:69], v[162:165], v[118:121]
	v_mfma_f32_16x16x32_bf16 v[94:97], v[50:53], v[190:193], v[94:97]
	v_mfma_f32_16x16x32_bf16 v[90:93], v[66:69], v[190:193], v[90:93]
	v_mfma_f32_16x16x32_bf16 v[142:145], v[70:73], v[150:153], v[134:137]
	v_mfma_f32_16x16x32_bf16 v[122:125], v[54:57], v[174:177], v[122:125]
	v_mfma_f32_16x16x32_bf16 v[118:121], v[70:73], v[174:177], v[118:121]
	v_mfma_f32_16x16x32_bf16 v[94:97], v[54:57], v[198:201], v[94:97]
	v_mfma_f32_16x16x32_bf16 v[90:93], v[70:73], v[198:201], v[90:93]
	s_setprio 0
	s_barrier
	v_add_u32_e32 v134, s44, v205
	s_mov_b32 m0, s45
	ds_read_b128 v[208:211], v134
	ds_read_b128 v[212:215], v134 offset:1024
	ds_read_b128 v[216:219], v134 offset:2048
	ds_read_b128 v[220:223], v134 offset:3072
	v_lshl_add_u64 v[134:135], v[202:203], 0, s[66:67]
	global_load_lds_dwordx4 v[134:135], off
	v_lshl_add_u64 v[134:135], v[242:243], 0, s[66:67]
	s_mov_b32 m0, s7
	s_nop 0
	global_load_lds_dwordx4 v[134:135], off
	s_barrier
	s_waitcnt lgkmcnt(0)
	s_setprio 1
	s_waitcnt lgkmcnt(0)
	v_mfma_f32_16x16x32_bf16 v[98:101], v[216:219], v[126:129], v[98:101]
	v_mfma_f32_16x16x32_bf16 v[134:137], v[208:211], v[126:129], v[158:161]
	v_mfma_f32_16x16x32_bf16 v[154:157], v[220:223], v[130:133], v[98:101]
	v_mfma_f32_16x16x32_bf16 v[98:101], v[208:211], v[138:141], v[110:113]
	v_mfma_f32_16x16x32_bf16 v[158:161], v[212:215], v[130:133], v[134:137]
	v_mfma_f32_16x16x32_bf16 v[134:137], v[212:215], v[150:153], v[98:101]
	v_mfma_f32_16x16x32_bf16 v[98:101], v[216:219], v[138:141], v[114:117]
	v_mfma_f32_16x16x32_bf16 v[126:129], v[220:223], v[150:153], v[98:101]
	v_mfma_f32_16x16x32_bf16 v[98:101], v[208:211], v[162:165], v[106:109]
	v_mfma_f32_16x16x32_bf16 v[106:109], v[212:215], v[174:177], v[98:101]
	v_mfma_f32_16x16x32_bf16 v[98:101], v[216:219], v[162:165], v[102:105]
	v_mfma_f32_16x16x32_bf16 v[86:89], v[208:211], v[190:193], v[86:89]
	v_mfma_f32_16x16x32_bf16 v[82:85], v[216:219], v[190:193], v[82:85]
	v_mfma_f32_16x16x32_bf16 v[102:105], v[220:223], v[174:177], v[98:101]
	v_mfma_f32_16x16x32_bf16 v[86:89], v[212:215], v[198:201], v[86:89]
	v_mfma_f32_16x16x32_bf16 v[82:85], v[220:223], v[198:201], v[82:85]
	s_setprio 0
	s_mov_b32 m0, s41
	v_lshl_add_u64 v[190:191], v[244:245], 0, s[66:67]
	s_barrier
	ds_read_b128 v[98:101], v206 offset:49152
	ds_read_b128 v[110:113], v206 offset:50176
	ds_read_b128 v[114:117], v206 offset:51200
	ds_read_b128 v[130:133], v206 offset:52224
	ds_read_b128 v[138:141], v206 offset:53248
	ds_read_b128 v[150:153], v206 offset:54272
	ds_read_b128 v[162:165], v206 offset:55296
	ds_read_b128 v[174:177], v206 offset:56320
	global_load_lds_dwordx4 v[190:191], off
	v_lshl_add_u64 v[190:191], v[246:247], 0, s[66:67]
	s_mov_b32 m0, s42
	s_nop 0
	global_load_lds_dwordx4 v[190:191], off
	s_barrier
	s_waitcnt lgkmcnt(0)
	s_setprio 1
	s_waitcnt lgkmcnt(0)
	v_mfma_f32_16x16x32_bf16 v[78:81], v[50:53], v[98:101], v[78:81]
	v_mfma_f32_16x16x32_bf16 v[74:77], v[66:69], v[98:101], v[74:77]
	v_mfma_f32_16x16x32_bf16 v[62:65], v[50:53], v[114:117], v[62:65]
	v_mfma_f32_16x16x32_bf16 v[58:61], v[66:69], v[114:117], v[58:61]
	v_mfma_f32_16x16x32_bf16 v[44:47], v[50:53], v[138:141], v[44:47]
	v_mfma_f32_16x16x32_bf16 v[40:43], v[66:69], v[138:141], v[40:43]
	v_mfma_f32_16x16x32_bf16 v[12:15], v[50:53], v[162:165], v[12:15]
	v_mfma_f32_16x16x32_bf16 v[8:11], v[66:69], v[162:165], v[8:11]
	v_mfma_f32_16x16x32_bf16 v[78:81], v[54:57], v[110:113], v[78:81]
	v_mfma_f32_16x16x32_bf16 v[74:77], v[70:73], v[110:113], v[74:77]
	v_mfma_f32_16x16x32_bf16 v[62:65], v[54:57], v[130:133], v[62:65]
	v_mfma_f32_16x16x32_bf16 v[58:61], v[70:73], v[130:133], v[58:61]
	v_mfma_f32_16x16x32_bf16 v[44:47], v[54:57], v[150:153], v[44:47]
	v_mfma_f32_16x16x32_bf16 v[40:43], v[70:73], v[150:153], v[40:43]
	v_mfma_f32_16x16x32_bf16 v[12:15], v[54:57], v[174:177], v[12:15]
	v_mfma_f32_16x16x32_bf16 v[8:11], v[70:73], v[174:177], v[8:11]
	s_setprio 0
	s_barrier
	s_mov_b32 m0, s50
	v_lshl_add_u64 v[50:51], s[18:19], 0, v[182:183]
	global_load_lds_dwordx4 v[50:51], off
	v_lshl_add_u64 v[50:51], s[18:19], 0, v[178:179]
	s_mov_b32 m0, s49
	s_nop 0
	global_load_lds_dwordx4 v[50:51], off
	s_waitcnt vmcnt(6)
	s_barrier
	s_setprio 1
	v_mfma_f32_16x16x32_bf16 v[16:19], v[208:211], v[98:101], v[16:19]
	v_mfma_f32_16x16x32_bf16 v[70:73], v[212:215], v[110:113], v[16:19]
	v_mfma_f32_16x16x32_bf16 v[16:19], v[216:219], v[98:101], v[20:23]
	v_mfma_f32_16x16x32_bf16 v[66:69], v[220:223], v[110:113], v[16:19]
	v_mfma_f32_16x16x32_bf16 v[16:19], v[208:211], v[114:117], v[32:35]
	v_mfma_f32_16x16x32_bf16 v[54:57], v[212:215], v[130:133], v[16:19]
	v_mfma_f32_16x16x32_bf16 v[16:19], v[216:219], v[114:117], v[36:39]
	v_mfma_f32_16x16x32_bf16 v[50:53], v[220:223], v[130:133], v[16:19]
	v_mfma_f32_16x16x32_bf16 v[16:19], v[208:211], v[138:141], v[28:31]
	v_mfma_f32_16x16x32_bf16 v[28:31], v[212:215], v[150:153], v[16:19]
	v_mfma_f32_16x16x32_bf16 v[16:19], v[216:219], v[138:141], v[24:27]
	v_mfma_f32_16x16x32_bf16 v[4:7], v[208:211], v[162:165], v[4:7]
	v_mfma_f32_16x16x32_bf16 v[0:3], v[216:219], v[162:165], v[0:3]
	v_mfma_f32_16x16x32_bf16 v[24:27], v[220:223], v[150:153], v[16:19]
	v_mfma_f32_16x16x32_bf16 v[4:7], v[212:215], v[174:177], v[4:7]
	v_mfma_f32_16x16x32_bf16 v[0:3], v[220:223], v[174:177], v[0:3]
	s_setprio 0
	s_andn2_b64 vcc, exec, s[16:17]
	s_mov_b64 s[18:19], -1
	s_mov_b64 s[16:17], 0
	s_movk_i32 s7, 0x100
	s_barrier
	s_cbranch_vccz .LBB0_982
	global_load_dwordx4 v[32:35], v[184:185], off offset:16
	global_load_dwordx4 v[36:39], v[184:185], off
	global_load_dwordx4 v[16:19], v[184:185], off offset:528
	global_load_dwordx4 v[20:23], v[184:185], off offset:512
	v_lshl_add_u32 v190, s12, 8, v204
	v_ashrrev_i32_e32 v191, 31, v190
	v_lshlrev_b64 v[98:99], 9, v[190:191]
	v_lshl_add_u64 v[98:99], v[186:187], 0, v[98:99]
	global_load_dwordx4 v[174:177], v[98:99], off
	global_load_dwordx4 v[162:165], v[98:99], off offset:256
	v_lshlrev_b64 v[202:203], 11, v[190:191]
	v_or_b32_e32 v200, 16, v190
	v_ashrrev_i32_e32 v201, 31, v200
	v_lshlrev_b64 v[98:99], 9, v[200:201]
	v_or_b32_e32 v198, 32, v190
	v_lshl_add_u64 v[98:99], v[186:187], 0, v[98:99]
	v_ashrrev_i32_e32 v199, 31, v198
	global_load_dwordx4 v[150:153], v[98:99], off
	global_load_dwordx4 v[138:141], v[98:99], off offset:256
	v_lshlrev_b64 v[98:99], 9, v[198:199]
	v_or_b32_e32 v192, 48, v190
	v_lshl_add_u64 v[98:99], v[186:187], 0, v[98:99]
	v_ashrrev_i32_e32 v193, 31, v192
	global_load_dwordx4 v[130:133], v[98:99], off
	global_load_dwordx4 v[114:117], v[98:99], off offset:256
	v_lshlrev_b64 v[98:99], 9, v[192:193]
	v_lshl_add_u64 v[98:99], v[186:187], 0, v[98:99]
	global_load_dwordx4 v[110:113], v[98:99], off
	s_nop 0
	global_load_dwordx4 v[98:101], v[98:99], off offset:256
	s_mov_b32 s12, s6
	s_waitcnt vmcnt(0)
	v_pk_add_f32 v[168:169], v[168:169], v[34:35]
	v_pk_add_f32 v[170:171], v[170:171], v[36:37]
	v_pk_add_f32 v[208:209], v[172:173], v[38:39]
	v_pk_add_f32 v[172:173], v[166:167], v[32:33]
	v_mul_f32_e32 v166, 0xbfb8aa3b, v170
	v_mul_f32_e32 v167, 0xbfb8aa3b, v171
	v_exp_f32_e32 v166, v166
	v_exp_f32_e32 v167, v167
	v_lshlrev_b32_e32 v170, 16, v174
	v_and_b32_e32 v171, 0xffff0000, v174
	v_mul_f32_e32 v172, 0xbfb8aa3b, v172
	v_pk_add_f32 v[166:167], v[166:167], 1.0 op_sel_hi:[1,0]
	v_mul_f32_e32 v173, 0xbfb8aa3b, v173
	v_exp_f32_e32 v172, v172
	v_exp_f32_e32 v173, v173
	v_mul_f32_e32 v168, 0xbfb8aa3b, v168
	v_rcp_f32_e32 v167, v167
	s_nop 0
	v_pk_add_f32 v[172:173], v[172:173], 1.0 op_sel_hi:[1,0]
	v_mul_f32_e32 v169, 0xbfb8aa3b, v169
	v_exp_f32_e32 v168, v168
	v_rcp_f32_e32 v166, v166
	s_nop 0
	v_pk_mul_f32 v[166:167], v[166:167], v[170:171]
	v_mul_f32_e32 v170, 0xbfb8aa3b, v208
	v_mul_f32_e32 v171, 0xbfb8aa3b, v209
	v_exp_f32_e32 v170, v170
	v_exp_f32_e32 v171, v171
	v_lshlrev_b32_e32 v174, 16, v175
	v_and_b32_e32 v175, 0xffff0000, v175
	v_exp_f32_e32 v169, v169
	v_pk_add_f32 v[170:171], v[170:171], 1.0 op_sel_hi:[1,0]
	v_pk_add_f32 v[158:159], v[158:159], v[20:21]
	v_pk_add_f32 v[168:169], v[168:169], 1.0 op_sel_hi:[1,0]
	v_pk_add_f32 v[160:161], v[160:161], v[22:23]
	v_pk_add_f32 v[156:157], v[156:157], v[18:19]
	v_rcp_f32_e32 v171, v171
	s_nop 0
	v_mul_f32_e32 v156, 0xbfb8aa3b, v156
	v_mul_f32_e32 v157, 0xbfb8aa3b, v157
	v_exp_f32_e32 v156, v156
	v_rcp_f32_e32 v170, v170
	s_nop 0
	v_pk_mul_f32 v[170:171], v[170:171], v[174:175]
	v_lshlrev_b32_e32 v174, 16, v176
	v_and_b32_e32 v175, 0xffff0000, v176
	v_exp_f32_e32 v157, v157
	v_pk_add_f32 v[146:147], v[146:147], v[36:37]
	v_pk_add_f32 v[148:149], v[148:149], v[38:39]
	v_rcp_f32_e32 v173, v173
	s_nop 0
	v_pk_add_f32 v[156:157], v[156:157], 1.0 op_sel_hi:[1,0]
	v_pk_add_f32 v[144:145], v[144:145], v[34:35]
	v_pk_add_f32 v[134:135], v[134:135], v[20:21]
	v_rcp_f32_e32 v172, v172
	s_nop 0
	v_div_scale_f32 v176, s[14:15], v169, v169, 1.0
	v_pk_mul_f32 v[172:173], v[172:173], v[174:175]
	v_lshlrev_b32_e32 v174, 16, v177
	v_and_b32_e32 v175, 0xffff0000, v177
	v_rcp_f32_e32 v177, v176
	v_mul_f32_e32 v144, 0xbfb8aa3b, v144
	v_mul_f32_e32 v145, 0xbfb8aa3b, v145
	v_exp_f32_e32 v144, v144
	v_fma_f32 v191, -v176, v177, 1.0
	v_fmac_f32_e32 v177, v191, v177
	v_div_scale_f32 v191, vcc, 1.0, v169, 1.0
	v_mul_f32_e32 v207, v191, v177
	v_fma_f32 v208, -v176, v207, v191
	v_fmac_f32_e32 v207, v208, v177
	v_fma_f32 v176, -v176, v207, v191
	v_div_fmas_f32 v176, v176, v177, v207
	v_div_fixup_f32 v169, v176, v169, 1.0
	v_exp_f32_e32 v145, v145
	v_pk_add_f32 v[136:137], v[136:137], v[22:23]
	v_pk_add_f32 v[128:129], v[128:129], v[18:19]
	v_rcp_f32_e32 v168, v168
	s_nop 0
	v_pk_mul_f32 v[174:175], v[168:169], v[174:175]
	v_cvt_pk_bf16_f32 v168, v166, v167
	v_cvt_pk_bf16_f32 v169, v170, v171
	v_cvt_pk_bf16_f32 v170, v172, v173
	v_cvt_pk_bf16_f32 v171, v174, v175
	v_lshl_add_u64 v[166:167], v[188:189], 0, v[202:203]
	global_store_dwordx4 v[166:167], v[168:171], off
	v_pk_add_f32 v[144:145], v[144:145], 1.0 op_sel_hi:[1,0]
	v_mul_f32_e32 v128, 0xbfb8aa3b, v128
	v_pk_add_f32 v[168:169], v[154:155], v[16:17]
	v_mul_f32_e32 v154, 0xbfb8aa3b, v158
	v_mul_f32_e32 v155, 0xbfb8aa3b, v159
	v_exp_f32_e32 v154, v154
	v_exp_f32_e32 v155, v155
	v_lshlrev_b32_e32 v158, 16, v162
	v_and_b32_e32 v159, 0xffff0000, v162
	v_mul_f32_e32 v129, 0xbfb8aa3b, v129
	v_pk_add_f32 v[154:155], v[154:155], 1.0 op_sel_hi:[1,0]
	v_exp_f32_e32 v128, v128
	v_exp_f32_e32 v129, v129
	v_pk_add_f32 v[122:123], v[122:123], v[36:37]
	v_pk_add_f32 v[124:125], v[124:125], v[38:39]
	v_rcp_f32_e32 v155, v155
	s_nop 0
	v_pk_add_f32 v[128:129], v[128:129], 1.0 op_sel_hi:[1,0]
	v_pk_add_f32 v[120:121], v[120:121], v[34:35]
	v_pk_add_f32 v[106:107], v[106:107], v[20:21]
	v_rcp_f32_e32 v154, v154
	s_nop 0
	v_pk_mul_f32 v[154:155], v[154:155], v[158:159]
	v_mul_f32_e32 v158, 0xbfb8aa3b, v160
	v_mul_f32_e32 v159, 0xbfb8aa3b, v161
	v_exp_f32_e32 v158, v158
	v_exp_f32_e32 v159, v159
	v_lshlrev_b32_e32 v160, 16, v163
	v_and_b32_e32 v161, 0xffff0000, v163
	v_cvt_pk_bf16_f32 v154, v154, v155
	v_pk_add_f32 v[158:159], v[158:159], 1.0 op_sel_hi:[1,0]
	v_mul_f32_e32 v120, 0xbfb8aa3b, v120
	v_mul_f32_e32 v121, 0xbfb8aa3b, v121
	v_exp_f32_e32 v120, v120
	v_exp_f32_e32 v121, v121
	v_rcp_f32_e32 v159, v159
	s_nop 0
	v_pk_add_f32 v[120:121], v[120:121], 1.0 op_sel_hi:[1,0]
	v_pk_add_f32 v[108:109], v[108:109], v[22:23]
	v_pk_add_f32 v[104:105], v[104:105], v[18:19]
	v_rcp_f32_e32 v158, v158
	s_nop 0
	v_pk_mul_f32 v[158:159], v[158:159], v[160:161]
	v_mul_f32_e32 v160, 0xbfb8aa3b, v168
	v_mul_f32_e32 v161, 0xbfb8aa3b, v169
	v_exp_f32_e32 v160, v160
	v_exp_f32_e32 v161, v161
	v_lshlrev_b32_e32 v162, 16, v164
	v_and_b32_e32 v163, 0xffff0000, v164
	v_cvt_pk_bf16_f32 v155, v158, v159
	v_pk_add_f32 v[160:161], v[160:161], 1.0 op_sel_hi:[1,0]
	v_mul_f32_e32 v104, 0xbfb8aa3b, v104
	v_mul_f32_e32 v105, 0xbfb8aa3b, v105
	v_exp_f32_e32 v104, v104
	v_exp_f32_e32 v105, v105
	v_rcp_f32_e32 v161, v161
	s_nop 0
	v_pk_add_f32 v[104:105], v[104:105], 1.0 op_sel_hi:[1,0]
	v_pk_add_f32 v[94:95], v[94:95], v[36:37]
	v_pk_add_f32 v[96:97], v[96:97], v[38:39]
	v_rcp_f32_e32 v160, v160
	s_nop 0
	v_div_scale_f32 v164, s[14:15], v157, v157, 1.0
	v_pk_mul_f32 v[160:161], v[160:161], v[162:163]
	v_lshlrev_b32_e32 v162, 16, v165
	v_and_b32_e32 v163, 0xffff0000, v165
	v_rcp_f32_e32 v165, v164
	v_pk_add_f32 v[92:93], v[92:93], v[34:35]
	v_pk_add_f32 v[86:87], v[86:87], v[20:21]
	v_mul_f32_e32 v92, 0xbfb8aa3b, v92
	v_fma_f32 v168, -v164, v165, 1.0
	v_fmac_f32_e32 v165, v168, v165
	v_div_scale_f32 v168, vcc, 1.0, v157, 1.0
	v_mul_f32_e32 v169, v168, v165
	v_fma_f32 v170, -v164, v169, v168
	v_fmac_f32_e32 v169, v170, v165
	v_fma_f32 v164, -v164, v169, v168
	v_div_fmas_f32 v164, v164, v165, v169
	v_div_fixup_f32 v157, v164, v157, 1.0
	v_mul_f32_e32 v93, 0xbfb8aa3b, v93
	v_exp_f32_e32 v92, v92
	v_exp_f32_e32 v93, v93
	v_rcp_f32_e32 v156, v156
	s_nop 0
	v_pk_mul_f32 v[162:163], v[156:157], v[162:163]
	v_cvt_pk_bf16_f32 v156, v160, v161
	v_cvt_pk_bf16_f32 v157, v162, v163
	global_store_dwordx4 v[166:167], v[154:157], off offset:256
	v_pk_add_f32 v[92:93], v[92:93], 1.0 op_sel_hi:[1,0]
	v_pk_add_f32 v[88:89], v[88:89], v[22:23]
	v_pk_add_f32 v[156:157], v[142:143], v[32:33]
	v_mul_f32_e32 v142, 0xbfb8aa3b, v146
	v_mul_f32_e32 v143, 0xbfb8aa3b, v147
	v_exp_f32_e32 v142, v142
	v_exp_f32_e32 v143, v143
	v_lshlrev_b32_e32 v146, 16, v150
	v_and_b32_e32 v147, 0xffff0000, v150
	v_lshlrev_b64 v[154:155], 11, v[200:201]
	v_pk_add_f32 v[142:143], v[142:143], 1.0 op_sel_hi:[1,0]
	v_pk_add_f32 v[84:85], v[84:85], v[18:19]
	v_mul_f32_e32 v84, 0xbfb8aa3b, v84
	v_mul_f32_e32 v85, 0xbfb8aa3b, v85
	v_exp_f32_e32 v84, v84
	v_rcp_f32_e32 v143, v143
	s_nop 0
	v_exp_f32_e32 v85, v85
	v_pk_add_f32 v[78:79], v[78:79], v[36:37]
	v_pk_add_f32 v[80:81], v[80:81], v[38:39]
	v_rcp_f32_e32 v142, v142
	s_nop 0
	v_pk_mul_f32 v[142:143], v[142:143], v[146:147]
	v_mul_f32_e32 v146, 0xbfb8aa3b, v148
	v_mul_f32_e32 v147, 0xbfb8aa3b, v149
	v_exp_f32_e32 v146, v146
	v_exp_f32_e32 v147, v147
	v_lshlrev_b32_e32 v148, 16, v151
	v_and_b32_e32 v149, 0xffff0000, v151
	v_pk_add_f32 v[84:85], v[84:85], 1.0 op_sel_hi:[1,0]
	v_pk_add_f32 v[146:147], v[146:147], 1.0 op_sel_hi:[1,0]
	v_pk_add_f32 v[76:77], v[76:77], v[34:35]
	v_mul_f32_e32 v76, 0xbfb8aa3b, v76
	v_mul_f32_e32 v77, 0xbfb8aa3b, v77
	v_exp_f32_e32 v76, v76
	v_rcp_f32_e32 v147, v147
	s_nop 0
	v_exp_f32_e32 v77, v77
	v_pk_add_f32 v[70:71], v[70:71], v[20:21]
	v_pk_add_f32 v[72:73], v[72:73], v[22:23]
	v_rcp_f32_e32 v146, v146
	s_nop 0
	v_pk_mul_f32 v[146:147], v[146:147], v[148:149]
	v_mul_f32_e32 v148, 0xbfb8aa3b, v156
	v_mul_f32_e32 v149, 0xbfb8aa3b, v157
	v_exp_f32_e32 v148, v148
	v_exp_f32_e32 v149, v149
	v_lshlrev_b32_e32 v150, 16, v152
	v_and_b32_e32 v151, 0xffff0000, v152
	v_pk_add_f32 v[76:77], v[76:77], 1.0 op_sel_hi:[1,0]
	v_pk_add_f32 v[148:149], v[148:149], 1.0 op_sel_hi:[1,0]
	v_pk_add_f32 v[68:69], v[68:69], v[18:19]
	v_mul_f32_e32 v68, 0xbfb8aa3b, v68
	v_mul_f32_e32 v69, 0xbfb8aa3b, v69
	v_exp_f32_e32 v68, v68
	v_rcp_f32_e32 v149, v149
	s_nop 0
	v_exp_f32_e32 v69, v69
	v_pk_add_f32 v[62:63], v[62:63], v[36:37]
	v_pk_add_f32 v[64:65], v[64:65], v[38:39]
	v_rcp_f32_e32 v148, v148
	s_nop 0
	v_div_scale_f32 v152, s[14:15], v145, v145, 1.0
	v_pk_mul_f32 v[148:149], v[148:149], v[150:151]
	v_lshlrev_b32_e32 v150, 16, v153
	v_and_b32_e32 v151, 0xffff0000, v153
	v_rcp_f32_e32 v153, v152
	v_pk_add_f32 v[68:69], v[68:69], 1.0 op_sel_hi:[1,0]
	v_pk_add_f32 v[60:61], v[60:61], v[34:35]
	v_pk_add_f32 v[54:55], v[54:55], v[20:21]
	v_fma_f32 v156, -v152, v153, 1.0
	v_fmac_f32_e32 v153, v156, v153
	v_div_scale_f32 v156, vcc, 1.0, v145, 1.0
	v_mul_f32_e32 v157, v156, v153
	v_fma_f32 v158, -v152, v157, v156
	v_fmac_f32_e32 v157, v158, v153
	v_fma_f32 v152, -v152, v157, v156
	v_div_fmas_f32 v152, v152, v153, v157
	v_div_fixup_f32 v145, v152, v145, 1.0
	v_mul_f32_e32 v60, 0xbfb8aa3b, v60
	v_mul_f32_e32 v61, 0xbfb8aa3b, v61
	v_exp_f32_e32 v60, v60
	v_rcp_f32_e32 v144, v144
	s_nop 0
	v_pk_mul_f32 v[150:151], v[144:145], v[150:151]
	v_cvt_pk_bf16_f32 v144, v142, v143
	v_cvt_pk_bf16_f32 v145, v146, v147
	v_cvt_pk_bf16_f32 v146, v148, v149
	v_cvt_pk_bf16_f32 v147, v150, v151
	v_lshl_add_u64 v[142:143], v[188:189], 0, v[154:155]
	global_store_dwordx4 v[142:143], v[144:147], off
	v_exp_f32_e32 v61, v61
	v_pk_add_f32 v[56:57], v[56:57], v[22:23]
	v_pk_add_f32 v[144:145], v[126:127], v[16:17]
	v_mul_f32_e32 v126, 0xbfb8aa3b, v134
	v_mul_f32_e32 v127, 0xbfb8aa3b, v135
	v_exp_f32_e32 v126, v126
	v_exp_f32_e32 v127, v127
	v_lshlrev_b32_e32 v134, 16, v138
	v_and_b32_e32 v135, 0xffff0000, v138
	v_pk_add_f32 v[60:61], v[60:61], 1.0 op_sel_hi:[1,0]
	v_pk_add_f32 v[126:127], v[126:127], 1.0 op_sel_hi:[1,0]
	v_pk_add_f32 v[52:53], v[52:53], v[18:19]
	v_mul_f32_e32 v52, 0xbfb8aa3b, v52
	v_mul_f32_e32 v53, 0xbfb8aa3b, v53
	v_exp_f32_e32 v52, v52
	v_rcp_f32_e32 v127, v127
	s_nop 0
	v_exp_f32_e32 v53, v53
	v_pk_add_f32 v[44:45], v[44:45], v[36:37]
	v_pk_add_f32 v[46:47], v[46:47], v[38:39]
	v_rcp_f32_e32 v126, v126
	s_nop 0
	v_pk_mul_f32 v[126:127], v[126:127], v[134:135]
	v_mul_f32_e32 v134, 0xbfb8aa3b, v136
	v_mul_f32_e32 v135, 0xbfb8aa3b, v137
	v_exp_f32_e32 v134, v134
	v_exp_f32_e32 v135, v135
	v_lshlrev_b32_e32 v136, 16, v139
	v_and_b32_e32 v137, 0xffff0000, v139
	v_cvt_pk_bf16_f32 v126, v126, v127
	v_pk_add_f32 v[134:135], v[134:135], 1.0 op_sel_hi:[1,0]
	v_pk_add_f32 v[52:53], v[52:53], 1.0 op_sel_hi:[1,0]
	v_pk_add_f32 v[42:43], v[42:43], v[34:35]
	v_pk_add_f32 v[28:29], v[28:29], v[20:21]
	v_mul_f32_e32 v42, 0xbfb8aa3b, v42
	v_rcp_f32_e32 v135, v135
	s_nop 0
	v_mul_f32_e32 v43, 0xbfb8aa3b, v43
	v_exp_f32_e32 v42, v42
	v_exp_f32_e32 v43, v43
	v_rcp_f32_e32 v134, v134
	s_nop 0
	v_pk_mul_f32 v[134:135], v[134:135], v[136:137]
	v_mul_f32_e32 v136, 0xbfb8aa3b, v144
	v_mul_f32_e32 v137, 0xbfb8aa3b, v145
	v_exp_f32_e32 v136, v136
	v_exp_f32_e32 v137, v137
	v_lshlrev_b32_e32 v138, 16, v140
	v_and_b32_e32 v139, 0xffff0000, v140
	v_cvt_pk_bf16_f32 v127, v134, v135
	v_pk_add_f32 v[136:137], v[136:137], 1.0 op_sel_hi:[1,0]
	v_pk_add_f32 v[42:43], v[42:43], 1.0 op_sel_hi:[1,0]
	v_pk_add_f32 v[30:31], v[30:31], v[22:23]
	v_pk_add_f32 v[26:27], v[26:27], v[18:19]
	v_pk_add_f32 v[12:13], v[12:13], v[36:37]
	v_rcp_f32_e32 v137, v137
	s_nop 0
	v_mul_f32_e32 v26, 0xbfb8aa3b, v26
	v_mul_f32_e32 v27, 0xbfb8aa3b, v27
	v_exp_f32_e32 v26, v26
	v_rcp_f32_e32 v136, v136
	s_nop 0
	v_div_scale_f32 v140, s[14:15], v129, v129, 1.0
	v_pk_mul_f32 v[136:137], v[136:137], v[138:139]
	v_lshlrev_b32_e32 v138, 16, v141
	v_and_b32_e32 v139, 0xffff0000, v141
	v_rcp_f32_e32 v141, v140
	v_exp_f32_e32 v27, v27
	v_pk_add_f32 v[14:15], v[14:15], v[38:39]
	v_pk_add_f32 v[10:11], v[10:11], v[34:35]
	v_fma_f32 v144, -v140, v141, 1.0
	v_fmac_f32_e32 v141, v144, v141
	v_div_scale_f32 v144, vcc, 1.0, v129, 1.0
	v_mul_f32_e32 v145, v144, v141
	v_fma_f32 v146, -v140, v145, v144
	v_fmac_f32_e32 v145, v146, v141
	v_fma_f32 v140, -v140, v145, v144
	v_div_fmas_f32 v140, v140, v141, v145
	v_div_fixup_f32 v129, v140, v129, 1.0
	v_pk_add_f32 v[26:27], v[26:27], 1.0 op_sel_hi:[1,0]
	v_mul_f32_e32 v10, 0xbfb8aa3b, v10
	v_mul_f32_e32 v11, 0xbfb8aa3b, v11
	v_rcp_f32_e32 v128, v128
	s_nop 0
	v_pk_mul_f32 v[138:139], v[128:129], v[138:139]
	v_cvt_pk_bf16_f32 v128, v136, v137
	v_cvt_pk_bf16_f32 v129, v138, v139
	global_store_dwordx4 v[142:143], v[126:129], off offset:256
	v_exp_f32_e32 v10, v10
	v_exp_f32_e32 v11, v11
	v_pk_add_f32 v[128:129], v[118:119], v[32:33]
	v_mul_f32_e32 v118, 0xbfb8aa3b, v122
	v_mul_f32_e32 v119, 0xbfb8aa3b, v123
	v_exp_f32_e32 v118, v118
	v_exp_f32_e32 v119, v119
	v_lshlrev_b32_e32 v122, 16, v130
	v_and_b32_e32 v123, 0xffff0000, v130
	v_lshlrev_b64 v[126:127], 11, v[198:199]
	v_pk_add_f32 v[118:119], v[118:119], 1.0 op_sel_hi:[1,0]
	v_pk_add_f32 v[10:11], v[10:11], 1.0 op_sel_hi:[1,0]
	v_pk_add_f32 v[4:5], v[4:5], v[20:21]
	v_pk_add_f32 v[6:7], v[6:7], v[22:23]
	v_pk_add_f32 v[2:3], v[2:3], v[18:19]
	v_rcp_f32_e32 v119, v119
	s_nop 0
	v_mul_f32_e32 v2, 0xbfb8aa3b, v2
	v_mul_f32_e32 v3, 0xbfb8aa3b, v3
	v_exp_f32_e32 v2, v2
	v_rcp_f32_e32 v118, v118
	s_nop 0
	v_pk_mul_f32 v[118:119], v[118:119], v[122:123]
	v_mul_f32_e32 v122, 0xbfb8aa3b, v124
	v_mul_f32_e32 v123, 0xbfb8aa3b, v125
	v_exp_f32_e32 v122, v122
	v_exp_f32_e32 v123, v123
	v_lshlrev_b32_e32 v124, 16, v131
	v_and_b32_e32 v125, 0xffff0000, v131
	v_exp_f32_e32 v3, v3
	v_pk_add_f32 v[122:123], v[122:123], 1.0 op_sel_hi:[1,0]
	v_pk_add_f32 v[2:3], v[2:3], 1.0 op_sel_hi:[1,0]
	s_nop 0
	v_rcp_f32_e32 v123, v123
	s_nop 0
	s_nop 0
	v_rcp_f32_e32 v122, v122
	s_nop 0
	v_pk_mul_f32 v[122:123], v[122:123], v[124:125]
	v_mul_f32_e32 v124, 0xbfb8aa3b, v128
	v_mul_f32_e32 v125, 0xbfb8aa3b, v129
	v_exp_f32_e32 v124, v124
	v_exp_f32_e32 v125, v125
	v_lshlrev_b32_e32 v128, 16, v132
	v_and_b32_e32 v129, 0xffff0000, v132
	v_pk_add_f32 v[124:125], v[124:125], 1.0 op_sel_hi:[1,0]
	s_nop 0
	s_nop 0
	v_rcp_f32_e32 v125, v125
	s_nop 0
	s_nop 0
	v_rcp_f32_e32 v124, v124
	s_nop 0
	v_div_scale_f32 v130, s[14:15], v121, v121, 1.0
	v_rcp_f32_e32 v131, v130
	v_pk_mul_f32 v[124:125], v[124:125], v[128:129]
	v_lshlrev_b32_e32 v128, 16, v133
	v_and_b32_e32 v129, 0xffff0000, v133
	v_fma_f32 v132, -v130, v131, 1.0
	v_fmac_f32_e32 v131, v132, v131
	v_div_scale_f32 v132, vcc, 1.0, v121, 1.0
	v_mul_f32_e32 v133, v132, v131
	v_fma_f32 v134, -v130, v133, v132
	v_fmac_f32_e32 v133, v134, v131
	v_fma_f32 v130, -v130, v133, v132
	v_div_fmas_f32 v130, v130, v131, v133
	v_div_fixup_f32 v121, v130, v121, 1.0
	s_nop 0
	v_rcp_f32_e32 v120, v120
	s_nop 0
	v_pk_mul_f32 v[128:129], v[120:121], v[128:129]
	v_cvt_pk_bf16_f32 v120, v118, v119
	v_cvt_pk_bf16_f32 v121, v122, v123
	v_cvt_pk_bf16_f32 v122, v124, v125
	v_cvt_pk_bf16_f32 v123, v128, v129
	v_lshl_add_u64 v[118:119], v[188:189], 0, v[126:127]
	global_store_dwordx4 v[118:119], v[120:123], off
	s_nop 1
	v_pk_add_f32 v[120:121], v[102:103], v[16:17]
	v_mul_f32_e32 v102, 0xbfb8aa3b, v106
	v_mul_f32_e32 v103, 0xbfb8aa3b, v107
	v_exp_f32_e32 v102, v102
	v_exp_f32_e32 v103, v103
	v_lshlrev_b32_e32 v106, 16, v114
	v_and_b32_e32 v107, 0xffff0000, v114
	v_pk_add_f32 v[102:103], v[102:103], 1.0 op_sel_hi:[1,0]
	s_nop 0
	s_nop 0
	v_rcp_f32_e32 v103, v103
	s_nop 0
	s_nop 0
	v_rcp_f32_e32 v102, v102
	s_nop 0
	v_pk_mul_f32 v[102:103], v[102:103], v[106:107]
	v_mul_f32_e32 v106, 0xbfb8aa3b, v108
	v_mul_f32_e32 v107, 0xbfb8aa3b, v109
	v_exp_f32_e32 v106, v106
	v_exp_f32_e32 v107, v107
	v_lshlrev_b32_e32 v108, 16, v115
	v_and_b32_e32 v109, 0xffff0000, v115
	v_cvt_pk_bf16_f32 v102, v102, v103
	v_pk_add_f32 v[106:107], v[106:107], 1.0 op_sel_hi:[1,0]
	s_nop 0
	s_nop 0
	v_rcp_f32_e32 v107, v107
	s_nop 0
	s_nop 0
	v_rcp_f32_e32 v106, v106
	s_nop 0
	v_pk_mul_f32 v[106:107], v[106:107], v[108:109]
	v_mul_f32_e32 v108, 0xbfb8aa3b, v120
	v_mul_f32_e32 v109, 0xbfb8aa3b, v121
	v_exp_f32_e32 v108, v108
	v_exp_f32_e32 v109, v109
	v_lshlrev_b32_e32 v114, 16, v116
	v_and_b32_e32 v115, 0xffff0000, v116
	v_cvt_pk_bf16_f32 v103, v106, v107
	v_pk_add_f32 v[108:109], v[108:109], 1.0 op_sel_hi:[1,0]
	s_nop 0
	s_nop 0
	v_rcp_f32_e32 v109, v109
	s_nop 0
	s_nop 0
	v_rcp_f32_e32 v108, v108
	s_nop 0
	v_div_scale_f32 v116, s[14:15], v105, v105, 1.0
	v_pk_mul_f32 v[108:109], v[108:109], v[114:115]
	v_lshlrev_b32_e32 v114, 16, v117
	v_and_b32_e32 v115, 0xffff0000, v117
	v_rcp_f32_e32 v117, v116
	s_nop 0
	v_fma_f32 v120, -v116, v117, 1.0
	v_fmac_f32_e32 v117, v120, v117
	v_div_scale_f32 v120, vcc, 1.0, v105, 1.0
	v_mul_f32_e32 v121, v120, v117
	v_fma_f32 v122, -v116, v121, v120
	v_fmac_f32_e32 v121, v122, v117
	v_fma_f32 v116, -v116, v121, v120
	v_div_fmas_f32 v116, v116, v117, v121
	v_div_fixup_f32 v105, v116, v105, 1.0
	s_nop 0
	v_rcp_f32_e32 v104, v104
	s_nop 0
	v_pk_mul_f32 v[114:115], v[104:105], v[114:115]
	v_cvt_pk_bf16_f32 v104, v108, v109
	v_cvt_pk_bf16_f32 v105, v114, v115
	global_store_dwordx4 v[118:119], v[102:105], off offset:256
	v_add_u32_e32 v120, 0x80, v190
	v_ashrrev_i32_e32 v121, 31, v120
	v_pk_add_f32 v[104:105], v[90:91], v[32:33]
	v_mul_f32_e32 v90, 0xbfb8aa3b, v94
	v_mul_f32_e32 v91, 0xbfb8aa3b, v95
	v_exp_f32_e32 v90, v90
	v_exp_f32_e32 v91, v91
	v_lshlrev_b32_e32 v94, 16, v110
	v_and_b32_e32 v95, 0xffff0000, v110
	v_lshlrev_b64 v[102:103], 11, v[192:193]
	v_pk_add_f32 v[90:91], v[90:91], 1.0 op_sel_hi:[1,0]
	v_pk_add_f32 v[122:123], v[74:75], v[32:33]
	v_mul_f32_e32 v74, 0xbfb8aa3b, v78
	v_mul_f32_e32 v75, 0xbfb8aa3b, v79
	v_exp_f32_e32 v74, v74
	v_rcp_f32_e32 v91, v91
	s_nop 0
	v_exp_f32_e32 v75, v75
	v_add_u32_e32 v118, 0x90, v190
	v_ashrrev_i32_e32 v119, 31, v118
	v_rcp_f32_e32 v90, v90
	s_nop 0
	v_pk_mul_f32 v[90:91], v[90:91], v[94:95]
	v_mul_f32_e32 v94, 0xbfb8aa3b, v96
	v_mul_f32_e32 v95, 0xbfb8aa3b, v97
	v_exp_f32_e32 v94, v94
	v_exp_f32_e32 v95, v95
	v_lshlrev_b32_e32 v96, 16, v111
	v_and_b32_e32 v97, 0xffff0000, v111
	v_pk_add_f32 v[74:75], v[74:75], 1.0 op_sel_hi:[1,0]
	v_pk_add_f32 v[94:95], v[94:95], 1.0 op_sel_hi:[1,0]
	v_add_u32_e32 v116, 0xa0, v190
	v_ashrrev_i32_e32 v117, 31, v116
	v_add_u32_e32 v114, 0xb0, v190
	v_ashrrev_i32_e32 v115, 31, v114
	v_rcp_f32_e32 v95, v95
	s_nop 0
	s_nop 0
	v_rcp_f32_e32 v94, v94
	s_nop 0
	v_pk_mul_f32 v[94:95], v[94:95], v[96:97]
	v_mul_f32_e32 v96, 0xbfb8aa3b, v104
	v_mul_f32_e32 v97, 0xbfb8aa3b, v105
	v_exp_f32_e32 v96, v96
	v_exp_f32_e32 v97, v97
	v_lshlrev_b32_e32 v104, 16, v112
	v_and_b32_e32 v105, 0xffff0000, v112
	v_pk_add_f32 v[96:97], v[96:97], 1.0 op_sel_hi:[1,0]
	s_nop 0
	s_nop 0
	v_rcp_f32_e32 v97, v97
	s_nop 0
	s_nop 0
	v_rcp_f32_e32 v96, v96
	s_nop 0
	v_pk_mul_f32 v[96:97], v[96:97], v[104:105]
	v_lshlrev_b32_e32 v104, 16, v113
	v_and_b32_e32 v105, 0xffff0000, v113
	v_rcp_f32_e32 v93, v93
	s_nop 0
	s_nop 0
	v_rcp_f32_e32 v92, v92
	s_nop 0
	v_pk_mul_f32 v[104:105], v[92:93], v[104:105]
	v_cvt_pk_bf16_f32 v92, v90, v91
	v_cvt_pk_bf16_f32 v93, v94, v95
	v_cvt_pk_bf16_f32 v94, v96, v97
	v_cvt_pk_bf16_f32 v95, v104, v105
	v_lshl_add_u64 v[90:91], v[188:189], 0, v[102:103]
	global_store_dwordx4 v[90:91], v[92:95], off
	s_nop 1
	v_pk_add_f32 v[92:93], v[82:83], v[16:17]
	v_mul_f32_e32 v82, 0xbfb8aa3b, v86
	v_mul_f32_e32 v83, 0xbfb8aa3b, v87
	v_exp_f32_e32 v82, v82
	v_exp_f32_e32 v83, v83
	v_lshlrev_b32_e32 v86, 16, v98
	v_and_b32_e32 v87, 0xffff0000, v98
	v_pk_add_f32 v[82:83], v[82:83], 1.0 op_sel_hi:[1,0]
	s_nop 0
	s_nop 0
	v_rcp_f32_e32 v83, v83
	s_nop 0
	s_nop 0
	v_rcp_f32_e32 v82, v82
	s_nop 0
	v_pk_mul_f32 v[82:83], v[82:83], v[86:87]
	v_mul_f32_e32 v86, 0xbfb8aa3b, v88
	v_mul_f32_e32 v87, 0xbfb8aa3b, v89
	v_exp_f32_e32 v86, v86
	v_exp_f32_e32 v87, v87
	v_lshlrev_b32_e32 v88, 16, v99
	v_and_b32_e32 v89, 0xffff0000, v99
	v_cvt_pk_bf16_f32 v82, v82, v83
	v_pk_add_f32 v[86:87], v[86:87], 1.0 op_sel_hi:[1,0]
	s_nop 0
	s_nop 0
	v_rcp_f32_e32 v87, v87
	s_nop 0
	s_nop 0
	v_rcp_f32_e32 v86, v86
	s_nop 0
	v_pk_mul_f32 v[86:87], v[86:87], v[88:89]
	v_mul_f32_e32 v88, 0xbfb8aa3b, v92
	v_mul_f32_e32 v89, 0xbfb8aa3b, v93
	v_exp_f32_e32 v88, v88
	v_exp_f32_e32 v89, v89
	v_lshlrev_b32_e32 v92, 16, v100
	v_and_b32_e32 v93, 0xffff0000, v100
	v_cvt_pk_bf16_f32 v83, v86, v87
	v_pk_add_f32 v[88:89], v[88:89], 1.0 op_sel_hi:[1,0]
	s_nop 0
	s_nop 0
	v_rcp_f32_e32 v89, v89
	s_nop 0
	s_nop 0
	v_rcp_f32_e32 v88, v88
	s_nop 0
	v_pk_mul_f32 v[88:89], v[88:89], v[92:93]
	v_lshlrev_b32_e32 v92, 16, v101
	v_and_b32_e32 v93, 0xffff0000, v101
	v_rcp_f32_e32 v85, v85
	s_nop 0
	s_nop 0
	v_rcp_f32_e32 v84, v84
	s_nop 0
	v_pk_mul_f32 v[92:93], v[84:85], v[92:93]
	v_cvt_pk_bf16_f32 v84, v88, v89
	v_cvt_pk_bf16_f32 v85, v92, v93
	global_store_dwordx4 v[90:91], v[82:85], off offset:256
	s_nop 1
	v_lshlrev_b64 v[82:83], 9, v[120:121]
	v_lshl_add_u64 v[82:83], v[186:187], 0, v[82:83]
	global_load_dwordx4 v[110:113], v[82:83], off
	global_load_dwordx4 v[106:109], v[82:83], off offset:256
	v_lshlrev_b64 v[82:83], 9, v[118:119]
	v_lshl_add_u64 v[82:83], v[186:187], 0, v[82:83]
	global_load_dwordx4 v[102:105], v[82:83], off
	global_load_dwordx4 v[98:101], v[82:83], off offset:256
	v_lshlrev_b64 v[82:83], 9, v[116:117]
	v_lshl_add_u64 v[82:83], v[186:187], 0, v[82:83]
	global_load_dwordx4 v[94:97], v[82:83], off
	global_load_dwordx4 v[90:93], v[82:83], off offset:256
	v_lshlrev_b64 v[82:83], 9, v[114:115]
	v_lshlrev_b64 v[120:121], 11, v[120:121]
	v_lshl_add_u64 v[82:83], v[186:187], 0, v[82:83]
	global_load_dwordx4 v[86:89], v[82:83], off
	s_nop 0
	global_load_dwordx4 v[82:85], v[82:83], off offset:256
	s_waitcnt vmcnt(0)
	v_lshlrev_b32_e32 v78, 16, v110
	v_and_b32_e32 v79, 0xffff0000, v110
	s_nop 0
	v_rcp_f32_e32 v75, v75
	s_nop 0
	s_nop 0
	v_rcp_f32_e32 v74, v74
	s_nop 0
	v_pk_mul_f32 v[74:75], v[74:75], v[78:79]
	v_mul_f32_e32 v78, 0xbfb8aa3b, v80
	v_mul_f32_e32 v79, 0xbfb8aa3b, v81
	v_exp_f32_e32 v78, v78
	v_exp_f32_e32 v79, v79
	v_lshlrev_b32_e32 v80, 16, v111
	v_and_b32_e32 v81, 0xffff0000, v111
	v_pk_add_f32 v[78:79], v[78:79], 1.0 op_sel_hi:[1,0]
	s_nop 0
	s_nop 0
	v_rcp_f32_e32 v79, v79
	s_nop 0
	s_nop 0
	v_rcp_f32_e32 v78, v78
	s_nop 0
	v_pk_mul_f32 v[78:79], v[78:79], v[80:81]
	v_mul_f32_e32 v80, 0xbfb8aa3b, v122
	v_mul_f32_e32 v81, 0xbfb8aa3b, v123
	v_exp_f32_e32 v80, v80
	v_exp_f32_e32 v81, v81
	v_lshlrev_b32_e32 v110, 16, v112
	v_and_b32_e32 v111, 0xffff0000, v112
	v_pk_add_f32 v[80:81], v[80:81], 1.0 op_sel_hi:[1,0]
	s_nop 0
	s_nop 0
	v_rcp_f32_e32 v81, v81
	s_nop 0
	s_nop 0
	v_rcp_f32_e32 v80, v80
	s_nop 0
	v_div_scale_f32 v112, s[14:15], v77, v77, 1.0
	v_pk_mul_f32 v[80:81], v[80:81], v[110:111]
	v_lshlrev_b32_e32 v110, 16, v113
	v_and_b32_e32 v111, 0xffff0000, v113
	v_rcp_f32_e32 v113, v112
	s_nop 0
	v_fma_f32 v122, -v112, v113, 1.0
	v_fmac_f32_e32 v113, v122, v113
	v_div_scale_f32 v122, vcc, 1.0, v77, 1.0
	v_mul_f32_e32 v123, v122, v113
	v_fma_f32 v124, -v112, v123, v122
	v_fmac_f32_e32 v123, v124, v113
	v_fma_f32 v112, -v112, v123, v122
	v_div_fmas_f32 v112, v112, v113, v123
	v_div_fixup_f32 v77, v112, v77, 1.0
	s_nop 0
	v_rcp_f32_e32 v76, v76
	s_nop 0
	v_pk_mul_f32 v[110:111], v[76:77], v[110:111]
	v_cvt_pk_bf16_f32 v76, v74, v75
	v_cvt_pk_bf16_f32 v77, v78, v79
	v_cvt_pk_bf16_f32 v78, v80, v81
	v_cvt_pk_bf16_f32 v79, v110, v111
	v_lshl_add_u64 v[74:75], v[188:189], 0, v[120:121]
	global_store_dwordx4 v[74:75], v[76:79], off
	s_nop 1
	v_pk_add_f32 v[76:77], v[66:67], v[16:17]
	v_mul_f32_e32 v66, 0xbfb8aa3b, v70
	v_mul_f32_e32 v67, 0xbfb8aa3b, v71
	v_exp_f32_e32 v66, v66
	v_exp_f32_e32 v67, v67
	v_lshlrev_b32_e32 v70, 16, v106
	v_and_b32_e32 v71, 0xffff0000, v106
	v_pk_add_f32 v[66:67], v[66:67], 1.0 op_sel_hi:[1,0]
	s_nop 0
	s_nop 0
	v_rcp_f32_e32 v67, v67
	s_nop 0
	s_nop 0
	v_rcp_f32_e32 v66, v66
	s_nop 0
	v_pk_mul_f32 v[66:67], v[66:67], v[70:71]
	v_mul_f32_e32 v70, 0xbfb8aa3b, v72
	v_mul_f32_e32 v71, 0xbfb8aa3b, v73
	v_exp_f32_e32 v70, v70
	v_exp_f32_e32 v71, v71
	v_lshlrev_b32_e32 v72, 16, v107
	v_and_b32_e32 v73, 0xffff0000, v107
	v_cvt_pk_bf16_f32 v66, v66, v67
	v_pk_add_f32 v[70:71], v[70:71], 1.0 op_sel_hi:[1,0]
	s_nop 0
	s_nop 0
	v_rcp_f32_e32 v71, v71
	s_nop 0
	s_nop 0
	v_rcp_f32_e32 v70, v70
	s_nop 0
	v_pk_mul_f32 v[70:71], v[70:71], v[72:73]
	v_mul_f32_e32 v72, 0xbfb8aa3b, v76
	v_mul_f32_e32 v73, 0xbfb8aa3b, v77
	v_exp_f32_e32 v72, v72
	v_exp_f32_e32 v73, v73
	v_lshlrev_b32_e32 v76, 16, v108
	v_and_b32_e32 v77, 0xffff0000, v108
	v_cvt_pk_bf16_f32 v67, v70, v71
	v_pk_add_f32 v[72:73], v[72:73], 1.0 op_sel_hi:[1,0]
	s_nop 0
	s_nop 0
	v_rcp_f32_e32 v73, v73
	s_nop 0
	s_nop 0
	v_rcp_f32_e32 v72, v72
	s_nop 0
	v_pk_mul_f32 v[72:73], v[72:73], v[76:77]
	v_lshlrev_b32_e32 v76, 16, v109
	v_and_b32_e32 v77, 0xffff0000, v109
	v_rcp_f32_e32 v69, v69
	s_nop 0
	s_nop 0
	v_rcp_f32_e32 v68, v68
	s_nop 0
	v_pk_mul_f32 v[76:77], v[68:69], v[76:77]
	v_cvt_pk_bf16_f32 v68, v72, v73
	v_cvt_pk_bf16_f32 v69, v76, v77
	global_store_dwordx4 v[74:75], v[66:69], off offset:256
	s_nop 1
	v_pk_add_f32 v[68:69], v[58:59], v[32:33]
	v_mul_f32_e32 v58, 0xbfb8aa3b, v62
	v_mul_f32_e32 v59, 0xbfb8aa3b, v63
	v_exp_f32_e32 v58, v58
	v_exp_f32_e32 v59, v59
	v_lshlrev_b32_e32 v62, 16, v102
	v_and_b32_e32 v63, 0xffff0000, v102
	v_lshlrev_b64 v[66:67], 11, v[118:119]
	v_pk_add_f32 v[58:59], v[58:59], 1.0 op_sel_hi:[1,0]
	s_nop 0
	s_nop 0
	v_rcp_f32_e32 v59, v59
	s_nop 0
	s_nop 0
	v_rcp_f32_e32 v58, v58
	s_nop 0
	v_pk_mul_f32 v[58:59], v[58:59], v[62:63]
	v_mul_f32_e32 v62, 0xbfb8aa3b, v64
	v_mul_f32_e32 v63, 0xbfb8aa3b, v65
	v_exp_f32_e32 v62, v62
	v_exp_f32_e32 v63, v63
	v_lshlrev_b32_e32 v64, 16, v103
	v_and_b32_e32 v65, 0xffff0000, v103
	v_pk_add_f32 v[62:63], v[62:63], 1.0 op_sel_hi:[1,0]
	s_nop 0
	s_nop 0
	v_rcp_f32_e32 v63, v63
	s_nop 0
	s_nop 0
	v_rcp_f32_e32 v62, v62
	s_nop 0
	v_pk_mul_f32 v[62:63], v[62:63], v[64:65]
	v_mul_f32_e32 v64, 0xbfb8aa3b, v68
	v_mul_f32_e32 v65, 0xbfb8aa3b, v69
	v_exp_f32_e32 v64, v64
	v_exp_f32_e32 v65, v65
	v_lshlrev_b32_e32 v68, 16, v104
	v_and_b32_e32 v69, 0xffff0000, v104
	v_pk_add_f32 v[64:65], v[64:65], 1.0 op_sel_hi:[1,0]
	s_nop 0
	s_nop 0
	v_rcp_f32_e32 v65, v65
	s_nop 0
	s_nop 0
	v_rcp_f32_e32 v64, v64
	s_nop 0
	v_pk_mul_f32 v[64:65], v[64:65], v[68:69]
	v_lshlrev_b32_e32 v68, 16, v105
	v_and_b32_e32 v69, 0xffff0000, v105
	v_rcp_f32_e32 v61, v61
	s_nop 0
	s_nop 0
	v_rcp_f32_e32 v60, v60
	s_nop 0
	v_pk_mul_f32 v[68:69], v[60:61], v[68:69]
	v_cvt_pk_bf16_f32 v60, v58, v59
	v_cvt_pk_bf16_f32 v61, v62, v63
	v_cvt_pk_bf16_f32 v62, v64, v65
	v_cvt_pk_bf16_f32 v63, v68, v69
	v_lshl_add_u64 v[58:59], v[188:189], 0, v[66:67]
	global_store_dwordx4 v[58:59], v[60:63], off
	s_nop 1
	v_pk_add_f32 v[60:61], v[50:51], v[16:17]
	v_mul_f32_e32 v50, 0xbfb8aa3b, v54
	v_mul_f32_e32 v51, 0xbfb8aa3b, v55
	v_exp_f32_e32 v50, v50
	v_exp_f32_e32 v51, v51
	v_lshlrev_b32_e32 v54, 16, v98
	v_and_b32_e32 v55, 0xffff0000, v98
	v_pk_add_f32 v[50:51], v[50:51], 1.0 op_sel_hi:[1,0]
	s_nop 0
	s_nop 0
	v_rcp_f32_e32 v51, v51
	s_nop 0
	s_nop 0
	v_rcp_f32_e32 v50, v50
	s_nop 0
	v_pk_mul_f32 v[50:51], v[50:51], v[54:55]
	v_mul_f32_e32 v54, 0xbfb8aa3b, v56
	v_mul_f32_e32 v55, 0xbfb8aa3b, v57
	v_exp_f32_e32 v54, v54
	v_exp_f32_e32 v55, v55
	v_lshlrev_b32_e32 v56, 16, v99
	v_and_b32_e32 v57, 0xffff0000, v99
	v_cvt_pk_bf16_f32 v50, v50, v51
	v_pk_add_f32 v[54:55], v[54:55], 1.0 op_sel_hi:[1,0]
	s_nop 0
	s_nop 0
	v_rcp_f32_e32 v55, v55
	s_nop 0
	s_nop 0
	v_rcp_f32_e32 v54, v54
	s_nop 0
	v_pk_mul_f32 v[54:55], v[54:55], v[56:57]
	v_mul_f32_e32 v56, 0xbfb8aa3b, v60
	v_mul_f32_e32 v57, 0xbfb8aa3b, v61
	v_exp_f32_e32 v56, v56
	v_exp_f32_e32 v57, v57
	v_lshlrev_b32_e32 v60, 16, v100
	v_and_b32_e32 v61, 0xffff0000, v100
	v_cvt_pk_bf16_f32 v51, v54, v55
	v_pk_add_f32 v[56:57], v[56:57], 1.0 op_sel_hi:[1,0]
	s_nop 0
	s_nop 0
	v_rcp_f32_e32 v57, v57
	s_nop 0
	s_nop 0
	v_rcp_f32_e32 v56, v56
	s_nop 0
	v_pk_mul_f32 v[56:57], v[56:57], v[60:61]
	v_lshlrev_b32_e32 v60, 16, v101
	v_and_b32_e32 v61, 0xffff0000, v101
	v_rcp_f32_e32 v53, v53
	s_nop 0
	s_nop 0
	v_rcp_f32_e32 v52, v52
	s_nop 0
	v_pk_mul_f32 v[60:61], v[52:53], v[60:61]
	v_cvt_pk_bf16_f32 v52, v56, v57
	v_cvt_pk_bf16_f32 v53, v60, v61
	global_store_dwordx4 v[58:59], v[50:53], off offset:256
	s_nop 1
	v_pk_add_f32 v[52:53], v[40:41], v[32:33]
	v_mul_f32_e32 v40, 0xbfb8aa3b, v44
	v_mul_f32_e32 v41, 0xbfb8aa3b, v45
	v_exp_f32_e32 v40, v40
	v_exp_f32_e32 v41, v41
	v_lshlrev_b32_e32 v44, 16, v94
	v_and_b32_e32 v45, 0xffff0000, v94
	v_lshlrev_b64 v[50:51], 11, v[116:117]
	v_pk_add_f32 v[40:41], v[40:41], 1.0 op_sel_hi:[1,0]
	s_nop 0
	s_nop 0
	v_rcp_f32_e32 v41, v41
	s_nop 0
	s_nop 0
	v_rcp_f32_e32 v40, v40
	s_nop 0
	v_pk_mul_f32 v[40:41], v[40:41], v[44:45]
	v_mul_f32_e32 v44, 0xbfb8aa3b, v46
	v_mul_f32_e32 v45, 0xbfb8aa3b, v47
	v_exp_f32_e32 v44, v44
	v_exp_f32_e32 v45, v45
	v_lshlrev_b32_e32 v46, 16, v95
	v_and_b32_e32 v47, 0xffff0000, v95
	v_pk_add_f32 v[44:45], v[44:45], 1.0 op_sel_hi:[1,0]
	s_nop 0
	s_nop 0
	v_rcp_f32_e32 v45, v45
	s_nop 0
	s_nop 0
	v_rcp_f32_e32 v44, v44
	s_nop 0
	v_pk_mul_f32 v[44:45], v[44:45], v[46:47]
	v_mul_f32_e32 v46, 0xbfb8aa3b, v52
	v_mul_f32_e32 v47, 0xbfb8aa3b, v53
	v_exp_f32_e32 v46, v46
	v_exp_f32_e32 v47, v47
	v_lshlrev_b32_e32 v52, 16, v96
	v_and_b32_e32 v53, 0xffff0000, v96
	v_pk_add_f32 v[46:47], v[46:47], 1.0 op_sel_hi:[1,0]
	s_nop 0
	s_nop 0
	v_rcp_f32_e32 v47, v47
	s_nop 0
	s_nop 0
	v_rcp_f32_e32 v46, v46
	s_nop 0
	v_pk_mul_f32 v[46:47], v[46:47], v[52:53]
	v_lshlrev_b32_e32 v52, 16, v97
	v_and_b32_e32 v53, 0xffff0000, v97
	v_rcp_f32_e32 v43, v43
	s_nop 0
	s_nop 0
	v_rcp_f32_e32 v42, v42
	s_nop 0
	v_pk_mul_f32 v[52:53], v[42:43], v[52:53]
	v_cvt_pk_bf16_f32 v42, v40, v41
	v_cvt_pk_bf16_f32 v43, v44, v45
	v_cvt_pk_bf16_f32 v44, v46, v47
	v_cvt_pk_bf16_f32 v45, v52, v53
	v_lshl_add_u64 v[40:41], v[188:189], 0, v[50:51]
	global_store_dwordx4 v[40:41], v[42:45], off
	s_nop 1
	v_pk_add_f32 v[42:43], v[24:25], v[16:17]
	v_mul_f32_e32 v24, 0xbfb8aa3b, v28
	v_mul_f32_e32 v25, 0xbfb8aa3b, v29
	v_exp_f32_e32 v24, v24
	v_exp_f32_e32 v25, v25
	v_lshlrev_b32_e32 v28, 16, v90
	v_and_b32_e32 v29, 0xffff0000, v90
	v_pk_add_f32 v[24:25], v[24:25], 1.0 op_sel_hi:[1,0]
	s_nop 0
	s_nop 0
	v_rcp_f32_e32 v25, v25
	s_nop 0
	s_nop 0
	v_rcp_f32_e32 v24, v24
	s_nop 0
	v_pk_mul_f32 v[24:25], v[24:25], v[28:29]
	v_mul_f32_e32 v28, 0xbfb8aa3b, v30
	v_mul_f32_e32 v29, 0xbfb8aa3b, v31
	v_exp_f32_e32 v28, v28
	v_exp_f32_e32 v29, v29
	v_lshlrev_b32_e32 v30, 16, v91
	v_and_b32_e32 v31, 0xffff0000, v91
	v_cvt_pk_bf16_f32 v24, v24, v25
	v_pk_add_f32 v[28:29], v[28:29], 1.0 op_sel_hi:[1,0]
	s_nop 0
	s_nop 0
	v_rcp_f32_e32 v29, v29
	s_nop 0
	s_nop 0
	v_rcp_f32_e32 v28, v28
	s_nop 0
	v_pk_mul_f32 v[28:29], v[28:29], v[30:31]
	v_mul_f32_e32 v30, 0xbfb8aa3b, v42
	v_mul_f32_e32 v31, 0xbfb8aa3b, v43
	v_exp_f32_e32 v30, v30
	v_exp_f32_e32 v31, v31
	v_lshlrev_b32_e32 v42, 16, v92
	v_and_b32_e32 v43, 0xffff0000, v92
	v_cvt_pk_bf16_f32 v25, v28, v29
	v_pk_add_f32 v[30:31], v[30:31], 1.0 op_sel_hi:[1,0]
	s_nop 0
	s_nop 0
	v_rcp_f32_e32 v31, v31
	s_nop 0
	s_nop 0
	v_rcp_f32_e32 v30, v30
	s_nop 0
	v_pk_mul_f32 v[30:31], v[30:31], v[42:43]
	v_lshlrev_b32_e32 v42, 16, v93
	v_and_b32_e32 v43, 0xffff0000, v93
	v_rcp_f32_e32 v27, v27
	s_nop 0
	s_nop 0
	v_rcp_f32_e32 v26, v26
	s_nop 0
	v_pk_mul_f32 v[42:43], v[26:27], v[42:43]
	v_cvt_pk_bf16_f32 v26, v30, v31
	v_cvt_pk_bf16_f32 v27, v42, v43
	global_store_dwordx4 v[40:41], v[24:27], off offset:256
	s_nop 1
	v_pk_add_f32 v[26:27], v[8:9], v[32:33]
	v_mul_f32_e32 v8, 0xbfb8aa3b, v12
	v_mul_f32_e32 v9, 0xbfb8aa3b, v13
	v_exp_f32_e32 v8, v8
	v_exp_f32_e32 v9, v9
	v_lshlrev_b32_e32 v12, 16, v86
	v_and_b32_e32 v13, 0xffff0000, v86
	v_lshlrev_b64 v[24:25], 11, v[114:115]
	v_pk_add_f32 v[8:9], v[8:9], 1.0 op_sel_hi:[1,0]
	s_nop 0
	s_nop 0
	v_rcp_f32_e32 v9, v9
	s_nop 0
	s_nop 0
	v_rcp_f32_e32 v8, v8
	s_nop 0
	v_pk_mul_f32 v[8:9], v[8:9], v[12:13]
	v_mul_f32_e32 v12, 0xbfb8aa3b, v14
	v_mul_f32_e32 v13, 0xbfb8aa3b, v15
	v_exp_f32_e32 v12, v12
	v_exp_f32_e32 v13, v13
	v_lshlrev_b32_e32 v14, 16, v87
	v_and_b32_e32 v15, 0xffff0000, v87
	v_pk_add_f32 v[12:13], v[12:13], 1.0 op_sel_hi:[1,0]
	s_nop 0
	s_nop 0
	v_rcp_f32_e32 v13, v13
	s_nop 0
	s_nop 0
	v_rcp_f32_e32 v12, v12
	s_nop 0
	v_pk_mul_f32 v[12:13], v[12:13], v[14:15]
	v_mul_f32_e32 v14, 0xbfb8aa3b, v26
	v_mul_f32_e32 v15, 0xbfb8aa3b, v27
	v_exp_f32_e32 v14, v14
	v_exp_f32_e32 v15, v15
	v_lshlrev_b32_e32 v26, 16, v88
	v_and_b32_e32 v27, 0xffff0000, v88
	v_pk_add_f32 v[14:15], v[14:15], 1.0 op_sel_hi:[1,0]
	s_nop 0
	s_nop 0
	v_rcp_f32_e32 v15, v15
	s_nop 0
	s_nop 0
	v_rcp_f32_e32 v14, v14
	s_nop 0
	v_pk_mul_f32 v[14:15], v[14:15], v[26:27]
	v_lshlrev_b32_e32 v26, 16, v89
	v_and_b32_e32 v27, 0xffff0000, v89
	v_rcp_f32_e32 v11, v11
	s_nop 0
	s_nop 0
	v_rcp_f32_e32 v10, v10
	s_nop 0
	v_pk_mul_f32 v[26:27], v[10:11], v[26:27]
	v_cvt_pk_bf16_f32 v10, v8, v9
	v_cvt_pk_bf16_f32 v11, v12, v13
	v_cvt_pk_bf16_f32 v12, v14, v15
	v_cvt_pk_bf16_f32 v13, v26, v27
	v_lshl_add_u64 v[8:9], v[188:189], 0, v[24:25]
	global_store_dwordx4 v[8:9], v[10:13], off
	s_nop 1
	v_pk_add_f32 v[10:11], v[0:1], v[16:17]
	v_mul_f32_e32 v0, 0xbfb8aa3b, v4
	v_mul_f32_e32 v1, 0xbfb8aa3b, v5
	v_exp_f32_e32 v0, v0
	v_exp_f32_e32 v1, v1
	v_lshlrev_b32_e32 v4, 16, v82
	v_and_b32_e32 v5, 0xffff0000, v82
	v_pk_add_f32 v[0:1], v[0:1], 1.0 op_sel_hi:[1,0]
	s_nop 0
	s_nop 0
	v_rcp_f32_e32 v1, v1
	s_nop 0
	s_nop 0
	v_rcp_f32_e32 v0, v0
	s_nop 0
	v_pk_mul_f32 v[0:1], v[0:1], v[4:5]
	v_mul_f32_e32 v4, 0xbfb8aa3b, v6
	v_mul_f32_e32 v5, 0xbfb8aa3b, v7
	v_exp_f32_e32 v4, v4
	v_exp_f32_e32 v5, v5
	v_lshlrev_b32_e32 v6, 16, v83
	v_and_b32_e32 v7, 0xffff0000, v83
	v_cvt_pk_bf16_f32 v0, v0, v1
	v_pk_add_f32 v[4:5], v[4:5], 1.0 op_sel_hi:[1,0]
	s_nop 0
	s_nop 0
	v_rcp_f32_e32 v5, v5
	s_nop 0
	s_nop 0
	v_rcp_f32_e32 v4, v4
	s_nop 0
	v_pk_mul_f32 v[4:5], v[4:5], v[6:7]
	v_mul_f32_e32 v6, 0xbfb8aa3b, v10
	v_mul_f32_e32 v7, 0xbfb8aa3b, v11
	v_exp_f32_e32 v6, v6
	v_exp_f32_e32 v7, v7
	v_lshlrev_b32_e32 v10, 16, v84
	v_and_b32_e32 v11, 0xffff0000, v84
	v_cvt_pk_bf16_f32 v1, v4, v5
	v_pk_add_f32 v[6:7], v[6:7], 1.0 op_sel_hi:[1,0]
	s_nop 0
	s_nop 0
	v_rcp_f32_e32 v7, v7
	s_nop 0
	s_nop 0
	v_rcp_f32_e32 v6, v6
	s_nop 0
	v_pk_mul_f32 v[6:7], v[6:7], v[10:11]
	v_lshlrev_b32_e32 v10, 16, v85
	v_and_b32_e32 v11, 0xffff0000, v85
	v_rcp_f32_e32 v3, v3
	s_nop 0
	s_mov_b64 s[14:15], s[10:11]
	v_rcp_f32_e32 v2, v2
	s_nop 0
	v_pk_mul_f32 v[10:11], v[2:3], v[10:11]
	v_cvt_pk_bf16_f32 v2, v6, v7
	v_cvt_pk_bf16_f32 v3, v10, v11
	s_and_b64 vcc, exec, s[8:9]
	global_store_dwordx4 v[8:9], v[0:3], off offset:256
	s_cbranch_vccz .LBB0_979
	s_waitcnt vmcnt(0)
	s_cmpk_gt_u32 s30, 0xff
	s_cbranch_scc1 .LBB0_986
	s_barrier

.LBB0_1076:
	s_waitcnt vmcnt(0)
	v_lshlrev_b32_e32 v212, 16, v190
	v_and_b32_e32 v213, 0xffff0000, v190
	v_mul_f32_e32 v190, 0xbfb8aa3b, v126
	v_exp_f32_e32 v218, v190
	v_mul_f32_e32 v190, 0xbfb8aa3b, v127
	v_exp_f32_e32 v219, v190
	s_lshl_b32 s56, s24, 5
	v_pk_add_f32 v[218:219], v[218:219], 1.0 op_sel_hi:[1,0]
	s_nop 0
	s_nop 0
	v_rcp_f32_e32 v219, v219
	s_nop 0
	s_nop 0
	v_rcp_f32_e32 v218, v218
	s_nop 0
	v_lshlrev_b32_e32 v220, 16, v186
	v_and_b32_e32 v221, 0xffff0000, v186
	v_mul_f32_e32 v186, 0xbfb8aa3b, v128
	v_pk_fma_f32 v[212:213], v[218:219], v[212:213], v[220:221]
	v_exp_f32_e32 v218, v186
	v_mul_f32_e32 v186, 0xbfb8aa3b, v129
	v_exp_f32_e32 v219, v186
	v_lshlrev_b32_e32 v190, 16, v191
	v_and_b32_e32 v191, 0xffff0000, v191
	v_pk_add_f32 v[218:219], v[218:219], 1.0 op_sel_hi:[1,0]
	s_nop 0
	s_nop 0
	v_rcp_f32_e32 v219, v219
	s_nop 0
	s_nop 0
	v_rcp_f32_e32 v218, v218
	s_nop 0
	v_lshlrev_b32_e32 v186, 16, v187
	v_and_b32_e32 v187, 0xffff0000, v187
	v_pk_fma_f32 v[190:191], v[218:219], v[190:191], v[186:187]
	v_lshlrev_b32_e32 v186, 16, v192
	v_and_b32_e32 v187, 0xffff0000, v192
	v_mul_f32_e32 v192, 0xbfb8aa3b, v122
	v_exp_f32_e32 v218, v192
	v_mul_f32_e32 v192, 0xbfb8aa3b, v123
	v_exp_f32_e32 v219, v192
	s_nop 0
	v_pk_add_f32 v[218:219], v[218:219], 1.0 op_sel_hi:[1,0]
	s_nop 0
	s_nop 0
	v_rcp_f32_e32 v219, v219
	s_nop 0
	s_nop 0
	v_lshlrev_b32_e32 v220, 16, v188
	v_and_b32_e32 v221, 0xffff0000, v188
	v_mul_f32_e32 v188, 0xbfb8aa3b, v124
	v_rcp_f32_e32 v218, v218
	s_nop 0
	v_exp_f32_e32 v192, v188
	v_mul_f32_e32 v188, 0xbfb8aa3b, v125
	v_pk_fma_f32 v[218:219], v[218:219], v[186:187], v[220:221]
	v_lshlrev_b32_e32 v186, 16, v193
	v_and_b32_e32 v187, 0xffff0000, v193
	v_exp_f32_e32 v193, v188
	s_nop 0
	v_pk_add_f32 v[192:193], v[192:193], 1.0 op_sel_hi:[1,0]
	s_nop 0
	s_nop 0
	v_rcp_f32_e32 v193, v193
	s_nop 0
	s_nop 0
	v_rcp_f32_e32 v192, v192
	s_nop 0
	v_lshlrev_b32_e32 v188, 16, v189
	v_and_b32_e32 v189, 0xffff0000, v189
	v_pk_fma_f32 v[192:193], v[192:193], v[186:187], v[188:189]
	v_cvt_pk_bf16_f32 v186, v212, v213
	v_cvt_pk_bf16_f32 v187, v190, v191
	v_cvt_pk_bf16_f32 v188, v218, v219
	v_cvt_pk_bf16_f32 v189, v192, v193
	global_store_dwordx4 v[210:211], v[186:189], off
	s_nop 1
	v_lshlrev_b32_e32 v186, 16, v182
	v_and_b32_e32 v187, 0xffff0000, v182
	v_mul_f32_e32 v182, 0xbfb8aa3b, v110
	v_exp_f32_e32 v188, v182
	v_mul_f32_e32 v182, 0xbfb8aa3b, v111
	v_exp_f32_e32 v189, v182
	s_nop 0
	v_pk_add_f32 v[188:189], v[188:189], 1.0 op_sel_hi:[1,0]
	s_nop 0
	s_nop 0
	v_rcp_f32_e32 v189, v189
	s_nop 0
	s_nop 0
	v_rcp_f32_e32 v188, v188
	s_nop 0
	v_lshlrev_b32_e32 v190, 16, v178
	v_and_b32_e32 v191, 0xffff0000, v178
	v_mul_f32_e32 v178, 0xbfb8aa3b, v112
	v_pk_fma_f32 v[186:187], v[188:189], v[186:187], v[190:191]
	v_exp_f32_e32 v188, v178
	v_mul_f32_e32 v178, 0xbfb8aa3b, v113
	v_exp_f32_e32 v189, v178
	v_lshlrev_b32_e32 v182, 16, v183
	v_and_b32_e32 v183, 0xffff0000, v183
	v_pk_add_f32 v[188:189], v[188:189], 1.0 op_sel_hi:[1,0]
	s_nop 0
	s_nop 0
	v_rcp_f32_e32 v189, v189
	s_nop 0
	s_nop 0
	v_rcp_f32_e32 v188, v188
	s_nop 0
	v_lshlrev_b32_e32 v178, 16, v179
	v_and_b32_e32 v179, 0xffff0000, v179
	v_pk_fma_f32 v[182:183], v[188:189], v[182:183], v[178:179]
	v_lshlrev_b32_e32 v178, 16, v184
	v_and_b32_e32 v179, 0xffff0000, v184
	v_mul_f32_e32 v184, 0xbfb8aa3b, v106
	v_exp_f32_e32 v188, v184
	v_mul_f32_e32 v184, 0xbfb8aa3b, v107
	v_exp_f32_e32 v189, v184
	s_nop 0
	v_pk_add_f32 v[188:189], v[188:189], 1.0 op_sel_hi:[1,0]
	s_nop 0
	s_nop 0
	v_rcp_f32_e32 v189, v189
	s_nop 0
	s_nop 0
	v_lshlrev_b32_e32 v190, 16, v180
	v_and_b32_e32 v191, 0xffff0000, v180
	v_mul_f32_e32 v180, 0xbfb8aa3b, v108
	v_rcp_f32_e32 v188, v188
	s_nop 0
	v_exp_f32_e32 v184, v180
	v_mul_f32_e32 v180, 0xbfb8aa3b, v109
	v_pk_fma_f32 v[188:189], v[188:189], v[178:179], v[190:191]
	v_lshlrev_b32_e32 v178, 16, v185
	v_and_b32_e32 v179, 0xffff0000, v185
	v_exp_f32_e32 v185, v180
	s_nop 0
	v_pk_add_f32 v[184:185], v[184:185], 1.0 op_sel_hi:[1,0]
	s_nop 0
	s_nop 0
	v_rcp_f32_e32 v185, v185
	s_nop 0
	s_nop 0
	v_rcp_f32_e32 v184, v184
	s_nop 0
	v_lshlrev_b32_e32 v180, 16, v181
	v_and_b32_e32 v181, 0xffff0000, v181
	v_pk_fma_f32 v[184:185], v[184:185], v[178:179], v[180:181]
	v_cvt_pk_bf16_f32 v178, v186, v187
	v_cvt_pk_bf16_f32 v179, v182, v183
	v_cvt_pk_bf16_f32 v180, v188, v189
	v_cvt_pk_bf16_f32 v181, v184, v185
	global_store_dwordx4 v[210:211], v[178:181], off offset:256
	v_mov_b32_e32 v188, 0
	v_mov_b32_e32 v189, 0
	v_lshlrev_b32_e32 v180, 16, v174
	v_and_b32_e32 v181, 0xffff0000, v174
	v_mul_f32_e32 v174, 0xbfb8aa3b, v118
	v_exp_f32_e32 v182, v174
	v_mul_f32_e32 v174, 0xbfb8aa3b, v119
	v_exp_f32_e32 v183, v174
	v_lshl_add_u64 v[178:179], v[210:211], 0, s[56:57]
	v_pk_add_f32 v[182:183], v[182:183], 1.0 op_sel_hi:[1,0]
	s_nop 0
	s_nop 0
	v_rcp_f32_e32 v183, v183
	s_nop 0
	s_nop 0
	v_rcp_f32_e32 v182, v182
	s_nop 0
	v_lshlrev_b32_e32 v184, 16, v170
	v_and_b32_e32 v185, 0xffff0000, v170
	v_mul_f32_e32 v170, 0xbfb8aa3b, v120
	v_pk_fma_f32 v[180:181], v[182:183], v[180:181], v[184:185]
	v_exp_f32_e32 v182, v170
	v_mul_f32_e32 v170, 0xbfb8aa3b, v121
	v_exp_f32_e32 v183, v170
	v_lshlrev_b32_e32 v174, 16, v175
	v_and_b32_e32 v175, 0xffff0000, v175
	v_pk_add_f32 v[182:183], v[182:183], 1.0 op_sel_hi:[1,0]
	s_nop 0
	s_nop 0
	v_rcp_f32_e32 v183, v183
	s_nop 0
	s_nop 0
	v_rcp_f32_e32 v182, v182
	s_nop 0
	v_lshlrev_b32_e32 v170, 16, v171
	v_and_b32_e32 v171, 0xffff0000, v171
	v_pk_fma_f32 v[174:175], v[182:183], v[174:175], v[170:171]
	v_lshlrev_b32_e32 v170, 16, v176
	v_and_b32_e32 v171, 0xffff0000, v176
	v_mul_f32_e32 v176, 0xbfb8aa3b, v114
	v_exp_f32_e32 v182, v176
	v_mul_f32_e32 v176, 0xbfb8aa3b, v115
	v_exp_f32_e32 v183, v176
	s_nop 0
	v_pk_add_f32 v[182:183], v[182:183], 1.0 op_sel_hi:[1,0]
	s_nop 0
	s_nop 0
	v_rcp_f32_e32 v183, v183
	s_nop 0
	s_nop 0
	v_lshlrev_b32_e32 v184, 16, v172
	v_and_b32_e32 v185, 0xffff0000, v172
	v_mul_f32_e32 v172, 0xbfb8aa3b, v116
	v_rcp_f32_e32 v182, v182
	s_nop 0
	v_exp_f32_e32 v176, v172
	v_mul_f32_e32 v172, 0xbfb8aa3b, v117
	v_pk_fma_f32 v[182:183], v[182:183], v[170:171], v[184:185]
	v_lshlrev_b32_e32 v170, 16, v177
	v_and_b32_e32 v171, 0xffff0000, v177
	v_exp_f32_e32 v177, v172
	s_nop 0
	v_pk_add_f32 v[176:177], v[176:177], 1.0 op_sel_hi:[1,0]
	s_nop 0
	s_nop 0
	v_rcp_f32_e32 v177, v177
	s_nop 0
	s_nop 0
	v_rcp_f32_e32 v176, v176
	s_nop 0
	v_lshlrev_b32_e32 v172, 16, v173
	v_and_b32_e32 v173, 0xffff0000, v173
	v_pk_fma_f32 v[176:177], v[176:177], v[170:171], v[172:173]
	v_cvt_pk_bf16_f32 v170, v180, v181
	v_cvt_pk_bf16_f32 v171, v174, v175
	v_cvt_pk_bf16_f32 v172, v182, v183
	v_cvt_pk_bf16_f32 v173, v176, v177
	global_store_dwordx4 v[178:179], v[170:173], off
	v_mov_b32_e32 v186, 0
	v_mov_b32_e32 v187, 0
	v_lshlrev_b32_e32 v170, 16, v166
	v_and_b32_e32 v171, 0xffff0000, v166
	v_mul_f32_e32 v166, 0xbfb8aa3b, v94
	v_exp_f32_e32 v172, v166
	v_mul_f32_e32 v166, 0xbfb8aa3b, v95
	v_exp_f32_e32 v173, v166
	s_nop 0
	v_pk_add_f32 v[172:173], v[172:173], 1.0 op_sel_hi:[1,0]
	s_nop 0
	s_nop 0
	v_rcp_f32_e32 v173, v173
	s_nop 0
	s_nop 0
	v_rcp_f32_e32 v172, v172
	s_nop 0
	v_lshlrev_b32_e32 v174, 16, v162
	v_and_b32_e32 v175, 0xffff0000, v162
	v_mul_f32_e32 v162, 0xbfb8aa3b, v96
	v_pk_fma_f32 v[170:171], v[172:173], v[170:171], v[174:175]
	v_exp_f32_e32 v172, v162
	v_mul_f32_e32 v162, 0xbfb8aa3b, v97
	v_exp_f32_e32 v173, v162
	v_lshlrev_b32_e32 v166, 16, v167
	v_and_b32_e32 v167, 0xffff0000, v167
	v_pk_add_f32 v[172:173], v[172:173], 1.0 op_sel_hi:[1,0]
	s_nop 0
	s_nop 0
	v_rcp_f32_e32 v173, v173
	s_nop 0
	s_nop 0
	v_rcp_f32_e32 v172, v172
	s_nop 0
	v_lshlrev_b32_e32 v162, 16, v163
	v_and_b32_e32 v163, 0xffff0000, v163
	v_pk_fma_f32 v[166:167], v[172:173], v[166:167], v[162:163]
	v_lshlrev_b32_e32 v162, 16, v168
	v_and_b32_e32 v163, 0xffff0000, v168
	v_mul_f32_e32 v168, 0xbfb8aa3b, v90
	v_exp_f32_e32 v172, v168
	v_mul_f32_e32 v168, 0xbfb8aa3b, v91
	v_exp_f32_e32 v173, v168
	s_nop 0
	v_pk_add_f32 v[172:173], v[172:173], 1.0 op_sel_hi:[1,0]
	s_nop 0
	s_nop 0
	v_rcp_f32_e32 v173, v173
	s_nop 0
	s_nop 0
	v_lshlrev_b32_e32 v174, 16, v164
	v_and_b32_e32 v175, 0xffff0000, v164
	v_mul_f32_e32 v164, 0xbfb8aa3b, v92
	v_rcp_f32_e32 v172, v172
	s_nop 0
	v_exp_f32_e32 v168, v164
	v_mul_f32_e32 v164, 0xbfb8aa3b, v93
	v_pk_fma_f32 v[172:173], v[172:173], v[162:163], v[174:175]
	v_lshlrev_b32_e32 v162, 16, v169
	v_and_b32_e32 v163, 0xffff0000, v169
	v_exp_f32_e32 v169, v164
	s_nop 0
	v_pk_add_f32 v[168:169], v[168:169], 1.0 op_sel_hi:[1,0]
	s_nop 0
	s_nop 0
	v_rcp_f32_e32 v169, v169
	s_nop 0
	s_nop 0
	v_rcp_f32_e32 v168, v168
	s_nop 0
	v_lshlrev_b32_e32 v164, 16, v165
	v_and_b32_e32 v165, 0xffff0000, v165
	v_pk_fma_f32 v[168:169], v[168:169], v[162:163], v[164:165]
	v_cvt_pk_bf16_f32 v162, v170, v171
	v_cvt_pk_bf16_f32 v163, v166, v167
	v_cvt_pk_bf16_f32 v164, v172, v173
	v_cvt_pk_bf16_f32 v165, v168, v169
	global_store_dwordx4 v[178:179], v[162:165], off offset:256
	s_nop 1
	v_lshlrev_b32_e32 v164, 16, v158
	v_and_b32_e32 v165, 0xffff0000, v158
	v_mul_f32_e32 v158, 0xbfb8aa3b, v102
	v_exp_f32_e32 v166, v158
	v_mul_f32_e32 v158, 0xbfb8aa3b, v103
	v_exp_f32_e32 v167, v158
	v_lshl_add_u64 v[162:163], v[178:179], 0, s[56:57]
	v_lshl_add_u64 v[210:211], v[162:163], 0, s[56:57]
	v_mov_b32_e32 v178, 0
	v_pk_add_f32 v[166:167], v[166:167], 1.0 op_sel_hi:[1,0]
	s_nop 0
	s_nop 0
	v_rcp_f32_e32 v167, v167
	s_nop 0
	s_nop 0
	v_rcp_f32_e32 v166, v166
	s_nop 0
	v_lshlrev_b32_e32 v168, 16, v154
	v_and_b32_e32 v169, 0xffff0000, v154
	v_mul_f32_e32 v154, 0xbfb8aa3b, v104
	v_pk_fma_f32 v[164:165], v[166:167], v[164:165], v[168:169]
	v_exp_f32_e32 v166, v154
	v_mul_f32_e32 v154, 0xbfb8aa3b, v105
	v_exp_f32_e32 v167, v154
	v_lshlrev_b32_e32 v158, 16, v159
	v_and_b32_e32 v159, 0xffff0000, v159
	v_pk_add_f32 v[166:167], v[166:167], 1.0 op_sel_hi:[1,0]
	s_nop 0
	s_nop 0
	v_rcp_f32_e32 v167, v167
	s_nop 0
	s_nop 0
	v_rcp_f32_e32 v166, v166
	s_nop 0
	v_lshlrev_b32_e32 v154, 16, v155
	v_and_b32_e32 v155, 0xffff0000, v155
	v_pk_fma_f32 v[158:159], v[166:167], v[158:159], v[154:155]
	v_lshlrev_b32_e32 v154, 16, v160
	v_and_b32_e32 v155, 0xffff0000, v160
	v_mul_f32_e32 v160, 0xbfb8aa3b, v98
	v_exp_f32_e32 v166, v160
	v_mul_f32_e32 v160, 0xbfb8aa3b, v99
	v_exp_f32_e32 v167, v160
	s_nop 0
	v_pk_add_f32 v[166:167], v[166:167], 1.0 op_sel_hi:[1,0]
	s_nop 0
	s_nop 0
	v_rcp_f32_e32 v167, v167
	s_nop 0
	s_nop 0
	v_lshlrev_b32_e32 v168, 16, v156
	v_and_b32_e32 v169, 0xffff0000, v156
	v_mul_f32_e32 v156, 0xbfb8aa3b, v100
	v_rcp_f32_e32 v166, v166
	s_nop 0
	v_exp_f32_e32 v160, v156
	v_mul_f32_e32 v156, 0xbfb8aa3b, v101
	v_pk_fma_f32 v[166:167], v[166:167], v[154:155], v[168:169]
	v_lshlrev_b32_e32 v154, 16, v161
	v_and_b32_e32 v155, 0xffff0000, v161
	v_exp_f32_e32 v161, v156
	s_nop 0
	v_pk_add_f32 v[160:161], v[160:161], 1.0 op_sel_hi:[1,0]
	s_nop 0
	s_nop 0
	v_rcp_f32_e32 v161, v161
	s_nop 0
	s_nop 0
	v_rcp_f32_e32 v160, v160
	s_nop 0
	v_lshlrev_b32_e32 v156, 16, v157
	v_and_b32_e32 v157, 0xffff0000, v157
	v_pk_fma_f32 v[160:161], v[160:161], v[154:155], v[156:157]
	v_cvt_pk_bf16_f32 v154, v164, v165
	v_cvt_pk_bf16_f32 v155, v158, v159
	v_cvt_pk_bf16_f32 v156, v166, v167
	v_cvt_pk_bf16_f32 v157, v160, v161
	global_store_dwordx4 v[162:163], v[154:157], off
	s_nop 1
	v_lshlrev_b32_e32 v154, 16, v150
	v_and_b32_e32 v155, 0xffff0000, v150
	v_mul_f32_e32 v150, 0xbfb8aa3b, v78
	v_exp_f32_e32 v156, v150
	v_mul_f32_e32 v150, 0xbfb8aa3b, v79
	v_exp_f32_e32 v157, v150
	s_nop 0
	v_pk_add_f32 v[156:157], v[156:157], 1.0 op_sel_hi:[1,0]
	s_nop 0
	s_nop 0
	v_rcp_f32_e32 v157, v157
	s_nop 0
	s_nop 0
	v_rcp_f32_e32 v156, v156
	s_nop 0
	v_lshlrev_b32_e32 v158, 16, v146
	v_and_b32_e32 v159, 0xffff0000, v146
	v_mul_f32_e32 v146, 0xbfb8aa3b, v80
	v_pk_fma_f32 v[154:155], v[156:157], v[154:155], v[158:159]
	v_exp_f32_e32 v156, v146
	v_mul_f32_e32 v146, 0xbfb8aa3b, v81
	v_exp_f32_e32 v157, v146
	v_lshlrev_b32_e32 v150, 16, v151
	v_and_b32_e32 v151, 0xffff0000, v151
	v_pk_add_f32 v[156:157], v[156:157], 1.0 op_sel_hi:[1,0]
	s_nop 0
	s_nop 0
	v_rcp_f32_e32 v157, v157
	s_nop 0
	s_nop 0
	v_rcp_f32_e32 v156, v156
	s_nop 0
	v_lshlrev_b32_e32 v146, 16, v147
	v_and_b32_e32 v147, 0xffff0000, v147
	v_pk_fma_f32 v[150:151], v[156:157], v[150:151], v[146:147]
	v_lshlrev_b32_e32 v146, 16, v152
	v_and_b32_e32 v147, 0xffff0000, v152
	v_mul_f32_e32 v152, 0xbfb8aa3b, v74
	v_exp_f32_e32 v156, v152
	v_mul_f32_e32 v152, 0xbfb8aa3b, v75
	v_exp_f32_e32 v157, v152
	s_nop 0
	v_pk_add_f32 v[156:157], v[156:157], 1.0 op_sel_hi:[1,0]
	s_nop 0
	s_nop 0
	v_rcp_f32_e32 v157, v157
	s_nop 0
	s_nop 0
	v_lshlrev_b32_e32 v158, 16, v148
	v_and_b32_e32 v159, 0xffff0000, v148
	v_mul_f32_e32 v148, 0xbfb8aa3b, v76
	v_rcp_f32_e32 v156, v156
	s_nop 0
	v_exp_f32_e32 v152, v148
	v_mul_f32_e32 v148, 0xbfb8aa3b, v77
	v_pk_fma_f32 v[156:157], v[156:157], v[146:147], v[158:159]
	v_lshlrev_b32_e32 v146, 16, v153
	v_and_b32_e32 v147, 0xffff0000, v153
	v_exp_f32_e32 v153, v148
	s_nop 0
	v_pk_add_f32 v[152:153], v[152:153], 1.0 op_sel_hi:[1,0]
	s_nop 0
	s_nop 0
	v_rcp_f32_e32 v153, v153
	s_nop 0
	s_nop 0
	v_rcp_f32_e32 v152, v152
	s_nop 0
	v_lshlrev_b32_e32 v148, 16, v149
	v_and_b32_e32 v149, 0xffff0000, v149
	v_pk_fma_f32 v[152:153], v[152:153], v[146:147], v[148:149]
	v_cvt_pk_bf16_f32 v146, v154, v155
	v_cvt_pk_bf16_f32 v147, v150, v151
	v_cvt_pk_bf16_f32 v148, v156, v157
	v_cvt_pk_bf16_f32 v149, v152, v153
	global_store_dwordx4 v[162:163], v[146:149], off offset:256
	s_nop 1
	v_lshlrev_b32_e32 v146, 16, v142
	v_and_b32_e32 v147, 0xffff0000, v142
	v_mul_f32_e32 v142, 0xbfb8aa3b, v86
	v_exp_f32_e32 v148, v142
	v_mul_f32_e32 v142, 0xbfb8aa3b, v87
	v_exp_f32_e32 v149, v142
	s_nop 0
	v_pk_add_f32 v[148:149], v[148:149], 1.0 op_sel_hi:[1,0]
	s_nop 0
	s_nop 0
	v_rcp_f32_e32 v149, v149
	s_nop 0
	s_nop 0
	v_rcp_f32_e32 v148, v148
	s_nop 0
	v_lshlrev_b32_e32 v150, 16, v138
	v_and_b32_e32 v151, 0xffff0000, v138
	v_mul_f32_e32 v138, 0xbfb8aa3b, v88
	v_pk_fma_f32 v[146:147], v[148:149], v[146:147], v[150:151]
	v_exp_f32_e32 v148, v138
	v_mul_f32_e32 v138, 0xbfb8aa3b, v89
	v_exp_f32_e32 v149, v138
	v_lshlrev_b32_e32 v142, 16, v143
	v_and_b32_e32 v143, 0xffff0000, v143
	v_pk_add_f32 v[148:149], v[148:149], 1.0 op_sel_hi:[1,0]
	s_nop 0
	s_nop 0
	v_rcp_f32_e32 v149, v149
	s_nop 0
	s_nop 0
	v_rcp_f32_e32 v148, v148
	s_nop 0
	v_lshlrev_b32_e32 v138, 16, v139
	v_and_b32_e32 v139, 0xffff0000, v139
	v_pk_fma_f32 v[142:143], v[148:149], v[142:143], v[138:139]
	v_lshlrev_b32_e32 v138, 16, v144
	v_and_b32_e32 v139, 0xffff0000, v144
	v_mul_f32_e32 v144, 0xbfb8aa3b, v82
	v_exp_f32_e32 v148, v144
	v_mul_f32_e32 v144, 0xbfb8aa3b, v83
	v_exp_f32_e32 v149, v144
	s_nop 0
	v_pk_add_f32 v[148:149], v[148:149], 1.0 op_sel_hi:[1,0]
	s_nop 0
	s_nop 0
	v_rcp_f32_e32 v149, v149
	s_nop 0
	s_nop 0
	v_lshlrev_b32_e32 v150, 16, v140
	v_and_b32_e32 v151, 0xffff0000, v140
	v_mul_f32_e32 v140, 0xbfb8aa3b, v84
	v_rcp_f32_e32 v148, v148
	s_nop 0
	v_exp_f32_e32 v144, v140
	v_mul_f32_e32 v140, 0xbfb8aa3b, v85
	v_pk_fma_f32 v[148:149], v[148:149], v[138:139], v[150:151]
	v_lshlrev_b32_e32 v138, 16, v145
	v_and_b32_e32 v139, 0xffff0000, v145
	v_exp_f32_e32 v145, v140
	s_nop 0
	v_pk_add_f32 v[144:145], v[144:145], 1.0 op_sel_hi:[1,0]
	s_nop 0
	s_nop 0
	v_rcp_f32_e32 v145, v145
	s_nop 0
	s_nop 0
	v_rcp_f32_e32 v144, v144
	s_nop 0
	v_lshlrev_b32_e32 v140, 16, v141
	v_and_b32_e32 v141, 0xffff0000, v141
	v_pk_fma_f32 v[144:145], v[144:145], v[138:139], v[140:141]
	v_cvt_pk_bf16_f32 v138, v146, v147
	v_cvt_pk_bf16_f32 v139, v142, v143
	v_cvt_pk_bf16_f32 v140, v148, v149
	v_cvt_pk_bf16_f32 v141, v144, v145
	global_store_dwordx4 v[210:211], v[138:141], off
	s_nop 1
	v_lshlrev_b32_e32 v138, 16, v134
	v_and_b32_e32 v139, 0xffff0000, v134
	v_mul_f32_e32 v134, 0xbfb8aa3b, v70
	v_exp_f32_e32 v140, v134
	v_mul_f32_e32 v134, 0xbfb8aa3b, v71
	v_exp_f32_e32 v141, v134
	s_nop 0
	v_pk_add_f32 v[140:141], v[140:141], 1.0 op_sel_hi:[1,0]
	s_nop 0
	s_nop 0
	v_rcp_f32_e32 v141, v141
	s_nop 0
	s_nop 0
	v_rcp_f32_e32 v140, v140
	s_nop 0
	v_lshlrev_b32_e32 v142, 16, v130
	v_and_b32_e32 v143, 0xffff0000, v130
	v_mul_f32_e32 v130, 0xbfb8aa3b, v72
	v_pk_fma_f32 v[138:139], v[140:141], v[138:139], v[142:143]
	v_exp_f32_e32 v140, v130
	v_mul_f32_e32 v130, 0xbfb8aa3b, v73
	v_exp_f32_e32 v141, v130
	v_lshlrev_b32_e32 v134, 16, v135
	v_and_b32_e32 v135, 0xffff0000, v135
	v_pk_add_f32 v[140:141], v[140:141], 1.0 op_sel_hi:[1,0]
	s_nop 0
	s_nop 0
	v_rcp_f32_e32 v141, v141
	s_nop 0
	s_nop 0
	v_rcp_f32_e32 v140, v140
	s_nop 0
	v_lshlrev_b32_e32 v130, 16, v131
	v_and_b32_e32 v131, 0xffff0000, v131
	v_pk_fma_f32 v[134:135], v[140:141], v[134:135], v[130:131]
	v_lshlrev_b32_e32 v130, 16, v136
	v_and_b32_e32 v131, 0xffff0000, v136
	v_mul_f32_e32 v136, 0xbfb8aa3b, v66
	v_exp_f32_e32 v140, v136
	v_mul_f32_e32 v136, 0xbfb8aa3b, v67
	v_exp_f32_e32 v141, v136
	s_nop 0
	v_pk_add_f32 v[140:141], v[140:141], 1.0 op_sel_hi:[1,0]
	s_nop 0
	s_nop 0
	v_rcp_f32_e32 v141, v141
	s_nop 0
	s_nop 0
	v_lshlrev_b32_e32 v142, 16, v132
	v_and_b32_e32 v143, 0xffff0000, v132
	v_mul_f32_e32 v132, 0xbfb8aa3b, v68
	v_rcp_f32_e32 v140, v140
	s_nop 0
	v_exp_f32_e32 v136, v132
	v_mul_f32_e32 v132, 0xbfb8aa3b, v69
	v_pk_fma_f32 v[140:141], v[140:141], v[130:131], v[142:143]
	v_lshlrev_b32_e32 v130, 16, v137
	v_and_b32_e32 v131, 0xffff0000, v137
	v_exp_f32_e32 v137, v132
	s_nop 0
	v_pk_add_f32 v[136:137], v[136:137], 1.0 op_sel_hi:[1,0]
	s_nop 0
	s_nop 0
	v_rcp_f32_e32 v137, v137
	s_nop 0
	s_nop 0
	v_rcp_f32_e32 v136, v136
	s_nop 0
	v_lshlrev_b32_e32 v132, 16, v133
	v_and_b32_e32 v133, 0xffff0000, v133
	v_pk_fma_f32 v[136:137], v[136:137], v[130:131], v[132:133]
	v_cvt_pk_bf16_f32 v130, v138, v139
	v_cvt_pk_bf16_f32 v131, v134, v135
	v_cvt_pk_bf16_f32 v132, v140, v141
	v_cvt_pk_bf16_f32 v133, v136, v137
	global_store_dwordx4 v[210:211], v[130:133], off offset:256
	s_nop 1
	v_add_co_u32_e32 v130, vcc, 0x10000, v208
	s_nop 1
	v_addc_co_u32_e32 v131, vcc, 0, v209, vcc
	global_load_dwordx4 v[190:193], v[130:131], off
	s_and_b64 vcc, exec, s[0:1]
	s_cbranch_vccnz .LBB0_1078
	v_add_co_u32_e32 v130, vcc, 0x30000, v208
	s_nop 1
	v_addc_co_u32_e32 v131, vcc, 0, v209, vcc
	global_load_dwordx4 v[186:189], v[130:131], off

.LBB0_1092:
	s_waitcnt vmcnt(0)
	v_lshlrev_b32_e32 v212, 16, v190
	v_and_b32_e32 v213, 0xffff0000, v190
	v_mul_f32_e32 v190, 0xbfb8aa3b, v62
	v_exp_f32_e32 v218, v190
	v_mul_f32_e32 v190, 0xbfb8aa3b, v63
	v_exp_f32_e32 v219, v190
	s_mul_i32 s0, s24, 0xa0
	s_mov_b32 s1, s57
	v_lshl_add_u64 v[210:211], v[210:211], 0, s[0:1]
	v_pk_add_f32 v[218:219], v[218:219], 1.0 op_sel_hi:[1,0]
	s_mov_b64 s[24:25], 0
	s_nop 0
	v_rcp_f32_e32 v219, v219
	s_nop 0
	s_nop 0
	v_rcp_f32_e32 v218, v218
	s_nop 0
	v_lshlrev_b32_e32 v220, 16, v186
	v_and_b32_e32 v221, 0xffff0000, v186
	v_mul_f32_e32 v186, 0xbfb8aa3b, v64
	v_pk_fma_f32 v[212:213], v[218:219], v[212:213], v[220:221]
	v_exp_f32_e32 v218, v186
	v_mul_f32_e32 v186, 0xbfb8aa3b, v65
	v_exp_f32_e32 v219, v186
	v_lshlrev_b32_e32 v190, 16, v191
	v_and_b32_e32 v191, 0xffff0000, v191
	v_pk_add_f32 v[218:219], v[218:219], 1.0 op_sel_hi:[1,0]
	s_nop 0
	s_nop 0
	v_rcp_f32_e32 v219, v219
	s_nop 0
	s_nop 0
	v_rcp_f32_e32 v218, v218
	s_nop 0
	v_lshlrev_b32_e32 v186, 16, v187
	v_and_b32_e32 v187, 0xffff0000, v187
	v_pk_fma_f32 v[190:191], v[218:219], v[190:191], v[186:187]
	v_lshlrev_b32_e32 v186, 16, v192
	v_and_b32_e32 v187, 0xffff0000, v192
	v_mul_f32_e32 v192, 0xbfb8aa3b, v58
	v_exp_f32_e32 v218, v192
	v_mul_f32_e32 v192, 0xbfb8aa3b, v59
	v_exp_f32_e32 v219, v192
	s_nop 0
	v_pk_add_f32 v[218:219], v[218:219], 1.0 op_sel_hi:[1,0]
	s_nop 0
	s_nop 0
	v_rcp_f32_e32 v219, v219
	s_nop 0
	s_nop 0
	v_lshlrev_b32_e32 v220, 16, v188
	v_and_b32_e32 v221, 0xffff0000, v188
	v_mul_f32_e32 v188, 0xbfb8aa3b, v60
	v_rcp_f32_e32 v218, v218
	s_nop 0
	v_exp_f32_e32 v192, v188
	v_mul_f32_e32 v188, 0xbfb8aa3b, v61
	v_pk_fma_f32 v[218:219], v[218:219], v[186:187], v[220:221]
	v_lshlrev_b32_e32 v186, 16, v193
	v_and_b32_e32 v187, 0xffff0000, v193
	v_exp_f32_e32 v193, v188
	s_nop 0
	v_pk_add_f32 v[192:193], v[192:193], 1.0 op_sel_hi:[1,0]
	s_nop 0
	s_nop 0
	v_rcp_f32_e32 v193, v193
	s_nop 0
	s_nop 0
	v_rcp_f32_e32 v192, v192
	s_nop 0
	v_lshlrev_b32_e32 v188, 16, v189
	v_and_b32_e32 v189, 0xffff0000, v189
	v_pk_fma_f32 v[192:193], v[192:193], v[186:187], v[188:189]
	v_cvt_pk_bf16_f32 v186, v212, v213
	v_cvt_pk_bf16_f32 v187, v190, v191
	v_cvt_pk_bf16_f32 v188, v218, v219
	v_cvt_pk_bf16_f32 v189, v192, v193
	global_store_dwordx4 v[210:211], v[186:189], off
	s_nop 1
	v_lshlrev_b32_e32 v186, 16, v182
	v_and_b32_e32 v187, 0xffff0000, v182
	v_mul_f32_e32 v182, 0xbfb8aa3b, v44
	v_exp_f32_e32 v188, v182
	v_mul_f32_e32 v182, 0xbfb8aa3b, v45
	v_exp_f32_e32 v189, v182
	s_nop 0
	v_pk_add_f32 v[188:189], v[188:189], 1.0 op_sel_hi:[1,0]
	s_nop 0
	s_nop 0
	v_rcp_f32_e32 v189, v189
	s_nop 0
	s_nop 0
	v_rcp_f32_e32 v188, v188
	s_nop 0
	v_lshlrev_b32_e32 v190, 16, v178
	v_and_b32_e32 v191, 0xffff0000, v178
	v_mul_f32_e32 v178, 0xbfb8aa3b, v46
	v_pk_fma_f32 v[186:187], v[188:189], v[186:187], v[190:191]
	v_exp_f32_e32 v188, v178
	v_mul_f32_e32 v178, 0xbfb8aa3b, v47
	v_exp_f32_e32 v189, v178
	v_lshlrev_b32_e32 v182, 16, v183
	v_and_b32_e32 v183, 0xffff0000, v183
	v_pk_add_f32 v[188:189], v[188:189], 1.0 op_sel_hi:[1,0]
	s_nop 0
	s_nop 0
	v_rcp_f32_e32 v189, v189
	s_nop 0
	s_nop 0
	v_rcp_f32_e32 v188, v188
	s_nop 0
	v_lshlrev_b32_e32 v178, 16, v179
	v_and_b32_e32 v179, 0xffff0000, v179
	v_pk_fma_f32 v[182:183], v[188:189], v[182:183], v[178:179]
	v_lshlrev_b32_e32 v178, 16, v184
	v_and_b32_e32 v179, 0xffff0000, v184
	v_mul_f32_e32 v184, 0xbfb8aa3b, v40
	v_exp_f32_e32 v188, v184
	v_mul_f32_e32 v184, 0xbfb8aa3b, v41
	v_exp_f32_e32 v189, v184
	s_nop 0
	v_pk_add_f32 v[188:189], v[188:189], 1.0 op_sel_hi:[1,0]
	s_nop 0
	s_nop 0
	v_rcp_f32_e32 v189, v189
	s_nop 0
	s_nop 0
	v_lshlrev_b32_e32 v190, 16, v180
	v_and_b32_e32 v191, 0xffff0000, v180
	v_mul_f32_e32 v180, 0xbfb8aa3b, v42
	v_rcp_f32_e32 v188, v188
	s_nop 0
	v_exp_f32_e32 v184, v180
	v_mul_f32_e32 v180, 0xbfb8aa3b, v43
	v_pk_fma_f32 v[188:189], v[188:189], v[178:179], v[190:191]
	v_lshlrev_b32_e32 v178, 16, v185
	v_and_b32_e32 v179, 0xffff0000, v185
	v_exp_f32_e32 v185, v180
	s_nop 0
	v_pk_add_f32 v[184:185], v[184:185], 1.0 op_sel_hi:[1,0]
	s_nop 0
	s_nop 0
	v_rcp_f32_e32 v185, v185
	s_nop 0
	s_nop 0
	v_rcp_f32_e32 v184, v184
	s_nop 0
	v_lshlrev_b32_e32 v180, 16, v181
	v_and_b32_e32 v181, 0xffff0000, v181
	v_pk_fma_f32 v[184:185], v[184:185], v[178:179], v[180:181]
	v_cvt_pk_bf16_f32 v178, v186, v187
	v_cvt_pk_bf16_f32 v179, v182, v183
	v_cvt_pk_bf16_f32 v180, v188, v189
	v_cvt_pk_bf16_f32 v181, v184, v185
	global_store_dwordx4 v[210:211], v[178:181], off offset:256
	s_nop 1
	v_lshlrev_b32_e32 v180, 16, v174
	v_and_b32_e32 v181, 0xffff0000, v174
	v_mul_f32_e32 v174, 0xbfb8aa3b, v54
	v_exp_f32_e32 v182, v174
	v_mul_f32_e32 v174, 0xbfb8aa3b, v55
	v_exp_f32_e32 v183, v174
	v_lshl_add_u64 v[178:179], v[210:211], 0, s[56:57]
	v_pk_add_f32 v[182:183], v[182:183], 1.0 op_sel_hi:[1,0]
	s_nop 0
	s_nop 0
	v_rcp_f32_e32 v183, v183
	s_nop 0
	s_nop 0
	v_rcp_f32_e32 v182, v182
	s_nop 0
	v_lshlrev_b32_e32 v184, 16, v170
	v_and_b32_e32 v185, 0xffff0000, v170
	v_mul_f32_e32 v170, 0xbfb8aa3b, v56
	v_pk_fma_f32 v[180:181], v[182:183], v[180:181], v[184:185]
	v_exp_f32_e32 v182, v170
	v_mul_f32_e32 v170, 0xbfb8aa3b, v57
	v_exp_f32_e32 v183, v170
	v_lshlrev_b32_e32 v174, 16, v175
	v_and_b32_e32 v175, 0xffff0000, v175
	v_pk_add_f32 v[182:183], v[182:183], 1.0 op_sel_hi:[1,0]
	s_nop 0
	s_nop 0
	v_rcp_f32_e32 v183, v183
	s_nop 0
	s_nop 0
	v_rcp_f32_e32 v182, v182
	s_nop 0
	v_lshlrev_b32_e32 v170, 16, v171
	v_and_b32_e32 v171, 0xffff0000, v171
	v_pk_fma_f32 v[174:175], v[182:183], v[174:175], v[170:171]
	v_lshlrev_b32_e32 v170, 16, v176
	v_and_b32_e32 v171, 0xffff0000, v176
	v_mul_f32_e32 v176, 0xbfb8aa3b, v50
	v_exp_f32_e32 v182, v176
	v_mul_f32_e32 v176, 0xbfb8aa3b, v51
	v_exp_f32_e32 v183, v176
	s_nop 0
	v_pk_add_f32 v[182:183], v[182:183], 1.0 op_sel_hi:[1,0]
	s_nop 0
	s_nop 0
	v_rcp_f32_e32 v183, v183
	s_nop 0
	s_nop 0
	v_lshlrev_b32_e32 v184, 16, v172
	v_and_b32_e32 v185, 0xffff0000, v172
	v_mul_f32_e32 v172, 0xbfb8aa3b, v52
	v_rcp_f32_e32 v182, v182
	s_nop 0
	v_exp_f32_e32 v176, v172
	v_mul_f32_e32 v172, 0xbfb8aa3b, v53
	v_pk_fma_f32 v[182:183], v[182:183], v[170:171], v[184:185]
	v_lshlrev_b32_e32 v170, 16, v177
	v_and_b32_e32 v171, 0xffff0000, v177
	v_exp_f32_e32 v177, v172
	s_nop 0
	v_pk_add_f32 v[176:177], v[176:177], 1.0 op_sel_hi:[1,0]
	s_nop 0
	s_nop 0
	v_rcp_f32_e32 v177, v177
	s_nop 0
	s_nop 0
	v_rcp_f32_e32 v176, v176
	s_nop 0
	v_lshlrev_b32_e32 v172, 16, v173
	v_and_b32_e32 v173, 0xffff0000, v173
	v_pk_fma_f32 v[176:177], v[176:177], v[170:171], v[172:173]
	v_cvt_pk_bf16_f32 v170, v180, v181
	v_cvt_pk_bf16_f32 v171, v174, v175
	v_cvt_pk_bf16_f32 v172, v182, v183
	v_cvt_pk_bf16_f32 v173, v176, v177
	global_store_dwordx4 v[178:179], v[170:173], off
	s_nop 1
	v_lshlrev_b32_e32 v170, 16, v166
	v_and_b32_e32 v171, 0xffff0000, v166
	v_mul_f32_e32 v166, 0xbfb8aa3b, v28
	v_exp_f32_e32 v172, v166
	v_mul_f32_e32 v166, 0xbfb8aa3b, v29
	v_exp_f32_e32 v173, v166
	s_nop 0
	v_pk_add_f32 v[172:173], v[172:173], 1.0 op_sel_hi:[1,0]
	s_nop 0
	s_nop 0
	v_rcp_f32_e32 v173, v173
	s_nop 0
	s_nop 0
	v_rcp_f32_e32 v172, v172
	s_nop 0
	v_lshlrev_b32_e32 v174, 16, v162
	v_and_b32_e32 v175, 0xffff0000, v162
	v_mul_f32_e32 v162, 0xbfb8aa3b, v30
	v_pk_fma_f32 v[170:171], v[172:173], v[170:171], v[174:175]
	v_exp_f32_e32 v172, v162
	v_mul_f32_e32 v162, 0xbfb8aa3b, v31
	v_exp_f32_e32 v173, v162
	v_lshlrev_b32_e32 v166, 16, v167
	v_and_b32_e32 v167, 0xffff0000, v167
	v_pk_add_f32 v[172:173], v[172:173], 1.0 op_sel_hi:[1,0]
	s_nop 0
	s_nop 0
	v_rcp_f32_e32 v173, v173
	s_nop 0
	s_nop 0
	v_rcp_f32_e32 v172, v172
	s_nop 0
	v_lshlrev_b32_e32 v162, 16, v163
	v_and_b32_e32 v163, 0xffff0000, v163
	v_pk_fma_f32 v[166:167], v[172:173], v[166:167], v[162:163]
	v_lshlrev_b32_e32 v162, 16, v168
	v_and_b32_e32 v163, 0xffff0000, v168
	v_mul_f32_e32 v168, 0xbfb8aa3b, v24
	v_exp_f32_e32 v172, v168
	v_mul_f32_e32 v168, 0xbfb8aa3b, v25
	v_exp_f32_e32 v173, v168
	s_nop 0
	v_pk_add_f32 v[172:173], v[172:173], 1.0 op_sel_hi:[1,0]
	s_nop 0
	s_nop 0
	v_rcp_f32_e32 v173, v173
	s_nop 0
	s_nop 0
	v_lshlrev_b32_e32 v174, 16, v164
	v_and_b32_e32 v175, 0xffff0000, v164
	v_mul_f32_e32 v164, 0xbfb8aa3b, v26
	v_rcp_f32_e32 v172, v172
	s_nop 0
	v_exp_f32_e32 v168, v164
	v_mul_f32_e32 v164, 0xbfb8aa3b, v27
	v_pk_fma_f32 v[172:173], v[172:173], v[162:163], v[174:175]
	v_lshlrev_b32_e32 v162, 16, v169
	v_and_b32_e32 v163, 0xffff0000, v169
	v_exp_f32_e32 v169, v164
	s_nop 0
	v_pk_add_f32 v[168:169], v[168:169], 1.0 op_sel_hi:[1,0]
	s_nop 0
	s_nop 0
	v_rcp_f32_e32 v169, v169
	s_nop 0
	s_nop 0
	v_rcp_f32_e32 v168, v168
	s_nop 0
	v_lshlrev_b32_e32 v164, 16, v165
	v_and_b32_e32 v165, 0xffff0000, v165
	v_pk_fma_f32 v[168:169], v[168:169], v[162:163], v[164:165]
	v_cvt_pk_bf16_f32 v162, v170, v171
	v_cvt_pk_bf16_f32 v163, v166, v167
	v_cvt_pk_bf16_f32 v164, v172, v173
	v_cvt_pk_bf16_f32 v165, v168, v169
	global_store_dwordx4 v[178:179], v[162:165], off offset:256
	s_nop 1
	v_lshlrev_b32_e32 v164, 16, v158
	v_and_b32_e32 v165, 0xffff0000, v158
	v_mul_f32_e32 v158, 0xbfb8aa3b, v36
	v_exp_f32_e32 v166, v158
	v_mul_f32_e32 v158, 0xbfb8aa3b, v37
	v_exp_f32_e32 v167, v158
	v_lshl_add_u64 v[162:163], v[178:179], 0, s[56:57]
	v_pk_add_f32 v[166:167], v[166:167], 1.0 op_sel_hi:[1,0]
	s_nop 0
	s_nop 0
	v_rcp_f32_e32 v167, v167
	s_nop 0
	s_nop 0
	v_rcp_f32_e32 v166, v166
	s_nop 0
	v_lshlrev_b32_e32 v168, 16, v154
	v_and_b32_e32 v169, 0xffff0000, v154
	v_mul_f32_e32 v154, 0xbfb8aa3b, v38
	v_pk_fma_f32 v[164:165], v[166:167], v[164:165], v[168:169]
	v_exp_f32_e32 v166, v154
	v_mul_f32_e32 v154, 0xbfb8aa3b, v39
	v_exp_f32_e32 v167, v154
	v_lshlrev_b32_e32 v158, 16, v159
	v_and_b32_e32 v159, 0xffff0000, v159
	v_pk_add_f32 v[166:167], v[166:167], 1.0 op_sel_hi:[1,0]
	s_nop 0
	s_nop 0
	v_rcp_f32_e32 v167, v167
	s_nop 0
	s_nop 0
	v_rcp_f32_e32 v166, v166
	s_nop 0
	v_lshlrev_b32_e32 v154, 16, v155
	v_and_b32_e32 v155, 0xffff0000, v155
	v_pk_fma_f32 v[158:159], v[166:167], v[158:159], v[154:155]
	v_lshlrev_b32_e32 v154, 16, v160
	v_and_b32_e32 v155, 0xffff0000, v160
	v_mul_f32_e32 v160, 0xbfb8aa3b, v32
	v_exp_f32_e32 v166, v160
	v_mul_f32_e32 v160, 0xbfb8aa3b, v33
	v_exp_f32_e32 v167, v160
	s_nop 0
	v_pk_add_f32 v[166:167], v[166:167], 1.0 op_sel_hi:[1,0]
	s_nop 0
	s_nop 0
	v_rcp_f32_e32 v167, v167
	s_nop 0
	s_nop 0
	v_lshlrev_b32_e32 v168, 16, v156
	v_and_b32_e32 v169, 0xffff0000, v156
	v_mul_f32_e32 v156, 0xbfb8aa3b, v34
	v_rcp_f32_e32 v166, v166
	s_nop 0
	v_exp_f32_e32 v160, v156
	v_mul_f32_e32 v156, 0xbfb8aa3b, v35
	v_pk_fma_f32 v[166:167], v[166:167], v[154:155], v[168:169]
	v_lshlrev_b32_e32 v154, 16, v161
	v_and_b32_e32 v155, 0xffff0000, v161
	v_exp_f32_e32 v161, v156
	s_nop 0
	v_pk_add_f32 v[160:161], v[160:161], 1.0 op_sel_hi:[1,0]
	s_nop 0
	s_nop 0
	v_rcp_f32_e32 v161, v161
	s_nop 0
	s_nop 0
	v_rcp_f32_e32 v160, v160
	s_nop 0
	v_lshlrev_b32_e32 v156, 16, v157
	v_and_b32_e32 v157, 0xffff0000, v157
	v_pk_fma_f32 v[160:161], v[160:161], v[154:155], v[156:157]
	v_cvt_pk_bf16_f32 v154, v164, v165
	v_cvt_pk_bf16_f32 v155, v158, v159
	v_cvt_pk_bf16_f32 v156, v166, v167
	v_cvt_pk_bf16_f32 v157, v160, v161
	global_store_dwordx4 v[162:163], v[154:157], off
	s_nop 1
	v_lshlrev_b32_e32 v154, 16, v150
	v_and_b32_e32 v155, 0xffff0000, v150
	v_mul_f32_e32 v150, 0xbfb8aa3b, v12
	v_exp_f32_e32 v156, v150
	v_mul_f32_e32 v150, 0xbfb8aa3b, v13
	v_exp_f32_e32 v157, v150
	s_nop 0
	v_pk_add_f32 v[156:157], v[156:157], 1.0 op_sel_hi:[1,0]
	s_nop 0
	s_nop 0
	v_rcp_f32_e32 v157, v157
	s_nop 0
	s_nop 0
	v_rcp_f32_e32 v156, v156
	s_nop 0
	v_lshlrev_b32_e32 v158, 16, v146
	v_and_b32_e32 v159, 0xffff0000, v146
	v_mul_f32_e32 v146, 0xbfb8aa3b, v14
	v_pk_fma_f32 v[154:155], v[156:157], v[154:155], v[158:159]
	v_exp_f32_e32 v156, v146
	v_mul_f32_e32 v146, 0xbfb8aa3b, v15
	v_exp_f32_e32 v157, v146
	v_lshlrev_b32_e32 v150, 16, v151
	v_and_b32_e32 v151, 0xffff0000, v151
	v_pk_add_f32 v[156:157], v[156:157], 1.0 op_sel_hi:[1,0]
	s_nop 0
	s_nop 0
	v_rcp_f32_e32 v157, v157
	s_nop 0
	s_nop 0
	v_rcp_f32_e32 v156, v156
	s_nop 0
	v_lshlrev_b32_e32 v146, 16, v147
	v_and_b32_e32 v147, 0xffff0000, v147
	v_pk_fma_f32 v[150:151], v[156:157], v[150:151], v[146:147]
	v_lshlrev_b32_e32 v146, 16, v152
	v_and_b32_e32 v147, 0xffff0000, v152
	v_mul_f32_e32 v152, 0xbfb8aa3b, v8
	v_exp_f32_e32 v156, v152
	v_mul_f32_e32 v152, 0xbfb8aa3b, v9
	v_exp_f32_e32 v157, v152
	s_nop 0
	v_pk_add_f32 v[156:157], v[156:157], 1.0 op_sel_hi:[1,0]
	s_nop 0
	s_nop 0
	v_rcp_f32_e32 v157, v157
	s_nop 0
	s_nop 0
	v_lshlrev_b32_e32 v158, 16, v148
	v_and_b32_e32 v159, 0xffff0000, v148
	v_mul_f32_e32 v148, 0xbfb8aa3b, v10
	v_rcp_f32_e32 v156, v156
	s_nop 0
	v_exp_f32_e32 v152, v148
	v_mul_f32_e32 v148, 0xbfb8aa3b, v11
	v_pk_fma_f32 v[156:157], v[156:157], v[146:147], v[158:159]
	v_lshlrev_b32_e32 v146, 16, v153
	v_and_b32_e32 v147, 0xffff0000, v153
	v_exp_f32_e32 v153, v148
	s_nop 0
	v_pk_add_f32 v[152:153], v[152:153], 1.0 op_sel_hi:[1,0]
	s_nop 0
	s_nop 0
	v_rcp_f32_e32 v153, v153
	s_nop 0
	s_nop 0
	v_rcp_f32_e32 v152, v152
	s_nop 0
	v_lshlrev_b32_e32 v148, 16, v149
	v_and_b32_e32 v149, 0xffff0000, v149
	v_pk_fma_f32 v[152:153], v[152:153], v[146:147], v[148:149]
	v_cvt_pk_bf16_f32 v146, v154, v155
	v_cvt_pk_bf16_f32 v147, v150, v151
	v_cvt_pk_bf16_f32 v148, v156, v157
	v_cvt_pk_bf16_f32 v149, v152, v153
	global_store_dwordx4 v[162:163], v[146:149], off offset:256
	s_nop 1
	v_lshlrev_b32_e32 v148, 16, v142
	v_and_b32_e32 v149, 0xffff0000, v142
	v_mul_f32_e32 v142, 0xbfb8aa3b, v20
	v_exp_f32_e32 v150, v142
	v_mul_f32_e32 v142, 0xbfb8aa3b, v21
	v_exp_f32_e32 v151, v142
	v_lshl_add_u64 v[146:147], v[162:163], 0, s[56:57]
	v_pk_add_f32 v[150:151], v[150:151], 1.0 op_sel_hi:[1,0]
	s_nop 0
	s_nop 0
	v_rcp_f32_e32 v151, v151
	s_nop 0
	s_nop 0
	v_rcp_f32_e32 v150, v150
	s_nop 0
	v_lshlrev_b32_e32 v152, 16, v138
	v_and_b32_e32 v153, 0xffff0000, v138
	v_mul_f32_e32 v138, 0xbfb8aa3b, v22
	v_pk_fma_f32 v[148:149], v[150:151], v[148:149], v[152:153]
	v_exp_f32_e32 v150, v138
	v_mul_f32_e32 v138, 0xbfb8aa3b, v23
	v_exp_f32_e32 v151, v138
	v_lshlrev_b32_e32 v142, 16, v143
	v_and_b32_e32 v143, 0xffff0000, v143
	v_pk_add_f32 v[150:151], v[150:151], 1.0 op_sel_hi:[1,0]
	s_nop 0
	s_nop 0
	v_rcp_f32_e32 v151, v151
	s_nop 0
	s_nop 0
	v_rcp_f32_e32 v150, v150
	s_nop 0
	v_lshlrev_b32_e32 v138, 16, v139
	v_and_b32_e32 v139, 0xffff0000, v139
	v_pk_fma_f32 v[142:143], v[150:151], v[142:143], v[138:139]
	v_lshlrev_b32_e32 v138, 16, v144
	v_and_b32_e32 v139, 0xffff0000, v144
	v_mul_f32_e32 v144, 0xbfb8aa3b, v16
	v_exp_f32_e32 v150, v144
	v_mul_f32_e32 v144, 0xbfb8aa3b, v17
	v_exp_f32_e32 v151, v144
	s_nop 0
	v_pk_add_f32 v[150:151], v[150:151], 1.0 op_sel_hi:[1,0]
	s_nop 0
	s_nop 0
	v_rcp_f32_e32 v151, v151
	s_nop 0
	s_nop 0
	v_lshlrev_b32_e32 v152, 16, v140
	v_and_b32_e32 v153, 0xffff0000, v140
	v_mul_f32_e32 v140, 0xbfb8aa3b, v18
	v_rcp_f32_e32 v150, v150
	s_nop 0
	v_exp_f32_e32 v144, v140
	v_mul_f32_e32 v140, 0xbfb8aa3b, v19
	v_pk_fma_f32 v[150:151], v[150:151], v[138:139], v[152:153]
	v_lshlrev_b32_e32 v138, 16, v145
	v_and_b32_e32 v139, 0xffff0000, v145
	v_exp_f32_e32 v145, v140
	s_nop 0
	v_pk_add_f32 v[144:145], v[144:145], 1.0 op_sel_hi:[1,0]
	s_nop 0
	s_nop 0
	v_rcp_f32_e32 v145, v145
	s_nop 0
	s_nop 0
	v_rcp_f32_e32 v144, v144
	s_nop 0
	v_lshlrev_b32_e32 v140, 16, v141
	v_and_b32_e32 v141, 0xffff0000, v141
	v_pk_fma_f32 v[144:145], v[144:145], v[138:139], v[140:141]
	v_cvt_pk_bf16_f32 v138, v148, v149
	v_cvt_pk_bf16_f32 v139, v142, v143
	v_cvt_pk_bf16_f32 v140, v150, v151
	v_cvt_pk_bf16_f32 v141, v144, v145
	global_store_dwordx4 v[146:147], v[138:141], off
	s_nop 1
	v_lshlrev_b32_e32 v138, 16, v134
	v_and_b32_e32 v139, 0xffff0000, v134
	v_mul_f32_e32 v134, 0xbfb8aa3b, v4
	v_exp_f32_e32 v140, v134
	v_mul_f32_e32 v134, 0xbfb8aa3b, v5
	v_exp_f32_e32 v141, v134
	s_nop 0
	v_pk_add_f32 v[140:141], v[140:141], 1.0 op_sel_hi:[1,0]
	s_nop 0
	s_nop 0
	v_rcp_f32_e32 v141, v141
	s_nop 0
	s_nop 0
	v_rcp_f32_e32 v140, v140
	s_nop 0
	v_lshlrev_b32_e32 v142, 16, v130
	v_and_b32_e32 v143, 0xffff0000, v130
	v_mul_f32_e32 v130, 0xbfb8aa3b, v6
	v_pk_fma_f32 v[138:139], v[140:141], v[138:139], v[142:143]
	v_exp_f32_e32 v140, v130
	v_mul_f32_e32 v130, 0xbfb8aa3b, v7
	v_exp_f32_e32 v141, v130
	v_lshlrev_b32_e32 v134, 16, v135
	v_and_b32_e32 v135, 0xffff0000, v135
	v_pk_add_f32 v[140:141], v[140:141], 1.0 op_sel_hi:[1,0]
	s_nop 0
	s_nop 0
	v_rcp_f32_e32 v141, v141
	s_nop 0
	s_nop 0
	v_rcp_f32_e32 v140, v140
	s_nop 0
	v_lshlrev_b32_e32 v130, 16, v131
	v_and_b32_e32 v131, 0xffff0000, v131
	v_pk_fma_f32 v[134:135], v[140:141], v[134:135], v[130:131]
	v_lshlrev_b32_e32 v130, 16, v136
	v_and_b32_e32 v131, 0xffff0000, v136
	v_mul_f32_e32 v136, 0xbfb8aa3b, v0
	v_exp_f32_e32 v140, v136
	v_mul_f32_e32 v136, 0xbfb8aa3b, v1
	v_exp_f32_e32 v141, v136
	s_nop 0
	v_pk_add_f32 v[140:141], v[140:141], 1.0 op_sel_hi:[1,0]
	s_nop 0
	s_nop 0
	v_rcp_f32_e32 v141, v141
	s_nop 0
	s_nop 0
	v_lshlrev_b32_e32 v142, 16, v132
	v_and_b32_e32 v143, 0xffff0000, v132
	v_mul_f32_e32 v132, 0xbfb8aa3b, v2
	v_rcp_f32_e32 v140, v140
	s_nop 0
	v_exp_f32_e32 v136, v132
	v_mul_f32_e32 v132, 0xbfb8aa3b, v3
	v_pk_fma_f32 v[140:141], v[140:141], v[130:131], v[142:143]
	v_lshlrev_b32_e32 v130, 16, v137
	v_and_b32_e32 v131, 0xffff0000, v137
	v_exp_f32_e32 v137, v132
	s_nop 0
	v_pk_add_f32 v[136:137], v[136:137], 1.0 op_sel_hi:[1,0]
	s_nop 0
	s_nop 0
	v_rcp_f32_e32 v137, v137
	s_nop 0
	s_nop 0
	v_rcp_f32_e32 v136, v136
	s_nop 0
	v_lshlrev_b32_e32 v132, 16, v133
	v_and_b32_e32 v133, 0xffff0000, v133
	v_pk_fma_f32 v[136:137], v[136:137], v[130:131], v[132:133]
	v_cvt_pk_bf16_f32 v130, v138, v139
	v_cvt_pk_bf16_f32 v131, v134, v135
	v_cvt_pk_bf16_f32 v132, v140, v141
	v_cvt_pk_bf16_f32 v133, v136, v137
	global_store_dwordx4 v[146:147], v[130:133], off offset:256

.LBB0_1356:
	s_add_u32 s28, s26, 0xfffc0080
	s_addc_u32 s29, s27, -1
	s_add_i32 s46, 0, 0x10000
	v_add_u32_e32 v140, s46, v143
	ds_read_b128 v[146:149], v140
	ds_read_b128 v[150:153], v140 offset:1024
	ds_read_b128 v[154:157], v140 offset:2048
	ds_read_b128 v[158:161], v140 offset:3072
	s_cmp_eq_u32 s45, 12
	s_cselect_b32 s31, s19, s29
	s_cselect_b32 s30, s18, s28
	s_cselect_b32 s29, s21, s17
	s_cselect_b32 s28, s20, s15
	v_lshl_add_u64 v[140:141], s[26:27], 0, v[136:137]
	s_add_i32 m0, s23, 0xc000
	ds_read_b128 v[162:165], v145
	ds_read_b128 v[166:169], v145 offset:1024
	ds_read_b128 v[170:173], v145 offset:2048
	ds_read_b128 v[174:177], v145 offset:3072
	ds_read_b128 v[178:181], v145 offset:4096
	ds_read_b128 v[182:185], v145 offset:5120
	ds_read_b128 v[186:189], v145 offset:6144
	ds_read_b128 v[190:193], v145 offset:7168
	global_load_lds_dwordx4 v[140:141], off
	v_lshl_add_u64 v[140:141], s[26:27], 0, v[138:139]
	s_add_i32 m0, s23, 0xe000
	s_nop 0
	global_load_lds_dwordx4 v[140:141], off
	s_waitcnt lgkmcnt(8)
	s_barrier
	s_waitcnt lgkmcnt(0)
	s_setprio 1
	s_waitcnt lgkmcnt(0)
	v_mfma_f32_16x16x32_bf16 v[126:129], v[146:149], v[162:165], v[126:129]
	v_mfma_f32_16x16x32_bf16 v[118:121], v[154:157], v[162:165], v[118:121]
	v_mfma_f32_16x16x32_bf16 v[110:113], v[146:149], v[170:173], v[110:113]
	v_mfma_f32_16x16x32_bf16 v[102:105], v[154:157], v[170:173], v[102:105]
	v_mfma_f32_16x16x32_bf16 v[94:97], v[146:149], v[178:181], v[94:97]
	v_mfma_f32_16x16x32_bf16 v[86:89], v[154:157], v[178:181], v[86:89]
	v_mfma_f32_16x16x32_bf16 v[78:81], v[146:149], v[186:189], v[78:81]
	v_mfma_f32_16x16x32_bf16 v[70:73], v[154:157], v[186:189], v[70:73]
	v_mfma_f32_16x16x32_bf16 v[126:129], v[150:153], v[166:169], v[126:129]
	v_mfma_f32_16x16x32_bf16 v[118:121], v[158:161], v[166:169], v[118:121]
	v_mfma_f32_16x16x32_bf16 v[110:113], v[150:153], v[174:177], v[110:113]
	v_mfma_f32_16x16x32_bf16 v[102:105], v[158:161], v[174:177], v[102:105]
	v_mfma_f32_16x16x32_bf16 v[94:97], v[150:153], v[182:185], v[94:97]
	v_mfma_f32_16x16x32_bf16 v[86:89], v[158:161], v[182:185], v[86:89]
	v_mfma_f32_16x16x32_bf16 v[78:81], v[150:153], v[190:193], v[78:81]
	v_mfma_f32_16x16x32_bf16 v[70:73], v[158:161], v[190:193], v[70:73]
	s_setprio 0
	s_barrier
	s_add_i32 s48, 0, 0x14000
	v_add_u32_e32 v140, s48, v143
	s_add_i32 s46, s46, s37
	ds_read_b128 v[198:201], v140
	ds_read_b128 v[202:205], v140 offset:1024
	ds_read_b128 v[206:209], v140 offset:2048
	ds_read_b128 v[210:213], v140 offset:3072
	v_lshl_add_u64 v[140:141], s[28:29], 0, v[48:49]
	s_mov_b32 m0, s46
	v_lshl_add_u64 v[214:215], s[28:29], 0, v[130:131]
	global_load_lds_dwordx4 v[140:141], off
	s_add_i32 m0, s46, 0x2000
	s_nop 0
	global_load_lds_dwordx4 v[214:215], off
	s_barrier
	s_waitcnt lgkmcnt(0)
	s_setprio 1
	s_waitcnt lgkmcnt(0)
	v_mfma_f32_16x16x32_bf16 v[122:125], v[198:201], v[162:165], v[122:125]
	v_mfma_f32_16x16x32_bf16 v[114:117], v[206:209], v[162:165], v[114:117]
	v_mfma_f32_16x16x32_bf16 v[106:109], v[198:201], v[170:173], v[106:109]
	v_mfma_f32_16x16x32_bf16 v[98:101], v[206:209], v[170:173], v[98:101]
	v_mfma_f32_16x16x32_bf16 v[90:93], v[198:201], v[178:181], v[90:93]
	v_mfma_f32_16x16x32_bf16 v[82:85], v[206:209], v[178:181], v[82:85]
	v_mfma_f32_16x16x32_bf16 v[74:77], v[198:201], v[186:189], v[74:77]
	v_mfma_f32_16x16x32_bf16 v[66:69], v[206:209], v[186:189], v[66:69]
	v_mfma_f32_16x16x32_bf16 v[122:125], v[202:205], v[166:169], v[122:125]
	v_mfma_f32_16x16x32_bf16 v[114:117], v[210:213], v[166:169], v[114:117]
	v_mfma_f32_16x16x32_bf16 v[106:109], v[202:205], v[174:177], v[106:109]
	v_mfma_f32_16x16x32_bf16 v[98:101], v[210:213], v[174:177], v[98:101]
	v_mfma_f32_16x16x32_bf16 v[90:93], v[202:205], v[182:185], v[90:93]
	v_mfma_f32_16x16x32_bf16 v[82:85], v[210:213], v[182:185], v[82:85]
	v_mfma_f32_16x16x32_bf16 v[74:77], v[202:205], v[190:193], v[74:77]
	v_mfma_f32_16x16x32_bf16 v[66:69], v[210:213], v[190:193], v[66:69]
	s_setprio 0
	s_mov_b32 m0, s23
	v_lshl_add_u64 v[216:217], s[30:31], 0, v[134:135]
	s_barrier
	ds_read_b128 v[162:165], v145 offset:16384
	ds_read_b128 v[166:169], v145 offset:17408
	ds_read_b128 v[170:173], v145 offset:18432
	ds_read_b128 v[174:177], v145 offset:19456
	ds_read_b128 v[178:181], v145 offset:20480
	ds_read_b128 v[182:185], v145 offset:21504
	ds_read_b128 v[186:189], v145 offset:22528
	ds_read_b128 v[190:193], v145 offset:23552
	global_load_lds_dwordx4 v[216:217], off
	v_lshl_add_u64 v[218:219], s[30:31], 0, v[132:133]
	s_mov_b32 m0, s25
	s_nop 0
	global_load_lds_dwordx4 v[218:219], off
	s_barrier
	s_waitcnt lgkmcnt(0)
	s_setprio 1
	s_waitcnt lgkmcnt(0)
	v_mfma_f32_16x16x32_bf16 v[62:65], v[146:149], v[162:165], v[62:65]
	v_mfma_f32_16x16x32_bf16 v[54:57], v[154:157], v[162:165], v[54:57]
	v_mfma_f32_16x16x32_bf16 v[44:47], v[146:149], v[170:173], v[44:47]
	v_mfma_f32_16x16x32_bf16 v[36:39], v[154:157], v[170:173], v[36:39]
	v_mfma_f32_16x16x32_bf16 v[28:31], v[146:149], v[178:181], v[28:31]
	v_mfma_f32_16x16x32_bf16 v[20:23], v[154:157], v[178:181], v[20:23]
	v_mfma_f32_16x16x32_bf16 v[12:15], v[146:149], v[186:189], v[12:15]
	v_mfma_f32_16x16x32_bf16 v[4:7], v[154:157], v[186:189], v[4:7]
	v_mfma_f32_16x16x32_bf16 v[62:65], v[150:153], v[166:169], v[62:65]
	v_mfma_f32_16x16x32_bf16 v[54:57], v[158:161], v[166:169], v[54:57]
	v_mfma_f32_16x16x32_bf16 v[44:47], v[150:153], v[174:177], v[44:47]
	v_mfma_f32_16x16x32_bf16 v[36:39], v[158:161], v[174:177], v[36:39]
	v_mfma_f32_16x16x32_bf16 v[28:31], v[150:153], v[182:185], v[28:31]
	v_mfma_f32_16x16x32_bf16 v[20:23], v[158:161], v[182:185], v[20:23]
	v_mfma_f32_16x16x32_bf16 v[12:15], v[150:153], v[190:193], v[12:15]
	v_mfma_f32_16x16x32_bf16 v[4:7], v[158:161], v[190:193], v[4:7]
	s_setprio 0
	s_barrier
	s_add_u32 s46, s28, 0x40000
	s_addc_u32 s47, s29, 0
	s_add_i32 s48, s48, s37
	v_lshl_add_u64 v[146:147], s[46:47], 0, v[48:49]
	s_mov_b32 m0, s48
	s_nop 0
	global_load_lds_dwordx4 v[146:147], off
	v_lshl_add_u64 v[146:147], s[46:47], 0, v[130:131]
	s_add_i32 m0, s48, 0x2000
	s_nop 0
	global_load_lds_dwordx4 v[146:147], off
	s_waitcnt vmcnt(6)
	s_barrier
	s_setprio 1
	v_mfma_f32_16x16x32_bf16 v[58:61], v[198:201], v[162:165], v[58:61]
	v_mfma_f32_16x16x32_bf16 v[50:53], v[206:209], v[162:165], v[50:53]
	v_mfma_f32_16x16x32_bf16 v[40:43], v[198:201], v[170:173], v[40:43]
	v_mfma_f32_16x16x32_bf16 v[32:35], v[206:209], v[170:173], v[32:35]
	v_mfma_f32_16x16x32_bf16 v[24:27], v[198:201], v[178:181], v[24:27]
	v_mfma_f32_16x16x32_bf16 v[16:19], v[206:209], v[178:181], v[16:19]
	v_mfma_f32_16x16x32_bf16 v[8:11], v[198:201], v[186:189], v[8:11]
	v_mfma_f32_16x16x32_bf16 v[0:3], v[206:209], v[186:189], v[0:3]
	v_mfma_f32_16x16x32_bf16 v[58:61], v[202:205], v[166:169], v[58:61]
	v_mfma_f32_16x16x32_bf16 v[50:53], v[210:213], v[166:169], v[50:53]
	v_mfma_f32_16x16x32_bf16 v[40:43], v[202:205], v[174:177], v[40:43]
	v_mfma_f32_16x16x32_bf16 v[32:35], v[210:213], v[174:177], v[32:35]
	v_mfma_f32_16x16x32_bf16 v[24:27], v[202:205], v[182:185], v[24:27]
	v_mfma_f32_16x16x32_bf16 v[16:19], v[210:213], v[182:185], v[16:19]
	v_mfma_f32_16x16x32_bf16 v[8:11], v[202:205], v[190:193], v[8:11]
	v_mfma_f32_16x16x32_bf16 v[0:3], v[210:213], v[190:193], v[0:3]
	s_setprio 0
	s_add_i32 s46, 0, 0x18000
	v_add_u32_e32 v158, s46, v143
	s_barrier
	ds_read_b128 v[146:149], v158
	ds_read_b128 v[150:153], v158 offset:1024
	ds_read_b128 v[154:157], v158 offset:2048
	ds_read_b128 v[158:161], v158 offset:3072
	s_add_u32 s30, s30, 0x40000
	s_addc_u32 s31, s31, 0
	s_mov_b32 m0, s40
	v_lshl_add_u64 v[198:199], s[30:31], 0, v[134:135]
	ds_read_b128 v[162:165], v145 offset:32768
	ds_read_b128 v[166:169], v145 offset:33792
	ds_read_b128 v[170:173], v145 offset:34816
	ds_read_b128 v[174:177], v145 offset:35840
	ds_read_b128 v[178:181], v145 offset:36864
	ds_read_b128 v[182:185], v145 offset:37888
	ds_read_b128 v[186:189], v145 offset:38912
	ds_read_b128 v[190:193], v145 offset:39936
	global_load_lds_dwordx4 v[198:199], off
	v_lshl_add_u64 v[198:199], s[30:31], 0, v[132:133]
	s_mov_b32 m0, s41
	s_nop 0
	global_load_lds_dwordx4 v[198:199], off
	s_waitcnt lgkmcnt(8)
	s_barrier
	s_waitcnt lgkmcnt(0)
	s_setprio 1
	s_waitcnt lgkmcnt(0)
	v_mfma_f32_16x16x32_bf16 v[126:129], v[146:149], v[162:165], v[126:129]
	v_mfma_f32_16x16x32_bf16 v[118:121], v[154:157], v[162:165], v[118:121]
	v_mfma_f32_16x16x32_bf16 v[110:113], v[146:149], v[170:173], v[110:113]
	v_mfma_f32_16x16x32_bf16 v[102:105], v[154:157], v[170:173], v[102:105]
	v_mfma_f32_16x16x32_bf16 v[94:97], v[146:149], v[178:181], v[94:97]
	v_mfma_f32_16x16x32_bf16 v[86:89], v[154:157], v[178:181], v[86:89]
	v_mfma_f32_16x16x32_bf16 v[78:81], v[146:149], v[186:189], v[78:81]
	v_mfma_f32_16x16x32_bf16 v[70:73], v[154:157], v[186:189], v[70:73]
	v_mfma_f32_16x16x32_bf16 v[126:129], v[150:153], v[166:169], v[126:129]
	v_mfma_f32_16x16x32_bf16 v[118:121], v[158:161], v[166:169], v[118:121]
	v_mfma_f32_16x16x32_bf16 v[110:113], v[150:153], v[174:177], v[110:113]
	v_mfma_f32_16x16x32_bf16 v[102:105], v[158:161], v[174:177], v[102:105]
	v_mfma_f32_16x16x32_bf16 v[94:97], v[150:153], v[182:185], v[94:97]
	v_mfma_f32_16x16x32_bf16 v[86:89], v[158:161], v[182:185], v[86:89]
	v_mfma_f32_16x16x32_bf16 v[78:81], v[150:153], v[190:193], v[78:81]
	v_mfma_f32_16x16x32_bf16 v[70:73], v[158:161], v[190:193], v[70:73]
	s_setprio 0
	s_barrier
	s_add_i32 s30, 0, 0x1c000
	s_add_i32 s31, s46, s37
	v_add_u32_e32 v210, s30, v143
	v_lshl_add_u64 v[140:141], v[140:141], 0, s[66:67]
	s_mov_b32 m0, s31
	ds_read_b128 v[198:201], v210
	ds_read_b128 v[202:205], v210 offset:1024
	ds_read_b128 v[206:209], v210 offset:2048
	ds_read_b128 v[210:213], v210 offset:3072
	global_load_lds_dwordx4 v[140:141], off
	v_lshl_add_u64 v[140:141], v[214:215], 0, s[66:67]
	s_add_i32 m0, s31, 0x2000
	s_nop 0
	global_load_lds_dwordx4 v[140:141], off
	s_barrier
	s_waitcnt lgkmcnt(0)
	s_setprio 1
	s_waitcnt lgkmcnt(0)
	v_mfma_f32_16x16x32_bf16 v[122:125], v[198:201], v[162:165], v[122:125]
	v_mfma_f32_16x16x32_bf16 v[114:117], v[206:209], v[162:165], v[114:117]
	v_mfma_f32_16x16x32_bf16 v[106:109], v[198:201], v[170:173], v[106:109]
	v_mfma_f32_16x16x32_bf16 v[98:101], v[206:209], v[170:173], v[98:101]
	v_mfma_f32_16x16x32_bf16 v[90:93], v[198:201], v[178:181], v[90:93]
	v_mfma_f32_16x16x32_bf16 v[82:85], v[206:209], v[178:181], v[82:85]
	v_mfma_f32_16x16x32_bf16 v[74:77], v[198:201], v[186:189], v[74:77]
	v_mfma_f32_16x16x32_bf16 v[66:69], v[206:209], v[186:189], v[66:69]
	v_mfma_f32_16x16x32_bf16 v[122:125], v[202:205], v[166:169], v[122:125]
	v_mfma_f32_16x16x32_bf16 v[114:117], v[210:213], v[166:169], v[114:117]
	v_mfma_f32_16x16x32_bf16 v[106:109], v[202:205], v[174:177], v[106:109]
	v_mfma_f32_16x16x32_bf16 v[98:101], v[210:213], v[174:177], v[98:101]
	v_mfma_f32_16x16x32_bf16 v[90:93], v[202:205], v[182:185], v[90:93]
	v_mfma_f32_16x16x32_bf16 v[82:85], v[210:213], v[182:185], v[82:85]
	v_mfma_f32_16x16x32_bf16 v[74:77], v[202:205], v[190:193], v[74:77]
	v_mfma_f32_16x16x32_bf16 v[66:69], v[210:213], v[190:193], v[66:69]
	s_setprio 0
	s_mov_b32 m0, s42
	v_lshl_add_u64 v[140:141], v[216:217], 0, s[66:67]
	s_barrier
	ds_read_b128 v[162:165], v145 offset:49152
	ds_read_b128 v[166:169], v145 offset:50176
	ds_read_b128 v[170:173], v145 offset:51200
	ds_read_b128 v[174:177], v145 offset:52224
	ds_read_b128 v[178:181], v145 offset:53248
	ds_read_b128 v[182:185], v145 offset:54272
	ds_read_b128 v[186:189], v145 offset:55296
	ds_read_b128 v[190:193], v145 offset:56320
	global_load_lds_dwordx4 v[140:141], off
	v_lshl_add_u64 v[140:141], v[218:219], 0, s[66:67]
	s_mov_b32 m0, s43
	s_nop 0
	global_load_lds_dwordx4 v[140:141], off
	s_barrier
	s_waitcnt lgkmcnt(0)
	s_setprio 1
	s_waitcnt lgkmcnt(0)
	v_mfma_f32_16x16x32_bf16 v[62:65], v[146:149], v[162:165], v[62:65]
	v_mfma_f32_16x16x32_bf16 v[54:57], v[154:157], v[162:165], v[54:57]
	v_mfma_f32_16x16x32_bf16 v[44:47], v[146:149], v[170:173], v[44:47]
	v_mfma_f32_16x16x32_bf16 v[36:39], v[154:157], v[170:173], v[36:39]
	v_mfma_f32_16x16x32_bf16 v[28:31], v[146:149], v[178:181], v[28:31]
	v_mfma_f32_16x16x32_bf16 v[20:23], v[154:157], v[178:181], v[20:23]
	v_mfma_f32_16x16x32_bf16 v[12:15], v[146:149], v[186:189], v[12:15]
	v_mfma_f32_16x16x32_bf16 v[4:7], v[154:157], v[186:189], v[4:7]
	v_mfma_f32_16x16x32_bf16 v[62:65], v[150:153], v[166:169], v[62:65]
	v_mfma_f32_16x16x32_bf16 v[54:57], v[158:161], v[166:169], v[54:57]
	v_mfma_f32_16x16x32_bf16 v[44:47], v[150:153], v[174:177], v[44:47]
	v_mfma_f32_16x16x32_bf16 v[36:39], v[158:161], v[174:177], v[36:39]
	v_mfma_f32_16x16x32_bf16 v[28:31], v[150:153], v[182:185], v[28:31]
	v_mfma_f32_16x16x32_bf16 v[20:23], v[158:161], v[182:185], v[20:23]
	v_mfma_f32_16x16x32_bf16 v[12:15], v[150:153], v[190:193], v[12:15]
	v_mfma_f32_16x16x32_bf16 v[4:7], v[158:161], v[190:193], v[4:7]
	s_setprio 0
	s_barrier
	s_add_u32 s28, s28, 0x40080
	s_addc_u32 s29, s29, 0
	s_add_i32 s30, s30, s37
	v_lshl_add_u64 v[140:141], s[28:29], 0, v[48:49]
	s_mov_b32 m0, s30
	s_nop 0
	global_load_lds_dwordx4 v[140:141], off
	v_lshl_add_u64 v[140:141], s[28:29], 0, v[130:131]
	s_add_i32 m0, s30, 0x2000
	s_nop 0
	global_load_lds_dwordx4 v[140:141], off
	s_waitcnt vmcnt(6)
	s_barrier
	s_setprio 1
	v_mfma_f32_16x16x32_bf16 v[58:61], v[198:201], v[162:165], v[58:61]
	v_mfma_f32_16x16x32_bf16 v[50:53], v[206:209], v[162:165], v[50:53]
	v_mfma_f32_16x16x32_bf16 v[40:43], v[198:201], v[170:173], v[40:43]
	v_mfma_f32_16x16x32_bf16 v[32:35], v[206:209], v[170:173], v[32:35]
	v_mfma_f32_16x16x32_bf16 v[24:27], v[198:201], v[178:181], v[24:27]
	v_mfma_f32_16x16x32_bf16 v[16:19], v[206:209], v[178:181], v[16:19]
	v_mfma_f32_16x16x32_bf16 v[8:11], v[198:201], v[186:189], v[8:11]
	v_mfma_f32_16x16x32_bf16 v[0:3], v[206:209], v[186:189], v[0:3]
	v_mfma_f32_16x16x32_bf16 v[58:61], v[202:205], v[166:169], v[58:61]
	v_mfma_f32_16x16x32_bf16 v[50:53], v[210:213], v[166:169], v[50:53]
	v_mfma_f32_16x16x32_bf16 v[40:43], v[202:205], v[174:177], v[40:43]
	v_mfma_f32_16x16x32_bf16 v[32:35], v[210:213], v[174:177], v[32:35]
	v_mfma_f32_16x16x32_bf16 v[24:27], v[202:205], v[182:185], v[24:27]
	v_mfma_f32_16x16x32_bf16 v[16:19], v[210:213], v[182:185], v[16:19]
	v_mfma_f32_16x16x32_bf16 v[8:11], v[202:205], v[190:193], v[8:11]
	v_mfma_f32_16x16x32_bf16 v[0:3], v[210:213], v[190:193], v[0:3]
	s_setprio 0
	s_add_i32 s45, s45, 2
	s_add_u32 s26, s26, 0x100
	s_addc_u32 s27, s27, 0
	s_add_u32 s15, s15, 0x100
	s_addc_u32 s17, s17, 0
	s_cmp_gt_u32 s45, 13
	s_barrier
	s_cbranch_scc0 .LBB0_1356
	v_mul_f32_e32 v147, 0xbfb8aa3b, v126
	v_exp_f32_e32 v148, v147
	v_mul_f32_e32 v147, 0xbfb8aa3b, v118
	v_exp_f32_e32 v150, v147
	v_mul_f32_e32 v147, 0xbfb8aa3b, v127
	v_exp_f32_e32 v149, v147
	v_lshl_or_b32 v140, s22, 7, v144
	v_lshl_add_u32 v146, s24, 8, v142
	v_ashrrev_i32_e32 v141, 31, v140
	v_pk_add_f32 v[148:149], v[148:149], 1.0 op_sel_hi:[1,0]
	s_movk_i32 s15, 0x1600
	s_mov_b32 s22, s14
	s_mov_b32 s24, s16
	s_mov_b64 s[28:29], s[20:21]
	v_rcp_f32_e32 v147, v149
	s_nop 0
	v_mul_f32_e32 v127, v127, v147
	s_nop 0
	v_rcp_f32_e32 v147, v148
	s_nop 0
	v_mul_f32_e32 v126, v126, v147
	v_pk_mul_f32 v[122:123], v[122:123], v[126:127]
	v_mul_f32_e32 v126, 0xbfb8aa3b, v119
	v_exp_f32_e32 v151, v126
	s_nop 0
	v_pk_add_f32 v[126:127], v[150:151], 1.0 op_sel_hi:[1,0]
	s_nop 0
	s_nop 0
	v_rcp_f32_e32 v147, v127
	s_nop 0
	v_mul_f32_e32 v119, v119, v147
	s_nop 0
	v_rcp_f32_e32 v127, v126
	s_nop 0
	v_mul_f32_e32 v118, v118, v127
	v_pk_mul_f32 v[114:115], v[114:115], v[118:119]
	v_mul_f32_e32 v119, 0xbfb8aa3b, v120
	v_mul_f32_e32 v118, 0xbfb8aa3b, v128
	v_exp_f32_e32 v126, v119
	v_mul_f32_e32 v119, 0xbfb8aa3b, v129
	v_exp_f32_e32 v118, v118
	v_exp_f32_e32 v119, v119
	s_nop 0
	v_pk_add_f32 v[118:119], v[118:119], 1.0 op_sel_hi:[1,0]
	s_nop 0
	s_nop 0
	v_rcp_f32_e32 v127, v119
	s_nop 0
	v_mul_f32_e32 v119, v129, v127
	s_nop 0
	v_rcp_f32_e32 v127, v118
	s_nop 0
	v_mul_f32_e32 v118, v128, v127
	v_pk_mul_f32 v[124:125], v[124:125], v[118:119]
	v_mul_f32_e32 v118, 0xbfb8aa3b, v121
	v_exp_f32_e32 v127, v118
	s_nop 0
	v_pk_add_f32 v[118:119], v[126:127], 1.0 op_sel_hi:[1,0]
	s_nop 0
	s_nop 0
	v_rcp_f32_e32 v126, v119
	s_nop 0
	v_mul_f32_e32 v119, v121, v126
	s_nop 0
	v_rcp_f32_e32 v121, v118
	s_nop 0
	v_mul_f32_e32 v118, v120, v121
	v_pk_mul_f32 v[116:117], v[116:117], v[118:119]
	v_cvt_pk_bf16_f32 v120, v114, v115
	v_mov_b64_e32 v[114:115], s[12:13]
	v_cvt_pk_bf16_f32 v118, v122, v123
	v_cvt_pk_bf16_f32 v121, v116, v117
	v_mad_i64_i32 v[122:123], s[26:27], v146, s15, v[114:115]
	v_lshlrev_b64 v[116:117], 1, v[140:141]
	v_cvt_pk_bf16_f32 v119, v124, v125
	v_lshl_add_u64 v[122:123], v[122:123], 0, v[116:117]
	global_store_dwordx4 v[122:123], v[118:121], off
	s_nop 1
	v_mul_f32_e32 v119, 0xbfb8aa3b, v102
	v_mul_f32_e32 v118, 0xbfb8aa3b, v110
	v_exp_f32_e32 v120, v119
	v_mul_f32_e32 v119, 0xbfb8aa3b, v111
	v_exp_f32_e32 v118, v118
	v_exp_f32_e32 v119, v119
	s_nop 0
	v_pk_add_f32 v[118:119], v[118:119], 1.0 op_sel_hi:[1,0]
	s_nop 0
	s_nop 0
	v_rcp_f32_e32 v121, v119
	s_nop 0
	v_mul_f32_e32 v111, v111, v121
	s_nop 0
	v_rcp_f32_e32 v119, v118
	s_nop 0
	v_mul_f32_e32 v110, v110, v119
	v_pk_mul_f32 v[106:107], v[106:107], v[110:111]
	v_mul_f32_e32 v110, 0xbfb8aa3b, v103
	v_exp_f32_e32 v121, v110
	s_nop 0
	v_pk_add_f32 v[110:111], v[120:121], 1.0 op_sel_hi:[1,0]
	s_nop 0
	s_nop 0
	v_rcp_f32_e32 v118, v111
	s_nop 0
	v_mul_f32_e32 v103, v103, v118
	s_nop 0
	v_rcp_f32_e32 v111, v110
	s_nop 0
	v_mul_f32_e32 v102, v102, v111
	v_pk_mul_f32 v[102:103], v[98:99], v[102:103]
	v_mul_f32_e32 v99, 0xbfb8aa3b, v104
	v_mul_f32_e32 v98, 0xbfb8aa3b, v112
	v_exp_f32_e32 v110, v99
	v_mul_f32_e32 v99, 0xbfb8aa3b, v113
	v_exp_f32_e32 v98, v98
	v_exp_f32_e32 v99, v99
	s_nop 0
	v_pk_add_f32 v[98:99], v[98:99], 1.0 op_sel_hi:[1,0]
	s_nop 0
	s_nop 0
	v_rcp_f32_e32 v111, v99
	s_nop 0
	v_mul_f32_e32 v99, v113, v111
	s_nop 0
	v_rcp_f32_e32 v111, v98
	s_nop 0
	v_mul_f32_e32 v98, v112, v111
	v_pk_mul_f32 v[108:109], v[108:109], v[98:99]
	v_mul_f32_e32 v98, 0xbfb8aa3b, v105
	v_exp_f32_e32 v111, v98
	s_nop 0
	v_pk_add_f32 v[98:99], v[110:111], 1.0 op_sel_hi:[1,0]
	s_nop 0
	s_nop 0
	v_rcp_f32_e32 v110, v99
	s_nop 0
	v_mul_f32_e32 v99, v105, v110
	s_nop 0
	v_rcp_f32_e32 v105, v98
	s_nop 0
	v_mul_f32_e32 v98, v104, v105
	v_or_b32_e32 v110, 16, v146
	v_pk_mul_f32 v[104:105], v[100:101], v[98:99]
	v_cvt_pk_bf16_f32 v100, v102, v103
	v_mad_i64_i32 v[102:103], s[26:27], v110, s15, v[114:115]
	v_cvt_pk_bf16_f32 v98, v106, v107
	v_cvt_pk_bf16_f32 v99, v108, v109
	v_cvt_pk_bf16_f32 v101, v104, v105
	v_lshl_add_u64 v[102:103], v[102:103], 0, v[116:117]
	global_store_dwordx4 v[102:103], v[98:101], off
	s_nop 1
	v_mul_f32_e32 v99, 0xbfb8aa3b, v86
	v_mul_f32_e32 v98, 0xbfb8aa3b, v94
	v_exp_f32_e32 v100, v99
	v_mul_f32_e32 v99, 0xbfb8aa3b, v95
	v_exp_f32_e32 v98, v98
	v_exp_f32_e32 v99, v99
	s_nop 0
	v_pk_add_f32 v[98:99], v[98:99], 1.0 op_sel_hi:[1,0]
	s_nop 0
	s_nop 0
	v_rcp_f32_e32 v101, v99
	s_nop 0
	v_mul_f32_e32 v95, v95, v101
	s_nop 0
	v_rcp_f32_e32 v99, v98
	s_nop 0
	v_mul_f32_e32 v94, v94, v99
	v_pk_mul_f32 v[90:91], v[90:91], v[94:95]
	v_mul_f32_e32 v94, 0xbfb8aa3b, v87
	v_exp_f32_e32 v101, v94
	s_nop 0
	v_pk_add_f32 v[94:95], v[100:101], 1.0 op_sel_hi:[1,0]
	s_nop 0
	s_nop 0
	v_rcp_f32_e32 v98, v95
	s_nop 0
	v_mul_f32_e32 v87, v87, v98
	s_nop 0
	v_rcp_f32_e32 v95, v94
	s_nop 0
	v_mul_f32_e32 v86, v86, v95
	v_pk_mul_f32 v[86:87], v[82:83], v[86:87]
	v_mul_f32_e32 v83, 0xbfb8aa3b, v88
	v_mul_f32_e32 v82, 0xbfb8aa3b, v96
	v_exp_f32_e32 v94, v83
	v_mul_f32_e32 v83, 0xbfb8aa3b, v97
	v_exp_f32_e32 v82, v82
	v_exp_f32_e32 v83, v83
	s_nop 0
	v_pk_add_f32 v[82:83], v[82:83], 1.0 op_sel_hi:[1,0]
	s_nop 0
	s_nop 0
	v_rcp_f32_e32 v95, v83
	s_nop 0
	v_mul_f32_e32 v83, v97, v95
	s_nop 0
	v_rcp_f32_e32 v95, v82
	s_nop 0
	v_mul_f32_e32 v82, v96, v95
	v_pk_mul_f32 v[92:93], v[92:93], v[82:83]
	v_mul_f32_e32 v82, 0xbfb8aa3b, v89
	v_exp_f32_e32 v95, v82
	s_nop 0
	v_pk_add_f32 v[82:83], v[94:95], 1.0 op_sel_hi:[1,0]
	s_nop 0
	s_nop 0
	v_rcp_f32_e32 v94, v83
	s_nop 0
	v_mul_f32_e32 v83, v89, v94
	s_nop 0
	v_rcp_f32_e32 v89, v82
	s_nop 0
	v_mul_f32_e32 v82, v88, v89
	v_or_b32_e32 v94, 32, v146
	v_pk_mul_f32 v[88:89], v[84:85], v[82:83]
	v_cvt_pk_bf16_f32 v84, v86, v87
	v_mad_i64_i32 v[86:87], s[26:27], v94, s15, v[114:115]
	v_cvt_pk_bf16_f32 v82, v90, v91
	v_cvt_pk_bf16_f32 v83, v92, v93
	v_cvt_pk_bf16_f32 v85, v88, v89
	v_lshl_add_u64 v[86:87], v[86:87], 0, v[116:117]
	global_store_dwordx4 v[86:87], v[82:85], off
	s_nop 1
	v_mul_f32_e32 v83, 0xbfb8aa3b, v70
	v_mul_f32_e32 v82, 0xbfb8aa3b, v78
	v_exp_f32_e32 v84, v83
	v_mul_f32_e32 v83, 0xbfb8aa3b, v79
	v_exp_f32_e32 v82, v82
	v_exp_f32_e32 v83, v83
	s_nop 0
	v_pk_add_f32 v[82:83], v[82:83], 1.0 op_sel_hi:[1,0]
	s_nop 0
	s_nop 0
	v_rcp_f32_e32 v85, v83
	s_nop 0
	v_mul_f32_e32 v79, v79, v85
	s_nop 0
	v_rcp_f32_e32 v83, v82
	s_nop 0
	v_mul_f32_e32 v78, v78, v83
	v_pk_mul_f32 v[74:75], v[74:75], v[78:79]
	v_mul_f32_e32 v78, 0xbfb8aa3b, v71
	v_exp_f32_e32 v85, v78
	s_nop 0
	v_pk_add_f32 v[78:79], v[84:85], 1.0 op_sel_hi:[1,0]
	s_nop 0
	s_nop 0
	v_rcp_f32_e32 v82, v79
	s_nop 0
	v_mul_f32_e32 v71, v71, v82
	s_nop 0
	v_rcp_f32_e32 v79, v78
	s_nop 0
	v_mul_f32_e32 v70, v70, v79
	v_pk_mul_f32 v[70:71], v[66:67], v[70:71]
	v_mul_f32_e32 v67, 0xbfb8aa3b, v72
	v_mul_f32_e32 v66, 0xbfb8aa3b, v80
	v_exp_f32_e32 v78, v67
	v_mul_f32_e32 v67, 0xbfb8aa3b, v81
	v_exp_f32_e32 v66, v66
	v_exp_f32_e32 v67, v67
	s_nop 0
	v_pk_add_f32 v[66:67], v[66:67], 1.0 op_sel_hi:[1,0]
	s_nop 0
	s_nop 0
	v_rcp_f32_e32 v79, v67
	s_nop 0
	v_mul_f32_e32 v67, v81, v79
	s_nop 0
	v_rcp_f32_e32 v79, v66
	s_nop 0
	v_mul_f32_e32 v66, v80, v79
	v_pk_mul_f32 v[76:77], v[76:77], v[66:67]
	v_mul_f32_e32 v66, 0xbfb8aa3b, v73
	v_exp_f32_e32 v79, v66
	s_nop 0
	v_pk_add_f32 v[66:67], v[78:79], 1.0 op_sel_hi:[1,0]
	s_nop 0
	s_nop 0
	v_rcp_f32_e32 v78, v67
	s_nop 0
	v_mul_f32_e32 v67, v73, v78
	s_nop 0
	v_rcp_f32_e32 v73, v66
	s_nop 0
	v_mul_f32_e32 v66, v72, v73
	v_or_b32_e32 v78, 48, v146
	v_pk_mul_f32 v[72:73], v[68:69], v[66:67]
	v_cvt_pk_bf16_f32 v68, v70, v71
	v_mad_i64_i32 v[70:71], s[26:27], v78, s15, v[114:115]
	v_cvt_pk_bf16_f32 v66, v74, v75
	v_cvt_pk_bf16_f32 v67, v76, v77
	v_cvt_pk_bf16_f32 v69, v72, v73
	v_lshl_add_u64 v[70:71], v[70:71], 0, v[116:117]
	global_store_dwordx4 v[70:71], v[66:69], off
	v_add_u32_e32 v70, 0x80, v146
	s_nop 0
	v_mul_f32_e32 v67, 0xbfb8aa3b, v54
	v_mul_f32_e32 v66, 0xbfb8aa3b, v62
	v_exp_f32_e32 v68, v67
	v_mul_f32_e32 v67, 0xbfb8aa3b, v63
	v_exp_f32_e32 v66, v66
	v_exp_f32_e32 v67, v67
	s_nop 0
	v_pk_add_f32 v[66:67], v[66:67], 1.0 op_sel_hi:[1,0]
	s_nop 0
	s_nop 0
	v_rcp_f32_e32 v69, v67
	s_nop 0
	v_mul_f32_e32 v63, v63, v69
	s_nop 0
	v_rcp_f32_e32 v67, v66
	s_nop 0
	v_mul_f32_e32 v62, v62, v67
	v_pk_mul_f32 v[58:59], v[58:59], v[62:63]
	v_mul_f32_e32 v62, 0xbfb8aa3b, v55
	v_exp_f32_e32 v69, v62
	s_nop 0
	v_pk_add_f32 v[62:63], v[68:69], 1.0 op_sel_hi:[1,0]
	s_nop 0
	s_nop 0
	v_rcp_f32_e32 v66, v63
	s_nop 0
	v_mul_f32_e32 v55, v55, v66
	s_nop 0
	v_rcp_f32_e32 v63, v62
	s_nop 0
	v_mul_f32_e32 v54, v54, v63
	v_pk_mul_f32 v[54:55], v[50:51], v[54:55]
	v_mul_f32_e32 v51, 0xbfb8aa3b, v56
	v_mul_f32_e32 v50, 0xbfb8aa3b, v64
	v_exp_f32_e32 v62, v51
	v_mul_f32_e32 v51, 0xbfb8aa3b, v65
	v_exp_f32_e32 v50, v50
	v_exp_f32_e32 v51, v51
	s_nop 0
	v_pk_add_f32 v[50:51], v[50:51], 1.0 op_sel_hi:[1,0]
	s_nop 0
	s_nop 0
	v_rcp_f32_e32 v63, v51
	s_nop 0
	v_mul_f32_e32 v51, v65, v63
	s_nop 0
	v_rcp_f32_e32 v63, v50
	s_nop 0
	v_mul_f32_e32 v50, v64, v63
	v_pk_mul_f32 v[60:61], v[60:61], v[50:51]
	v_mul_f32_e32 v50, 0xbfb8aa3b, v57
	v_exp_f32_e32 v63, v50
	s_nop 0
	v_pk_add_f32 v[50:51], v[62:63], 1.0 op_sel_hi:[1,0]
	s_nop 0
	s_nop 0
	v_rcp_f32_e32 v62, v51
	s_nop 0
	v_mul_f32_e32 v51, v57, v62
	s_nop 0
	v_rcp_f32_e32 v57, v50
	s_nop 0
	v_mul_f32_e32 v50, v56, v57
	v_pk_mul_f32 v[56:57], v[52:53], v[50:51]
	v_cvt_pk_bf16_f32 v52, v54, v55
	v_mad_i64_i32 v[54:55], s[26:27], v70, s15, v[114:115]
	v_cvt_pk_bf16_f32 v50, v58, v59
	v_cvt_pk_bf16_f32 v51, v60, v61
	v_cvt_pk_bf16_f32 v53, v56, v57
	v_lshl_add_u64 v[54:55], v[54:55], 0, v[116:117]
	global_store_dwordx4 v[54:55], v[50:53], off
	s_nop 1
	v_mul_f32_e32 v51, 0xbfb8aa3b, v36
	v_mul_f32_e32 v50, 0xbfb8aa3b, v44
	v_exp_f32_e32 v52, v51
	v_mul_f32_e32 v51, 0xbfb8aa3b, v45
	v_exp_f32_e32 v50, v50
	v_exp_f32_e32 v51, v51
	s_nop 0
	v_pk_add_f32 v[50:51], v[50:51], 1.0 op_sel_hi:[1,0]
	s_nop 0
	s_nop 0
	v_rcp_f32_e32 v53, v51
	s_nop 0
	v_mul_f32_e32 v45, v45, v53
	s_nop 0
	v_rcp_f32_e32 v51, v50
	s_nop 0
	v_mul_f32_e32 v44, v44, v51
	v_pk_mul_f32 v[40:41], v[40:41], v[44:45]
	v_mul_f32_e32 v44, 0xbfb8aa3b, v37
	v_exp_f32_e32 v53, v44
	s_nop 0
	v_pk_add_f32 v[44:45], v[52:53], 1.0 op_sel_hi:[1,0]
	s_nop 0
	s_nop 0
	v_rcp_f32_e32 v50, v45
	s_nop 0
	v_mul_f32_e32 v37, v37, v50
	s_nop 0
	v_rcp_f32_e32 v45, v44
	s_nop 0
	v_mul_f32_e32 v36, v36, v45
	v_pk_mul_f32 v[36:37], v[32:33], v[36:37]
	v_mul_f32_e32 v33, 0xbfb8aa3b, v38
	v_mul_f32_e32 v32, 0xbfb8aa3b, v46
	v_exp_f32_e32 v44, v33
	v_mul_f32_e32 v33, 0xbfb8aa3b, v47
	v_exp_f32_e32 v32, v32
	v_exp_f32_e32 v33, v33
	s_nop 0
	v_pk_add_f32 v[32:33], v[32:33], 1.0 op_sel_hi:[1,0]
	s_nop 0
	s_nop 0
	v_rcp_f32_e32 v45, v33
	s_nop 0
	v_mul_f32_e32 v33, v47, v45
	s_nop 0
	v_rcp_f32_e32 v45, v32
	s_nop 0
	v_mul_f32_e32 v32, v46, v45
	v_pk_mul_f32 v[42:43], v[42:43], v[32:33]
	v_mul_f32_e32 v32, 0xbfb8aa3b, v39
	v_exp_f32_e32 v45, v32
	s_nop 0
	v_pk_add_f32 v[32:33], v[44:45], 1.0 op_sel_hi:[1,0]
	s_nop 0
	s_nop 0
	v_rcp_f32_e32 v44, v33
	s_nop 0
	v_mul_f32_e32 v33, v39, v44
	s_nop 0
	v_rcp_f32_e32 v39, v32
	s_nop 0
	v_mul_f32_e32 v32, v38, v39
	v_add_u32_e32 v44, 0x90, v146
	v_pk_mul_f32 v[38:39], v[34:35], v[32:33]
	v_cvt_pk_bf16_f32 v34, v36, v37
	v_mad_i64_i32 v[36:37], s[26:27], v44, s15, v[114:115]
	v_cvt_pk_bf16_f32 v32, v40, v41
	v_cvt_pk_bf16_f32 v33, v42, v43
	v_cvt_pk_bf16_f32 v35, v38, v39
	v_lshl_add_u64 v[36:37], v[36:37], 0, v[116:117]
	global_store_dwordx4 v[36:37], v[32:35], off
	s_nop 1
	v_mul_f32_e32 v33, 0xbfb8aa3b, v20
	v_mul_f32_e32 v32, 0xbfb8aa3b, v28
	v_exp_f32_e32 v34, v33
	v_mul_f32_e32 v33, 0xbfb8aa3b, v29
	v_exp_f32_e32 v32, v32
	v_exp_f32_e32 v33, v33
	s_nop 0
	v_pk_add_f32 v[32:33], v[32:33], 1.0 op_sel_hi:[1,0]
	s_nop 0
	s_nop 0
	v_rcp_f32_e32 v35, v33
	s_nop 0
	v_mul_f32_e32 v29, v29, v35
	s_nop 0
	v_rcp_f32_e32 v33, v32
	s_nop 0
	v_mul_f32_e32 v28, v28, v33
	v_pk_mul_f32 v[24:25], v[24:25], v[28:29]
	v_mul_f32_e32 v28, 0xbfb8aa3b, v21
	v_exp_f32_e32 v35, v28
	s_nop 0
	v_pk_add_f32 v[28:29], v[34:35], 1.0 op_sel_hi:[1,0]
	s_nop 0
	s_nop 0
	v_rcp_f32_e32 v32, v29
	s_nop 0
	v_mul_f32_e32 v21, v21, v32
	s_nop 0
	v_rcp_f32_e32 v29, v28
	s_nop 0
	v_mul_f32_e32 v20, v20, v29
	v_pk_mul_f32 v[20:21], v[16:17], v[20:21]
	v_mul_f32_e32 v17, 0xbfb8aa3b, v22
	v_mul_f32_e32 v16, 0xbfb8aa3b, v30
	v_exp_f32_e32 v28, v17
	v_mul_f32_e32 v17, 0xbfb8aa3b, v31
	v_exp_f32_e32 v16, v16
	v_exp_f32_e32 v17, v17
	s_nop 0
	v_pk_add_f32 v[16:17], v[16:17], 1.0 op_sel_hi:[1,0]
	s_nop 0
	s_nop 0
	v_rcp_f32_e32 v29, v17
	s_nop 0
	v_mul_f32_e32 v17, v31, v29
	s_nop 0
	v_rcp_f32_e32 v29, v16
	s_nop 0
	v_mul_f32_e32 v16, v30, v29
	v_pk_mul_f32 v[26:27], v[26:27], v[16:17]
	v_mul_f32_e32 v16, 0xbfb8aa3b, v23
	v_exp_f32_e32 v29, v16
	s_nop 0
	v_pk_add_f32 v[16:17], v[28:29], 1.0 op_sel_hi:[1,0]
	s_nop 0
	s_nop 0
	v_rcp_f32_e32 v28, v17
	s_nop 0
	v_mul_f32_e32 v17, v23, v28
	s_nop 0
	v_rcp_f32_e32 v23, v16
	s_nop 0
	v_mul_f32_e32 v16, v22, v23
	v_add_u32_e32 v28, 0xa0, v146
	v_pk_mul_f32 v[22:23], v[18:19], v[16:17]
	v_cvt_pk_bf16_f32 v18, v20, v21
	v_mad_i64_i32 v[20:21], s[26:27], v28, s15, v[114:115]
	v_cvt_pk_bf16_f32 v16, v24, v25
	v_cvt_pk_bf16_f32 v17, v26, v27
	v_cvt_pk_bf16_f32 v19, v22, v23
	v_lshl_add_u64 v[20:21], v[20:21], 0, v[116:117]
	global_store_dwordx4 v[20:21], v[16:19], off
	s_nop 1
	v_mul_f32_e32 v17, 0xbfb8aa3b, v4
	v_mul_f32_e32 v16, 0xbfb8aa3b, v12
	v_exp_f32_e32 v18, v17
	v_mul_f32_e32 v17, 0xbfb8aa3b, v13
	v_exp_f32_e32 v16, v16
	v_exp_f32_e32 v17, v17
	s_nop 0
	v_pk_add_f32 v[16:17], v[16:17], 1.0 op_sel_hi:[1,0]
	s_nop 0
	s_nop 0
	v_rcp_f32_e32 v19, v17
	s_nop 0
	v_mul_f32_e32 v13, v13, v19
	s_nop 0
	v_rcp_f32_e32 v17, v16
	s_nop 0
	v_mul_f32_e32 v12, v12, v17
	v_pk_mul_f32 v[8:9], v[8:9], v[12:13]
	v_mul_f32_e32 v12, 0xbfb8aa3b, v5
	v_exp_f32_e32 v19, v12
	s_nop 0
	v_pk_add_f32 v[12:13], v[18:19], 1.0 op_sel_hi:[1,0]
	s_nop 0
	s_nop 0
	v_rcp_f32_e32 v16, v13
	s_nop 0
	v_mul_f32_e32 v5, v5, v16
	s_nop 0
	v_rcp_f32_e32 v13, v12
	s_nop 0
	v_mul_f32_e32 v4, v4, v13
	v_pk_mul_f32 v[4:5], v[0:1], v[4:5]
	v_mul_f32_e32 v1, 0xbfb8aa3b, v6
	v_mul_f32_e32 v0, 0xbfb8aa3b, v14
	v_exp_f32_e32 v12, v1
	v_mul_f32_e32 v1, 0xbfb8aa3b, v15
	v_exp_f32_e32 v0, v0
	v_exp_f32_e32 v1, v1
	s_nop 0
	v_pk_add_f32 v[0:1], v[0:1], 1.0 op_sel_hi:[1,0]
	s_nop 0
	s_nop 0
	v_rcp_f32_e32 v13, v1
	s_nop 0
	v_mul_f32_e32 v1, v15, v13
	s_nop 0
	v_rcp_f32_e32 v13, v0
	s_nop 0
	v_mul_f32_e32 v0, v14, v13
	v_pk_mul_f32 v[10:11], v[10:11], v[0:1]
	v_mul_f32_e32 v0, 0xbfb8aa3b, v7
	v_exp_f32_e32 v13, v0
	s_nop 0
	v_pk_add_f32 v[0:1], v[12:13], 1.0 op_sel_hi:[1,0]
	s_nop 0
	s_nop 0
	v_rcp_f32_e32 v12, v1
	s_nop 0
	v_mul_f32_e32 v1, v7, v12
	s_nop 0
	v_rcp_f32_e32 v7, v0
	s_nop 0
	v_mul_f32_e32 v0, v6, v7
	v_add_u32_e32 v12, 0xb0, v146
	v_pk_mul_f32 v[6:7], v[2:3], v[0:1]
	v_cvt_pk_bf16_f32 v2, v4, v5
	v_mad_i64_i32 v[4:5], s[26:27], v12, s15, v[114:115]
	v_cvt_pk_bf16_f32 v0, v8, v9
	v_cvt_pk_bf16_f32 v1, v10, v11
	v_cvt_pk_bf16_f32 v3, v6, v7
	v_lshl_add_u64 v[4:5], v[4:5], 0, v[116:117]
	s_and_b64 vcc, exec, s[0:1]
	s_mov_b64 s[26:27], s[18:19]
	global_store_dwordx4 v[4:5], v[0:3], off
	s_cbranch_vccz .LBB0_1353
	s_waitcnt vmcnt(0)
	s_cmpk_gt_u32 s5, 0xff
	s_cbranch_scc1 .LBB0_1360
	s_barrier
